# GEMM K-loops: load-segment scalar/vector address setup (non-m0) hoisted into the shadow of the same wave's preceding MFMA block; load segments now hold only m0 writes, LDS reads, LDS-DMA and waits
# speedup vs baseline: 1.0187x; 1.0088x over previous
; #define PG8_STAGE(bufoff, gbase, voff) do { _Pragma("unroll") for (int _i = 0; _i < 2; ++_i) \
;         __builtin_amdgcn_global_load_lds((const unsigned*)((const char*)(gbase) + (voff)[_i]), (LAS unsigned*)(lds + (bufoff) + ldsw + _i * 8192), 16, 0, 0); } while (0)
; #define PG8_LDA(dst, b, h) do { _Pragma("unroll") for (int m = 0; m < 4; ++m) _Pragma("unroll") for (int k = 0; k < 2; ++k) dst[m][k] = *(const LAS bf16x8*)(lds + PG8_SA(b, h) + aoff + m * 2048 + k * 1024); } while (0)
; #define PG8_LDB(dst, b, h) do { _Pragma("unroll") for (int n = 0; n < 2; ++n) _Pragma("unroll") for (int k = 0; k < 2; ++k) dst[n][k] = *(const LAS bf16x8*)(lds + PG8_SB(b, h) + boff + n * 2048 + k * 1024); } while (0)
; #define PG8_MMA(ai, bj, At, Bt) do { __builtin_amdgcn_s_setprio(1); _Pragma("unroll") for (int m = 0; m < 4; ++m) _Pragma("unroll") for (int n = 0; n < 2; ++n) _Pragma("unroll") for (int k = 0; k < 2; ++k) \
;         acc[ai][bj][m][n] = __builtin_amdgcn_mfma_f32_16x16x32_bf16(Bt[n][k], At[m][k], acc[ai][bj][m][n], 0, 0, 0); __builtin_amdgcn_s_setprio(0); } while (0)
; #define PG8_WAIT_V(n) asm volatile("s_waitcnt vmcnt(" #n ")" ::: "memory")
; #define PG8_WAIT_L(n) asm volatile("s_waitcnt lgkmcnt(" #n ")" ::: "memory")
; #define PG8_BAR __builtin_amdgcn_s_barrier()
; #define PG8_SCHED __builtin_amdgcn_sched_barrier(0)
; template <class Map, class Epi>
; DI void gemm_phase(LAS unsigned char* lds, const Map& MP, const Epi& E, const int nM, const int nN, const int K, const int lda, const int ldb) {
;     ...
;             PG8_LDB(B0, 0, 0); PG8_SCHED; PG8_LDA(At, 0, 0); PG8_STAGE(PG8_SA(1, 1), a1 + hstepA, voffA);
;             PG8_WAIT_L(8); PG8_BAR; PG8_WAIT_L(0); PG8_MMA(0, 0, At, B0); PG8_BAR; PG8_SCHED;
;             PG8_LDB(B1, 0, 1); PG8_STAGE(PG8_SB(0, 0), b2, voffB);
;             PG8_BAR; PG8_WAIT_L(0); PG8_MMA(0, 1, At, B1); PG8_BAR;
;             PG8_LDA(At, 0, 1); PG8_STAGE(PG8_SA(0, 0), a2, voffA);
;             PG8_BAR; PG8_WAIT_L(0); PG8_MMA(1, 0, At, B0); PG8_BAR; PG8_SCHED;
;             PG8_STAGE(PG8_SB(0, 1), b2 + hstepB, voffB);
;             PG8_WAIT_V(6); PG8_BAR; PG8_MMA(1, 1, At, B1); PG8_BAR;
;             PG8_LDB(B0, 1, 0); PG8_SCHED; PG8_LDA(At, 1, 0); PG8_STAGE(PG8_SA(0, 1), a2 + hstepA, voffA);
.LBB1_229:
	s_add_u32 s26, s24, 0xfff80080
	s_addc_u32 s27, s25, -1
	s_cmp_eq_u32 s57, 4
	s_cselect_b32 s29, s17, s27
	s_cselect_b32 s28, s43, s26
	s_cselect_b32 s27, s53, s56
	s_cselect_b32 s26, s54, s55
	s_add_i32 m0, s2, 0xc000
	ds_read_b128 v[160:163], v168
	ds_read_b128 v[170:173], v168 offset:1024
	ds_read_b128 v[174:177], v168 offset:2048
	ds_read_b128 v[178:181], v168 offset:3072
	ds_read_b128 v[182:185], v168 offset:4096
	ds_read_b128 v[186:189], v168 offset:5120
	ds_read_b128 v[190:193], v168 offset:6144
	ds_read_b128 v[198:201], v168 offset:7168
	global_load_lds_dwordx4 v154, s[24:25]
	s_add_i32 m0, s2, 0xe000
	s_nop 0
	global_load_lds_dwordx4 v152, s[24:25]
	s_waitcnt lgkmcnt(8)
	s_setprio 1
	s_barrier
	s_waitcnt lgkmcnt(7)
	v_mfma_f32_16x16x32_bf16 v[140:143], v[72:75], v[160:163], v[140:143]
	v_mfma_f32_16x16x32_bf16 v[136:139], v[80:83], v[160:163], v[136:139]
	s_waitcnt lgkmcnt(5)
	v_mfma_f32_16x16x32_bf16 v[124:127], v[72:75], v[174:177], v[124:127]
	v_mfma_f32_16x16x32_bf16 v[120:123], v[80:83], v[174:177], v[120:123]
	s_waitcnt lgkmcnt(3)
	v_mfma_f32_16x16x32_bf16 v[108:111], v[72:75], v[182:185], v[108:111]
	v_mfma_f32_16x16x32_bf16 v[104:107], v[80:83], v[182:185], v[104:107]
	s_waitcnt lgkmcnt(1)
	v_mfma_f32_16x16x32_bf16 v[92:95], v[72:75], v[190:193], v[92:95]
	v_mfma_f32_16x16x32_bf16 v[88:91], v[80:83], v[190:193], v[88:91]
	v_mfma_f32_16x16x32_bf16 v[140:143], v[76:79], v[170:173], v[140:143]
	s_add_i32 s58, s48, s34
	v_mfma_f32_16x16x32_bf16 v[136:139], v[84:87], v[170:173], v[136:139]
	v_lshl_add_u64 v[194:195], s[26:27], 0, v[148:149]
	v_mfma_f32_16x16x32_bf16 v[124:127], v[76:79], v[178:181], v[124:127]
	v_lshl_add_u64 v[218:219], s[26:27], 0, v[144:145]
	v_mfma_f32_16x16x32_bf16 v[120:123], v[84:87], v[178:181], v[120:123]
	v_mfma_f32_16x16x32_bf16 v[108:111], v[76:79], v[186:189], v[108:111]
	v_mfma_f32_16x16x32_bf16 v[104:107], v[84:87], v[186:189], v[104:107]
	s_waitcnt lgkmcnt(0)
	v_mfma_f32_16x16x32_bf16 v[92:95], v[76:79], v[198:201], v[92:95]
	v_mfma_f32_16x16x32_bf16 v[88:91], v[84:87], v[198:201], v[88:91]
	s_barrier
	s_setprio 0
	s_mov_b32 m0, s58
	ds_read_b128 v[202:205], v169
	ds_read_b128 v[206:209], v169 offset:1024
	ds_read_b128 v[210:213], v169 offset:2048
	ds_read_b128 v[214:217], v169 offset:3072
	global_load_lds_dwordx4 v[194:195], off
	s_add_i32 m0, s58, 0x2000
	s_nop 0
	global_load_lds_dwordx4 v[218:219], off
	s_setprio 1
	s_barrier
	s_waitcnt lgkmcnt(3)
	v_mfma_f32_16x16x32_bf16 v[132:135], v[202:205], v[160:163], v[132:135]
	s_waitcnt lgkmcnt(1)
	v_mfma_f32_16x16x32_bf16 v[128:131], v[210:213], v[160:163], v[128:131]
	v_mfma_f32_16x16x32_bf16 v[116:119], v[202:205], v[174:177], v[116:119]
	v_mfma_f32_16x16x32_bf16 v[112:115], v[210:213], v[174:177], v[112:115]
	v_mfma_f32_16x16x32_bf16 v[100:103], v[202:205], v[182:185], v[100:103]
	v_mfma_f32_16x16x32_bf16 v[96:99], v[210:213], v[182:185], v[96:99]
	v_mfma_f32_16x16x32_bf16 v[68:71], v[202:205], v[190:193], v[68:71]
	v_mfma_f32_16x16x32_bf16 v[64:67], v[210:213], v[190:193], v[64:67]
	v_mfma_f32_16x16x32_bf16 v[132:135], v[206:209], v[170:173], v[132:135]
	v_lshl_add_u64 v[222:223], s[28:29], 0, v[146:147]
	s_mov_b32 m0, s2
	s_waitcnt lgkmcnt(0)
	v_mfma_f32_16x16x32_bf16 v[128:131], v[214:217], v[170:173], v[128:131]
	v_lshl_add_u64 v[220:221], s[28:29], 0, v[150:151]
	v_mfma_f32_16x16x32_bf16 v[116:119], v[206:209], v[178:181], v[116:119]
	v_mfma_f32_16x16x32_bf16 v[112:115], v[214:217], v[178:181], v[112:115]
	v_mfma_f32_16x16x32_bf16 v[100:103], v[206:209], v[186:189], v[100:103]
	v_mfma_f32_16x16x32_bf16 v[96:99], v[214:217], v[186:189], v[96:99]
	v_mfma_f32_16x16x32_bf16 v[68:71], v[206:209], v[198:201], v[68:71]
	v_mfma_f32_16x16x32_bf16 v[64:67], v[214:217], v[198:201], v[64:67]
	s_barrier
	s_setprio 0
	ds_read_b128 v[160:163], v168 offset:16384
	ds_read_b128 v[170:173], v168 offset:17408
	ds_read_b128 v[174:177], v168 offset:18432
	ds_read_b128 v[178:181], v168 offset:19456
	ds_read_b128 v[182:185], v168 offset:20480
	ds_read_b128 v[186:189], v168 offset:21504
	ds_read_b128 v[190:193], v168 offset:22528
	ds_read_b128 v[198:201], v168 offset:23552
	global_load_lds_dwordx4 v[220:221], off
	s_mov_b32 m0, s4
	s_nop 0
	global_load_lds_dwordx4 v[222:223], off
	s_waitcnt vmcnt(10)
	s_setprio 1
	s_barrier
	s_waitcnt lgkmcnt(7)
	v_mfma_f32_16x16x32_bf16 v[60:63], v[72:75], v[160:163], v[60:63]
	v_mfma_f32_16x16x32_bf16 v[56:59], v[80:83], v[160:163], v[56:59]
	s_waitcnt lgkmcnt(5)
	v_mfma_f32_16x16x32_bf16 v[44:47], v[72:75], v[174:177], v[44:47]
	v_mfma_f32_16x16x32_bf16 v[40:43], v[80:83], v[174:177], v[40:43]
	s_waitcnt lgkmcnt(3)
	v_mfma_f32_16x16x32_bf16 v[28:31], v[72:75], v[182:185], v[28:31]
	v_mfma_f32_16x16x32_bf16 v[24:27], v[80:83], v[182:185], v[24:27]
	s_waitcnt lgkmcnt(1)
	v_mfma_f32_16x16x32_bf16 v[12:15], v[72:75], v[190:193], v[12:15]
	v_mfma_f32_16x16x32_bf16 v[8:11], v[80:83], v[190:193], v[8:11]
	v_mfma_f32_16x16x32_bf16 v[60:63], v[76:79], v[170:173], v[60:63]
	s_add_u32 s58, s26, 0x20000
	s_addc_u32 s59, s27, 0
	v_mfma_f32_16x16x32_bf16 v[56:59], v[84:87], v[170:173], v[56:59]
	s_add_i32 s60, s49, s34
	v_mfma_f32_16x16x32_bf16 v[44:47], v[76:79], v[178:181], v[44:47]
	v_mfma_f32_16x16x32_bf16 v[40:43], v[84:87], v[178:181], v[40:43]
	v_mfma_f32_16x16x32_bf16 v[28:31], v[76:79], v[186:189], v[28:31]
	v_mfma_f32_16x16x32_bf16 v[24:27], v[84:87], v[186:189], v[24:27]
	s_waitcnt lgkmcnt(0)
	v_mfma_f32_16x16x32_bf16 v[12:15], v[76:79], v[198:201], v[12:15]
	v_mfma_f32_16x16x32_bf16 v[8:11], v[84:87], v[198:201], v[8:11]
	s_barrier
; #define PG8_STAGE(bufoff, gbase, voff) do { _Pragma("unroll") for (int _i = 0; _i < 2; ++_i) \
;         __builtin_amdgcn_global_load_lds((const unsigned*)((const char*)(gbase) + (voff)[_i]), (LAS unsigned*)(lds + (bufoff) + ldsw + _i * 8192), 16, 0, 0); } while (0)
; #define PG8_LDA(dst, b, h) do { _Pragma("unroll") for (int m = 0; m < 4; ++m) _Pragma("unroll") for (int k = 0; k < 2; ++k) dst[m][k] = *(const LAS bf16x8*)(lds + PG8_SA(b, h) + aoff + m * 2048 + k * 1024); } while (0)
; #define PG8_LDB(dst, b, h) do { _Pragma("unroll") for (int n = 0; n < 2; ++n) _Pragma("unroll") for (int k = 0; k < 2; ++k) dst[n][k] = *(const LAS bf16x8*)(lds + PG8_SB(b, h) + boff + n * 2048 + k * 1024); } while (0)
; #define PG8_MMA(ai, bj, At, Bt) do { __builtin_amdgcn_s_setprio(1); _Pragma("unroll") for (int m = 0; m < 4; ++m) _Pragma("unroll") for (int n = 0; n < 2; ++n) _Pragma("unroll") for (int k = 0; k < 2; ++k) \
;         acc[ai][bj][m][n] = __builtin_amdgcn_mfma_f32_16x16x32_bf16(Bt[n][k], At[m][k], acc[ai][bj][m][n], 0, 0, 0); __builtin_amdgcn_s_setprio(0); } while (0)
; #define PG8_WAIT_V(n) asm volatile("s_waitcnt vmcnt(" #n ")" ::: "memory")
; #define PG8_WAIT_L(n) asm volatile("s_waitcnt lgkmcnt(" #n ")" ::: "memory")
; #define PG8_BAR __builtin_amdgcn_s_barrier()
; #define PG8_SCHED __builtin_amdgcn_sched_barrier(0)
; template <class Map, class Epi>
; DI void gemm_phase(LAS unsigned char* lds, const Map& MP, const Epi& E, const int nM, const int nN, const int K, const int lda, const int ldb) {
;     ...
;             PG8_BAR; PG8_WAIT_L(0); PG8_MMA(1, 0, At, B0); PG8_BAR; PG8_SCHED;
;             PG8_STAGE(PG8_SB(0, 1), b2 + hstepB, voffB);
;             PG8_WAIT_V(6); PG8_BAR; PG8_MMA(1, 1, At, B1); PG8_BAR;
;             PG8_LDB(B0, 1, 0); PG8_SCHED; PG8_LDA(At, 1, 0); PG8_STAGE(PG8_SA(0, 1), a2 + hstepA, voffA);
;             PG8_WAIT_L(8); PG8_BAR; PG8_WAIT_L(0); PG8_MMA(0, 0, At, B0); PG8_BAR; PG8_SCHED;
;             PG8_LDB(B1, 1, 1); PG8_STAGE(PG8_SB(1, 0), b3, voffB);
;             PG8_BAR; PG8_WAIT_L(0); PG8_MMA(0, 1, At, B1); PG8_BAR;
;             PG8_LDA(At, 1, 1); PG8_STAGE(PG8_SA(1, 0), a3, voffA);
	s_setprio 0
	s_mov_b32 m0, s60
	s_nop 0
	global_load_lds_dwordx4 v148, s[58:59]
	s_add_i32 m0, s60, 0x2000
	s_nop 0
	global_load_lds_dwordx4 v144, s[58:59]
	s_waitcnt vmcnt(6)
	s_setprio 1
	s_barrier
	v_mfma_f32_16x16x32_bf16 v[52:55], v[202:205], v[160:163], v[52:55]
	v_mfma_f32_16x16x32_bf16 v[48:51], v[210:213], v[160:163], v[48:51]
	s_add_i32 s58, 0, 0x18000
	v_add_u32_e32 v84, s58, v166
	ds_read_b128 v[72:75], v84
	v_mfma_f32_16x16x32_bf16 v[36:39], v[202:205], v[174:177], v[36:39]
	v_mfma_f32_16x16x32_bf16 v[32:35], v[210:213], v[174:177], v[32:35]
	ds_read_b128 v[76:79], v84 offset:1024
	v_mfma_f32_16x16x32_bf16 v[20:23], v[202:205], v[182:185], v[20:23]
	v_mfma_f32_16x16x32_bf16 v[16:19], v[210:213], v[182:185], v[16:19]
	ds_read_b128 v[80:83], v84 offset:2048
	v_mfma_f32_16x16x32_bf16 v[4:7], v[202:205], v[190:193], v[4:7]
	v_mfma_f32_16x16x32_bf16 v[0:3], v[210:213], v[190:193], v[0:3]
	ds_read_b128 v[84:87], v84 offset:3072
	v_mfma_f32_16x16x32_bf16 v[52:55], v[206:209], v[170:173], v[52:55]
	s_add_u32 s28, s28, 0x80000
	s_addc_u32 s29, s29, 0
	v_mfma_f32_16x16x32_bf16 v[48:51], v[214:217], v[170:173], v[48:51]
	v_mfma_f32_16x16x32_bf16 v[36:39], v[206:209], v[178:181], v[36:39]
	v_mfma_f32_16x16x32_bf16 v[32:35], v[214:217], v[178:181], v[32:35]
	v_mfma_f32_16x16x32_bf16 v[20:23], v[206:209], v[186:189], v[20:23]
	v_mfma_f32_16x16x32_bf16 v[16:19], v[214:217], v[186:189], v[16:19]
	v_mfma_f32_16x16x32_bf16 v[4:7], v[206:209], v[198:201], v[4:7]
	v_mfma_f32_16x16x32_bf16 v[0:3], v[214:217], v[198:201], v[0:3]
	s_barrier
	s_setprio 0
	s_mov_b32 m0, s5
	ds_read_b128 v[160:163], v168 offset:32768
	ds_read_b128 v[170:173], v168 offset:33792
	ds_read_b128 v[174:177], v168 offset:34816
	ds_read_b128 v[178:181], v168 offset:35840
	ds_read_b128 v[182:185], v168 offset:36864
	ds_read_b128 v[186:189], v168 offset:37888
	ds_read_b128 v[190:193], v168 offset:38912
	ds_read_b128 v[198:201], v168 offset:39936
	global_load_lds_dwordx4 v150, s[28:29]
	s_mov_b32 m0, s23
	s_nop 0
	global_load_lds_dwordx4 v146, s[28:29]
	s_waitcnt lgkmcnt(8)
	s_setprio 1
	s_barrier
	s_waitcnt lgkmcnt(7)
	v_mfma_f32_16x16x32_bf16 v[140:143], v[72:75], v[160:163], v[140:143]
	v_mfma_f32_16x16x32_bf16 v[136:139], v[80:83], v[160:163], v[136:139]
	s_waitcnt lgkmcnt(5)
	v_mfma_f32_16x16x32_bf16 v[124:127], v[72:75], v[174:177], v[124:127]
	v_mfma_f32_16x16x32_bf16 v[120:123], v[80:83], v[174:177], v[120:123]
	s_waitcnt lgkmcnt(3)
	v_mfma_f32_16x16x32_bf16 v[108:111], v[72:75], v[182:185], v[108:111]
	v_mfma_f32_16x16x32_bf16 v[104:107], v[80:83], v[182:185], v[104:107]
	s_waitcnt lgkmcnt(1)
	v_mfma_f32_16x16x32_bf16 v[92:95], v[72:75], v[190:193], v[92:95]
	v_mfma_f32_16x16x32_bf16 v[88:91], v[80:83], v[190:193], v[88:91]
	v_mfma_f32_16x16x32_bf16 v[140:143], v[76:79], v[170:173], v[140:143]
	s_add_i32 s28, 0, 0x1c000
	v_mfma_f32_16x16x32_bf16 v[136:139], v[84:87], v[170:173], v[136:139]
	s_add_i32 s29, s58, s34
	v_mfma_f32_16x16x32_bf16 v[124:127], v[76:79], v[178:181], v[124:127]
	v_add_u32_e32 v196, s28, v166
	v_mfma_f32_16x16x32_bf16 v[120:123], v[84:87], v[178:181], v[120:123]
	v_lshl_add_u64 v[194:195], v[194:195], 0, s[12:13]
	v_mfma_f32_16x16x32_bf16 v[108:111], v[76:79], v[186:189], v[108:111]
	v_mfma_f32_16x16x32_bf16 v[104:107], v[84:87], v[186:189], v[104:107]
	s_waitcnt lgkmcnt(0)
	v_mfma_f32_16x16x32_bf16 v[92:95], v[76:79], v[198:201], v[92:95]
	v_mfma_f32_16x16x32_bf16 v[88:91], v[84:87], v[198:201], v[88:91]
	s_barrier
	s_setprio 0
	s_mov_b32 m0, s29
	ds_read_b128 v[202:205], v196
	ds_read_b128 v[206:209], v196 offset:1024
	ds_read_b128 v[210:213], v196 offset:2048
	ds_read_b128 v[214:217], v196 offset:3072
	global_load_lds_dwordx4 v[194:195], off
	v_lshl_add_u64 v[194:195], v[218:219], 0, s[12:13]
	s_add_i32 m0, s29, 0x2000
	s_nop 0
	global_load_lds_dwordx4 v[194:195], off
	s_setprio 1
	s_barrier
	s_waitcnt lgkmcnt(3)
	v_mfma_f32_16x16x32_bf16 v[132:135], v[202:205], v[160:163], v[132:135]
	s_waitcnt lgkmcnt(1)
	v_mfma_f32_16x16x32_bf16 v[128:131], v[210:213], v[160:163], v[128:131]
	v_mfma_f32_16x16x32_bf16 v[116:119], v[202:205], v[174:177], v[116:119]
	v_mfma_f32_16x16x32_bf16 v[112:115], v[210:213], v[174:177], v[112:115]
	v_mfma_f32_16x16x32_bf16 v[100:103], v[202:205], v[182:185], v[100:103]
	v_mfma_f32_16x16x32_bf16 v[96:99], v[210:213], v[182:185], v[96:99]
	v_mfma_f32_16x16x32_bf16 v[68:71], v[202:205], v[190:193], v[68:71]
	v_mfma_f32_16x16x32_bf16 v[64:67], v[210:213], v[190:193], v[64:67]
	v_mfma_f32_16x16x32_bf16 v[132:135], v[206:209], v[170:173], v[132:135]
	s_mov_b32 m0, s39
	s_waitcnt lgkmcnt(0)
	v_mfma_f32_16x16x32_bf16 v[128:131], v[214:217], v[170:173], v[128:131]
	v_lshl_add_u64 v[194:195], v[220:221], 0, s[12:13]
	v_mfma_f32_16x16x32_bf16 v[116:119], v[206:209], v[178:181], v[116:119]
	v_mfma_f32_16x16x32_bf16 v[112:115], v[214:217], v[178:181], v[112:115]
	v_mfma_f32_16x16x32_bf16 v[100:103], v[206:209], v[186:189], v[100:103]
	v_mfma_f32_16x16x32_bf16 v[96:99], v[214:217], v[186:189], v[96:99]
	v_mfma_f32_16x16x32_bf16 v[68:71], v[206:209], v[198:201], v[68:71]
	v_mfma_f32_16x16x32_bf16 v[64:67], v[214:217], v[198:201], v[64:67]
	s_barrier
; #define PG8_STAGE(bufoff, gbase, voff) do { _Pragma("unroll") for (int _i = 0; _i < 2; ++_i) \
;         __builtin_amdgcn_global_load_lds((const unsigned*)((const char*)(gbase) + (voff)[_i]), (LAS unsigned*)(lds + (bufoff) + ldsw + _i * 8192), 16, 0, 0); } while (0)
; #define PG8_LDA(dst, b, h) do { _Pragma("unroll") for (int m = 0; m < 4; ++m) _Pragma("unroll") for (int k = 0; k < 2; ++k) dst[m][k] = *(const LAS bf16x8*)(lds + PG8_SA(b, h) + aoff + m * 2048 + k * 1024); } while (0)
; #define PG8_MMA(ai, bj, At, Bt) do { __builtin_amdgcn_s_setprio(1); _Pragma("unroll") for (int m = 0; m < 4; ++m) _Pragma("unroll") for (int n = 0; n < 2; ++n) _Pragma("unroll") for (int k = 0; k < 2; ++k) \
;         acc[ai][bj][m][n] = __builtin_amdgcn_mfma_f32_16x16x32_bf16(Bt[n][k], At[m][k], acc[ai][bj][m][n], 0, 0, 0); __builtin_amdgcn_s_setprio(0); } while (0)
; #define PG8_WAIT_V(n) asm volatile("s_waitcnt vmcnt(" #n ")" ::: "memory")
; #define PG8_WAIT_L(n) asm volatile("s_waitcnt lgkmcnt(" #n ")" ::: "memory")
; #define PG8_BAR __builtin_amdgcn_s_barrier()
; #define PG8_SCHED __builtin_amdgcn_sched_barrier(0)
;     DI void operator()(const f32x4 (&acc)[2][2][4][2], const Unit& u, int wr, int wc, int fr, int fq) const {
;         const int row0 = u.pm * BM + wr * 64 + fr, col0 = u.pn * BM + wc * 32 + 8 * fq;
;         f32x4 sc[2][2];
; #pragma unroll
;         for (int bj = 0; bj < 2; ++bj)
; #pragma unroll
;             for (int n = 0; n < 2; ++n) sc[bj][n] = scale ? *(const f32x4*)(scale + col0 + bj * HALF + 4 * n) : (f32x4){1.f, 1.f, 1.f, 1.f};
; template <class Map, class Epi>
; DI void gemm_phase(LAS unsigned char* lds, const Map& MP, const Epi& E, const int nM, const int nN, const int K, const int lda, const int ldb) {
;     ...
;             PG8_LDA(At, 1, 1); PG8_STAGE(PG8_SA(1, 0), a3, voffA);
;             PG8_BAR; PG8_WAIT_L(0); PG8_MMA(1, 0, At, B0); PG8_BAR; PG8_SCHED;
;             PG8_STAGE(PG8_SB(1, 1), b3 + hstepB, voffB);
;             PG8_WAIT_V(6); PG8_BAR; PG8_MMA(1, 1, At, B1); PG8_BAR;
	s_setprio 0
	ds_read_b128 v[160:163], v168 offset:49152
	ds_read_b128 v[170:173], v168 offset:50176
	ds_read_b128 v[174:177], v168 offset:51200
	ds_read_b128 v[178:181], v168 offset:52224
	ds_read_b128 v[182:185], v168 offset:53248
	ds_read_b128 v[186:189], v168 offset:54272
	ds_read_b128 v[190:193], v168 offset:55296
	ds_read_b128 v[198:201], v168 offset:56320
	global_load_lds_dwordx4 v[194:195], off
	v_lshl_add_u64 v[194:195], v[222:223], 0, s[12:13]
	s_mov_b32 m0, s46
	s_nop 0
	global_load_lds_dwordx4 v[194:195], off
	s_waitcnt vmcnt(10)
	s_setprio 1
	s_barrier
	s_waitcnt lgkmcnt(7)
	v_mfma_f32_16x16x32_bf16 v[60:63], v[72:75], v[160:163], v[60:63]
	v_mfma_f32_16x16x32_bf16 v[56:59], v[80:83], v[160:163], v[56:59]
	s_waitcnt lgkmcnt(5)
	v_mfma_f32_16x16x32_bf16 v[44:47], v[72:75], v[174:177], v[44:47]
	v_mfma_f32_16x16x32_bf16 v[40:43], v[80:83], v[174:177], v[40:43]
	s_waitcnt lgkmcnt(3)
	v_mfma_f32_16x16x32_bf16 v[28:31], v[72:75], v[182:185], v[28:31]
	v_mfma_f32_16x16x32_bf16 v[24:27], v[80:83], v[182:185], v[24:27]
	s_waitcnt lgkmcnt(1)
	v_mfma_f32_16x16x32_bf16 v[12:15], v[72:75], v[190:193], v[12:15]
	v_mfma_f32_16x16x32_bf16 v[8:11], v[80:83], v[190:193], v[8:11]
	v_mfma_f32_16x16x32_bf16 v[60:63], v[76:79], v[170:173], v[60:63]
	s_add_u32 s26, s26, 0x20080
	s_addc_u32 s27, s27, 0
	v_mfma_f32_16x16x32_bf16 v[56:59], v[84:87], v[170:173], v[56:59]
	s_add_i32 s28, s28, s34
	v_mfma_f32_16x16x32_bf16 v[44:47], v[76:79], v[178:181], v[44:47]
	v_mfma_f32_16x16x32_bf16 v[40:43], v[84:87], v[178:181], v[40:43]
	v_mfma_f32_16x16x32_bf16 v[28:31], v[76:79], v[186:189], v[28:31]
	v_mfma_f32_16x16x32_bf16 v[24:27], v[84:87], v[186:189], v[24:27]
	s_waitcnt lgkmcnt(0)
	v_mfma_f32_16x16x32_bf16 v[12:15], v[76:79], v[198:201], v[12:15]
	v_mfma_f32_16x16x32_bf16 v[8:11], v[84:87], v[198:201], v[8:11]
	s_barrier
	s_setprio 0
	s_mov_b32 m0, s28
	s_nop 0
	global_load_lds_dwordx4 v148, s[26:27]
	s_add_i32 m0, s28, 0x2000
	s_nop 0
	global_load_lds_dwordx4 v144, s[26:27]
	s_waitcnt vmcnt(6)
	s_setprio 1
	s_barrier
	v_mfma_f32_16x16x32_bf16 v[52:55], v[202:205], v[160:163], v[52:55]
	v_mfma_f32_16x16x32_bf16 v[48:51], v[210:213], v[160:163], v[48:51]
	ds_read_b128 v[72:75], v167
	v_mfma_f32_16x16x32_bf16 v[36:39], v[202:205], v[174:177], v[36:39]
	v_mfma_f32_16x16x32_bf16 v[32:35], v[210:213], v[174:177], v[32:35]
	ds_read_b128 v[76:79], v167 offset:1024
	v_mfma_f32_16x16x32_bf16 v[20:23], v[202:205], v[182:185], v[20:23]
	v_mfma_f32_16x16x32_bf16 v[16:19], v[210:213], v[182:185], v[16:19]
	ds_read_b128 v[80:83], v167 offset:2048
	v_mfma_f32_16x16x32_bf16 v[4:7], v[202:205], v[190:193], v[4:7]
	v_mfma_f32_16x16x32_bf16 v[0:3], v[210:213], v[190:193], v[0:3]
	ds_read_b128 v[84:87], v167 offset:3072
	v_mfma_f32_16x16x32_bf16 v[52:55], v[206:209], v[170:173], v[52:55]
	s_add_i32 s57, s57, 2
	v_mfma_f32_16x16x32_bf16 v[48:51], v[214:217], v[170:173], v[48:51]
	s_add_u32 s55, s55, 0x100
	s_addc_u32 s56, s56, 0
	v_mfma_f32_16x16x32_bf16 v[36:39], v[206:209], v[178:181], v[36:39]
	s_add_u32 s24, s24, 0x100
	s_addc_u32 s25, s25, 0
	v_mfma_f32_16x16x32_bf16 v[32:35], v[214:217], v[178:181], v[32:35]
	s_cmp_gt_u32 s57, 5
	v_mfma_f32_16x16x32_bf16 v[20:23], v[206:209], v[186:189], v[20:23]
	v_mfma_f32_16x16x32_bf16 v[16:19], v[214:217], v[186:189], v[16:19]
	v_mfma_f32_16x16x32_bf16 v[4:7], v[206:209], v[198:201], v[4:7]
	v_mfma_f32_16x16x32_bf16 v[0:3], v[214:217], v[198:201], v[0:3]
	s_barrier
	s_setprio 0
	s_cbranch_scc0 .LBB1_229
	s_waitcnt lgkmcnt(0)
	s_lshl_b32 s17, s42, 8
	v_mov_b32_e32 v170, v164
	v_mov_b32_e32 v72, v165
	s_or_b32 s17, s17, s38
	v_mov_b32_e32 v80, 1.0
	v_lshl_add_u32 v160, v72, 3, s17
	v_ashrrev_i32_e32 v161, 31, v160
	v_cndmask_b32_e64 v72, 0, 1, s[14:15]
	v_lshl_add_u64 v[162:163], v[160:161], 2, s[8:9]
	v_cmp_ne_u32_e64 s[42:43], 1, v72
	s_andn2_b64 vcc, exec, s[14:15]
	v_mov_b32_e32 v84, 1.0
	v_mov_b32_e32 v85, 1.0
	v_mov_b32_e32 v86, 1.0
	v_mov_b32_e32 v87, 1.0
	s_cbranch_vccnz .LBB1_232
	global_load_dwordx4 v[84:87], v[162:163], off

; #define PG8_STAGE(bufoff, gbase, voff) do { _Pragma("unroll") for (int _i = 0; _i < 2; ++_i) \
;         __builtin_amdgcn_global_load_lds((const unsigned*)((const char*)(gbase) + (voff)[_i]), (LAS unsigned*)(lds + (bufoff) + ldsw + _i * 8192), 16, 0, 0); } while (0)
; #define PG8_LDA(dst, b, h) do { _Pragma("unroll") for (int m = 0; m < 4; ++m) _Pragma("unroll") for (int k = 0; k < 2; ++k) dst[m][k] = *(const LAS bf16x8*)(lds + PG8_SA(b, h) + aoff + m * 2048 + k * 1024); } while (0)
; #define PG8_LDB(dst, b, h) do { _Pragma("unroll") for (int n = 0; n < 2; ++n) _Pragma("unroll") for (int k = 0; k < 2; ++k) dst[n][k] = *(const LAS bf16x8*)(lds + PG8_SB(b, h) + boff + n * 2048 + k * 1024); } while (0)
; #define PG8_MMA(ai, bj, At, Bt) do { __builtin_amdgcn_s_setprio(1); _Pragma("unroll") for (int m = 0; m < 4; ++m) _Pragma("unroll") for (int n = 0; n < 2; ++n) _Pragma("unroll") for (int k = 0; k < 2; ++k) \
;         acc[ai][bj][m][n] = __builtin_amdgcn_mfma_f32_16x16x32_bf16(Bt[n][k], At[m][k], acc[ai][bj][m][n], 0, 0, 0); __builtin_amdgcn_s_setprio(0); } while (0)
; #define PG8_WAIT_V(n) asm volatile("s_waitcnt vmcnt(" #n ")" ::: "memory")
; #define PG8_WAIT_L(n) asm volatile("s_waitcnt lgkmcnt(" #n ")" ::: "memory")
; #define PG8_BAR __builtin_amdgcn_s_barrier()
; #define PG8_SCHED __builtin_amdgcn_sched_barrier(0)
; template <class Map, class Epi>
; DI void gemm_phase(LAS unsigned char* lds, const Map& MP, const Epi& E, const int nM, const int nN, const int K, const int lda, const int ldb) {
;     ...
;             PG8_LDB(B0, 0, 0); PG8_SCHED; PG8_LDA(At, 0, 0); PG8_STAGE(PG8_SA(1, 1), a1 + hstepA, voffA);
;             PG8_WAIT_L(8); PG8_BAR; PG8_WAIT_L(0); PG8_MMA(0, 0, At, B0); PG8_BAR; PG8_SCHED;
;             PG8_LDB(B1, 0, 1); PG8_STAGE(PG8_SB(0, 0), b2, voffB);
;             PG8_BAR; PG8_WAIT_L(0); PG8_MMA(0, 1, At, B1); PG8_BAR;
;             PG8_LDA(At, 0, 1); PG8_STAGE(PG8_SA(0, 0), a2, voffA);
;             PG8_BAR; PG8_WAIT_L(0); PG8_MMA(1, 0, At, B0); PG8_BAR; PG8_SCHED;
;             PG8_STAGE(PG8_SB(0, 1), b2 + hstepB, voffB);
;             PG8_WAIT_V(6); PG8_BAR; PG8_MMA(1, 1, At, B1); PG8_BAR;
;             PG8_LDB(B0, 1, 0); PG8_SCHED; PG8_LDA(At, 1, 0); PG8_STAGE(PG8_SA(0, 1), a2 + hstepA, voffA);
.LBB1_380:
	s_add_u32 s28, s44, 0xfff80080
	s_addc_u32 s29, s45, -1
	s_cmp_eq_u32 vcc_hi, 28
	s_cselect_b32 s47, s23, s29
	s_cselect_b32 s46, s61, s28
	s_cselect_b32 s29, s21, vcc_lo
	s_cselect_b32 s28, s58, s59
	s_add_i32 m0, s38, 0xc000
	ds_read_b128 v[96:99], v190
	ds_read_b128 v[100:103], v190 offset:1024
	ds_read_b128 v[108:111], v190 offset:2048
	ds_read_b128 v[112:115], v190 offset:3072
	ds_read_b128 v[160:163], v190 offset:4096
	ds_read_b128 v[164:167], v190 offset:5120
	ds_read_b128 v[198:201], v190 offset:6144
	ds_read_b128 v[202:205], v190 offset:7168
	global_load_lds_dwordx4 v178, s[44:45]
	s_add_i32 m0, s38, 0xe000
	s_nop 0
	global_load_lds_dwordx4 v176, s[44:45]
	s_waitcnt lgkmcnt(8)
	s_setprio 1
	s_barrier
	s_waitcnt lgkmcnt(7)
	v_mfma_f32_16x16x32_bf16 v[148:151], v[80:83], v[96:99], v[148:151]
	v_mfma_f32_16x16x32_bf16 v[144:147], v[88:91], v[96:99], v[144:147]
	s_waitcnt lgkmcnt(5)
	v_mfma_f32_16x16x32_bf16 v[136:139], v[80:83], v[108:111], v[136:139]
	v_mfma_f32_16x16x32_bf16 v[128:131], v[88:91], v[108:111], v[128:131]
	s_waitcnt lgkmcnt(3)
	v_mfma_f32_16x16x32_bf16 v[120:123], v[80:83], v[160:163], v[120:123]
	v_mfma_f32_16x16x32_bf16 v[104:107], v[88:91], v[160:163], v[104:107]
	s_waitcnt lgkmcnt(1)
	v_mfma_f32_16x16x32_bf16 v[76:79], v[80:83], v[198:201], v[76:79]
	v_mfma_f32_16x16x32_bf16 v[72:75], v[88:91], v[198:201], v[72:75]
	v_mfma_f32_16x16x32_bf16 v[148:151], v[84:87], v[100:103], v[148:151]
	s_add_i32 s68, s5, s37
	v_mfma_f32_16x16x32_bf16 v[144:147], v[92:95], v[100:103], v[144:147]
	v_lshl_add_u64 v[184:185], s[28:29], 0, v[172:173]
	v_mfma_f32_16x16x32_bf16 v[136:139], v[84:87], v[112:115], v[136:139]
	v_lshl_add_u64 v[194:195], s[28:29], 0, v[168:169]
	v_mfma_f32_16x16x32_bf16 v[128:131], v[92:95], v[112:115], v[128:131]
	v_mfma_f32_16x16x32_bf16 v[120:123], v[84:87], v[164:167], v[120:123]
	v_mfma_f32_16x16x32_bf16 v[104:107], v[92:95], v[164:167], v[104:107]
	s_waitcnt lgkmcnt(0)
	v_mfma_f32_16x16x32_bf16 v[76:79], v[84:87], v[202:205], v[76:79]
	v_mfma_f32_16x16x32_bf16 v[72:75], v[92:95], v[202:205], v[72:75]
	s_barrier
	s_setprio 0
	s_mov_b32 m0, s68
	ds_read_b128 v[206:209], v191
	ds_read_b128 v[210:213], v191 offset:1024
	ds_read_b128 v[214:217], v191 offset:2048
	ds_read_b128 v[218:221], v191 offset:3072
	global_load_lds_dwordx4 v[184:185], off
	s_add_i32 m0, s68, 0x2000
	s_nop 0
	global_load_lds_dwordx4 v[194:195], off
	s_setprio 1
	s_barrier
	s_waitcnt lgkmcnt(3)
	v_mfma_f32_16x16x32_bf16 v[156:159], v[206:209], v[96:99], v[156:159]
	s_waitcnt lgkmcnt(1)
	v_mfma_f32_16x16x32_bf16 v[96:99], v[214:217], v[96:99], v[152:155]
	v_mfma_f32_16x16x32_bf16 v[156:159], v[210:213], v[100:103], v[156:159]
	s_waitcnt lgkmcnt(0)
	v_mfma_f32_16x16x32_bf16 v[96:99], v[218:221], v[100:103], v[96:99]
	v_mfma_f32_16x16x32_bf16 v[100:103], v[206:209], v[108:111], v[140:143]
	v_mfma_f32_16x16x32_bf16 v[108:111], v[214:217], v[108:111], v[132:135]
	v_mfma_f32_16x16x32_bf16 v[116:119], v[214:217], v[160:163], v[116:119]
	v_mfma_f32_16x16x32_bf16 v[68:71], v[206:209], v[198:201], v[68:71]
	v_mfma_f32_16x16x32_bf16 v[64:67], v[214:217], v[198:201], v[64:67]
	v_lshl_add_u64 v[234:235], s[46:47], 0, v[170:171]
	s_mov_b32 m0, s38
	v_mfma_f32_16x16x32_bf16 v[100:103], v[210:213], v[112:115], v[100:103]
	v_lshl_add_u64 v[226:227], s[46:47], 0, v[174:175]
	v_mfma_f32_16x16x32_bf16 v[108:111], v[218:221], v[112:115], v[108:111]
	v_mfma_f32_16x16x32_bf16 v[112:115], v[206:209], v[160:163], v[124:127]
	v_mfma_f32_16x16x32_bf16 v[116:119], v[218:221], v[164:167], v[116:119]
	v_mfma_f32_16x16x32_bf16 v[68:71], v[210:213], v[202:205], v[68:71]
	v_mfma_f32_16x16x32_bf16 v[64:67], v[218:221], v[202:205], v[64:67]
	v_mfma_f32_16x16x32_bf16 v[112:115], v[210:213], v[164:167], v[112:115]
	s_barrier
	s_setprio 0
	ds_read_b128 v[124:127], v190 offset:16384
	ds_read_b128 v[132:135], v190 offset:17408
	ds_read_b128 v[140:143], v190 offset:18432
	ds_read_b128 v[152:155], v190 offset:19456
	ds_read_b128 v[160:163], v190 offset:20480
	ds_read_b128 v[164:167], v190 offset:21504
	ds_read_b128 v[198:201], v190 offset:22528
	ds_read_b128 v[202:205], v190 offset:23552
	global_load_lds_dwordx4 v[226:227], off
	s_mov_b32 m0, s39
	s_nop 0
	global_load_lds_dwordx4 v[234:235], off
	s_waitcnt vmcnt(10)
	s_setprio 1
	s_barrier
	s_waitcnt lgkmcnt(7)
	v_mfma_f32_16x16x32_bf16 v[60:63], v[80:83], v[124:127], v[60:63]
	v_mfma_f32_16x16x32_bf16 v[48:51], v[88:91], v[124:127], v[48:51]
	s_waitcnt lgkmcnt(5)
	v_mfma_f32_16x16x32_bf16 v[40:43], v[80:83], v[140:143], v[40:43]
	v_mfma_f32_16x16x32_bf16 v[32:35], v[88:91], v[140:143], v[32:35]
	s_waitcnt lgkmcnt(3)
	v_mfma_f32_16x16x32_bf16 v[24:27], v[80:83], v[160:163], v[24:27]
	v_mfma_f32_16x16x32_bf16 v[16:19], v[88:91], v[160:163], v[16:19]
	s_waitcnt lgkmcnt(1)
	v_mfma_f32_16x16x32_bf16 v[12:15], v[80:83], v[198:201], v[12:15]
	v_mfma_f32_16x16x32_bf16 v[8:11], v[88:91], v[198:201], v[8:11]
	v_mfma_f32_16x16x32_bf16 v[60:63], v[84:87], v[132:135], v[60:63]
	s_add_u32 s68, s28, 0x80000
	s_addc_u32 s69, s29, 0
	v_mfma_f32_16x16x32_bf16 v[48:51], v[92:95], v[132:135], v[48:51]
	s_add_i32 s70, s2, s37
	v_mfma_f32_16x16x32_bf16 v[40:43], v[84:87], v[152:155], v[40:43]
	v_mfma_f32_16x16x32_bf16 v[32:35], v[92:95], v[152:155], v[32:35]
	v_mfma_f32_16x16x32_bf16 v[24:27], v[84:87], v[164:167], v[24:27]
	v_mfma_f32_16x16x32_bf16 v[16:19], v[92:95], v[164:167], v[16:19]
	s_waitcnt lgkmcnt(0)
	v_mfma_f32_16x16x32_bf16 v[12:15], v[84:87], v[202:205], v[12:15]
	v_mfma_f32_16x16x32_bf16 v[8:11], v[92:95], v[202:205], v[8:11]
	s_barrier
; #define PG8_STAGE(bufoff, gbase, voff) do { _Pragma("unroll") for (int _i = 0; _i < 2; ++_i) \
;         __builtin_amdgcn_global_load_lds((const unsigned*)((const char*)(gbase) + (voff)[_i]), (LAS unsigned*)(lds + (bufoff) + ldsw + _i * 8192), 16, 0, 0); } while (0)
; #define PG8_LDA(dst, b, h) do { _Pragma("unroll") for (int m = 0; m < 4; ++m) _Pragma("unroll") for (int k = 0; k < 2; ++k) dst[m][k] = *(const LAS bf16x8*)(lds + PG8_SA(b, h) + aoff + m * 2048 + k * 1024); } while (0)
; #define PG8_LDB(dst, b, h) do { _Pragma("unroll") for (int n = 0; n < 2; ++n) _Pragma("unroll") for (int k = 0; k < 2; ++k) dst[n][k] = *(const LAS bf16x8*)(lds + PG8_SB(b, h) + boff + n * 2048 + k * 1024); } while (0)
; #define PG8_MMA(ai, bj, At, Bt) do { __builtin_amdgcn_s_setprio(1); _Pragma("unroll") for (int m = 0; m < 4; ++m) _Pragma("unroll") for (int n = 0; n < 2; ++n) _Pragma("unroll") for (int k = 0; k < 2; ++k) \
;         acc[ai][bj][m][n] = __builtin_amdgcn_mfma_f32_16x16x32_bf16(Bt[n][k], At[m][k], acc[ai][bj][m][n], 0, 0, 0); __builtin_amdgcn_s_setprio(0); } while (0)
; #define PG8_WAIT_V(n) asm volatile("s_waitcnt vmcnt(" #n ")" ::: "memory")
; #define PG8_WAIT_L(n) asm volatile("s_waitcnt lgkmcnt(" #n ")" ::: "memory")
; #define PG8_BAR __builtin_amdgcn_s_barrier()
; #define PG8_SCHED __builtin_amdgcn_sched_barrier(0)
; template <class Map, class Epi>
; DI void gemm_phase(LAS unsigned char* lds, const Map& MP, const Epi& E, const int nM, const int nN, const int K, const int lda, const int ldb) {
;     ...
;             PG8_BAR; PG8_WAIT_L(0); PG8_MMA(1, 0, At, B0); PG8_BAR; PG8_SCHED;
;             PG8_STAGE(PG8_SB(0, 1), b2 + hstepB, voffB);
;             PG8_WAIT_V(6); PG8_BAR; PG8_MMA(1, 1, At, B1); PG8_BAR;
;             PG8_LDB(B0, 1, 0); PG8_SCHED; PG8_LDA(At, 1, 0); PG8_STAGE(PG8_SA(0, 1), a2 + hstepA, voffA);
;             PG8_WAIT_L(8); PG8_BAR; PG8_WAIT_L(0); PG8_MMA(0, 0, At, B0); PG8_BAR; PG8_SCHED;
;             PG8_LDB(B1, 1, 1); PG8_STAGE(PG8_SB(1, 0), b3, voffB);
;             PG8_BAR; PG8_WAIT_L(0); PG8_MMA(0, 1, At, B1); PG8_BAR;
;             PG8_LDA(At, 1, 1); PG8_STAGE(PG8_SA(1, 0), a3, voffA);
	s_setprio 0
	s_mov_b32 m0, s70
	s_nop 0
	global_load_lds_dwordx4 v172, s[68:69]
	s_add_i32 m0, s70, 0x2000
	s_nop 0
	global_load_lds_dwordx4 v168, s[68:69]
	s_waitcnt vmcnt(6)
	s_setprio 1
	s_barrier
	v_mfma_f32_16x16x32_bf16 v[56:59], v[206:209], v[124:127], v[56:59]
	v_mfma_f32_16x16x32_bf16 v[52:55], v[214:217], v[124:127], v[52:55]
	s_add_i32 s68, 0, 0x18000
	v_add_u32_e32 v92, s68, v188
	ds_read_b128 v[80:83], v92
	v_mfma_f32_16x16x32_bf16 v[44:47], v[206:209], v[140:143], v[44:47]
	v_mfma_f32_16x16x32_bf16 v[36:39], v[214:217], v[140:143], v[36:39]
	ds_read_b128 v[84:87], v92 offset:1024
	v_mfma_f32_16x16x32_bf16 v[28:31], v[206:209], v[160:163], v[28:31]
	v_mfma_f32_16x16x32_bf16 v[20:23], v[214:217], v[160:163], v[20:23]
	ds_read_b128 v[88:91], v92 offset:2048
	v_mfma_f32_16x16x32_bf16 v[4:7], v[206:209], v[198:201], v[4:7]
	v_mfma_f32_16x16x32_bf16 v[0:3], v[214:217], v[198:201], v[0:3]
	ds_read_b128 v[92:95], v92 offset:3072
	v_mfma_f32_16x16x32_bf16 v[56:59], v[210:213], v[132:135], v[56:59]
	s_add_u32 s46, s46, 0x80000
	s_addc_u32 s47, s47, 0
	v_mfma_f32_16x16x32_bf16 v[52:55], v[218:221], v[132:135], v[52:55]
	v_mfma_f32_16x16x32_bf16 v[44:47], v[210:213], v[152:155], v[44:47]
	v_mfma_f32_16x16x32_bf16 v[36:39], v[218:221], v[152:155], v[36:39]
	v_mfma_f32_16x16x32_bf16 v[28:31], v[210:213], v[164:167], v[28:31]
	v_mfma_f32_16x16x32_bf16 v[20:23], v[218:221], v[164:167], v[20:23]
	v_mfma_f32_16x16x32_bf16 v[4:7], v[210:213], v[202:205], v[4:7]
	v_mfma_f32_16x16x32_bf16 v[0:3], v[218:221], v[202:205], v[0:3]
	s_barrier
	s_setprio 0
	s_mov_b32 m0, s56
	ds_read_b128 v[124:127], v190 offset:32768
	ds_read_b128 v[132:135], v190 offset:33792
	ds_read_b128 v[160:163], v190 offset:34816
	ds_read_b128 v[164:167], v190 offset:35840
	ds_read_b128 v[198:201], v190 offset:36864
	ds_read_b128 v[202:205], v190 offset:37888
	ds_read_b128 v[206:209], v190 offset:38912
	ds_read_b128 v[210:213], v190 offset:39936
	global_load_lds_dwordx4 v174, s[46:47]
	s_mov_b32 m0, s57
	s_nop 0
	global_load_lds_dwordx4 v170, s[46:47]
	s_waitcnt lgkmcnt(8)
	s_setprio 1
	s_barrier
	s_waitcnt lgkmcnt(7)
	v_mfma_f32_16x16x32_bf16 v[140:143], v[80:83], v[124:127], v[148:151]
	s_waitcnt lgkmcnt(6)
	v_mfma_f32_16x16x32_bf16 v[148:151], v[84:87], v[132:135], v[140:143]
	v_mfma_f32_16x16x32_bf16 v[140:143], v[88:91], v[124:127], v[144:147]
	s_waitcnt lgkmcnt(5)
	v_mfma_f32_16x16x32_bf16 v[136:139], v[80:83], v[160:163], v[136:139]
	v_mfma_f32_16x16x32_bf16 v[128:131], v[88:91], v[160:163], v[128:131]
	s_waitcnt lgkmcnt(3)
	v_mfma_f32_16x16x32_bf16 v[120:123], v[80:83], v[198:201], v[120:123]
	v_mfma_f32_16x16x32_bf16 v[104:107], v[88:91], v[198:201], v[104:107]
	s_waitcnt lgkmcnt(1)
	v_mfma_f32_16x16x32_bf16 v[76:79], v[80:83], v[206:209], v[76:79]
	v_mfma_f32_16x16x32_bf16 v[72:75], v[88:91], v[206:209], v[72:75]
	s_add_i32 s46, 0, 0x1c000
	v_mfma_f32_16x16x32_bf16 v[144:147], v[92:95], v[132:135], v[140:143]
	v_add_u32_e32 v140, s46, v188
	v_mfma_f32_16x16x32_bf16 v[136:139], v[84:87], v[164:167], v[136:139]
	s_add_i32 s47, s68, s37
	v_mfma_f32_16x16x32_bf16 v[128:131], v[92:95], v[164:167], v[128:131]
	v_mfma_f32_16x16x32_bf16 v[120:123], v[84:87], v[202:205], v[120:123]
	v_mfma_f32_16x16x32_bf16 v[104:107], v[92:95], v[202:205], v[104:107]
	s_waitcnt lgkmcnt(0)
	v_mfma_f32_16x16x32_bf16 v[76:79], v[84:87], v[210:213], v[76:79]
	v_mfma_f32_16x16x32_bf16 v[72:75], v[92:95], v[210:213], v[72:75]
	s_barrier
	s_setprio 0
	ds_read_b128 v[214:217], v140
	ds_read_b128 v[218:221], v140 offset:1024
	ds_read_b128 v[222:225], v140 offset:2048
	ds_read_b128 v[230:233], v140 offset:3072
	v_lshl_add_u64 v[140:141], v[184:185], 0, s[14:15]
	s_mov_b32 m0, s47
	s_nop 0
	global_load_lds_dwordx4 v[140:141], off
	v_lshl_add_u64 v[140:141], v[194:195], 0, s[14:15]
	s_add_i32 m0, s47, 0x2000
	s_nop 0
	global_load_lds_dwordx4 v[140:141], off
	s_setprio 1
	s_barrier
	s_waitcnt lgkmcnt(1)
	v_mfma_f32_16x16x32_bf16 v[96:99], v[222:225], v[124:127], v[96:99]
	v_mfma_f32_16x16x32_bf16 v[140:143], v[214:217], v[124:127], v[156:159]
	s_waitcnt lgkmcnt(0)
	v_mfma_f32_16x16x32_bf16 v[152:155], v[230:233], v[132:135], v[96:99]
	v_mfma_f32_16x16x32_bf16 v[96:99], v[214:217], v[160:163], v[100:103]
	v_mfma_f32_16x16x32_bf16 v[156:159], v[218:221], v[132:135], v[140:143]
	v_mfma_f32_16x16x32_bf16 v[140:143], v[218:221], v[164:167], v[96:99]
	v_mfma_f32_16x16x32_bf16 v[96:99], v[222:225], v[160:163], v[108:111]
	v_mfma_f32_16x16x32_bf16 v[132:135], v[230:233], v[164:167], v[96:99]
	v_mfma_f32_16x16x32_bf16 v[96:99], v[214:217], v[198:201], v[112:115]
	s_mov_b32 m0, s62
	v_mfma_f32_16x16x32_bf16 v[124:127], v[218:221], v[202:205], v[96:99]
	v_lshl_add_u64 v[184:185], v[226:227], 0, s[14:15]
	v_mfma_f32_16x16x32_bf16 v[96:99], v[222:225], v[198:201], v[116:119]
	v_mfma_f32_16x16x32_bf16 v[68:71], v[214:217], v[206:209], v[68:71]
	v_mfma_f32_16x16x32_bf16 v[64:67], v[222:225], v[206:209], v[64:67]
	v_mfma_f32_16x16x32_bf16 v[116:119], v[230:233], v[202:205], v[96:99]
	v_mfma_f32_16x16x32_bf16 v[68:71], v[218:221], v[210:213], v[68:71]
	v_mfma_f32_16x16x32_bf16 v[64:67], v[230:233], v[210:213], v[64:67]
	s_barrier
	s_setprio 0
	ds_read_b128 v[96:99], v190 offset:49152
	ds_read_b128 v[100:103], v190 offset:50176
	ds_read_b128 v[108:111], v190 offset:51200
	ds_read_b128 v[112:115], v190 offset:52224
	ds_read_b128 v[160:163], v190 offset:53248
	ds_read_b128 v[164:167], v190 offset:54272
	ds_read_b128 v[198:201], v190 offset:55296
	ds_read_b128 v[202:205], v190 offset:56320
	global_load_lds_dwordx4 v[184:185], off
	v_lshl_add_u64 v[184:185], v[234:235], 0, s[14:15]
	s_mov_b32 m0, s63
	s_nop 0
	global_load_lds_dwordx4 v[184:185], off
	s_waitcnt vmcnt(10)
	s_setprio 1
	s_barrier
; #define PG8_STAGE(bufoff, gbase, voff) do { _Pragma("unroll") for (int _i = 0; _i < 2; ++_i) \
;         __builtin_amdgcn_global_load_lds((const unsigned*)((const char*)(gbase) + (voff)[_i]), (LAS unsigned*)(lds + (bufoff) + ldsw + _i * 8192), 16, 0, 0); } while (0)
; #define PG8_LDA(dst, b, h) do { _Pragma("unroll") for (int m = 0; m < 4; ++m) _Pragma("unroll") for (int k = 0; k < 2; ++k) dst[m][k] = *(const LAS bf16x8*)(lds + PG8_SA(b, h) + aoff + m * 2048 + k * 1024); } while (0)
; #define PG8_MMA(ai, bj, At, Bt) do { __builtin_amdgcn_s_setprio(1); _Pragma("unroll") for (int m = 0; m < 4; ++m) _Pragma("unroll") for (int n = 0; n < 2; ++n) _Pragma("unroll") for (int k = 0; k < 2; ++k) \
;         acc[ai][bj][m][n] = __builtin_amdgcn_mfma_f32_16x16x32_bf16(Bt[n][k], At[m][k], acc[ai][bj][m][n], 0, 0, 0); __builtin_amdgcn_s_setprio(0); } while (0)
; #define PG8_WAIT_V(n) asm volatile("s_waitcnt vmcnt(" #n ")" ::: "memory")
; #define PG8_WAIT_L(n) asm volatile("s_waitcnt lgkmcnt(" #n ")" ::: "memory")
; #define PG8_BAR __builtin_amdgcn_s_barrier()
; #define PG8_SCHED __builtin_amdgcn_sched_barrier(0)
; template <class Map, class Epi>
; DI void gemm_phase(LAS unsigned char* lds, const Map& MP, const Epi& E, const int nM, const int nN, const int K, const int lda, const int ldb) {
;     ...
;             PG8_LDA(At, 1, 1); PG8_STAGE(PG8_SA(1, 0), a3, voffA);
;             PG8_BAR; PG8_WAIT_L(0); PG8_MMA(1, 0, At, B0); PG8_BAR; PG8_SCHED;
;             PG8_STAGE(PG8_SB(1, 1), b3 + hstepB, voffB);
;             PG8_WAIT_V(6); PG8_BAR; PG8_MMA(1, 1, At, B1); PG8_BAR;
	s_waitcnt lgkmcnt(7)
	v_mfma_f32_16x16x32_bf16 v[60:63], v[80:83], v[96:99], v[60:63]
	v_mfma_f32_16x16x32_bf16 v[48:51], v[88:91], v[96:99], v[48:51]
	s_waitcnt lgkmcnt(5)
	v_mfma_f32_16x16x32_bf16 v[40:43], v[80:83], v[108:111], v[40:43]
	v_mfma_f32_16x16x32_bf16 v[32:35], v[88:91], v[108:111], v[32:35]
	s_waitcnt lgkmcnt(3)
	v_mfma_f32_16x16x32_bf16 v[24:27], v[80:83], v[160:163], v[24:27]
	v_mfma_f32_16x16x32_bf16 v[16:19], v[88:91], v[160:163], v[16:19]
	s_waitcnt lgkmcnt(1)
	v_mfma_f32_16x16x32_bf16 v[12:15], v[80:83], v[198:201], v[12:15]
	v_mfma_f32_16x16x32_bf16 v[8:11], v[88:91], v[198:201], v[8:11]
	v_mfma_f32_16x16x32_bf16 v[60:63], v[84:87], v[100:103], v[60:63]
	s_add_u32 s28, s28, 0x80080
	s_addc_u32 s29, s29, 0
	v_mfma_f32_16x16x32_bf16 v[48:51], v[92:95], v[100:103], v[48:51]
	s_add_i32 s46, s46, s37
	v_mfma_f32_16x16x32_bf16 v[40:43], v[84:87], v[112:115], v[40:43]
	v_mfma_f32_16x16x32_bf16 v[32:35], v[92:95], v[112:115], v[32:35]
	v_mfma_f32_16x16x32_bf16 v[24:27], v[84:87], v[164:167], v[24:27]
	v_mfma_f32_16x16x32_bf16 v[16:19], v[92:95], v[164:167], v[16:19]
	s_waitcnt lgkmcnt(0)
	v_mfma_f32_16x16x32_bf16 v[12:15], v[84:87], v[202:205], v[12:15]
	v_mfma_f32_16x16x32_bf16 v[8:11], v[92:95], v[202:205], v[8:11]
	s_barrier
	s_setprio 0
	s_mov_b32 m0, s46
	s_nop 0
	global_load_lds_dwordx4 v172, s[28:29]
	s_add_i32 m0, s46, 0x2000
	s_nop 0
	global_load_lds_dwordx4 v168, s[28:29]
	s_waitcnt vmcnt(6)
	s_setprio 1
	s_barrier
	v_mfma_f32_16x16x32_bf16 v[56:59], v[214:217], v[96:99], v[56:59]
	v_mfma_f32_16x16x32_bf16 v[52:55], v[222:225], v[96:99], v[52:55]
	ds_read_b128 v[80:83], v189
	v_mfma_f32_16x16x32_bf16 v[44:47], v[214:217], v[108:111], v[44:47]
	v_mfma_f32_16x16x32_bf16 v[36:39], v[222:225], v[108:111], v[36:39]
	ds_read_b128 v[84:87], v189 offset:1024
	v_mfma_f32_16x16x32_bf16 v[28:31], v[214:217], v[160:163], v[28:31]
	v_mfma_f32_16x16x32_bf16 v[20:23], v[222:225], v[160:163], v[20:23]
	ds_read_b128 v[88:91], v189 offset:2048
	v_mfma_f32_16x16x32_bf16 v[4:7], v[214:217], v[198:201], v[4:7]
	v_mfma_f32_16x16x32_bf16 v[0:3], v[222:225], v[198:201], v[0:3]
	ds_read_b128 v[92:95], v189 offset:3072
	v_mfma_f32_16x16x32_bf16 v[56:59], v[218:221], v[100:103], v[56:59]
	s_add_i32 vcc_hi, vcc_hi, 2
	v_mfma_f32_16x16x32_bf16 v[52:55], v[230:233], v[100:103], v[52:55]
	s_add_u32 s59, s59, 0x100
	s_addc_u32 vcc_lo, vcc_lo, 0
	v_mfma_f32_16x16x32_bf16 v[44:47], v[218:221], v[112:115], v[44:47]
	s_add_u32 s44, s44, 0x100
	s_addc_u32 s45, s45, 0
	v_mfma_f32_16x16x32_bf16 v[36:39], v[230:233], v[112:115], v[36:39]
	s_cmp_gt_u32 vcc_hi, 29
	v_mfma_f32_16x16x32_bf16 v[28:31], v[218:221], v[164:167], v[28:31]
	v_mfma_f32_16x16x32_bf16 v[20:23], v[230:233], v[164:167], v[20:23]
	v_mfma_f32_16x16x32_bf16 v[4:7], v[218:221], v[202:205], v[4:7]
	v_mfma_f32_16x16x32_bf16 v[0:3], v[230:233], v[202:205], v[0:3]
	s_barrier
	s_setprio 0
	s_cbranch_scc0 .LBB1_380
; DI float silu_mul(float g, float v) { return g * v * __builtin_amdgcn_rcpf(1.0f + __builtin_amdgcn_exp2f(-LOG2E * g)); }
;     DI void operator()(const f32x4 (&acc)[2][2][4][2], const Unit& u, int wr, int wc, int fr, int fq) const {
;         const int row0 = u.pm * BM + wr * 64 + fr, ch0 = u.pn * 128 + wc * 32 + 8 * fq;
;         f32x4 w0[2], w1[2], w2[2], bb[2];
; #pragma unroll
;         for (int n = 0; n < 2; ++n) { w0[n] = *(const f32x4*)(cw + ch0 + 4 * n); w1[n] = *(const f32x4*)(cw + DFF + ch0 + 4 * n); w2[n] = *(const f32x4*)(cw + 2 * DFF + ch0 + 4 * n); bb[n] = *(const f32x4*)(cb + ch0 + 4 * n); }
; #pragma unroll
;         for (int ai = 0; ai < 2; ++ai)
; #pragma unroll
;             for (int m = 0; m < 4; ++m) {
;                 const bool efirst = (m == 0) && (fr == 0), elast = (m == 3) && (fr == 15);
;                 const int row = row0 + ai * HALF + m * 16;
;                 f32x4 gc[2];
; #pragma unroll
;                 for (int n = 0; n < 2; ++n) {
;                     const f32x4 g = acc[ai][0][m][n];
;                     const f32x4 gprev = acc[ai][0][m > 0 ? m - 1 : 0][n], gnext = acc[ai][0][m < 3 ? m + 1 : 3][n];
;                     f32x4 up, dn;
; #pragma unroll
;                     for (int e = 0; e < 4; ++e) {
;                         const float pu = (m > 0 && fr == 15) ? gprev[e] : g[e];
;                         const float pd = (m < 3 && fr == 0) ? gnext[e] : g[e];
;                         up[e] = dpp_ror1(pu); dn[e] = dpp_ror15(pd);
;                     }
;                     if (efirst) up = (f32x4){0.f, 0.f, 0.f, 0.f};
;                     if (elast) dn = (f32x4){0.f, 0.f, 0.f, 0.f};
;                     gc[n] = w0[n] * up + w1[n] * g + w2[n] * dn + bb[n];
;                 }
;                 if (efirst || elast) {
;                     const size_t eo = (size_t)((row >> 6) * 2 + (elast ? 1 : 0)) * DFF + ch0;
; #pragma unroll
;                     for (int n = 0; n < 2; ++n) { *(f32x4*)(EP + eo + 4 * n) = gc[n]; *(f32x4*)(ER + eo + 4 * n) = acc[ai][0][m][n]; *(f32x4*)(EV + eo + 4 * n) = acc[ai][1][m][n]; }
;                 } else {
;                     const f32x4 v0 = acc[ai][1][m][0], v1 = acc[ai][1][m][1];
;                     u32x4 o;
;                     o[0] = pack2(silu_mul(gc[0][0], v0[0]), silu_mul(gc[0][1], v0[1])); o[1] = pack2(silu_mul(gc[0][2], v0[2]), silu_mul(gc[0][3], v0[3]));
	s_waitcnt lgkmcnt(0)
	s_lshl_b32 s23, s43, 7
	v_mov_b32_e32 v194, v186
	v_mov_b32_e32 v80, v187
	s_or_b32 s23, s23, s67
	v_lshl_add_u32 v184, v80, 3, s23
	v_ashrrev_i32_e32 v185, 31, v184
	v_lshlrev_b64 v[80:81], 2, v[184:185]
	v_lshl_add_u64 v[84:85], s[52:53], 0, v[80:81]
	v_lshl_add_u64 v[88:89], s[16:17], 0, v[80:81]
	v_lshl_add_u64 v[92:93], s[18:19], 0, v[80:81]
	v_lshl_add_u64 v[112:113], s[54:55], 0, v[80:81]
	global_load_dwordx4 v[80:83], v[84:85], off offset:16
	global_load_dwordx4 v[96:99], v[84:85], off
	s_nop 0
	global_load_dwordx4 v[84:87], v[88:89], off offset:16
	global_load_dwordx4 v[100:103], v[88:89], off
	s_nop 0
	global_load_dwordx4 v[88:91], v[92:93], off offset:16
	global_load_dwordx4 v[108:111], v[92:93], off
	s_nop 0
	global_load_dwordx4 v[92:95], v[112:113], off offset:16
	s_nop 0
	global_load_dwordx4 v[112:115], v[112:113], off
	v_cmp_eq_u32_e32 vcc, 0, v194
	s_nop 0
	s_nop 0
	v_cndmask_b32_e32 v161, v148, v136, vcc
	v_cndmask_b32_e32 v162, v149, v137, vcc
	v_cndmask_b32_e32 v163, v150, v138, vcc
	v_mov_b32_dpp v160, v161 row_ror:15 row_mask:0xf bank_mask:0xf
	s_nop 0
	s_nop 0
	v_mov_b32_dpp v161, v162 row_ror:15 row_mask:0xf bank_mask:0xf
	v_mov_b32_dpp v164, v150 row_ror:1 row_mask:0xf bank_mask:0xf
	v_cndmask_b32_e32 v165, v151, v139, vcc
	v_mov_b32_dpp v162, v163 row_ror:15 row_mask:0xf bank_mask:0xf
	v_mov_b32_dpp v195, v151 row_ror:1 row_mask:0xf bank_mask:0xf
	v_mov_b32_dpp v166, v148 row_ror:1 row_mask:0xf bank_mask:0xf
	v_mov_b32_dpp v167, v149 row_ror:1 row_mask:0xf bank_mask:0xf
	v_mov_b32_dpp v163, v165 row_ror:15 row_mask:0xf bank_mask:0xf
	v_cndmask_b32_e64 v165, v195, 0, vcc
	v_cndmask_b32_e64 v164, v164, 0, vcc
	v_cndmask_b32_e64 v167, v167, 0, vcc
	v_cndmask_b32_e64 v166, v166, 0, vcc
	s_nop 0
	s_nop 0
	v_mov_b32_dpp v195, v144 row_ror:1 row_mask:0xf bank_mask:0xf
	v_mov_b32_dpp v196, v145 row_ror:1 row_mask:0xf bank_mask:0xf
	v_mov_b32_dpp v198, v146 row_ror:1 row_mask:0xf bank_mask:0xf
	v_cndmask_b32_e32 v199, v147, v131, vcc
	v_mov_b32_dpp v200, v147 row_ror:1 row_mask:0xf bank_mask:0xf
	v_cndmask_b32_e64 v198, v198, 0, vcc
	v_cndmask_b32_e64 v201, v196, 0, vcc
	s_lshl_b32 s21, s42, 8
	s_add_i32 s21, s21, s49
	v_add_u32_e32 v193, s21, v194
	v_cmp_ne_u32_e64 s[46:47], 0, v194
	s_waitcnt vmcnt(0)
	v_pk_mul_f32 v[164:165], v[98:99], v[164:165]
	v_pk_mul_f32 v[166:167], v[96:97], v[166:167]
	v_pk_fma_f32 v[164:165], v[150:151], v[102:103], v[164:165]
	v_pk_fma_f32 v[166:167], v[148:149], v[100:101], v[166:167]
	v_pk_fma_f32 v[162:163], v[110:111], v[162:163], v[164:165]
	v_cndmask_b32_e32 v165, v144, v128, vcc
	v_pk_fma_f32 v[160:161], v[108:109], v[160:161], v[166:167]
	v_cndmask_b32_e32 v166, v145, v129, vcc
	v_mov_b32_dpp v164, v165 row_ror:15 row_mask:0xf bank_mask:0xf
	v_cndmask_b32_e32 v167, v146, v130, vcc
	v_pk_add_f32 v[162:163], v[114:115], v[162:163]
	v_mov_b32_dpp v165, v166 row_ror:15 row_mask:0xf bank_mask:0xf
	v_pk_add_f32 v[160:161], v[112:113], v[160:161]
	s_nop 0
	v_mov_b32_dpp v166, v167 row_ror:15 row_mask:0xf bank_mask:0xf
	s_nop 1
	v_mov_b32_dpp v167, v199 row_ror:15 row_mask:0xf bank_mask:0xf
	v_cndmask_b32_e64 v199, v200, 0, vcc
	v_cndmask_b32_e64 v200, v195, 0, vcc
	v_pk_mul_f32 v[200:201], v[80:81], v[200:201]
	v_pk_mul_f32 v[198:199], v[82:83], v[198:199]
	v_pk_fma_f32 v[200:201], v[144:145], v[84:85], v[200:201]
	v_pk_fma_f32 v[198:199], v[146:147], v[86:87], v[198:199]
	v_pk_fma_f32 v[164:165], v[88:89], v[164:165], v[200:201]
	v_pk_fma_f32 v[166:167], v[90:91], v[166:167], v[198:199]
	v_pk_add_f32 v[164:165], v[92:93], v[164:165]
	v_pk_add_f32 v[166:167], v[94:95], v[166:167]
	s_and_saveexec_b64 s[28:29], s[46:47]
	s_xor_b64 s[28:29], exec, s[28:29]
	s_cbranch_execz .LBB1_383
	v_mul_f32_e32 v195, 0xbfb8aa3b, v160
	v_exp_f32_e32 v195, v195
	v_mul_f32_e32 v196, 0xbfb8aa3b, v161
	v_exp_f32_e32 v196, v196
	v_pk_mul_f32 v[160:161], v[156:157], v[160:161]
	v_add_f32_e32 v195, 1.0, v195
	v_rcp_f32_e32 v198, v195
	v_add_f32_e32 v196, 1.0, v196
	v_mul_f32_e32 v195, 0xbfb8aa3b, v162
	v_rcp_f32_e32 v199, v196
	v_exp_f32_e32 v195, v195
	v_mul_f32_e32 v196, 0xbfb8aa3b, v163
	v_exp_f32_e32 v196, v196
	v_pk_mul_f32 v[160:161], v[160:161], v[198:199]
	v_add_f32_e32 v195, 1.0, v195
	v_rcp_f32_e32 v200, v195
	v_add_f32_e32 v195, 1.0, v196
	v_rcp_f32_e32 v201, v195
	v_cvt_pk_bf16_f32 v160, v160, v161
	v_mul_f32_e32 v161, 0xbfb8aa3b, v164
	v_exp_f32_e32 v195, v161
	v_mul_f32_e32 v161, 0xbfb8aa3b, v165
	v_exp_f32_e32 v196, v161
	v_pk_mul_f32 v[162:163], v[158:159], v[162:163]
	v_pk_mul_f32 v[164:165], v[152:153], v[164:165]
	v_pk_mul_f32 v[162:163], v[162:163], v[200:201]
	s_nop 0
	v_cvt_pk_bf16_f32 v161, v162, v163
	v_add_f32_e32 v162, 1.0, v195
	v_mul_f32_e32 v195, 0xbfb8aa3b, v166
	v_add_f32_e32 v163, 1.0, v196
	v_exp_f32_e32 v195, v195
	v_mul_f32_e32 v196, 0xbfb8aa3b, v167
	v_exp_f32_e32 v196, v196
	v_rcp_f32_e32 v162, v162
	v_add_f32_e32 v195, 1.0, v195
	v_rcp_f32_e32 v198, v195
	v_add_f32_e32 v195, 1.0, v196
	v_rcp_f32_e32 v163, v163
	v_rcp_f32_e32 v199, v195
	v_pk_mul_f32 v[166:167], v[154:155], v[166:167]
	v_pk_mul_f32 v[162:163], v[164:165], v[162:163]
	v_pk_mul_f32 v[164:165], v[166:167], v[198:199]
	v_cvt_pk_bf16_f32 v162, v162, v163
	v_cvt_pk_bf16_f32 v163, v164, v165
	v_mov_b64_e32 v[164:165], s[6:7]
	v_mad_i64_i32 v[164:165], s[42:43], v193, s30, v[164:165]
	v_lshl_add_u64 v[164:165], v[184:185], 1, v[164:165]
	global_store_dwordx4 v[164:165], v[160:163], off

; #define PG8_STAGE(bufoff, gbase, voff) do { _Pragma("unroll") for (int _i = 0; _i < 2; ++_i) \
;         __builtin_amdgcn_global_load_lds((const unsigned*)((const char*)(gbase) + (voff)[_i]), (LAS unsigned*)(lds + (bufoff) + ldsw + _i * 8192), 16, 0, 0); } while (0)
; #define PG8_LDA(dst, b, h) do { _Pragma("unroll") for (int m = 0; m < 4; ++m) _Pragma("unroll") for (int k = 0; k < 2; ++k) dst[m][k] = *(const LAS bf16x8*)(lds + PG8_SA(b, h) + aoff + m * 2048 + k * 1024); } while (0)
; #define PG8_LDB(dst, b, h) do { _Pragma("unroll") for (int n = 0; n < 2; ++n) _Pragma("unroll") for (int k = 0; k < 2; ++k) dst[n][k] = *(const LAS bf16x8*)(lds + PG8_SB(b, h) + boff + n * 2048 + k * 1024); } while (0)
; #define PG8_MMA(ai, bj, At, Bt) do { __builtin_amdgcn_s_setprio(1); _Pragma("unroll") for (int m = 0; m < 4; ++m) _Pragma("unroll") for (int n = 0; n < 2; ++n) _Pragma("unroll") for (int k = 0; k < 2; ++k) \
;         acc[ai][bj][m][n] = __builtin_amdgcn_mfma_f32_16x16x32_bf16(Bt[n][k], At[m][k], acc[ai][bj][m][n], 0, 0, 0); __builtin_amdgcn_s_setprio(0); } while (0)
; #define PG8_WAIT_V(n) asm volatile("s_waitcnt vmcnt(" #n ")" ::: "memory")
; #define PG8_WAIT_L(n) asm volatile("s_waitcnt lgkmcnt(" #n ")" ::: "memory")
; #define PG8_BAR __builtin_amdgcn_s_barrier()
; #define PG8_SCHED __builtin_amdgcn_sched_barrier(0)
; template <class Map, class Epi>
; DI void gemm_phase(LAS unsigned char* lds, const Map& MP, const Epi& E, const int nM, const int nN, const int K, const int lda, const int ldb) {
;     ...
;             PG8_LDB(B0, 0, 0); PG8_SCHED; PG8_LDA(At, 0, 0); PG8_STAGE(PG8_SA(1, 1), a1 + hstepA, voffA);
;             PG8_WAIT_L(8); PG8_BAR; PG8_WAIT_L(0); PG8_MMA(0, 0, At, B0); PG8_BAR; PG8_SCHED;
;             PG8_LDB(B1, 0, 1); PG8_STAGE(PG8_SB(0, 0), b2, voffB);
;             PG8_BAR; PG8_WAIT_L(0); PG8_MMA(0, 1, At, B1); PG8_BAR;
;             PG8_LDA(At, 0, 1); PG8_STAGE(PG8_SA(0, 0), a2, voffA);
;             PG8_BAR; PG8_WAIT_L(0); PG8_MMA(1, 0, At, B0); PG8_BAR; PG8_SCHED;
;             PG8_STAGE(PG8_SB(0, 1), b2 + hstepB, voffB);
;             PG8_WAIT_V(6); PG8_BAR; PG8_MMA(1, 1, At, B1); PG8_BAR;
;             PG8_LDB(B0, 1, 0); PG8_SCHED; PG8_LDA(At, 1, 0); PG8_STAGE(PG8_SA(0, 1), a2 + hstepA, voffA);
.LBB1_550:
	s_add_u32 s10, s8, 0x100
	s_addc_u32 s11, s9, 0
	s_cmpk_eq_i32 s3, 0x54
	s_cselect_b32 s15, s43, s11
	s_cselect_b32 s14, s42, s10
	s_cselect_b32 s13, s7, s38
	s_cselect_b32 s12, s6, s5
	s_add_i32 m0, s24, 0xc000
	ds_read_b128 v[168:171], v150
	ds_read_b128 v[172:175], v150 offset:1024
	ds_read_b128 v[176:179], v150 offset:2048
	ds_read_b128 v[180:183], v150 offset:3072
	ds_read_b128 v[184:187], v150 offset:4096
	ds_read_b128 v[188:191], v150 offset:5120
	ds_read_b128 v[192:195], v150 offset:6144
	ds_read_b128 v[198:201], v150 offset:7168
	global_load_lds_dwordx4 v138, s[8:9]
	s_add_i32 m0, s24, 0xe000
	s_nop 0
	global_load_lds_dwordx4 v136, s[8:9]
	s_waitcnt lgkmcnt(8)
	s_setprio 1
	s_barrier
	s_waitcnt lgkmcnt(7)
	v_mfma_f32_16x16x32_bf16 v[124:127], v[152:155], v[168:171], v[124:127]
	v_mfma_f32_16x16x32_bf16 v[120:123], v[160:163], v[168:171], v[120:123]
	s_waitcnt lgkmcnt(5)
	v_mfma_f32_16x16x32_bf16 v[108:111], v[152:155], v[176:179], v[108:111]
	v_mfma_f32_16x16x32_bf16 v[104:107], v[160:163], v[176:179], v[104:107]
	s_waitcnt lgkmcnt(3)
	v_mfma_f32_16x16x32_bf16 v[92:95], v[152:155], v[184:187], v[92:95]
	v_mfma_f32_16x16x32_bf16 v[88:91], v[160:163], v[184:187], v[88:91]
	s_waitcnt lgkmcnt(1)
	v_mfma_f32_16x16x32_bf16 v[76:79], v[152:155], v[192:195], v[76:79]
	v_mfma_f32_16x16x32_bf16 v[72:75], v[160:163], v[192:195], v[72:75]
	v_mfma_f32_16x16x32_bf16 v[124:127], v[156:159], v[172:175], v[124:127]
	s_add_i32 s8, s35, s22
	v_mfma_f32_16x16x32_bf16 v[120:123], v[164:167], v[172:175], v[120:123]
	v_lshl_add_u64 v[144:145], s[12:13], 0, v[132:133]
	v_mfma_f32_16x16x32_bf16 v[108:111], v[156:159], v[180:183], v[108:111]
	v_lshl_add_u64 v[218:219], s[12:13], 0, v[128:129]
	v_mfma_f32_16x16x32_bf16 v[104:107], v[164:167], v[180:183], v[104:107]
	v_mfma_f32_16x16x32_bf16 v[92:95], v[156:159], v[188:191], v[92:95]
	v_mfma_f32_16x16x32_bf16 v[88:91], v[164:167], v[188:191], v[88:91]
	s_waitcnt lgkmcnt(0)
	v_mfma_f32_16x16x32_bf16 v[76:79], v[156:159], v[198:201], v[76:79]
	v_mfma_f32_16x16x32_bf16 v[72:75], v[164:167], v[198:201], v[72:75]
	s_barrier
	s_setprio 0
	s_mov_b32 m0, s8
	ds_read_b128 v[202:205], v151
	ds_read_b128 v[206:209], v151 offset:1024
	ds_read_b128 v[210:213], v151 offset:2048
	ds_read_b128 v[214:217], v151 offset:3072
	global_load_lds_dwordx4 v[144:145], off
	s_add_i32 m0, s8, 0x2000
	s_nop 0
	global_load_lds_dwordx4 v[218:219], off
	s_setprio 1
	s_barrier
	s_waitcnt lgkmcnt(3)
	v_mfma_f32_16x16x32_bf16 v[116:119], v[202:205], v[168:171], v[116:119]
	s_waitcnt lgkmcnt(1)
	v_mfma_f32_16x16x32_bf16 v[112:115], v[210:213], v[168:171], v[112:115]
	v_mfma_f32_16x16x32_bf16 v[100:103], v[202:205], v[176:179], v[100:103]
	v_mfma_f32_16x16x32_bf16 v[96:99], v[210:213], v[176:179], v[96:99]
	v_mfma_f32_16x16x32_bf16 v[84:87], v[202:205], v[184:187], v[84:87]
	v_mfma_f32_16x16x32_bf16 v[80:83], v[210:213], v[184:187], v[80:83]
	v_mfma_f32_16x16x32_bf16 v[68:71], v[202:205], v[192:195], v[68:71]
	v_mfma_f32_16x16x32_bf16 v[64:67], v[210:213], v[192:195], v[64:67]
	v_mfma_f32_16x16x32_bf16 v[116:119], v[206:209], v[172:175], v[116:119]
	v_lshl_add_u64 v[222:223], s[14:15], 0, v[130:131]
	s_mov_b32 m0, s24
	s_waitcnt lgkmcnt(0)
	v_mfma_f32_16x16x32_bf16 v[112:115], v[214:217], v[172:175], v[112:115]
	v_lshl_add_u64 v[220:221], s[14:15], 0, v[134:135]
	v_mfma_f32_16x16x32_bf16 v[100:103], v[206:209], v[180:183], v[100:103]
	v_mfma_f32_16x16x32_bf16 v[96:99], v[214:217], v[180:183], v[96:99]
	v_mfma_f32_16x16x32_bf16 v[84:87], v[206:209], v[188:191], v[84:87]
	v_mfma_f32_16x16x32_bf16 v[80:83], v[214:217], v[188:191], v[80:83]
	v_mfma_f32_16x16x32_bf16 v[68:71], v[206:209], v[198:201], v[68:71]
	v_mfma_f32_16x16x32_bf16 v[64:67], v[214:217], v[198:201], v[64:67]
	s_barrier
	s_setprio 0
	ds_read_b128 v[168:171], v150 offset:16384
	ds_read_b128 v[172:175], v150 offset:17408
	ds_read_b128 v[176:179], v150 offset:18432
	ds_read_b128 v[180:183], v150 offset:19456
	ds_read_b128 v[184:187], v150 offset:20480
	ds_read_b128 v[188:191], v150 offset:21504
	ds_read_b128 v[192:195], v150 offset:22528
	ds_read_b128 v[198:201], v150 offset:23552
	global_load_lds_dwordx4 v[220:221], off
	s_mov_b32 m0, s25
	s_nop 0
	global_load_lds_dwordx4 v[222:223], off
	s_waitcnt vmcnt(10)
	s_setprio 1
	s_barrier
	s_waitcnt lgkmcnt(7)
	v_mfma_f32_16x16x32_bf16 v[60:63], v[152:155], v[168:171], v[60:63]
	v_mfma_f32_16x16x32_bf16 v[56:59], v[160:163], v[168:171], v[56:59]
	s_waitcnt lgkmcnt(5)
	v_mfma_f32_16x16x32_bf16 v[44:47], v[152:155], v[176:179], v[44:47]
	v_mfma_f32_16x16x32_bf16 v[40:43], v[160:163], v[176:179], v[40:43]
	s_waitcnt lgkmcnt(3)
	v_mfma_f32_16x16x32_bf16 v[28:31], v[152:155], v[184:187], v[28:31]
	v_mfma_f32_16x16x32_bf16 v[24:27], v[160:163], v[184:187], v[24:27]
	s_waitcnt lgkmcnt(1)
	v_mfma_f32_16x16x32_bf16 v[12:15], v[152:155], v[192:195], v[12:15]
	v_mfma_f32_16x16x32_bf16 v[8:11], v[160:163], v[192:195], v[8:11]
	v_mfma_f32_16x16x32_bf16 v[60:63], v[156:159], v[172:175], v[60:63]
	s_add_u32 s8, s12, 0x160000
	s_addc_u32 s9, s13, 0
	v_mfma_f32_16x16x32_bf16 v[56:59], v[164:167], v[172:175], v[56:59]
	s_add_i32 s39, s36, s22
	v_mfma_f32_16x16x32_bf16 v[44:47], v[156:159], v[180:183], v[44:47]
	v_mfma_f32_16x16x32_bf16 v[40:43], v[164:167], v[180:183], v[40:43]
	v_mfma_f32_16x16x32_bf16 v[28:31], v[156:159], v[188:191], v[28:31]
	v_mfma_f32_16x16x32_bf16 v[24:27], v[164:167], v[188:191], v[24:27]
	s_waitcnt lgkmcnt(0)
	v_mfma_f32_16x16x32_bf16 v[12:15], v[156:159], v[198:201], v[12:15]
	v_mfma_f32_16x16x32_bf16 v[8:11], v[164:167], v[198:201], v[8:11]
	s_barrier
; #define PG8_STAGE(bufoff, gbase, voff) do { _Pragma("unroll") for (int _i = 0; _i < 2; ++_i) \
;         __builtin_amdgcn_global_load_lds((const unsigned*)((const char*)(gbase) + (voff)[_i]), (LAS unsigned*)(lds + (bufoff) + ldsw + _i * 8192), 16, 0, 0); } while (0)
; #define PG8_LDA(dst, b, h) do { _Pragma("unroll") for (int m = 0; m < 4; ++m) _Pragma("unroll") for (int k = 0; k < 2; ++k) dst[m][k] = *(const LAS bf16x8*)(lds + PG8_SA(b, h) + aoff + m * 2048 + k * 1024); } while (0)
; #define PG8_LDB(dst, b, h) do { _Pragma("unroll") for (int n = 0; n < 2; ++n) _Pragma("unroll") for (int k = 0; k < 2; ++k) dst[n][k] = *(const LAS bf16x8*)(lds + PG8_SB(b, h) + boff + n * 2048 + k * 1024); } while (0)
; #define PG8_MMA(ai, bj, At, Bt) do { __builtin_amdgcn_s_setprio(1); _Pragma("unroll") for (int m = 0; m < 4; ++m) _Pragma("unroll") for (int n = 0; n < 2; ++n) _Pragma("unroll") for (int k = 0; k < 2; ++k) \
;         acc[ai][bj][m][n] = __builtin_amdgcn_mfma_f32_16x16x32_bf16(Bt[n][k], At[m][k], acc[ai][bj][m][n], 0, 0, 0); __builtin_amdgcn_s_setprio(0); } while (0)
; #define PG8_WAIT_V(n) asm volatile("s_waitcnt vmcnt(" #n ")" ::: "memory")
; #define PG8_WAIT_L(n) asm volatile("s_waitcnt lgkmcnt(" #n ")" ::: "memory")
; #define PG8_BAR __builtin_amdgcn_s_barrier()
; #define PG8_SCHED __builtin_amdgcn_sched_barrier(0)
; template <class Map, class Epi>
; DI void gemm_phase(LAS unsigned char* lds, const Map& MP, const Epi& E, const int nM, const int nN, const int K, const int lda, const int ldb) {
;     ...
;             PG8_BAR; PG8_WAIT_L(0); PG8_MMA(1, 0, At, B0); PG8_BAR; PG8_SCHED;
;             PG8_STAGE(PG8_SB(0, 1), b2 + hstepB, voffB);
;             PG8_WAIT_V(6); PG8_BAR; PG8_MMA(1, 1, At, B1); PG8_BAR;
;             PG8_LDB(B0, 1, 0); PG8_SCHED; PG8_LDA(At, 1, 0); PG8_STAGE(PG8_SA(0, 1), a2 + hstepA, voffA);
;             PG8_WAIT_L(8); PG8_BAR; PG8_WAIT_L(0); PG8_MMA(0, 0, At, B0); PG8_BAR; PG8_SCHED;
;             PG8_LDB(B1, 1, 1); PG8_STAGE(PG8_SB(1, 0), b3, voffB);
;             PG8_BAR; PG8_WAIT_L(0); PG8_MMA(0, 1, At, B1); PG8_BAR;
;             PG8_LDA(At, 1, 1); PG8_STAGE(PG8_SA(1, 0), a3, voffA);
;             PG8_BAR; PG8_WAIT_L(0); PG8_MMA(1, 0, At, B0); PG8_BAR; PG8_SCHED;
	s_setprio 0
	s_mov_b32 m0, s39
	s_nop 0
	global_load_lds_dwordx4 v132, s[8:9]
	s_add_i32 m0, s39, 0x2000
	s_nop 0
	global_load_lds_dwordx4 v128, s[8:9]
	s_waitcnt vmcnt(6)
	s_setprio 1
	s_barrier
	v_mfma_f32_16x16x32_bf16 v[52:55], v[202:205], v[168:171], v[52:55]
	v_mfma_f32_16x16x32_bf16 v[48:51], v[210:213], v[168:171], v[48:51]
	s_add_i32 s39, 0, 0x18000
	v_add_u32_e32 v164, s39, v148
	ds_read_b128 v[152:155], v164
	v_mfma_f32_16x16x32_bf16 v[36:39], v[202:205], v[176:179], v[36:39]
	v_mfma_f32_16x16x32_bf16 v[32:35], v[210:213], v[176:179], v[32:35]
	ds_read_b128 v[156:159], v164 offset:1024
	v_mfma_f32_16x16x32_bf16 v[20:23], v[202:205], v[184:187], v[20:23]
	v_mfma_f32_16x16x32_bf16 v[16:19], v[210:213], v[184:187], v[16:19]
	ds_read_b128 v[160:163], v164 offset:2048
	v_mfma_f32_16x16x32_bf16 v[4:7], v[202:205], v[192:195], v[4:7]
	v_mfma_f32_16x16x32_bf16 v[0:3], v[210:213], v[192:195], v[0:3]
	ds_read_b128 v[164:167], v164 offset:3072
	v_mfma_f32_16x16x32_bf16 v[52:55], v[206:209], v[172:175], v[52:55]
	s_add_u32 s8, s14, 0x160000
	s_addc_u32 s9, s15, 0
	v_mfma_f32_16x16x32_bf16 v[48:51], v[214:217], v[172:175], v[48:51]
	v_mfma_f32_16x16x32_bf16 v[36:39], v[206:209], v[180:183], v[36:39]
	v_mfma_f32_16x16x32_bf16 v[32:35], v[214:217], v[180:183], v[32:35]
	v_mfma_f32_16x16x32_bf16 v[20:23], v[206:209], v[188:191], v[20:23]
	v_mfma_f32_16x16x32_bf16 v[16:19], v[214:217], v[188:191], v[16:19]
	v_mfma_f32_16x16x32_bf16 v[4:7], v[206:209], v[198:201], v[4:7]
	v_mfma_f32_16x16x32_bf16 v[0:3], v[214:217], v[198:201], v[0:3]
	s_barrier
	s_setprio 0
	s_mov_b32 m0, s26
	ds_read_b128 v[168:171], v150 offset:32768
	ds_read_b128 v[172:175], v150 offset:33792
	ds_read_b128 v[176:179], v150 offset:34816
	ds_read_b128 v[180:183], v150 offset:35840
	ds_read_b128 v[184:187], v150 offset:36864
	ds_read_b128 v[188:191], v150 offset:37888
	ds_read_b128 v[192:195], v150 offset:38912
	ds_read_b128 v[198:201], v150 offset:39936
	global_load_lds_dwordx4 v134, s[8:9]
	s_mov_b32 m0, s27
	s_nop 0
	global_load_lds_dwordx4 v130, s[8:9]
	s_waitcnt lgkmcnt(8)
	s_setprio 1
	s_barrier
	s_waitcnt lgkmcnt(7)
	v_mfma_f32_16x16x32_bf16 v[124:127], v[152:155], v[168:171], v[124:127]
	v_mfma_f32_16x16x32_bf16 v[120:123], v[160:163], v[168:171], v[120:123]
	s_waitcnt lgkmcnt(5)
	v_mfma_f32_16x16x32_bf16 v[108:111], v[152:155], v[176:179], v[108:111]
	v_mfma_f32_16x16x32_bf16 v[104:107], v[160:163], v[176:179], v[104:107]
	s_waitcnt lgkmcnt(3)
	v_mfma_f32_16x16x32_bf16 v[92:95], v[152:155], v[184:187], v[92:95]
	v_mfma_f32_16x16x32_bf16 v[88:91], v[160:163], v[184:187], v[88:91]
	s_waitcnt lgkmcnt(1)
	v_mfma_f32_16x16x32_bf16 v[76:79], v[152:155], v[192:195], v[76:79]
	v_mfma_f32_16x16x32_bf16 v[72:75], v[160:163], v[192:195], v[72:75]
	v_mfma_f32_16x16x32_bf16 v[124:127], v[156:159], v[172:175], v[124:127]
	s_add_i32 s14, 0, 0x1c000
	v_mfma_f32_16x16x32_bf16 v[120:123], v[164:167], v[172:175], v[120:123]
	s_add_i32 s8, s39, s22
	v_mfma_f32_16x16x32_bf16 v[108:111], v[156:159], v[180:183], v[108:111]
	v_add_u32_e32 v196, s14, v148
	v_mfma_f32_16x16x32_bf16 v[104:107], v[164:167], v[180:183], v[104:107]
	v_lshl_add_u64 v[144:145], v[144:145], 0, s[52:53]
	v_mfma_f32_16x16x32_bf16 v[92:95], v[156:159], v[188:191], v[92:95]
	v_mfma_f32_16x16x32_bf16 v[88:91], v[164:167], v[188:191], v[88:91]
	s_waitcnt lgkmcnt(0)
	v_mfma_f32_16x16x32_bf16 v[76:79], v[156:159], v[198:201], v[76:79]
	v_mfma_f32_16x16x32_bf16 v[72:75], v[164:167], v[198:201], v[72:75]
	s_barrier
	s_setprio 0
	s_mov_b32 m0, s8
	ds_read_b128 v[202:205], v196
	ds_read_b128 v[206:209], v196 offset:1024
	ds_read_b128 v[210:213], v196 offset:2048
	ds_read_b128 v[214:217], v196 offset:3072
	global_load_lds_dwordx4 v[144:145], off
	v_lshl_add_u64 v[144:145], v[218:219], 0, s[52:53]
	s_add_i32 m0, s8, 0x2000
	s_nop 0
	global_load_lds_dwordx4 v[144:145], off
	s_setprio 1
	s_barrier
	s_waitcnt lgkmcnt(3)
	v_mfma_f32_16x16x32_bf16 v[116:119], v[202:205], v[168:171], v[116:119]
	s_waitcnt lgkmcnt(1)
	v_mfma_f32_16x16x32_bf16 v[112:115], v[210:213], v[168:171], v[112:115]
	v_mfma_f32_16x16x32_bf16 v[100:103], v[202:205], v[176:179], v[100:103]
	v_mfma_f32_16x16x32_bf16 v[96:99], v[210:213], v[176:179], v[96:99]
	v_mfma_f32_16x16x32_bf16 v[84:87], v[202:205], v[184:187], v[84:87]
	v_mfma_f32_16x16x32_bf16 v[80:83], v[210:213], v[184:187], v[80:83]
	v_mfma_f32_16x16x32_bf16 v[68:71], v[202:205], v[192:195], v[68:71]
	v_mfma_f32_16x16x32_bf16 v[64:67], v[210:213], v[192:195], v[64:67]
	v_mfma_f32_16x16x32_bf16 v[116:119], v[206:209], v[172:175], v[116:119]
	s_mov_b32 m0, s30
	s_waitcnt lgkmcnt(0)
	v_mfma_f32_16x16x32_bf16 v[112:115], v[214:217], v[172:175], v[112:115]
	v_lshl_add_u64 v[144:145], v[220:221], 0, s[52:53]
	v_mfma_f32_16x16x32_bf16 v[100:103], v[206:209], v[180:183], v[100:103]
	v_mfma_f32_16x16x32_bf16 v[96:99], v[214:217], v[180:183], v[96:99]
	v_mfma_f32_16x16x32_bf16 v[84:87], v[206:209], v[188:191], v[84:87]
	v_mfma_f32_16x16x32_bf16 v[80:83], v[214:217], v[188:191], v[80:83]
	v_mfma_f32_16x16x32_bf16 v[68:71], v[206:209], v[198:201], v[68:71]
	v_mfma_f32_16x16x32_bf16 v[64:67], v[214:217], v[198:201], v[64:67]
	s_barrier
	s_setprio 0
	ds_read_b128 v[168:171], v150 offset:49152
	ds_read_b128 v[172:175], v150 offset:50176
	ds_read_b128 v[176:179], v150 offset:51200
	ds_read_b128 v[180:183], v150 offset:52224
	ds_read_b128 v[184:187], v150 offset:53248
	ds_read_b128 v[188:191], v150 offset:54272
	ds_read_b128 v[192:195], v150 offset:55296
	ds_read_b128 v[198:201], v150 offset:56320
	global_load_lds_dwordx4 v[144:145], off
	v_lshl_add_u64 v[144:145], v[222:223], 0, s[52:53]
	s_mov_b32 m0, s31
	s_nop 0
	global_load_lds_dwordx4 v[144:145], off
	s_waitcnt vmcnt(10)
	s_setprio 1
	s_barrier
; DI unsigned pack2(float a, float b) { f32x2 v = {a, b}; hwbf16x2 r = __builtin_convertvector(v, hwbf16x2); return __builtin_bit_cast(unsigned, r); }
; DI float bflo(unsigned w) { return __uint_as_float(w << 16); }
; DI float bfhi(unsigned w) { return __uint_as_float(w & 0xffff0000u); }
; #define PG8_WAIT_V(n) asm volatile("s_waitcnt vmcnt(" #n ")" ::: "memory")
; #define PG8_BAR __builtin_amdgcn_s_barrier()
;     DI void operator()(const f32x4 (&acc)[2][2][4][2], const Unit& u, int wr, int wc, int fr, int fq) const {
;         const int row0 = u.pm * BM + wr * 64 + fr, col0 = u.pn * BM + wc * 32 + 8 * fq;
;         f32x4 sc[2][2];
; #pragma unroll
;         for (int bj = 0; bj < 2; ++bj)
; #pragma unroll
;             for (int n = 0; n < 2; ++n) sc[bj][n] = scale ? *(const f32x4*)(scale + col0 + bj * HALF + 4 * n) : (f32x4){1.f, 1.f, 1.f, 1.f};
; #pragma unroll
;         for (int ai = 0; ai < 2; ++ai)
; #pragma unroll
;             for (int m = 0; m < 4; ++m) { const size_t ro = (size_t)(row0 + ai * HALF + m * 16) * D + col0;
; #pragma unroll
;                 for (int bj = 0; bj < 2; ++bj) {
;                     f32x4 x0, x1;
;                     if constexpr (IB) { const u32x4 w = *(const u32x4*)((const bf16_t*)Xin + ro + bj * HALF);
;                         x0 = (f32x4){bflo(w[0]), bfhi(w[0]), bflo(w[1]), bfhi(w[1])}; x1 = (f32x4){bflo(w[2]), bfhi(w[2]), bflo(w[3]), bfhi(w[3])}; }
;                     else { x0 = *(const f32x4*)((const float*)Xin + ro + bj * HALF); x1 = *(const f32x4*)((const float*)Xin + ro + bj * HALF + 4); }
;                     x0 += acc[ai][bj][m][0] * sc[bj][0]; x1 += acc[ai][bj][m][1] * sc[bj][1];
;                     if constexpr (OB) { u32x4 o; o[0] = pack2(x0[0], x0[1]); o[1] = pack2(x0[2], x0[3]); o[2] = pack2(x1[0], x1[1]); o[3] = pack2(x1[2], x1[3]);
;                         *(u32x4*)((bf16_t*)Xout + ro + bj * HALF) = o; }
;                     else { *(f32x4*)((float*)Xout + ro + bj * HALF) = x0; *(f32x4*)((float*)Xout + ro + bj * HALF + 4) = x1; } } }
; template <class Map, class Epi>
; DI void gemm_phase(LAS unsigned char* lds, const Map& MP, const Epi& E, const int nM, const int nN, const int K, const int lda, const int ldb) {
;     ...
;             PG8_STAGE(PG8_SB(1, 1), b3 + hstepB, voffB);
;             PG8_WAIT_V(6); PG8_BAR; PG8_MMA(1, 1, At, B1); PG8_BAR;
	s_waitcnt lgkmcnt(7)
	v_mfma_f32_16x16x32_bf16 v[60:63], v[152:155], v[168:171], v[60:63]
	v_mfma_f32_16x16x32_bf16 v[56:59], v[160:163], v[168:171], v[56:59]
	s_waitcnt lgkmcnt(5)
	v_mfma_f32_16x16x32_bf16 v[44:47], v[152:155], v[176:179], v[44:47]
	v_mfma_f32_16x16x32_bf16 v[40:43], v[160:163], v[176:179], v[40:43]
	s_waitcnt lgkmcnt(3)
	v_mfma_f32_16x16x32_bf16 v[28:31], v[152:155], v[184:187], v[28:31]
	v_mfma_f32_16x16x32_bf16 v[24:27], v[160:163], v[184:187], v[24:27]
	s_waitcnt lgkmcnt(1)
	v_mfma_f32_16x16x32_bf16 v[12:15], v[152:155], v[192:195], v[12:15]
	v_mfma_f32_16x16x32_bf16 v[8:11], v[160:163], v[192:195], v[8:11]
	v_mfma_f32_16x16x32_bf16 v[60:63], v[156:159], v[172:175], v[60:63]
	s_add_u32 s8, s12, 0x160080
	s_addc_u32 s9, s13, 0
	v_mfma_f32_16x16x32_bf16 v[56:59], v[164:167], v[172:175], v[56:59]
	s_add_i32 s12, s14, s22
	v_mfma_f32_16x16x32_bf16 v[44:47], v[156:159], v[180:183], v[44:47]
	v_mfma_f32_16x16x32_bf16 v[40:43], v[164:167], v[180:183], v[40:43]
	v_mfma_f32_16x16x32_bf16 v[28:31], v[156:159], v[188:191], v[28:31]
	v_mfma_f32_16x16x32_bf16 v[24:27], v[164:167], v[188:191], v[24:27]
	s_waitcnt lgkmcnt(0)
	v_mfma_f32_16x16x32_bf16 v[12:15], v[156:159], v[198:201], v[12:15]
	v_mfma_f32_16x16x32_bf16 v[8:11], v[164:167], v[198:201], v[8:11]
	s_barrier
	s_setprio 0
	s_mov_b32 m0, s12
	s_nop 0
	global_load_lds_dwordx4 v132, s[8:9]
	s_add_i32 m0, s12, 0x2000
	s_nop 0
	global_load_lds_dwordx4 v128, s[8:9]
	s_waitcnt vmcnt(6)
	s_setprio 1
	s_barrier
	v_mfma_f32_16x16x32_bf16 v[52:55], v[202:205], v[168:171], v[52:55]
	v_mfma_f32_16x16x32_bf16 v[48:51], v[210:213], v[168:171], v[48:51]
	ds_read_b128 v[152:155], v149
	v_mfma_f32_16x16x32_bf16 v[36:39], v[202:205], v[176:179], v[36:39]
	v_mfma_f32_16x16x32_bf16 v[32:35], v[210:213], v[176:179], v[32:35]
	ds_read_b128 v[156:159], v149 offset:1024
	v_mfma_f32_16x16x32_bf16 v[20:23], v[202:205], v[184:187], v[20:23]
	v_mfma_f32_16x16x32_bf16 v[16:19], v[210:213], v[184:187], v[16:19]
	ds_read_b128 v[160:163], v149 offset:2048
	v_mfma_f32_16x16x32_bf16 v[4:7], v[202:205], v[192:195], v[4:7]
	v_mfma_f32_16x16x32_bf16 v[0:3], v[210:213], v[192:195], v[0:3]
	ds_read_b128 v[164:167], v149 offset:3072
	v_mfma_f32_16x16x32_bf16 v[52:55], v[206:209], v[172:175], v[52:55]
	s_add_i32 s3, s3, 2
	v_mfma_f32_16x16x32_bf16 v[48:51], v[214:217], v[172:175], v[48:51]
	s_add_u32 s5, s5, 0x100
	s_addc_u32 s38, s38, 0
	v_mfma_f32_16x16x32_bf16 v[36:39], v[206:209], v[180:183], v[36:39]
	s_cmpk_gt_u32 s3, 0x55
	v_mfma_f32_16x16x32_bf16 v[32:35], v[214:217], v[180:183], v[32:35]
	s_mov_b64 s[8:9], s[10:11]
	v_mfma_f32_16x16x32_bf16 v[20:23], v[206:209], v[188:191], v[20:23]
	v_mfma_f32_16x16x32_bf16 v[16:19], v[214:217], v[188:191], v[16:19]
	v_mfma_f32_16x16x32_bf16 v[4:7], v[206:209], v[198:201], v[4:7]
	v_mfma_f32_16x16x32_bf16 v[0:3], v[214:217], v[198:201], v[0:3]
	s_barrier
	s_setprio 0
	s_cbranch_scc0 .LBB1_550
	s_waitcnt lgkmcnt(0)
	v_mov_b32_e32 v144, v146
	v_mov_b32_e32 v152, v147
	s_lshl_b32 s2, s2, 8
	s_add_i32 s2, s2, s29
	s_lshl_b32 s3, s4, 8
	v_add_u32_e32 v152, s2, v152
	s_or_b32 s3, s3, s54
	v_ashrrev_i32_e32 v153, 31, v152
	v_lshl_add_u32 v144, v144, 3, s3
	v_lshlrev_b64 v[152:153], 12, v[152:153]
	v_ashrrev_i32_e32 v145, 31, v144
	v_lshl_add_u64 v[152:153], s[46:47], 0, v[152:153]
	v_lshl_add_u64 v[144:145], v[144:145], 1, v[152:153]
	global_load_dwordx4 v[160:163], v[144:145], off
	global_load_dwordx4 v[164:167], v[144:145], off offset:256
	s_mov_b64 s[98:99], 0x10000
	v_lshl_add_u64 v[154:155], v[144:145], 0, s[98:99]
	global_load_dwordx4 v[168:171], v[154:155], off
	global_load_dwordx4 v[172:175], v[154:155], off offset:256
	s_mov_b64 s[98:99], 0x20000
	v_lshl_add_u64 v[154:155], v[144:145], 0, s[98:99]
	global_load_dwordx4 v[176:179], v[154:155], off
	global_load_dwordx4 v[180:183], v[154:155], off offset:256
	s_mov_b64 s[98:99], 0x30000
	v_lshl_add_u64 v[154:155], v[144:145], 0, s[98:99]
	global_load_dwordx4 v[184:187], v[154:155], off
	global_load_dwordx4 v[188:191], v[154:155], off offset:256
	s_mov_b64 s[98:99], 0x80000
	v_lshl_add_u64 v[154:155], v[144:145], 0, s[98:99]
	global_load_dwordx4 v[192:195], v[154:155], off
	global_load_dwordx4 v[198:201], v[154:155], off offset:256
	s_mov_b64 s[98:99], 0x90000
	v_lshl_add_u64 v[154:155], v[144:145], 0, s[98:99]
	global_load_dwordx4 v[202:205], v[154:155], off
	global_load_dwordx4 v[206:209], v[154:155], off offset:256
	s_mov_b64 s[98:99], 0xa0000
	v_lshl_add_u64 v[154:155], v[144:145], 0, s[98:99]
	global_load_dwordx4 v[210:213], v[154:155], off
	global_load_dwordx4 v[214:217], v[154:155], off offset:256
	s_mov_b64 s[98:99], 0xb0000
	v_lshl_add_u64 v[154:155], v[144:145], 0, s[98:99]
	global_load_dwordx4 v[248:251], v[154:155], off
	global_load_dwordx4 v[252:255], v[154:155], off offset:256
	s_waitcnt vmcnt(15)
	s_nop 1
	v_mov_b32_e32 v152, v160
	v_mov_b32_e32 v153, v161
	v_mov_b32_e32 v154, v162
	v_mov_b32_e32 v155, v163
	s_mov_b64 s[2:3], 0x10000
	s_mov_b32 s4, s37
	s_mov_b64 s[10:11], s[6:7]
	s_mov_b64 s[8:9], s[42:43]
	s_waitcnt lgkmcnt(0)
	v_lshlrev_b32_e32 v156, 16, v152
	v_and_b32_e32 v157, 0xffff0000, v152
	v_lshlrev_b32_e32 v152, 16, v153
	v_and_b32_e32 v153, 0xffff0000, v153
	v_lshlrev_b32_e32 v158, 16, v154
	v_and_b32_e32 v159, 0xffff0000, v154
	v_lshlrev_b32_e32 v154, 16, v155
	v_and_b32_e32 v155, 0xffff0000, v155
	v_pk_add_f32 v[126:127], v[126:127], v[152:153]
	v_pk_add_f32 v[124:125], v[124:125], v[156:157]
	v_pk_add_f32 v[152:153], v[122:123], v[154:155]
	v_pk_add_f32 v[122:123], v[120:121], v[158:159]
	v_cvt_pk_bf16_f32 v120, v124, v125
	v_cvt_pk_bf16_f32 v121, v126, v127
	v_cvt_pk_bf16_f32 v122, v122, v123
	v_cvt_pk_bf16_f32 v123, v152, v153
	global_store_dwordx4 v[144:145], v[120:123], off
	s_waitcnt vmcnt(15)
; DI unsigned pack2(float a, float b) { f32x2 v = {a, b}; hwbf16x2 r = __builtin_convertvector(v, hwbf16x2); return __builtin_bit_cast(unsigned, r); }
; DI float bflo(unsigned w) { return __uint_as_float(w << 16); }
; DI float bfhi(unsigned w) { return __uint_as_float(w & 0xffff0000u); }
;     DI void operator()(const f32x4 (&acc)[2][2][4][2], const Unit& u, int wr, int wc, int fr, int fq) const {
;     ...
;         for (int ai = 0; ai < 2; ++ai)
; #pragma unroll
;             for (int m = 0; m < 4; ++m) { const size_t ro = (size_t)(row0 + ai * HALF + m * 16) * D + col0;
; #pragma unroll
;                 for (int bj = 0; bj < 2; ++bj) {
;                     f32x4 x0, x1;
;                     if constexpr (IB) { const u32x4 w = *(const u32x4*)((const bf16_t*)Xin + ro + bj * HALF);
;                         x0 = (f32x4){bflo(w[0]), bfhi(w[0]), bflo(w[1]), bfhi(w[1])}; x1 = (f32x4){bflo(w[2]), bfhi(w[2]), bflo(w[3]), bfhi(w[3])}; }
;                     else { x0 = *(const f32x4*)((const float*)Xin + ro + bj * HALF); x1 = *(const f32x4*)((const float*)Xin + ro + bj * HALF + 4); }
;                     x0 += acc[ai][bj][m][0] * sc[bj][0]; x1 += acc[ai][bj][m][1] * sc[bj][1];
;                     if constexpr (OB) { u32x4 o; o[0] = pack2(x0[0], x0[1]); o[1] = pack2(x0[2], x0[3]); o[2] = pack2(x1[0], x1[1]); o[3] = pack2(x1[2], x1[3]);
;                         *(u32x4*)((bf16_t*)Xout + ro + bj * HALF) = o; }
;                     else { *(f32x4*)((float*)Xout + ro + bj * HALF) = x0; *(f32x4*)((float*)Xout + ro + bj * HALF + 4) = x1; } } }
	s_nop 1
	v_mov_b32_e32 v120, v164
	v_mov_b32_e32 v121, v165
	v_mov_b32_e32 v122, v166
	v_mov_b32_e32 v123, v167
	s_waitcnt lgkmcnt(0)
	v_lshlrev_b32_e32 v124, 16, v120
	v_and_b32_e32 v125, 0xffff0000, v120
	v_lshlrev_b32_e32 v120, 16, v121
	v_and_b32_e32 v121, 0xffff0000, v121
	v_lshlrev_b32_e32 v126, 16, v122
	v_and_b32_e32 v127, 0xffff0000, v122
	v_lshlrev_b32_e32 v122, 16, v123
	v_and_b32_e32 v123, 0xffff0000, v123
	v_pk_add_f32 v[116:117], v[116:117], v[124:125]
	v_pk_add_f32 v[118:119], v[118:119], v[120:121]
	v_pk_add_f32 v[120:121], v[114:115], v[122:123]
	v_pk_add_f32 v[114:115], v[112:113], v[126:127]
	v_cvt_pk_bf16_f32 v112, v116, v117
	v_lshl_add_u64 v[116:117], v[144:145], 0, s[2:3]
	s_mov_b32 s2, 0x10000
	v_cvt_pk_bf16_f32 v113, v118, v119
	v_add_co_u32_e32 v118, vcc, s2, v144
	v_cvt_pk_bf16_f32 v114, v114, v115
	v_cvt_pk_bf16_f32 v115, v120, v121
	v_addc_co_u32_e32 v119, vcc, 0, v145, vcc
	global_store_dwordx4 v[144:145], v[112:115], off offset:256
	s_waitcnt vmcnt(15)
	s_nop 1
	v_mov_b32_e32 v112, v168
	v_mov_b32_e32 v113, v169
	v_mov_b32_e32 v114, v170
	v_mov_b32_e32 v115, v171
	s_mov_b64 s[2:3], 0x20000
	s_waitcnt lgkmcnt(0)
	v_lshlrev_b32_e32 v120, 16, v112
	v_and_b32_e32 v121, 0xffff0000, v112
	v_lshlrev_b32_e32 v112, 16, v113
	v_and_b32_e32 v113, 0xffff0000, v113
	v_lshlrev_b32_e32 v122, 16, v114
	v_and_b32_e32 v123, 0xffff0000, v114
	v_lshlrev_b32_e32 v114, 16, v115
	v_and_b32_e32 v115, 0xffff0000, v115
	v_pk_add_f32 v[110:111], v[110:111], v[112:113]
	v_pk_add_f32 v[108:109], v[108:109], v[120:121]
	v_pk_add_f32 v[112:113], v[106:107], v[114:115]
	v_pk_add_f32 v[106:107], v[104:105], v[122:123]
	v_cvt_pk_bf16_f32 v104, v108, v109
	v_cvt_pk_bf16_f32 v105, v110, v111
	v_cvt_pk_bf16_f32 v106, v106, v107
	v_cvt_pk_bf16_f32 v107, v112, v113
	global_store_dwordx4 v[118:119], v[104:107], off
	s_waitcnt vmcnt(15)
	s_nop 1
	v_mov_b32_e32 v104, v172
	v_mov_b32_e32 v105, v173
	v_mov_b32_e32 v106, v174
	v_mov_b32_e32 v107, v175
	s_waitcnt lgkmcnt(0)
	v_lshlrev_b32_e32 v108, 16, v104
	v_and_b32_e32 v109, 0xffff0000, v104
	v_lshlrev_b32_e32 v104, 16, v105
	v_and_b32_e32 v105, 0xffff0000, v105
	v_lshlrev_b32_e32 v110, 16, v106
	v_and_b32_e32 v111, 0xffff0000, v106
	v_lshlrev_b32_e32 v106, 16, v107
	v_and_b32_e32 v107, 0xffff0000, v107
	v_pk_add_f32 v[100:101], v[100:101], v[108:109]
	v_pk_add_f32 v[102:103], v[102:103], v[104:105]
	v_pk_add_f32 v[104:105], v[98:99], v[106:107]
	v_pk_add_f32 v[98:99], v[96:97], v[110:111]
	v_cvt_pk_bf16_f32 v96, v100, v101
	v_lshl_add_u64 v[100:101], v[144:145], 0, s[2:3]
	s_mov_b32 s2, 0x20000
	v_cvt_pk_bf16_f32 v97, v102, v103
	v_add_co_u32_e32 v102, vcc, s2, v144
	v_cvt_pk_bf16_f32 v98, v98, v99
	v_cvt_pk_bf16_f32 v99, v104, v105
	v_addc_co_u32_e32 v103, vcc, 0, v145, vcc
	global_store_dwordx4 v[116:117], v[96:99], off offset:256
	s_waitcnt vmcnt(15)
	s_nop 1
	v_mov_b32_e32 v96, v176
	v_mov_b32_e32 v97, v177
	v_mov_b32_e32 v98, v178
	v_mov_b32_e32 v99, v179
	s_mov_b64 s[2:3], 0x30000
	s_waitcnt lgkmcnt(0)
	v_lshlrev_b32_e32 v104, 16, v96
	v_and_b32_e32 v105, 0xffff0000, v96
	v_lshlrev_b32_e32 v96, 16, v97
	v_and_b32_e32 v97, 0xffff0000, v97
	v_lshlrev_b32_e32 v106, 16, v98
	v_and_b32_e32 v107, 0xffff0000, v98
	v_lshlrev_b32_e32 v98, 16, v99
	v_and_b32_e32 v99, 0xffff0000, v99
	v_pk_add_f32 v[94:95], v[94:95], v[96:97]
	v_pk_add_f32 v[92:93], v[92:93], v[104:105]
	v_pk_add_f32 v[96:97], v[90:91], v[98:99]
	v_pk_add_f32 v[90:91], v[88:89], v[106:107]
	v_cvt_pk_bf16_f32 v88, v92, v93
	v_cvt_pk_bf16_f32 v89, v94, v95
	v_cvt_pk_bf16_f32 v90, v90, v91
	v_cvt_pk_bf16_f32 v91, v96, v97
	global_store_dwordx4 v[102:103], v[88:91], off
	s_waitcnt vmcnt(15)
	s_nop 1
	v_mov_b32_e32 v88, v180
	v_mov_b32_e32 v89, v181
	v_mov_b32_e32 v90, v182
	v_mov_b32_e32 v91, v183
	s_waitcnt lgkmcnt(0)
	v_lshlrev_b32_e32 v92, 16, v88
	v_and_b32_e32 v93, 0xffff0000, v88
	v_lshlrev_b32_e32 v88, 16, v89
	v_and_b32_e32 v89, 0xffff0000, v89
	v_lshlrev_b32_e32 v94, 16, v90
	v_and_b32_e32 v95, 0xffff0000, v90
	v_lshlrev_b32_e32 v90, 16, v91
	v_and_b32_e32 v91, 0xffff0000, v91
	v_pk_add_f32 v[86:87], v[86:87], v[88:89]
	v_pk_add_f32 v[84:85], v[84:85], v[92:93]
	v_pk_add_f32 v[88:89], v[82:83], v[90:91]
	v_pk_add_f32 v[82:83], v[80:81], v[94:95]
	v_cvt_pk_bf16_f32 v80, v84, v85
	v_cvt_pk_bf16_f32 v81, v86, v87
	v_cvt_pk_bf16_f32 v82, v82, v83
	v_cvt_pk_bf16_f32 v83, v88, v89
	global_store_dwordx4 v[100:101], v[80:83], off offset:256
	s_nop 1
	v_lshl_add_u64 v[80:81], v[144:145], 0, s[2:3]
	s_mov_b32 s2, 0x30000
	v_add_co_u32_e32 v86, vcc, s2, v144
	s_mov_b64 s[2:3], 0x80000
	s_nop 0
	v_addc_co_u32_e32 v87, vcc, 0, v145, vcc
	s_waitcnt vmcnt(15)
	s_nop 1
	v_mov_b32_e32 v82, v184
	v_mov_b32_e32 v83, v185
	v_mov_b32_e32 v84, v186
	v_mov_b32_e32 v85, v187
	s_waitcnt lgkmcnt(0)
	v_lshlrev_b32_e32 v88, 16, v82
	v_and_b32_e32 v89, 0xffff0000, v82
	v_lshlrev_b32_e32 v82, 16, v83
	v_and_b32_e32 v83, 0xffff0000, v83
	v_lshlrev_b32_e32 v90, 16, v84
	v_and_b32_e32 v91, 0xffff0000, v84
	v_lshlrev_b32_e32 v84, 16, v85
	v_and_b32_e32 v85, 0xffff0000, v85
	v_pk_add_f32 v[78:79], v[78:79], v[82:83]
	v_pk_add_f32 v[76:77], v[76:77], v[88:89]
	v_pk_add_f32 v[82:83], v[74:75], v[84:85]
	v_pk_add_f32 v[74:75], v[72:73], v[90:91]
	v_cvt_pk_bf16_f32 v72, v76, v77
	v_cvt_pk_bf16_f32 v73, v78, v79
	v_cvt_pk_bf16_f32 v74, v74, v75
	v_cvt_pk_bf16_f32 v75, v82, v83
	global_store_dwordx4 v[86:87], v[72:75], off
	s_waitcnt vmcnt(15)
	s_nop 1
	v_mov_b32_e32 v72, v188
	v_mov_b32_e32 v73, v189
	v_mov_b32_e32 v74, v190
	v_mov_b32_e32 v75, v191
	s_waitcnt lgkmcnt(0)
; DI unsigned pack2(float a, float b) { f32x2 v = {a, b}; hwbf16x2 r = __builtin_convertvector(v, hwbf16x2); return __builtin_bit_cast(unsigned, r); }
; DI float bflo(unsigned w) { return __uint_as_float(w << 16); }
; DI float bfhi(unsigned w) { return __uint_as_float(w & 0xffff0000u); }
;     DI void operator()(const f32x4 (&acc)[2][2][4][2], const Unit& u, int wr, int wc, int fr, int fq) const {
;     ...
;         for (int ai = 0; ai < 2; ++ai)
; #pragma unroll
;             for (int m = 0; m < 4; ++m) { const size_t ro = (size_t)(row0 + ai * HALF + m * 16) * D + col0;
; #pragma unroll
;                 for (int bj = 0; bj < 2; ++bj) {
;                     f32x4 x0, x1;
;                     if constexpr (IB) { const u32x4 w = *(const u32x4*)((const bf16_t*)Xin + ro + bj * HALF);
;                         x0 = (f32x4){bflo(w[0]), bfhi(w[0]), bflo(w[1]), bfhi(w[1])}; x1 = (f32x4){bflo(w[2]), bfhi(w[2]), bflo(w[3]), bfhi(w[3])}; }
;                     else { x0 = *(const f32x4*)((const float*)Xin + ro + bj * HALF); x1 = *(const f32x4*)((const float*)Xin + ro + bj * HALF + 4); }
;                     x0 += acc[ai][bj][m][0] * sc[bj][0]; x1 += acc[ai][bj][m][1] * sc[bj][1];
;                     if constexpr (OB) { u32x4 o; o[0] = pack2(x0[0], x0[1]); o[1] = pack2(x0[2], x0[3]); o[2] = pack2(x1[0], x1[1]); o[3] = pack2(x1[2], x1[3]);
;                         *(u32x4*)((bf16_t*)Xout + ro + bj * HALF) = o; }
;                     else { *(f32x4*)((float*)Xout + ro + bj * HALF) = x0; *(f32x4*)((float*)Xout + ro + bj * HALF + 4) = x1; } } }
	v_lshlrev_b32_e32 v76, 16, v72
	v_and_b32_e32 v77, 0xffff0000, v72
	v_lshlrev_b32_e32 v72, 16, v73
	v_and_b32_e32 v73, 0xffff0000, v73
	v_lshlrev_b32_e32 v78, 16, v74
	v_and_b32_e32 v79, 0xffff0000, v74
	v_lshlrev_b32_e32 v74, 16, v75
	v_and_b32_e32 v75, 0xffff0000, v75
	v_pk_add_f32 v[70:71], v[70:71], v[72:73]
	v_pk_add_f32 v[68:69], v[68:69], v[76:77]
	v_pk_add_f32 v[72:73], v[66:67], v[74:75]
	v_pk_add_f32 v[66:67], v[64:65], v[78:79]
	v_cvt_pk_bf16_f32 v64, v68, v69
	v_cvt_pk_bf16_f32 v65, v70, v71
	v_cvt_pk_bf16_f32 v66, v66, v67
	v_cvt_pk_bf16_f32 v67, v72, v73
	global_store_dwordx4 v[80:81], v[64:67], off offset:256
	s_nop 1
	v_lshl_add_u64 v[64:65], v[144:145], 0, s[2:3]
	s_mov_b32 s2, 0x80000
	v_add_co_u32_e32 v70, vcc, s2, v144
	s_mov_b64 s[2:3], 0x90000
	s_nop 0
	v_addc_co_u32_e32 v71, vcc, 0, v145, vcc
	s_waitcnt vmcnt(15)
	s_nop 1
	v_mov_b32_e32 v66, v192
	v_mov_b32_e32 v67, v193
	v_mov_b32_e32 v68, v194
	v_mov_b32_e32 v69, v195
	s_waitcnt lgkmcnt(0)
	v_lshlrev_b32_e32 v72, 16, v66
	v_and_b32_e32 v73, 0xffff0000, v66
	v_lshlrev_b32_e32 v66, 16, v67
	v_and_b32_e32 v67, 0xffff0000, v67
	v_lshlrev_b32_e32 v74, 16, v68
	v_and_b32_e32 v75, 0xffff0000, v68
	v_lshlrev_b32_e32 v68, 16, v69
	v_and_b32_e32 v69, 0xffff0000, v69
	v_pk_add_f32 v[62:63], v[62:63], v[66:67]
	v_pk_add_f32 v[60:61], v[60:61], v[72:73]
	v_pk_add_f32 v[66:67], v[58:59], v[68:69]
	v_pk_add_f32 v[58:59], v[56:57], v[74:75]
	v_cvt_pk_bf16_f32 v56, v60, v61
	v_cvt_pk_bf16_f32 v57, v62, v63
	v_cvt_pk_bf16_f32 v58, v58, v59
	v_cvt_pk_bf16_f32 v59, v66, v67
	global_store_dwordx4 v[70:71], v[56:59], off
	s_waitcnt vmcnt(15)
	s_nop 1
	v_mov_b32_e32 v56, v198
	v_mov_b32_e32 v57, v199
	v_mov_b32_e32 v58, v200
	v_mov_b32_e32 v59, v201
	s_waitcnt lgkmcnt(0)
	v_lshlrev_b32_e32 v60, 16, v56
	v_and_b32_e32 v61, 0xffff0000, v56
	v_lshlrev_b32_e32 v56, 16, v57
	v_and_b32_e32 v57, 0xffff0000, v57
	v_lshlrev_b32_e32 v62, 16, v58
	v_and_b32_e32 v63, 0xffff0000, v58
	v_lshlrev_b32_e32 v58, 16, v59
	v_and_b32_e32 v59, 0xffff0000, v59
	v_pk_add_f32 v[54:55], v[54:55], v[56:57]
	v_pk_add_f32 v[52:53], v[52:53], v[60:61]
	v_pk_add_f32 v[56:57], v[50:51], v[58:59]
	v_pk_add_f32 v[50:51], v[48:49], v[62:63]
	v_cvt_pk_bf16_f32 v48, v52, v53
	v_cvt_pk_bf16_f32 v49, v54, v55
	v_cvt_pk_bf16_f32 v50, v50, v51
	v_cvt_pk_bf16_f32 v51, v56, v57
	global_store_dwordx4 v[64:65], v[48:51], off offset:256
	s_nop 1
	v_lshl_add_u64 v[48:49], v[144:145], 0, s[2:3]
	s_mov_b32 s2, 0x90000
	v_add_co_u32_e32 v54, vcc, s2, v144
	s_mov_b64 s[2:3], 0xa0000
	s_nop 0
	v_addc_co_u32_e32 v55, vcc, 0, v145, vcc
	s_waitcnt vmcnt(15)
	s_nop 1
	v_mov_b32_e32 v50, v202
	v_mov_b32_e32 v51, v203
	v_mov_b32_e32 v52, v204
	v_mov_b32_e32 v53, v205
	s_waitcnt lgkmcnt(0)
	v_lshlrev_b32_e32 v56, 16, v50
	v_and_b32_e32 v57, 0xffff0000, v50
	v_lshlrev_b32_e32 v50, 16, v51
	v_and_b32_e32 v51, 0xffff0000, v51
	v_lshlrev_b32_e32 v58, 16, v52
	v_and_b32_e32 v59, 0xffff0000, v52
	v_lshlrev_b32_e32 v52, 16, v53
	v_and_b32_e32 v53, 0xffff0000, v53
	v_pk_add_f32 v[46:47], v[46:47], v[50:51]
	v_pk_add_f32 v[44:45], v[44:45], v[56:57]
	v_pk_add_f32 v[50:51], v[42:43], v[52:53]
	v_pk_add_f32 v[42:43], v[40:41], v[58:59]
	v_cvt_pk_bf16_f32 v40, v44, v45
	v_cvt_pk_bf16_f32 v41, v46, v47
	v_cvt_pk_bf16_f32 v42, v42, v43
	v_cvt_pk_bf16_f32 v43, v50, v51
	global_store_dwordx4 v[54:55], v[40:43], off
	s_waitcnt vmcnt(15)
	s_nop 1
	v_mov_b32_e32 v40, v206
	v_mov_b32_e32 v41, v207
	v_mov_b32_e32 v42, v208
	v_mov_b32_e32 v43, v209
	s_waitcnt lgkmcnt(0)
; DI unsigned pack2(float a, float b) { f32x2 v = {a, b}; hwbf16x2 r = __builtin_convertvector(v, hwbf16x2); return __builtin_bit_cast(unsigned, r); }
; DI float bflo(unsigned w) { return __uint_as_float(w << 16); }
; DI float bfhi(unsigned w) { return __uint_as_float(w & 0xffff0000u); }
;     DI const char* a(const Unit& u) const { return (const char*)(A + (size_t)u.pm * BM * lda); }
;     DI void operator()(const f32x4 (&acc)[2][2][4][2], const Unit& u, int wr, int wc, int fr, int fq) const {
;     ...
;         for (int ai = 0; ai < 2; ++ai)
; #pragma unroll
;             for (int m = 0; m < 4; ++m) { const size_t ro = (size_t)(row0 + ai * HALF + m * 16) * D + col0;
; #pragma unroll
;                 for (int bj = 0; bj < 2; ++bj) {
;                     f32x4 x0, x1;
;                     if constexpr (IB) { const u32x4 w = *(const u32x4*)((const bf16_t*)Xin + ro + bj * HALF);
;                         x0 = (f32x4){bflo(w[0]), bfhi(w[0]), bflo(w[1]), bfhi(w[1])}; x1 = (f32x4){bflo(w[2]), bfhi(w[2]), bflo(w[3]), bfhi(w[3])}; }
;                     else { x0 = *(const f32x4*)((const float*)Xin + ro + bj * HALF); x1 = *(const f32x4*)((const float*)Xin + ro + bj * HALF + 4); }
;                     x0 += acc[ai][bj][m][0] * sc[bj][0]; x1 += acc[ai][bj][m][1] * sc[bj][1];
;                     if constexpr (OB) { u32x4 o; o[0] = pack2(x0[0], x0[1]); o[1] = pack2(x0[2], x0[3]); o[2] = pack2(x1[0], x1[1]); o[3] = pack2(x1[2], x1[3]);
;                         *(u32x4*)((bf16_t*)Xout + ro + bj * HALF) = o; }
;                     else { *(f32x4*)((float*)Xout + ro + bj * HALF) = x0; *(f32x4*)((float*)Xout + ro + bj * HALF + 4) = x1; } } }
; template <class Map, class Epi>
; DI void gemm_phase(LAS unsigned char* lds, const Map& MP, const Epi& E, const int nM, const int nN, const int K, const int lda, const int ldb) {
;     ...
;         { int frr = fr, fqq = fq; asm volatile("" : "+v"(frr), "+v"(fqq)); E(acc, cur, wr, wc, frr, fqq); }
;         if (!has_next) break;
; #pragma unroll
;         for (int a = 0; a < 2; ++a)
; #pragma unroll
;             for (int b = 0; b < 2; ++b)
; #pragma unroll
;                 for (int m = 0; m < 4; ++m)
; #pragma unroll
;                     for (int n = 0; n < 2; ++n) acc[a][b][m][n] = (f32x4){0.f, 0.f, 0.f, 0.f};
;         cur = nxt; cA = nA; cB = nB; ++ui;
;     }
;     PG8_WAIT_V(0);
;     if (wr == 0) PG8_BAR;
;     PG8_BAR;
	v_lshlrev_b32_e32 v44, 16, v40
	v_and_b32_e32 v45, 0xffff0000, v40
	v_lshlrev_b32_e32 v40, 16, v41
	v_and_b32_e32 v41, 0xffff0000, v41
	v_lshlrev_b32_e32 v46, 16, v42
	v_and_b32_e32 v47, 0xffff0000, v42
	v_lshlrev_b32_e32 v42, 16, v43
	v_and_b32_e32 v43, 0xffff0000, v43
	v_pk_add_f32 v[38:39], v[38:39], v[40:41]
	v_pk_add_f32 v[36:37], v[36:37], v[44:45]
	v_pk_add_f32 v[40:41], v[34:35], v[42:43]
	v_pk_add_f32 v[34:35], v[32:33], v[46:47]
	v_cvt_pk_bf16_f32 v32, v36, v37
	v_cvt_pk_bf16_f32 v33, v38, v39
	v_cvt_pk_bf16_f32 v34, v34, v35
	v_cvt_pk_bf16_f32 v35, v40, v41
	global_store_dwordx4 v[48:49], v[32:35], off offset:256
	s_nop 1
	v_lshl_add_u64 v[32:33], v[144:145], 0, s[2:3]
	s_mov_b32 s2, 0xa0000
	v_add_co_u32_e32 v38, vcc, s2, v144
	s_mov_b64 s[2:3], 0xb0000
	s_nop 0
	v_addc_co_u32_e32 v39, vcc, 0, v145, vcc
	s_waitcnt vmcnt(15)
	s_nop 1
	v_mov_b32_e32 v34, v210
	v_mov_b32_e32 v35, v211
	v_mov_b32_e32 v36, v212
	v_mov_b32_e32 v37, v213
	s_waitcnt lgkmcnt(0)
	v_lshlrev_b32_e32 v40, 16, v34
	v_and_b32_e32 v41, 0xffff0000, v34
	v_lshlrev_b32_e32 v34, 16, v35
	v_and_b32_e32 v35, 0xffff0000, v35
	v_lshlrev_b32_e32 v42, 16, v36
	v_and_b32_e32 v43, 0xffff0000, v36
	v_lshlrev_b32_e32 v36, 16, v37
	v_and_b32_e32 v37, 0xffff0000, v37
	v_pk_add_f32 v[30:31], v[30:31], v[34:35]
	v_pk_add_f32 v[28:29], v[28:29], v[40:41]
	v_pk_add_f32 v[34:35], v[26:27], v[36:37]
	v_pk_add_f32 v[26:27], v[24:25], v[42:43]
	v_cvt_pk_bf16_f32 v24, v28, v29
	v_cvt_pk_bf16_f32 v25, v30, v31
	v_cvt_pk_bf16_f32 v26, v26, v27
	v_cvt_pk_bf16_f32 v27, v34, v35
	global_store_dwordx4 v[38:39], v[24:27], off
	s_waitcnt vmcnt(15)
	s_nop 1
	v_mov_b32_e32 v24, v214
	v_mov_b32_e32 v25, v215
	v_mov_b32_e32 v26, v216
	v_mov_b32_e32 v27, v217
	s_waitcnt lgkmcnt(0)
	v_lshlrev_b32_e32 v28, 16, v24
	v_and_b32_e32 v29, 0xffff0000, v24
	v_lshlrev_b32_e32 v24, 16, v25
	v_and_b32_e32 v25, 0xffff0000, v25
	v_lshlrev_b32_e32 v30, 16, v26
	v_and_b32_e32 v31, 0xffff0000, v26
	v_lshlrev_b32_e32 v26, 16, v27
	v_and_b32_e32 v27, 0xffff0000, v27
	v_pk_add_f32 v[22:23], v[22:23], v[24:25]
	v_pk_add_f32 v[20:21], v[20:21], v[28:29]
	v_pk_add_f32 v[24:25], v[18:19], v[26:27]
	v_pk_add_f32 v[18:19], v[16:17], v[30:31]
	v_cvt_pk_bf16_f32 v16, v20, v21
	v_cvt_pk_bf16_f32 v17, v22, v23
	v_cvt_pk_bf16_f32 v18, v18, v19
	v_cvt_pk_bf16_f32 v19, v24, v25
	global_store_dwordx4 v[32:33], v[16:19], off offset:256
	s_nop 1
	v_lshl_add_u64 v[16:17], v[144:145], 0, s[2:3]
	s_mov_b32 s2, 0xb0000
	v_add_co_u32_e32 v22, vcc, s2, v144
	s_mov_b32 s2, s55
	s_nop 0
	v_addc_co_u32_e32 v23, vcc, 0, v145, vcc
	s_waitcnt vmcnt(15)
	s_nop 1
	v_mov_b32_e32 v18, v248
	v_mov_b32_e32 v19, v249
	v_mov_b32_e32 v20, v250
	v_mov_b32_e32 v21, v251
	s_and_b64 vcc, exec, s[40:41]
	s_waitcnt lgkmcnt(0)
	v_lshlrev_b32_e32 v24, 16, v18
	v_and_b32_e32 v25, 0xffff0000, v18
	v_lshlrev_b32_e32 v18, 16, v19
	v_and_b32_e32 v19, 0xffff0000, v19
	v_lshlrev_b32_e32 v26, 16, v20
	v_and_b32_e32 v27, 0xffff0000, v20
	v_lshlrev_b32_e32 v20, 16, v21
	v_and_b32_e32 v21, 0xffff0000, v21
	v_pk_add_f32 v[14:15], v[14:15], v[18:19]
	v_pk_add_f32 v[12:13], v[12:13], v[24:25]
	v_pk_add_f32 v[18:19], v[10:11], v[20:21]
	v_pk_add_f32 v[10:11], v[8:9], v[26:27]
	v_cvt_pk_bf16_f32 v8, v12, v13
	v_cvt_pk_bf16_f32 v9, v14, v15
	v_cvt_pk_bf16_f32 v10, v10, v11
	v_cvt_pk_bf16_f32 v11, v18, v19
	global_store_dwordx4 v[22:23], v[8:11], off
	s_waitcnt vmcnt(15)
	s_nop 1
	v_mov_b32_e32 v8, v252
	v_mov_b32_e32 v9, v253
	v_mov_b32_e32 v10, v254
	v_mov_b32_e32 v11, v255
	s_waitcnt lgkmcnt(0)
	v_lshlrev_b32_e32 v12, 16, v8
	v_and_b32_e32 v13, 0xffff0000, v8
	v_lshlrev_b32_e32 v8, 16, v9
	v_and_b32_e32 v9, 0xffff0000, v9
	v_lshlrev_b32_e32 v14, 16, v10
	v_and_b32_e32 v15, 0xffff0000, v10
	v_lshlrev_b32_e32 v10, 16, v11
	v_and_b32_e32 v11, 0xffff0000, v11
	v_pk_add_f32 v[6:7], v[6:7], v[8:9]
	v_pk_add_f32 v[4:5], v[4:5], v[12:13]
	v_pk_add_f32 v[8:9], v[2:3], v[10:11]
	v_pk_add_f32 v[2:3], v[0:1], v[14:15]
	v_cvt_pk_bf16_f32 v0, v4, v5
	v_cvt_pk_bf16_f32 v1, v6, v7
	v_cvt_pk_bf16_f32 v2, v2, v3
	v_cvt_pk_bf16_f32 v3, v8, v9
	global_store_dwordx4 v[16:17], v[0:3], off offset:256
	s_cbranch_vccz .LBB1_543
	s_waitcnt vmcnt(0)
	s_cmpk_gt_u32 s17, 0xff
	s_cbranch_scc1 .LBB1_554
	s_barrier

; #define PG8_STAGE(bufoff, gbase, voff) do { _Pragma("unroll") for (int _i = 0; _i < 2; ++_i) \
;         __builtin_amdgcn_global_load_lds((const unsigned*)((const char*)(gbase) + (voff)[_i]), (LAS unsigned*)(lds + (bufoff) + ldsw + _i * 8192), 16, 0, 0); } while (0)
; #define PG8_LDA(dst, b, h) do { _Pragma("unroll") for (int m = 0; m < 4; ++m) _Pragma("unroll") for (int k = 0; k < 2; ++k) dst[m][k] = *(const LAS bf16x8*)(lds + PG8_SA(b, h) + aoff + m * 2048 + k * 1024); } while (0)
; #define PG8_LDB(dst, b, h) do { _Pragma("unroll") for (int n = 0; n < 2; ++n) _Pragma("unroll") for (int k = 0; k < 2; ++k) dst[n][k] = *(const LAS bf16x8*)(lds + PG8_SB(b, h) + boff + n * 2048 + k * 1024); } while (0)
; #define PG8_MMA(ai, bj, At, Bt) do { __builtin_amdgcn_s_setprio(1); _Pragma("unroll") for (int m = 0; m < 4; ++m) _Pragma("unroll") for (int n = 0; n < 2; ++n) _Pragma("unroll") for (int k = 0; k < 2; ++k) \
;         acc[ai][bj][m][n] = __builtin_amdgcn_mfma_f32_16x16x32_bf16(Bt[n][k], At[m][k], acc[ai][bj][m][n], 0, 0, 0); __builtin_amdgcn_s_setprio(0); } while (0)
; #define PG8_WAIT_V(n) asm volatile("s_waitcnt vmcnt(" #n ")" ::: "memory")
; #define PG8_WAIT_L(n) asm volatile("s_waitcnt lgkmcnt(" #n ")" ::: "memory")
; template <class Map, class Epi>
; DI void gemm_phase(LAS unsigned char* lds, const Map& MP, const Epi& E, const int nM, const int nN, const int K, const int lda, const int ldb) {
;     ...
;             const bool last = (t == nt - 2);
;             const char* a1 = cA + (size_t)(t + 1) * kstep;
;             const char* a2 = last ? nA : cA + (size_t)(t + 2) * kstep; const char* b2 = last ? nB : cB + (size_t)(t + 2) * kstep;
;             const char* a3 = a2 + kstep; const char* b3 = b2 + kstep;
;             PG8_LDB(B0, 0, 0); PG8_SCHED; PG8_LDA(At, 0, 0); PG8_STAGE(PG8_SA(1, 1), a1 + hstepA, voffA);
;             PG8_WAIT_L(8); PG8_BAR; PG8_WAIT_L(0); PG8_MMA(0, 0, At, B0); PG8_BAR; PG8_SCHED;
;             PG8_LDB(B1, 0, 1); PG8_STAGE(PG8_SB(0, 0), b2, voffB);
;             PG8_BAR; PG8_WAIT_L(0); PG8_MMA(0, 1, At, B1); PG8_BAR;
;             PG8_LDA(At, 0, 1); PG8_STAGE(PG8_SA(0, 0), a2, voffA);
;             PG8_BAR; PG8_WAIT_L(0); PG8_MMA(1, 0, At, B0); PG8_BAR; PG8_SCHED;
;             PG8_STAGE(PG8_SB(0, 1), b2 + hstepB, voffB);
;             PG8_WAIT_V(6); PG8_BAR; PG8_MMA(1, 1, At, B1); PG8_BAR;
.LBB1_693:
	s_add_u32 s3, s20, 0xfff80080
	s_addc_u32 s22, s21, -1
	s_cmp_eq_u32 s54, 28
	s_cselect_b32 s25, s15, s22
	s_cselect_b32 s24, s48, s3
	s_cselect_b32 s23, s13, s53
	s_cselect_b32 s22, s49, s52
	s_add_i32 m0, s31, 0xc000
	ds_read_b128 v[166:169], v148
	ds_read_b128 v[170:173], v148 offset:1024
	ds_read_b128 v[174:177], v148 offset:2048
	ds_read_b128 v[178:181], v148 offset:3072
	ds_read_b128 v[182:185], v148 offset:4096
	ds_read_b128 v[186:189], v148 offset:5120
	ds_read_b128 v[190:193], v148 offset:6144
	ds_read_b128 v[198:201], v148 offset:7168
	global_load_lds_dwordx4 v138, s[20:21]
	s_add_i32 m0, s31, 0xe000
	s_nop 0
	global_load_lds_dwordx4 v136, s[20:21]
	s_waitcnt lgkmcnt(8)
	s_setprio 1
	s_barrier
	s_waitcnt lgkmcnt(7)
	v_mfma_f32_16x16x32_bf16 v[124:127], v[150:153], v[166:169], v[124:127]
	v_mfma_f32_16x16x32_bf16 v[120:123], v[158:161], v[166:169], v[120:123]
	s_waitcnt lgkmcnt(5)
	v_mfma_f32_16x16x32_bf16 v[116:119], v[150:153], v[174:177], v[116:119]
	v_mfma_f32_16x16x32_bf16 v[112:115], v[158:161], v[174:177], v[112:115]
	s_waitcnt lgkmcnt(3)
	v_mfma_f32_16x16x32_bf16 v[100:103], v[150:153], v[182:185], v[100:103]
	v_mfma_f32_16x16x32_bf16 v[96:99], v[158:161], v[182:185], v[96:99]
	s_waitcnt lgkmcnt(1)
	v_mfma_f32_16x16x32_bf16 v[84:87], v[150:153], v[190:193], v[84:87]
	v_mfma_f32_16x16x32_bf16 v[80:83], v[158:161], v[190:193], v[80:83]
	v_mfma_f32_16x16x32_bf16 v[124:127], v[154:157], v[170:173], v[124:127]
	s_add_i32 s3, s44, s29
	v_mfma_f32_16x16x32_bf16 v[120:123], v[162:165], v[170:173], v[120:123]
	v_lshl_add_u64 v[194:195], s[22:23], 0, v[132:133]
	v_mfma_f32_16x16x32_bf16 v[116:119], v[154:157], v[178:181], v[116:119]
	v_lshl_add_u64 v[218:219], s[22:23], 0, v[128:129]
	v_mfma_f32_16x16x32_bf16 v[112:115], v[162:165], v[178:181], v[112:115]
	v_mfma_f32_16x16x32_bf16 v[100:103], v[154:157], v[186:189], v[100:103]
	v_mfma_f32_16x16x32_bf16 v[96:99], v[162:165], v[186:189], v[96:99]
	s_waitcnt lgkmcnt(0)
	v_mfma_f32_16x16x32_bf16 v[84:87], v[154:157], v[198:201], v[84:87]
	v_mfma_f32_16x16x32_bf16 v[80:83], v[162:165], v[198:201], v[80:83]
	s_barrier
	s_setprio 0
	s_mov_b32 m0, s3
	ds_read_b128 v[202:205], v149
	ds_read_b128 v[206:209], v149 offset:1024
	ds_read_b128 v[210:213], v149 offset:2048
	ds_read_b128 v[214:217], v149 offset:3072
	global_load_lds_dwordx4 v[194:195], off
	s_add_i32 m0, s3, 0x2000
	s_nop 0
	global_load_lds_dwordx4 v[218:219], off
	s_setprio 1
	s_barrier
	s_waitcnt lgkmcnt(3)
	v_mfma_f32_16x16x32_bf16 v[108:111], v[202:205], v[166:169], v[108:111]
	s_waitcnt lgkmcnt(1)
	v_mfma_f32_16x16x32_bf16 v[104:107], v[210:213], v[166:169], v[104:107]
	v_mfma_f32_16x16x32_bf16 v[92:95], v[202:205], v[174:177], v[92:95]
	v_mfma_f32_16x16x32_bf16 v[88:91], v[210:213], v[174:177], v[88:91]
	v_mfma_f32_16x16x32_bf16 v[76:79], v[202:205], v[182:185], v[76:79]
	v_mfma_f32_16x16x32_bf16 v[72:75], v[210:213], v[182:185], v[72:75]
	v_mfma_f32_16x16x32_bf16 v[68:71], v[202:205], v[190:193], v[68:71]
	v_mfma_f32_16x16x32_bf16 v[64:67], v[210:213], v[190:193], v[64:67]
	v_mfma_f32_16x16x32_bf16 v[108:111], v[206:209], v[170:173], v[108:111]
	v_lshl_add_u64 v[222:223], s[24:25], 0, v[130:131]
	s_mov_b32 m0, s31
	s_waitcnt lgkmcnt(0)
	v_mfma_f32_16x16x32_bf16 v[104:107], v[214:217], v[170:173], v[104:107]
	v_lshl_add_u64 v[220:221], s[24:25], 0, v[134:135]
	v_mfma_f32_16x16x32_bf16 v[92:95], v[206:209], v[178:181], v[92:95]
	v_mfma_f32_16x16x32_bf16 v[88:91], v[214:217], v[178:181], v[88:91]
	v_mfma_f32_16x16x32_bf16 v[76:79], v[206:209], v[186:189], v[76:79]
	v_mfma_f32_16x16x32_bf16 v[72:75], v[214:217], v[186:189], v[72:75]
	v_mfma_f32_16x16x32_bf16 v[68:71], v[206:209], v[198:201], v[68:71]
	v_mfma_f32_16x16x32_bf16 v[64:67], v[214:217], v[198:201], v[64:67]
	s_barrier
	s_setprio 0
	ds_read_b128 v[166:169], v148 offset:16384
	ds_read_b128 v[170:173], v148 offset:17408
	ds_read_b128 v[174:177], v148 offset:18432
	ds_read_b128 v[178:181], v148 offset:19456
	ds_read_b128 v[182:185], v148 offset:20480
	ds_read_b128 v[186:189], v148 offset:21504
	ds_read_b128 v[190:193], v148 offset:22528
	ds_read_b128 v[198:201], v148 offset:23552
	global_load_lds_dwordx4 v[220:221], off
	s_mov_b32 m0, s11
	s_nop 0
	global_load_lds_dwordx4 v[222:223], off
	s_waitcnt vmcnt(10)
	s_setprio 1
	s_barrier
	s_waitcnt lgkmcnt(7)
	v_mfma_f32_16x16x32_bf16 v[60:63], v[150:153], v[166:169], v[60:63]
	v_mfma_f32_16x16x32_bf16 v[56:59], v[158:161], v[166:169], v[56:59]
	s_waitcnt lgkmcnt(5)
	v_mfma_f32_16x16x32_bf16 v[52:55], v[150:153], v[174:177], v[52:55]
	v_mfma_f32_16x16x32_bf16 v[48:51], v[158:161], v[174:177], v[48:51]
	s_waitcnt lgkmcnt(3)
	v_mfma_f32_16x16x32_bf16 v[36:39], v[150:153], v[182:185], v[36:39]
	v_mfma_f32_16x16x32_bf16 v[32:35], v[158:161], v[182:185], v[32:35]
	s_waitcnt lgkmcnt(1)
	v_mfma_f32_16x16x32_bf16 v[20:23], v[150:153], v[190:193], v[20:23]
	v_mfma_f32_16x16x32_bf16 v[16:19], v[158:161], v[190:193], v[16:19]
	v_mfma_f32_16x16x32_bf16 v[60:63], v[154:157], v[170:173], v[60:63]
	s_add_u32 s56, s22, 0x80000
	s_addc_u32 s57, s23, 0
	v_mfma_f32_16x16x32_bf16 v[56:59], v[162:165], v[170:173], v[56:59]
	s_add_i32 s3, s45, s29
	v_mfma_f32_16x16x32_bf16 v[52:55], v[154:157], v[178:181], v[52:55]
	v_mfma_f32_16x16x32_bf16 v[48:51], v[162:165], v[178:181], v[48:51]
	v_mfma_f32_16x16x32_bf16 v[36:39], v[154:157], v[186:189], v[36:39]
	v_mfma_f32_16x16x32_bf16 v[32:35], v[162:165], v[186:189], v[32:35]
	s_waitcnt lgkmcnt(0)
	v_mfma_f32_16x16x32_bf16 v[20:23], v[154:157], v[198:201], v[20:23]
	v_mfma_f32_16x16x32_bf16 v[16:19], v[162:165], v[198:201], v[16:19]
	s_barrier
; #define PG8_STAGE(bufoff, gbase, voff) do { _Pragma("unroll") for (int _i = 0; _i < 2; ++_i) \
;         __builtin_amdgcn_global_load_lds((const unsigned*)((const char*)(gbase) + (voff)[_i]), (LAS unsigned*)(lds + (bufoff) + ldsw + _i * 8192), 16, 0, 0); } while (0)
; #define PG8_LDA(dst, b, h) do { _Pragma("unroll") for (int m = 0; m < 4; ++m) _Pragma("unroll") for (int k = 0; k < 2; ++k) dst[m][k] = *(const LAS bf16x8*)(lds + PG8_SA(b, h) + aoff + m * 2048 + k * 1024); } while (0)
; #define PG8_LDB(dst, b, h) do { _Pragma("unroll") for (int n = 0; n < 2; ++n) _Pragma("unroll") for (int k = 0; k < 2; ++k) dst[n][k] = *(const LAS bf16x8*)(lds + PG8_SB(b, h) + boff + n * 2048 + k * 1024); } while (0)
; #define PG8_MMA(ai, bj, At, Bt) do { __builtin_amdgcn_s_setprio(1); _Pragma("unroll") for (int m = 0; m < 4; ++m) _Pragma("unroll") for (int n = 0; n < 2; ++n) _Pragma("unroll") for (int k = 0; k < 2; ++k) \
;         acc[ai][bj][m][n] = __builtin_amdgcn_mfma_f32_16x16x32_bf16(Bt[n][k], At[m][k], acc[ai][bj][m][n], 0, 0, 0); __builtin_amdgcn_s_setprio(0); } while (0)
; #define PG8_WAIT_V(n) asm volatile("s_waitcnt vmcnt(" #n ")" ::: "memory")
; #define PG8_WAIT_L(n) asm volatile("s_waitcnt lgkmcnt(" #n ")" ::: "memory")
; #define PG8_BAR __builtin_amdgcn_s_barrier()
; #define PG8_SCHED __builtin_amdgcn_sched_barrier(0)
; template <class Map, class Epi>
; DI void gemm_phase(LAS unsigned char* lds, const Map& MP, const Epi& E, const int nM, const int nN, const int K, const int lda, const int ldb) {
;     ...
;             PG8_WAIT_V(6); PG8_BAR; PG8_MMA(1, 1, At, B1); PG8_BAR;
;             PG8_LDB(B0, 1, 0); PG8_SCHED; PG8_LDA(At, 1, 0); PG8_STAGE(PG8_SA(0, 1), a2 + hstepA, voffA);
;             PG8_WAIT_L(8); PG8_BAR; PG8_WAIT_L(0); PG8_MMA(0, 0, At, B0); PG8_BAR; PG8_SCHED;
;             PG8_LDB(B1, 1, 1); PG8_STAGE(PG8_SB(1, 0), b3, voffB);
;             PG8_BAR; PG8_WAIT_L(0); PG8_MMA(0, 1, At, B1); PG8_BAR;
;             PG8_LDA(At, 1, 1); PG8_STAGE(PG8_SA(1, 0), a3, voffA);
;             PG8_BAR; PG8_WAIT_L(0); PG8_MMA(1, 0, At, B0); PG8_BAR; PG8_SCHED;
	s_setprio 0
	s_mov_b32 m0, s3
	s_nop 0
	global_load_lds_dwordx4 v132, s[56:57]
	s_add_i32 m0, s3, 0x2000
	s_nop 0
	global_load_lds_dwordx4 v128, s[56:57]
	s_waitcnt vmcnt(6)
	s_setprio 1
	s_barrier
	v_mfma_f32_16x16x32_bf16 v[44:47], v[202:205], v[166:169], v[44:47]
	v_mfma_f32_16x16x32_bf16 v[40:43], v[210:213], v[166:169], v[40:43]
	s_add_i32 s3, 0, 0x18000
	v_add_u32_e32 v162, s3, v146
	ds_read_b128 v[150:153], v162
	v_mfma_f32_16x16x32_bf16 v[28:31], v[202:205], v[174:177], v[28:31]
	v_mfma_f32_16x16x32_bf16 v[24:27], v[210:213], v[174:177], v[24:27]
	ds_read_b128 v[154:157], v162 offset:1024
	v_mfma_f32_16x16x32_bf16 v[12:15], v[202:205], v[182:185], v[12:15]
	v_mfma_f32_16x16x32_bf16 v[8:11], v[210:213], v[182:185], v[8:11]
	ds_read_b128 v[158:161], v162 offset:2048
	v_mfma_f32_16x16x32_bf16 v[4:7], v[202:205], v[190:193], v[4:7]
	v_mfma_f32_16x16x32_bf16 v[0:3], v[210:213], v[190:193], v[0:3]
	ds_read_b128 v[162:165], v162 offset:3072
	v_mfma_f32_16x16x32_bf16 v[44:47], v[206:209], v[170:173], v[44:47]
	s_add_u32 s24, s24, 0x80000
	s_addc_u32 s25, s25, 0
	v_mfma_f32_16x16x32_bf16 v[40:43], v[214:217], v[170:173], v[40:43]
	v_mfma_f32_16x16x32_bf16 v[28:31], v[206:209], v[178:181], v[28:31]
	v_mfma_f32_16x16x32_bf16 v[24:27], v[214:217], v[178:181], v[24:27]
	v_mfma_f32_16x16x32_bf16 v[12:15], v[206:209], v[186:189], v[12:15]
	v_mfma_f32_16x16x32_bf16 v[8:11], v[214:217], v[186:189], v[8:11]
	v_mfma_f32_16x16x32_bf16 v[4:7], v[206:209], v[198:201], v[4:7]
	v_mfma_f32_16x16x32_bf16 v[0:3], v[214:217], v[198:201], v[0:3]
	s_barrier
	s_setprio 0
	s_mov_b32 m0, s34
	ds_read_b128 v[166:169], v148 offset:32768
	ds_read_b128 v[170:173], v148 offset:33792
	ds_read_b128 v[174:177], v148 offset:34816
	ds_read_b128 v[178:181], v148 offset:35840
	ds_read_b128 v[182:185], v148 offset:36864
	ds_read_b128 v[186:189], v148 offset:37888
	ds_read_b128 v[190:193], v148 offset:38912
	ds_read_b128 v[198:201], v148 offset:39936
	global_load_lds_dwordx4 v134, s[24:25]
	s_mov_b32 m0, s35
	s_nop 0
	global_load_lds_dwordx4 v130, s[24:25]
	s_waitcnt lgkmcnt(8)
	s_setprio 1
	s_barrier
	s_waitcnt lgkmcnt(7)
	v_mfma_f32_16x16x32_bf16 v[124:127], v[150:153], v[166:169], v[124:127]
	v_mfma_f32_16x16x32_bf16 v[120:123], v[158:161], v[166:169], v[120:123]
	s_waitcnt lgkmcnt(5)
	v_mfma_f32_16x16x32_bf16 v[116:119], v[150:153], v[174:177], v[116:119]
	v_mfma_f32_16x16x32_bf16 v[112:115], v[158:161], v[174:177], v[112:115]
	s_waitcnt lgkmcnt(3)
	v_mfma_f32_16x16x32_bf16 v[100:103], v[150:153], v[182:185], v[100:103]
	v_mfma_f32_16x16x32_bf16 v[96:99], v[158:161], v[182:185], v[96:99]
	s_waitcnt lgkmcnt(1)
	v_mfma_f32_16x16x32_bf16 v[84:87], v[150:153], v[190:193], v[84:87]
	v_mfma_f32_16x16x32_bf16 v[80:83], v[158:161], v[190:193], v[80:83]
	v_mfma_f32_16x16x32_bf16 v[124:127], v[154:157], v[170:173], v[124:127]
	s_add_i32 s24, 0, 0x1c000
	v_mfma_f32_16x16x32_bf16 v[120:123], v[162:165], v[170:173], v[120:123]
	s_add_i32 s3, s3, s29
	v_mfma_f32_16x16x32_bf16 v[116:119], v[154:157], v[178:181], v[116:119]
	v_add_u32_e32 v196, s24, v146
	v_mfma_f32_16x16x32_bf16 v[112:115], v[162:165], v[178:181], v[112:115]
	v_lshl_add_u64 v[194:195], v[194:195], 0, s[8:9]
	v_mfma_f32_16x16x32_bf16 v[100:103], v[154:157], v[186:189], v[100:103]
	v_mfma_f32_16x16x32_bf16 v[96:99], v[162:165], v[186:189], v[96:99]
	s_waitcnt lgkmcnt(0)
	v_mfma_f32_16x16x32_bf16 v[84:87], v[154:157], v[198:201], v[84:87]
	v_mfma_f32_16x16x32_bf16 v[80:83], v[162:165], v[198:201], v[80:83]
	s_barrier
	s_setprio 0
	s_mov_b32 m0, s3
	ds_read_b128 v[202:205], v196
	ds_read_b128 v[206:209], v196 offset:1024
	ds_read_b128 v[210:213], v196 offset:2048
	ds_read_b128 v[214:217], v196 offset:3072
	global_load_lds_dwordx4 v[194:195], off
	v_lshl_add_u64 v[194:195], v[218:219], 0, s[8:9]
	s_add_i32 m0, s3, 0x2000
	s_nop 0
	global_load_lds_dwordx4 v[194:195], off
	s_setprio 1
	s_barrier
	s_waitcnt lgkmcnt(3)
	v_mfma_f32_16x16x32_bf16 v[108:111], v[202:205], v[166:169], v[108:111]
	s_waitcnt lgkmcnt(1)
	v_mfma_f32_16x16x32_bf16 v[104:107], v[210:213], v[166:169], v[104:107]
	v_mfma_f32_16x16x32_bf16 v[92:95], v[202:205], v[174:177], v[92:95]
	v_mfma_f32_16x16x32_bf16 v[88:91], v[210:213], v[174:177], v[88:91]
	v_mfma_f32_16x16x32_bf16 v[76:79], v[202:205], v[182:185], v[76:79]
	v_mfma_f32_16x16x32_bf16 v[72:75], v[210:213], v[182:185], v[72:75]
	v_mfma_f32_16x16x32_bf16 v[68:71], v[202:205], v[190:193], v[68:71]
	v_mfma_f32_16x16x32_bf16 v[64:67], v[210:213], v[190:193], v[64:67]
	v_mfma_f32_16x16x32_bf16 v[108:111], v[206:209], v[170:173], v[108:111]
	s_mov_b32 m0, s39
	s_waitcnt lgkmcnt(0)
	v_mfma_f32_16x16x32_bf16 v[104:107], v[214:217], v[170:173], v[104:107]
	v_lshl_add_u64 v[194:195], v[220:221], 0, s[8:9]
	v_mfma_f32_16x16x32_bf16 v[92:95], v[206:209], v[178:181], v[92:95]
	v_mfma_f32_16x16x32_bf16 v[88:91], v[214:217], v[178:181], v[88:91]
	v_mfma_f32_16x16x32_bf16 v[76:79], v[206:209], v[186:189], v[76:79]
	v_mfma_f32_16x16x32_bf16 v[72:75], v[214:217], v[186:189], v[72:75]
	v_mfma_f32_16x16x32_bf16 v[68:71], v[206:209], v[198:201], v[68:71]
	v_mfma_f32_16x16x32_bf16 v[64:67], v[214:217], v[198:201], v[64:67]
	s_barrier
	s_setprio 0
	ds_read_b128 v[166:169], v148 offset:49152
	ds_read_b128 v[170:173], v148 offset:50176
	ds_read_b128 v[174:177], v148 offset:51200
	ds_read_b128 v[178:181], v148 offset:52224
	ds_read_b128 v[182:185], v148 offset:53248
	ds_read_b128 v[186:189], v148 offset:54272
	ds_read_b128 v[190:193], v148 offset:55296
	ds_read_b128 v[198:201], v148 offset:56320
	global_load_lds_dwordx4 v[194:195], off
	v_lshl_add_u64 v[194:195], v[222:223], 0, s[8:9]
	s_mov_b32 m0, s42
	s_nop 0
	global_load_lds_dwordx4 v[194:195], off
	s_waitcnt vmcnt(10)
	s_setprio 1
	s_barrier
; #define PG8_STAGE(bufoff, gbase, voff) do { _Pragma("unroll") for (int _i = 0; _i < 2; ++_i) \
;         __builtin_amdgcn_global_load_lds((const unsigned*)((const char*)(gbase) + (voff)[_i]), (LAS unsigned*)(lds + (bufoff) + ldsw + _i * 8192), 16, 0, 0); } while (0)
; #define PG8_MMA(ai, bj, At, Bt) do { __builtin_amdgcn_s_setprio(1); _Pragma("unroll") for (int m = 0; m < 4; ++m) _Pragma("unroll") for (int n = 0; n < 2; ++n) _Pragma("unroll") for (int k = 0; k < 2; ++k) \
;         acc[ai][bj][m][n] = __builtin_amdgcn_mfma_f32_16x16x32_bf16(Bt[n][k], At[m][k], acc[ai][bj][m][n], 0, 0, 0); __builtin_amdgcn_s_setprio(0); } while (0)
; #define PG8_WAIT_V(n) asm volatile("s_waitcnt vmcnt(" #n ")" ::: "memory")
; #define PG8_BAR __builtin_amdgcn_s_barrier()
; template <class Map, class Epi>
; DI void gemm_phase(LAS unsigned char* lds, const Map& MP, const Epi& E, const int nM, const int nN, const int K, const int lda, const int ldb) {
;     ...
;             PG8_STAGE(PG8_SB(1, 1), b3 + hstepB, voffB);
;             PG8_WAIT_V(6); PG8_BAR; PG8_MMA(1, 1, At, B1); PG8_BAR;
	s_waitcnt lgkmcnt(7)
	v_mfma_f32_16x16x32_bf16 v[60:63], v[150:153], v[166:169], v[60:63]
	v_mfma_f32_16x16x32_bf16 v[56:59], v[158:161], v[166:169], v[56:59]
	s_waitcnt lgkmcnt(5)
	v_mfma_f32_16x16x32_bf16 v[52:55], v[150:153], v[174:177], v[52:55]
	v_mfma_f32_16x16x32_bf16 v[48:51], v[158:161], v[174:177], v[48:51]
	s_waitcnt lgkmcnt(3)
	v_mfma_f32_16x16x32_bf16 v[36:39], v[150:153], v[182:185], v[36:39]
	v_mfma_f32_16x16x32_bf16 v[32:35], v[158:161], v[182:185], v[32:35]
	s_waitcnt lgkmcnt(1)
	v_mfma_f32_16x16x32_bf16 v[20:23], v[150:153], v[190:193], v[20:23]
	v_mfma_f32_16x16x32_bf16 v[16:19], v[158:161], v[190:193], v[16:19]
	v_mfma_f32_16x16x32_bf16 v[60:63], v[154:157], v[170:173], v[60:63]
	s_add_u32 s22, s22, 0x80080
	s_addc_u32 s23, s23, 0
	v_mfma_f32_16x16x32_bf16 v[56:59], v[162:165], v[170:173], v[56:59]
	s_add_i32 s3, s24, s29
	v_mfma_f32_16x16x32_bf16 v[52:55], v[154:157], v[178:181], v[52:55]
	v_mfma_f32_16x16x32_bf16 v[48:51], v[162:165], v[178:181], v[48:51]
	v_mfma_f32_16x16x32_bf16 v[36:39], v[154:157], v[186:189], v[36:39]
	v_mfma_f32_16x16x32_bf16 v[32:35], v[162:165], v[186:189], v[32:35]
	s_waitcnt lgkmcnt(0)
	v_mfma_f32_16x16x32_bf16 v[20:23], v[154:157], v[198:201], v[20:23]
	v_mfma_f32_16x16x32_bf16 v[16:19], v[162:165], v[198:201], v[16:19]
	s_barrier
	s_setprio 0
	s_mov_b32 m0, s3
	s_nop 0
	global_load_lds_dwordx4 v132, s[22:23]
	s_add_i32 m0, s3, 0x2000
	s_nop 0
	global_load_lds_dwordx4 v128, s[22:23]
	s_waitcnt vmcnt(6)
	s_setprio 1
	s_barrier
	v_mfma_f32_16x16x32_bf16 v[44:47], v[202:205], v[166:169], v[44:47]
	v_mfma_f32_16x16x32_bf16 v[40:43], v[210:213], v[166:169], v[40:43]
	ds_read_b128 v[150:153], v147
	v_mfma_f32_16x16x32_bf16 v[28:31], v[202:205], v[174:177], v[28:31]
	v_mfma_f32_16x16x32_bf16 v[24:27], v[210:213], v[174:177], v[24:27]
	ds_read_b128 v[154:157], v147 offset:1024
	v_mfma_f32_16x16x32_bf16 v[12:15], v[202:205], v[182:185], v[12:15]
	v_mfma_f32_16x16x32_bf16 v[8:11], v[210:213], v[182:185], v[8:11]
	ds_read_b128 v[158:161], v147 offset:2048
	v_mfma_f32_16x16x32_bf16 v[4:7], v[202:205], v[190:193], v[4:7]
	v_mfma_f32_16x16x32_bf16 v[0:3], v[210:213], v[190:193], v[0:3]
	ds_read_b128 v[162:165], v147 offset:3072
	v_mfma_f32_16x16x32_bf16 v[44:47], v[206:209], v[170:173], v[44:47]
	s_add_i32 s54, s54, 2
	v_mfma_f32_16x16x32_bf16 v[40:43], v[214:217], v[170:173], v[40:43]
	s_add_u32 s52, s52, 0x100
	s_addc_u32 s53, s53, 0
	v_mfma_f32_16x16x32_bf16 v[28:31], v[206:209], v[178:181], v[28:31]
	s_add_u32 s20, s20, 0x100
	s_addc_u32 s21, s21, 0
	v_mfma_f32_16x16x32_bf16 v[24:27], v[214:217], v[178:181], v[24:27]
	s_cmp_gt_u32 s54, 29
	v_mfma_f32_16x16x32_bf16 v[12:15], v[206:209], v[186:189], v[12:15]
	v_mfma_f32_16x16x32_bf16 v[8:11], v[214:217], v[186:189], v[8:11]
	v_mfma_f32_16x16x32_bf16 v[4:7], v[206:209], v[198:201], v[4:7]
	v_mfma_f32_16x16x32_bf16 v[0:3], v[214:217], v[198:201], v[0:3]
	s_barrier
	s_setprio 0
	s_cbranch_scc0 .LBB1_693
; DI unsigned pack2(float a, float b) { f32x2 v = {a, b}; hwbf16x2 r = __builtin_convertvector(v, hwbf16x2); return __builtin_bit_cast(unsigned, r); }
;     DI const char* a(const Unit& u) const { return (const char*)(A + (size_t)u.pm * BM * lda); }
;     DI const char* a(const Unit& u) const { return (const char*)(A + (size_t)u.pm * BM * 2048 + (u.pn >> 1) * 512); }
;     DI const char* a(const Unit& u) const { return (const char*)((u.pn < 12 ? A1 : A2) + (size_t)u.pm * BM * 512); }
; #define PG8_WAIT_V(n) asm volatile("s_waitcnt vmcnt(" #n ")" ::: "memory")
; #define PG8_BAR __builtin_amdgcn_s_barrier()
;     DI void operator()(const f32x4 (&acc)[2][2][4][2], const Unit& u, int wr, int wc, int fr, int fq) const {
;         bf16_t* O = O1; int ldc = ldc1, pn = u.pn; if (pn >= split) { O = O2; ldc = ldc2; pn -= split; }
;         const int row0 = u.pm * BM + wr * 64 + fr, col0 = pn * BM + wc * 32 + 8 * fq;
; #pragma unroll
;         for (int ai = 0; ai < 2; ++ai)
; #pragma unroll
;             for (int m = 0; m < 4; ++m) { bf16_t* rowp = O + (size_t)(row0 + ai * HALF + m * 16) * ldc + col0;
; #pragma unroll
;                 for (int bj = 0; bj < 2; ++bj) { const f32x4 v0 = acc[ai][bj][m][0], v1 = acc[ai][bj][m][1];
;                     u32x4 o; o[0] = pack2(v0[0], v0[1]); o[1] = pack2(v0[2], v0[3]); o[2] = pack2(v1[0], v1[1]); o[3] = pack2(v1[2], v1[3]);
;                     *(u32x4*)(rowp + bj * HALF) = o; } }
;     }
; template <class Map, class Epi>
; DI void gemm_phase(LAS unsigned char* lds, const Map& MP, const Epi& E, const int nM, const int nN, const int K, const int lda, const int ldb) {
;     ...
;         { int frr = fr, fqq = fq; asm volatile("" : "+v"(frr), "+v"(fqq)); E(acc, cur, wr, wc, frr, fqq); }
;         if (!has_next) break;
; #pragma unroll
;         for (int a = 0; a < 2; ++a)
; #pragma unroll
;             for (int b = 0; b < 2; ++b)
; #pragma unroll
;                 for (int m = 0; m < 4; ++m)
; #pragma unroll
;                     for (int n = 0; n < 2; ++n) acc[a][b][m][n] = (f32x4){0.f, 0.f, 0.f, 0.f};
;         cur = nxt; cA = nA; cB = nB; ++ui;
;     }
;     PG8_WAIT_V(0);
;     if (wr == 0) PG8_BAR;
;     PG8_BAR;
	s_waitcnt lgkmcnt(0)
	s_lshl_b32 s3, s10, 8
	v_mov_b32_e32 v150, v144
	v_mov_b32_e32 v151, v145
	s_add_i32 s3, s3, s37
	v_cvt_pk_bf16_f32 v68, v68, v69
	v_add_u32_e32 v154, s3, v150
	s_lshl_b32 s3, s47, 8
	s_or_b32 s3, s3, s38
	v_lshl_add_u32 v150, v151, 3, s3
	v_ashrrev_i32_e32 v151, 31, v150
	v_lshl_add_u64 v[150:151], v[150:151], 1, s[6:7]
	v_cvt_pk_bf16_f32 v69, v70, v71
	v_cvt_pk_bf16_f32 v70, v64, v65
	v_add_u32_e32 v64, 0x80, v154
	v_mad_i64_i32 v[152:153], s[20:21], v154, s46, v[150:151]
	v_cvt_pk_bf16_f32 v108, v108, v109
	v_cvt_pk_bf16_f32 v109, v110, v111
	v_cvt_pk_bf16_f32 v110, v104, v105
	v_cvt_pk_bf16_f32 v111, v106, v107
	v_add_u32_e32 v104, 16, v154
	v_mad_i64_i32 v[64:65], s[20:21], v64, s46, v[150:151]
	v_cvt_pk_bf16_f32 v44, v44, v45
	v_cvt_pk_bf16_f32 v45, v46, v47
	v_cvt_pk_bf16_f32 v46, v40, v41
	v_cvt_pk_bf16_f32 v47, v42, v43
	v_add_u32_e32 v40, 0x90, v154
	global_store_dwordx4 v[152:153], v[108:111], off offset:256
	v_cvt_pk_bf16_f32 v92, v92, v93
	v_cvt_pk_bf16_f32 v93, v94, v95
	v_mad_i64_i32 v[108:109], s[20:21], v104, s46, v[150:151]
	v_cvt_pk_bf16_f32 v94, v88, v89
	v_cvt_pk_bf16_f32 v95, v90, v91
	v_add_u32_e32 v88, 32, v154
	global_store_dwordx4 v[64:65], v[44:47], off offset:256
	v_cvt_pk_bf16_f32 v28, v28, v29
	v_cvt_pk_bf16_f32 v29, v30, v31
	v_mad_i64_i32 v[44:45], s[20:21], v40, s46, v[150:151]
	v_cvt_pk_bf16_f32 v30, v24, v25
	v_cvt_pk_bf16_f32 v31, v26, v27
	v_add_u32_e32 v24, 0xa0, v154
	global_store_dwordx4 v[108:109], v[92:95], off offset:256
	v_cvt_pk_bf16_f32 v76, v76, v77
	v_cvt_pk_bf16_f32 v77, v78, v79
	v_mad_i64_i32 v[92:93], s[20:21], v88, s46, v[150:151]
	v_cvt_pk_bf16_f32 v78, v72, v73
	v_cvt_pk_bf16_f32 v79, v74, v75
	v_add_u32_e32 v72, 48, v154
	global_store_dwordx4 v[44:45], v[28:31], off offset:256
	v_cvt_pk_bf16_f32 v12, v12, v13
	v_cvt_pk_bf16_f32 v13, v14, v15
	v_mad_i64_i32 v[28:29], s[20:21], v24, s46, v[150:151]
	v_cvt_pk_bf16_f32 v14, v8, v9
	v_cvt_pk_bf16_f32 v15, v10, v11
	v_add_u32_e32 v8, 0xb0, v154
	global_store_dwordx4 v[92:93], v[76:79], off offset:256
	global_store_dwordx4 v[28:29], v[12:15], off offset:256
	v_cvt_pk_bf16_f32 v124, v124, v125
	v_mad_i64_i32 v[76:77], s[20:21], v72, s46, v[150:151]
	v_mad_i64_i32 v[12:13], s[20:21], v8, s46, v[150:151]
	v_cvt_pk_bf16_f32 v125, v126, v127
	v_cvt_pk_bf16_f32 v126, v120, v121
	v_cvt_pk_bf16_f32 v127, v122, v123
	v_cvt_pk_bf16_f32 v104, v116, v117
	v_cvt_pk_bf16_f32 v105, v118, v119
	v_cvt_pk_bf16_f32 v106, v112, v113
	v_cvt_pk_bf16_f32 v107, v114, v115
	v_cvt_pk_bf16_f32 v88, v100, v101
	v_cvt_pk_bf16_f32 v89, v102, v103
	v_cvt_pk_bf16_f32 v90, v96, v97
	v_cvt_pk_bf16_f32 v91, v98, v99
	v_cvt_pk_bf16_f32 v72, v84, v85
	v_cvt_pk_bf16_f32 v73, v86, v87
	v_cvt_pk_bf16_f32 v74, v80, v81
	v_cvt_pk_bf16_f32 v75, v82, v83
	v_cvt_pk_bf16_f32 v71, v66, v67
	v_cvt_pk_bf16_f32 v60, v60, v61
	v_cvt_pk_bf16_f32 v61, v62, v63
	v_cvt_pk_bf16_f32 v62, v56, v57
	v_cvt_pk_bf16_f32 v63, v58, v59
	v_cvt_pk_bf16_f32 v40, v52, v53
	v_cvt_pk_bf16_f32 v41, v54, v55
	v_cvt_pk_bf16_f32 v42, v48, v49
	v_cvt_pk_bf16_f32 v43, v50, v51
	v_cvt_pk_bf16_f32 v24, v36, v37
	v_cvt_pk_bf16_f32 v25, v38, v39
	v_cvt_pk_bf16_f32 v26, v32, v33
	v_cvt_pk_bf16_f32 v27, v34, v35
	v_cvt_pk_bf16_f32 v8, v20, v21
	v_cvt_pk_bf16_f32 v9, v22, v23
	v_cvt_pk_bf16_f32 v10, v16, v17
	v_cvt_pk_bf16_f32 v11, v18, v19
	v_cvt_pk_bf16_f32 v4, v4, v5
	v_cvt_pk_bf16_f32 v5, v6, v7
	v_cvt_pk_bf16_f32 v6, v0, v1
	v_cvt_pk_bf16_f32 v7, v2, v3
	s_and_b64 vcc, exec, s[40:41]
	s_mov_b32 s47, s12
	s_mov_b32 s10, s14
	s_mov_b64 s[20:21], s[18:19]
	s_mov_b64 s[22:23], s[16:17]
	global_store_dwordx4 v[152:153], v[124:127], off
	global_store_dwordx4 v[108:109], v[104:107], off
	global_store_dwordx4 v[92:93], v[88:91], off
	global_store_dwordx4 v[76:77], v[72:75], off
	global_store_dwordx4 v[76:77], v[68:71], off offset:256
	global_store_dwordx4 v[64:65], v[60:63], off
	global_store_dwordx4 v[44:45], v[40:43], off
	global_store_dwordx4 v[28:29], v[24:27], off
	global_store_dwordx4 v[12:13], v[8:11], off
	global_store_dwordx4 v[12:13], v[4:7], off offset:256
	s_cbranch_vccz .LBB1_690
	s_waitcnt vmcnt(0)
	s_cmpk_gt_u32 s4, 0xff
	s_cbranch_scc1 .LBB1_697
	s_barrier

; #define PG8_STAGE(bufoff, gbase, voff) do { _Pragma("unroll") for (int _i = 0; _i < 2; ++_i) \
;         __builtin_amdgcn_global_load_lds((const unsigned*)((const char*)(gbase) + (voff)[_i]), (LAS unsigned*)(lds + (bufoff) + ldsw + _i * 8192), 16, 0, 0); } while (0)
; #define PG8_LDA(dst, b, h) do { _Pragma("unroll") for (int m = 0; m < 4; ++m) _Pragma("unroll") for (int k = 0; k < 2; ++k) dst[m][k] = *(const LAS bf16x8*)(lds + PG8_SA(b, h) + aoff + m * 2048 + k * 1024); } while (0)
; #define PG8_LDB(dst, b, h) do { _Pragma("unroll") for (int n = 0; n < 2; ++n) _Pragma("unroll") for (int k = 0; k < 2; ++k) dst[n][k] = *(const LAS bf16x8*)(lds + PG8_SB(b, h) + boff + n * 2048 + k * 1024); } while (0)
; #define PG8_MMA(ai, bj, At, Bt) do { __builtin_amdgcn_s_setprio(1); _Pragma("unroll") for (int m = 0; m < 4; ++m) _Pragma("unroll") for (int n = 0; n < 2; ++n) _Pragma("unroll") for (int k = 0; k < 2; ++k) \
;         acc[ai][bj][m][n] = __builtin_amdgcn_mfma_f32_16x16x32_bf16(Bt[n][k], At[m][k], acc[ai][bj][m][n], 0, 0, 0); __builtin_amdgcn_s_setprio(0); } while (0)
; #define PG8_WAIT_V(n) asm volatile("s_waitcnt vmcnt(" #n ")" ::: "memory")
; #define PG8_WAIT_L(n) asm volatile("s_waitcnt lgkmcnt(" #n ")" ::: "memory")
; template <class Map, class Epi>
; DI void gemm_phase(LAS unsigned char* lds, const Map& MP, const Epi& E, const int nM, const int nN, const int K, const int lda, const int ldb) {
;     ...
;             const bool last = (t == nt - 2);
;             const char* a1 = cA + (size_t)(t + 1) * kstep;
;             const char* a2 = last ? nA : cA + (size_t)(t + 2) * kstep; const char* b2 = last ? nB : cB + (size_t)(t + 2) * kstep;
;             const char* a3 = a2 + kstep; const char* b3 = b2 + kstep;
;             PG8_LDB(B0, 0, 0); PG8_SCHED; PG8_LDA(At, 0, 0); PG8_STAGE(PG8_SA(1, 1), a1 + hstepA, voffA);
;             PG8_WAIT_L(8); PG8_BAR; PG8_WAIT_L(0); PG8_MMA(0, 0, At, B0); PG8_BAR; PG8_SCHED;
;             PG8_LDB(B1, 0, 1); PG8_STAGE(PG8_SB(0, 0), b2, voffB);
;             PG8_BAR; PG8_WAIT_L(0); PG8_MMA(0, 1, At, B1); PG8_BAR;
;             PG8_LDA(At, 0, 1); PG8_STAGE(PG8_SA(0, 0), a2, voffA);
;             PG8_BAR; PG8_WAIT_L(0); PG8_MMA(1, 0, At, B0); PG8_BAR; PG8_SCHED;
;             PG8_STAGE(PG8_SB(0, 1), b2 + hstepB, voffB);
;             PG8_WAIT_V(6); PG8_BAR; PG8_MMA(1, 1, At, B1); PG8_BAR;
.LBB1_925:
	s_add_u32 s3, s10, 0xfff80080
	s_addc_u32 s12, s11, -1
	s_cmp_eq_u32 s48, 28
	s_cselect_b32 s15, s4, s12
	s_cselect_b32 s14, s5, s3
	s_cselect_b32 s13, s37, s47
	s_cselect_b32 s12, s38, s39
	s_add_i32 m0, s24, 0xc000
	ds_read_b128 v[168:171], v150
	ds_read_b128 v[172:175], v150 offset:1024
	ds_read_b128 v[176:179], v150 offset:2048
	ds_read_b128 v[180:183], v150 offset:3072
	ds_read_b128 v[184:187], v150 offset:4096
	ds_read_b128 v[188:191], v150 offset:5120
	ds_read_b128 v[192:195], v150 offset:6144
	ds_read_b128 v[198:201], v150 offset:7168
	global_load_lds_dwordx4 v138, s[10:11]
	s_add_i32 m0, s24, 0xe000
	s_nop 0
	global_load_lds_dwordx4 v136, s[10:11]
	s_waitcnt lgkmcnt(8)
	s_setprio 1
	s_barrier
	s_waitcnt lgkmcnt(7)
	v_mfma_f32_16x16x32_bf16 v[124:127], v[152:155], v[168:171], v[124:127]
	v_mfma_f32_16x16x32_bf16 v[120:123], v[160:163], v[168:171], v[120:123]
	s_waitcnt lgkmcnt(5)
	v_mfma_f32_16x16x32_bf16 v[108:111], v[152:155], v[176:179], v[108:111]
	v_mfma_f32_16x16x32_bf16 v[104:107], v[160:163], v[176:179], v[104:107]
	s_waitcnt lgkmcnt(3)
	v_mfma_f32_16x16x32_bf16 v[92:95], v[152:155], v[184:187], v[92:95]
	v_mfma_f32_16x16x32_bf16 v[88:91], v[160:163], v[184:187], v[88:91]
	s_waitcnt lgkmcnt(1)
	v_mfma_f32_16x16x32_bf16 v[76:79], v[152:155], v[192:195], v[76:79]
	v_mfma_f32_16x16x32_bf16 v[72:75], v[160:163], v[192:195], v[72:75]
	v_mfma_f32_16x16x32_bf16 v[124:127], v[156:159], v[172:175], v[124:127]
	s_add_i32 s3, s35, s22
	v_mfma_f32_16x16x32_bf16 v[120:123], v[164:167], v[172:175], v[120:123]
	v_lshl_add_u64 v[144:145], s[12:13], 0, v[132:133]
	v_mfma_f32_16x16x32_bf16 v[108:111], v[156:159], v[180:183], v[108:111]
	v_lshl_add_u64 v[218:219], s[12:13], 0, v[128:129]
	v_mfma_f32_16x16x32_bf16 v[104:107], v[164:167], v[180:183], v[104:107]
	v_mfma_f32_16x16x32_bf16 v[92:95], v[156:159], v[188:191], v[92:95]
	v_mfma_f32_16x16x32_bf16 v[88:91], v[164:167], v[188:191], v[88:91]
	s_waitcnt lgkmcnt(0)
	v_mfma_f32_16x16x32_bf16 v[76:79], v[156:159], v[198:201], v[76:79]
	v_mfma_f32_16x16x32_bf16 v[72:75], v[164:167], v[198:201], v[72:75]
	s_barrier
	s_setprio 0
	s_mov_b32 m0, s3
	ds_read_b128 v[202:205], v151
	ds_read_b128 v[206:209], v151 offset:1024
	ds_read_b128 v[210:213], v151 offset:2048
	ds_read_b128 v[214:217], v151 offset:3072
	global_load_lds_dwordx4 v[144:145], off
	s_add_i32 m0, s3, 0x2000
	s_nop 0
	global_load_lds_dwordx4 v[218:219], off
	s_setprio 1
	s_barrier
	s_waitcnt lgkmcnt(3)
	v_mfma_f32_16x16x32_bf16 v[116:119], v[202:205], v[168:171], v[116:119]
	s_waitcnt lgkmcnt(1)
	v_mfma_f32_16x16x32_bf16 v[112:115], v[210:213], v[168:171], v[112:115]
	v_mfma_f32_16x16x32_bf16 v[100:103], v[202:205], v[176:179], v[100:103]
	v_mfma_f32_16x16x32_bf16 v[96:99], v[210:213], v[176:179], v[96:99]
	v_mfma_f32_16x16x32_bf16 v[84:87], v[202:205], v[184:187], v[84:87]
	v_mfma_f32_16x16x32_bf16 v[80:83], v[210:213], v[184:187], v[80:83]
	v_mfma_f32_16x16x32_bf16 v[68:71], v[202:205], v[192:195], v[68:71]
	v_mfma_f32_16x16x32_bf16 v[64:67], v[210:213], v[192:195], v[64:67]
	v_mfma_f32_16x16x32_bf16 v[116:119], v[206:209], v[172:175], v[116:119]
	v_lshl_add_u64 v[222:223], s[14:15], 0, v[130:131]
	s_mov_b32 m0, s24
	s_waitcnt lgkmcnt(0)
	v_mfma_f32_16x16x32_bf16 v[112:115], v[214:217], v[172:175], v[112:115]
	v_lshl_add_u64 v[220:221], s[14:15], 0, v[134:135]
	v_mfma_f32_16x16x32_bf16 v[100:103], v[206:209], v[180:183], v[100:103]
	v_mfma_f32_16x16x32_bf16 v[96:99], v[214:217], v[180:183], v[96:99]
	v_mfma_f32_16x16x32_bf16 v[84:87], v[206:209], v[188:191], v[84:87]
	v_mfma_f32_16x16x32_bf16 v[80:83], v[214:217], v[188:191], v[80:83]
	v_mfma_f32_16x16x32_bf16 v[68:71], v[206:209], v[198:201], v[68:71]
	v_mfma_f32_16x16x32_bf16 v[64:67], v[214:217], v[198:201], v[64:67]
	s_barrier
	s_setprio 0
	ds_read_b128 v[168:171], v150 offset:16384
	ds_read_b128 v[172:175], v150 offset:17408
	ds_read_b128 v[176:179], v150 offset:18432
	ds_read_b128 v[180:183], v150 offset:19456
	ds_read_b128 v[184:187], v150 offset:20480
	ds_read_b128 v[188:191], v150 offset:21504
	ds_read_b128 v[192:195], v150 offset:22528
	ds_read_b128 v[198:201], v150 offset:23552
	global_load_lds_dwordx4 v[220:221], off
	s_mov_b32 m0, s9
	s_nop 0
	global_load_lds_dwordx4 v[222:223], off
	s_waitcnt vmcnt(10)
	s_setprio 1
	s_barrier
	s_waitcnt lgkmcnt(7)
	v_mfma_f32_16x16x32_bf16 v[60:63], v[152:155], v[168:171], v[60:63]
	v_mfma_f32_16x16x32_bf16 v[56:59], v[160:163], v[168:171], v[56:59]
	s_waitcnt lgkmcnt(5)
	v_mfma_f32_16x16x32_bf16 v[44:47], v[152:155], v[176:179], v[44:47]
	v_mfma_f32_16x16x32_bf16 v[40:43], v[160:163], v[176:179], v[40:43]
	s_waitcnt lgkmcnt(3)
	v_mfma_f32_16x16x32_bf16 v[28:31], v[152:155], v[184:187], v[28:31]
	v_mfma_f32_16x16x32_bf16 v[24:27], v[160:163], v[184:187], v[24:27]
	s_waitcnt lgkmcnt(1)
	v_mfma_f32_16x16x32_bf16 v[12:15], v[152:155], v[192:195], v[12:15]
	v_mfma_f32_16x16x32_bf16 v[8:11], v[160:163], v[192:195], v[8:11]
	v_mfma_f32_16x16x32_bf16 v[60:63], v[156:159], v[172:175], v[60:63]
	s_add_u32 s56, s12, 0x80000
	s_addc_u32 s57, s13, 0
	v_mfma_f32_16x16x32_bf16 v[56:59], v[164:167], v[172:175], v[56:59]
	s_add_i32 s3, s36, s22
	v_mfma_f32_16x16x32_bf16 v[44:47], v[156:159], v[180:183], v[44:47]
	v_mfma_f32_16x16x32_bf16 v[40:43], v[164:167], v[180:183], v[40:43]
	v_mfma_f32_16x16x32_bf16 v[28:31], v[156:159], v[188:191], v[28:31]
	v_mfma_f32_16x16x32_bf16 v[24:27], v[164:167], v[188:191], v[24:27]
	s_waitcnt lgkmcnt(0)
	v_mfma_f32_16x16x32_bf16 v[12:15], v[156:159], v[198:201], v[12:15]
	v_mfma_f32_16x16x32_bf16 v[8:11], v[164:167], v[198:201], v[8:11]
	s_barrier
; #define PG8_STAGE(bufoff, gbase, voff) do { _Pragma("unroll") for (int _i = 0; _i < 2; ++_i) \
;         __builtin_amdgcn_global_load_lds((const unsigned*)((const char*)(gbase) + (voff)[_i]), (LAS unsigned*)(lds + (bufoff) + ldsw + _i * 8192), 16, 0, 0); } while (0)
; #define PG8_LDA(dst, b, h) do { _Pragma("unroll") for (int m = 0; m < 4; ++m) _Pragma("unroll") for (int k = 0; k < 2; ++k) dst[m][k] = *(const LAS bf16x8*)(lds + PG8_SA(b, h) + aoff + m * 2048 + k * 1024); } while (0)
; #define PG8_LDB(dst, b, h) do { _Pragma("unroll") for (int n = 0; n < 2; ++n) _Pragma("unroll") for (int k = 0; k < 2; ++k) dst[n][k] = *(const LAS bf16x8*)(lds + PG8_SB(b, h) + boff + n * 2048 + k * 1024); } while (0)
; #define PG8_MMA(ai, bj, At, Bt) do { __builtin_amdgcn_s_setprio(1); _Pragma("unroll") for (int m = 0; m < 4; ++m) _Pragma("unroll") for (int n = 0; n < 2; ++n) _Pragma("unroll") for (int k = 0; k < 2; ++k) \
;         acc[ai][bj][m][n] = __builtin_amdgcn_mfma_f32_16x16x32_bf16(Bt[n][k], At[m][k], acc[ai][bj][m][n], 0, 0, 0); __builtin_amdgcn_s_setprio(0); } while (0)
; #define PG8_WAIT_V(n) asm volatile("s_waitcnt vmcnt(" #n ")" ::: "memory")
; #define PG8_WAIT_L(n) asm volatile("s_waitcnt lgkmcnt(" #n ")" ::: "memory")
; #define PG8_BAR __builtin_amdgcn_s_barrier()
; #define PG8_SCHED __builtin_amdgcn_sched_barrier(0)
; template <class Map, class Epi>
; DI void gemm_phase(LAS unsigned char* lds, const Map& MP, const Epi& E, const int nM, const int nN, const int K, const int lda, const int ldb) {
;     ...
;             PG8_WAIT_V(6); PG8_BAR; PG8_MMA(1, 1, At, B1); PG8_BAR;
;             PG8_LDB(B0, 1, 0); PG8_SCHED; PG8_LDA(At, 1, 0); PG8_STAGE(PG8_SA(0, 1), a2 + hstepA, voffA);
;             PG8_WAIT_L(8); PG8_BAR; PG8_WAIT_L(0); PG8_MMA(0, 0, At, B0); PG8_BAR; PG8_SCHED;
;             PG8_LDB(B1, 1, 1); PG8_STAGE(PG8_SB(1, 0), b3, voffB);
;             PG8_BAR; PG8_WAIT_L(0); PG8_MMA(0, 1, At, B1); PG8_BAR;
;             PG8_LDA(At, 1, 1); PG8_STAGE(PG8_SA(1, 0), a3, voffA);
;             PG8_BAR; PG8_WAIT_L(0); PG8_MMA(1, 0, At, B0); PG8_BAR; PG8_SCHED;
	s_setprio 0
	s_mov_b32 m0, s3
	s_nop 0
	global_load_lds_dwordx4 v132, s[56:57]
	s_add_i32 m0, s3, 0x2000
	s_nop 0
	global_load_lds_dwordx4 v128, s[56:57]
	s_waitcnt vmcnt(6)
	s_setprio 1
	s_barrier
	v_mfma_f32_16x16x32_bf16 v[52:55], v[202:205], v[168:171], v[52:55]
	v_mfma_f32_16x16x32_bf16 v[48:51], v[210:213], v[168:171], v[48:51]
	s_add_i32 s3, 0, 0x18000
	v_add_u32_e32 v164, s3, v148
	ds_read_b128 v[152:155], v164
	v_mfma_f32_16x16x32_bf16 v[36:39], v[202:205], v[176:179], v[36:39]
	v_mfma_f32_16x16x32_bf16 v[32:35], v[210:213], v[176:179], v[32:35]
	ds_read_b128 v[156:159], v164 offset:1024
	v_mfma_f32_16x16x32_bf16 v[20:23], v[202:205], v[184:187], v[20:23]
	v_mfma_f32_16x16x32_bf16 v[16:19], v[210:213], v[184:187], v[16:19]
	ds_read_b128 v[160:163], v164 offset:2048
	v_mfma_f32_16x16x32_bf16 v[4:7], v[202:205], v[192:195], v[4:7]
	v_mfma_f32_16x16x32_bf16 v[0:3], v[210:213], v[192:195], v[0:3]
	ds_read_b128 v[164:167], v164 offset:3072
	v_mfma_f32_16x16x32_bf16 v[52:55], v[206:209], v[172:175], v[52:55]
	s_add_u32 s14, s14, 0x80000
	s_addc_u32 s15, s15, 0
	v_mfma_f32_16x16x32_bf16 v[48:51], v[214:217], v[172:175], v[48:51]
	v_mfma_f32_16x16x32_bf16 v[36:39], v[206:209], v[180:183], v[36:39]
	v_mfma_f32_16x16x32_bf16 v[32:35], v[214:217], v[180:183], v[32:35]
	v_mfma_f32_16x16x32_bf16 v[20:23], v[206:209], v[188:191], v[20:23]
	v_mfma_f32_16x16x32_bf16 v[16:19], v[214:217], v[188:191], v[16:19]
	v_mfma_f32_16x16x32_bf16 v[4:7], v[206:209], v[198:201], v[4:7]
	v_mfma_f32_16x16x32_bf16 v[0:3], v[214:217], v[198:201], v[0:3]
	s_barrier
	s_setprio 0
	s_mov_b32 m0, s25
	ds_read_b128 v[168:171], v150 offset:32768
	ds_read_b128 v[172:175], v150 offset:33792
	ds_read_b128 v[176:179], v150 offset:34816
	ds_read_b128 v[180:183], v150 offset:35840
	ds_read_b128 v[184:187], v150 offset:36864
	ds_read_b128 v[188:191], v150 offset:37888
	ds_read_b128 v[192:195], v150 offset:38912
	ds_read_b128 v[198:201], v150 offset:39936
	global_load_lds_dwordx4 v134, s[14:15]
	s_mov_b32 m0, s26
	s_nop 0
	global_load_lds_dwordx4 v130, s[14:15]
	s_waitcnt lgkmcnt(8)
	s_setprio 1
	s_barrier
	s_waitcnt lgkmcnt(7)
	v_mfma_f32_16x16x32_bf16 v[124:127], v[152:155], v[168:171], v[124:127]
	v_mfma_f32_16x16x32_bf16 v[120:123], v[160:163], v[168:171], v[120:123]
	s_waitcnt lgkmcnt(5)
	v_mfma_f32_16x16x32_bf16 v[108:111], v[152:155], v[176:179], v[108:111]
	v_mfma_f32_16x16x32_bf16 v[104:107], v[160:163], v[176:179], v[104:107]
	s_waitcnt lgkmcnt(3)
	v_mfma_f32_16x16x32_bf16 v[92:95], v[152:155], v[184:187], v[92:95]
	v_mfma_f32_16x16x32_bf16 v[88:91], v[160:163], v[184:187], v[88:91]
	s_waitcnt lgkmcnt(1)
	v_mfma_f32_16x16x32_bf16 v[76:79], v[152:155], v[192:195], v[76:79]
	v_mfma_f32_16x16x32_bf16 v[72:75], v[160:163], v[192:195], v[72:75]
	v_mfma_f32_16x16x32_bf16 v[124:127], v[156:159], v[172:175], v[124:127]
	s_add_i32 s14, 0, 0x1c000
	v_mfma_f32_16x16x32_bf16 v[120:123], v[164:167], v[172:175], v[120:123]
	s_add_i32 s3, s3, s22
	v_mfma_f32_16x16x32_bf16 v[108:111], v[156:159], v[180:183], v[108:111]
	v_add_u32_e32 v196, s14, v148
	v_mfma_f32_16x16x32_bf16 v[104:107], v[164:167], v[180:183], v[104:107]
	v_lshl_add_u64 v[144:145], v[144:145], 0, s[44:45]
	v_mfma_f32_16x16x32_bf16 v[92:95], v[156:159], v[188:191], v[92:95]
	v_mfma_f32_16x16x32_bf16 v[88:91], v[164:167], v[188:191], v[88:91]
	s_waitcnt lgkmcnt(0)
	v_mfma_f32_16x16x32_bf16 v[76:79], v[156:159], v[198:201], v[76:79]
	v_mfma_f32_16x16x32_bf16 v[72:75], v[164:167], v[198:201], v[72:75]
	s_barrier
	s_setprio 0
	s_mov_b32 m0, s3
	ds_read_b128 v[202:205], v196
	ds_read_b128 v[206:209], v196 offset:1024
	ds_read_b128 v[210:213], v196 offset:2048
	ds_read_b128 v[214:217], v196 offset:3072
	global_load_lds_dwordx4 v[144:145], off
	v_lshl_add_u64 v[144:145], v[218:219], 0, s[44:45]
	s_add_i32 m0, s3, 0x2000
	s_nop 0
	global_load_lds_dwordx4 v[144:145], off
	s_setprio 1
	s_barrier
	s_waitcnt lgkmcnt(3)
	v_mfma_f32_16x16x32_bf16 v[116:119], v[202:205], v[168:171], v[116:119]
	s_waitcnt lgkmcnt(1)
	v_mfma_f32_16x16x32_bf16 v[112:115], v[210:213], v[168:171], v[112:115]
	v_mfma_f32_16x16x32_bf16 v[100:103], v[202:205], v[176:179], v[100:103]
	v_mfma_f32_16x16x32_bf16 v[96:99], v[210:213], v[176:179], v[96:99]
	v_mfma_f32_16x16x32_bf16 v[84:87], v[202:205], v[184:187], v[84:87]
	v_mfma_f32_16x16x32_bf16 v[80:83], v[210:213], v[184:187], v[80:83]
	v_mfma_f32_16x16x32_bf16 v[68:71], v[202:205], v[192:195], v[68:71]
	v_mfma_f32_16x16x32_bf16 v[64:67], v[210:213], v[192:195], v[64:67]
	v_mfma_f32_16x16x32_bf16 v[116:119], v[206:209], v[172:175], v[116:119]
	s_mov_b32 m0, s30
	s_waitcnt lgkmcnt(0)
	v_mfma_f32_16x16x32_bf16 v[112:115], v[214:217], v[172:175], v[112:115]
	v_lshl_add_u64 v[144:145], v[220:221], 0, s[44:45]
	v_mfma_f32_16x16x32_bf16 v[100:103], v[206:209], v[180:183], v[100:103]
	v_mfma_f32_16x16x32_bf16 v[96:99], v[214:217], v[180:183], v[96:99]
	v_mfma_f32_16x16x32_bf16 v[84:87], v[206:209], v[188:191], v[84:87]
	v_mfma_f32_16x16x32_bf16 v[80:83], v[214:217], v[188:191], v[80:83]
	v_mfma_f32_16x16x32_bf16 v[68:71], v[206:209], v[198:201], v[68:71]
	v_mfma_f32_16x16x32_bf16 v[64:67], v[214:217], v[198:201], v[64:67]
	s_barrier
	s_setprio 0
	ds_read_b128 v[168:171], v150 offset:49152
	ds_read_b128 v[172:175], v150 offset:50176
	ds_read_b128 v[176:179], v150 offset:51200
	ds_read_b128 v[180:183], v150 offset:52224
	ds_read_b128 v[184:187], v150 offset:53248
	ds_read_b128 v[188:191], v150 offset:54272
	ds_read_b128 v[192:195], v150 offset:55296
	ds_read_b128 v[198:201], v150 offset:56320
	global_load_lds_dwordx4 v[144:145], off
	v_lshl_add_u64 v[144:145], v[222:223], 0, s[44:45]
	s_mov_b32 m0, s31
	s_nop 0
	global_load_lds_dwordx4 v[144:145], off
	s_waitcnt vmcnt(10)
	s_setprio 1
	s_barrier
; DI unsigned pack2(float a, float b) { f32x2 v = {a, b}; hwbf16x2 r = __builtin_convertvector(v, hwbf16x2); return __builtin_bit_cast(unsigned, r); }
; DI float bflo(unsigned w) { return __uint_as_float(w << 16); }
; DI float bfhi(unsigned w) { return __uint_as_float(w & 0xffff0000u); }
; #define PG8_WAIT_V(n) asm volatile("s_waitcnt vmcnt(" #n ")" ::: "memory")
; #define PG8_BAR __builtin_amdgcn_s_barrier()
;     DI void operator()(const f32x4 (&acc)[2][2][4][2], const Unit& u, int wr, int wc, int fr, int fq) const {
;         const int row0 = u.pm * BM + wr * 64 + fr, col0 = u.pn * BM + wc * 32 + 8 * fq;
;         f32x4 sc[2][2];
; #pragma unroll
;         for (int bj = 0; bj < 2; ++bj)
; #pragma unroll
;             for (int n = 0; n < 2; ++n) sc[bj][n] = scale ? *(const f32x4*)(scale + col0 + bj * HALF + 4 * n) : (f32x4){1.f, 1.f, 1.f, 1.f};
; #pragma unroll
;         for (int ai = 0; ai < 2; ++ai)
; #pragma unroll
;             for (int m = 0; m < 4; ++m) { const size_t ro = (size_t)(row0 + ai * HALF + m * 16) * D + col0;
; #pragma unroll
;                 for (int bj = 0; bj < 2; ++bj) {
;                     f32x4 x0, x1;
;                     if constexpr (IB) { const u32x4 w = *(const u32x4*)((const bf16_t*)Xin + ro + bj * HALF);
;                         x0 = (f32x4){bflo(w[0]), bfhi(w[0]), bflo(w[1]), bfhi(w[1])}; x1 = (f32x4){bflo(w[2]), bfhi(w[2]), bflo(w[3]), bfhi(w[3])}; }
;                     else { x0 = *(const f32x4*)((const float*)Xin + ro + bj * HALF); x1 = *(const f32x4*)((const float*)Xin + ro + bj * HALF + 4); }
;                     x0 += acc[ai][bj][m][0] * sc[bj][0]; x1 += acc[ai][bj][m][1] * sc[bj][1];
;                     if constexpr (OB) { u32x4 o; o[0] = pack2(x0[0], x0[1]); o[1] = pack2(x0[2], x0[3]); o[2] = pack2(x1[0], x1[1]); o[3] = pack2(x1[2], x1[3]);
;                         *(u32x4*)((bf16_t*)Xout + ro + bj * HALF) = o; }
;                     else { *(f32x4*)((float*)Xout + ro + bj * HALF) = x0; *(f32x4*)((float*)Xout + ro + bj * HALF + 4) = x1; } } }
; template <class Map, class Epi>
; DI void gemm_phase(LAS unsigned char* lds, const Map& MP, const Epi& E, const int nM, const int nN, const int K, const int lda, const int ldb) {
;     ...
;             PG8_STAGE(PG8_SB(1, 1), b3 + hstepB, voffB);
;             PG8_WAIT_V(6); PG8_BAR; PG8_MMA(1, 1, At, B1); PG8_BAR;
	s_waitcnt lgkmcnt(7)
	v_mfma_f32_16x16x32_bf16 v[60:63], v[152:155], v[168:171], v[60:63]
	v_mfma_f32_16x16x32_bf16 v[56:59], v[160:163], v[168:171], v[56:59]
	s_waitcnt lgkmcnt(5)
	v_mfma_f32_16x16x32_bf16 v[44:47], v[152:155], v[176:179], v[44:47]
	v_mfma_f32_16x16x32_bf16 v[40:43], v[160:163], v[176:179], v[40:43]
	s_waitcnt lgkmcnt(3)
	v_mfma_f32_16x16x32_bf16 v[28:31], v[152:155], v[184:187], v[28:31]
	v_mfma_f32_16x16x32_bf16 v[24:27], v[160:163], v[184:187], v[24:27]
	s_waitcnt lgkmcnt(1)
	v_mfma_f32_16x16x32_bf16 v[12:15], v[152:155], v[192:195], v[12:15]
	v_mfma_f32_16x16x32_bf16 v[8:11], v[160:163], v[192:195], v[8:11]
	v_mfma_f32_16x16x32_bf16 v[60:63], v[156:159], v[172:175], v[60:63]
	s_add_u32 s12, s12, 0x80080
	s_addc_u32 s13, s13, 0
	v_mfma_f32_16x16x32_bf16 v[56:59], v[164:167], v[172:175], v[56:59]
	s_add_i32 s3, s14, s22
	v_mfma_f32_16x16x32_bf16 v[44:47], v[156:159], v[180:183], v[44:47]
	v_mfma_f32_16x16x32_bf16 v[40:43], v[164:167], v[180:183], v[40:43]
	v_mfma_f32_16x16x32_bf16 v[28:31], v[156:159], v[188:191], v[28:31]
	v_mfma_f32_16x16x32_bf16 v[24:27], v[164:167], v[188:191], v[24:27]
	s_waitcnt lgkmcnt(0)
	v_mfma_f32_16x16x32_bf16 v[12:15], v[156:159], v[198:201], v[12:15]
	v_mfma_f32_16x16x32_bf16 v[8:11], v[164:167], v[198:201], v[8:11]
	s_barrier
	s_setprio 0
	s_mov_b32 m0, s3
	s_nop 0
	global_load_lds_dwordx4 v132, s[12:13]
	s_add_i32 m0, s3, 0x2000
	s_nop 0
	global_load_lds_dwordx4 v128, s[12:13]
	s_waitcnt vmcnt(6)
	s_setprio 1
	s_barrier
	v_mfma_f32_16x16x32_bf16 v[52:55], v[202:205], v[168:171], v[52:55]
	v_mfma_f32_16x16x32_bf16 v[48:51], v[210:213], v[168:171], v[48:51]
	ds_read_b128 v[152:155], v149
	v_mfma_f32_16x16x32_bf16 v[36:39], v[202:205], v[176:179], v[36:39]
	v_mfma_f32_16x16x32_bf16 v[32:35], v[210:213], v[176:179], v[32:35]
	ds_read_b128 v[156:159], v149 offset:1024
	v_mfma_f32_16x16x32_bf16 v[20:23], v[202:205], v[184:187], v[20:23]
	v_mfma_f32_16x16x32_bf16 v[16:19], v[210:213], v[184:187], v[16:19]
	ds_read_b128 v[160:163], v149 offset:2048
	v_mfma_f32_16x16x32_bf16 v[4:7], v[202:205], v[192:195], v[4:7]
	v_mfma_f32_16x16x32_bf16 v[0:3], v[210:213], v[192:195], v[0:3]
	ds_read_b128 v[164:167], v149 offset:3072
	v_mfma_f32_16x16x32_bf16 v[52:55], v[206:209], v[172:175], v[52:55]
	s_add_i32 s48, s48, 2
	v_mfma_f32_16x16x32_bf16 v[48:51], v[214:217], v[172:175], v[48:51]
	s_add_u32 s39, s39, 0x100
	s_addc_u32 s47, s47, 0
	v_mfma_f32_16x16x32_bf16 v[36:39], v[206:209], v[180:183], v[36:39]
	s_add_u32 s10, s10, 0x100
	s_addc_u32 s11, s11, 0
	v_mfma_f32_16x16x32_bf16 v[32:35], v[214:217], v[180:183], v[32:35]
	s_cmp_gt_u32 s48, 29
	v_mfma_f32_16x16x32_bf16 v[20:23], v[206:209], v[188:191], v[20:23]
	v_mfma_f32_16x16x32_bf16 v[16:19], v[214:217], v[188:191], v[16:19]
	v_mfma_f32_16x16x32_bf16 v[4:7], v[206:209], v[198:201], v[4:7]
	v_mfma_f32_16x16x32_bf16 v[0:3], v[214:217], v[198:201], v[0:3]
	s_barrier
	s_setprio 0
	s_cbranch_scc0 .LBB1_925
	s_waitcnt lgkmcnt(0)
	v_mov_b32_e32 v152, v147
	v_mov_b32_e32 v144, v146
	s_lshl_b32 s2, s2, 8
	s_or_b32 s2, s2, s29
	v_lshl_add_u32 v144, v144, 3, s2
	s_lshl_b32 s2, s8, 8
	s_add_i32 s2, s2, s28
	v_add_u32_e32 v152, s2, v152
	v_ashrrev_i32_e32 v153, 31, v152
	v_lshlrev_b64 v[152:153], 12, v[152:153]
	v_ashrrev_i32_e32 v145, 31, v144
	v_lshl_add_u64 v[152:153], s[42:43], 0, v[152:153]
	v_lshl_add_u64 v[144:145], v[144:145], 1, v[152:153]
	global_load_dwordx4 v[160:163], v[144:145], off
	global_load_dwordx4 v[164:167], v[144:145], off offset:256
	s_mov_b64 s[98:99], 0x10000
	v_lshl_add_u64 v[154:155], v[144:145], 0, s[98:99]
	global_load_dwordx4 v[168:171], v[154:155], off
	global_load_dwordx4 v[172:175], v[154:155], off offset:256
	s_mov_b64 s[98:99], 0x20000
	v_lshl_add_u64 v[154:155], v[144:145], 0, s[98:99]
	global_load_dwordx4 v[176:179], v[154:155], off
	global_load_dwordx4 v[180:183], v[154:155], off offset:256
	s_mov_b64 s[98:99], 0x30000
	v_lshl_add_u64 v[154:155], v[144:145], 0, s[98:99]
	global_load_dwordx4 v[184:187], v[154:155], off
	global_load_dwordx4 v[188:191], v[154:155], off offset:256
	s_mov_b64 s[98:99], 0x80000
	v_lshl_add_u64 v[154:155], v[144:145], 0, s[98:99]
	global_load_dwordx4 v[192:195], v[154:155], off
	global_load_dwordx4 v[198:201], v[154:155], off offset:256
	s_mov_b64 s[98:99], 0x90000
	v_lshl_add_u64 v[154:155], v[144:145], 0, s[98:99]
	global_load_dwordx4 v[202:205], v[154:155], off
	global_load_dwordx4 v[206:209], v[154:155], off offset:256
	s_mov_b64 s[98:99], 0xa0000
	v_lshl_add_u64 v[154:155], v[144:145], 0, s[98:99]
	global_load_dwordx4 v[210:213], v[154:155], off
	global_load_dwordx4 v[214:217], v[154:155], off offset:256
	s_mov_b64 s[98:99], 0xb0000
	v_lshl_add_u64 v[154:155], v[144:145], 0, s[98:99]
	global_load_dwordx4 v[248:251], v[154:155], off
	global_load_dwordx4 v[252:255], v[154:155], off offset:256
	s_waitcnt vmcnt(15)
	s_nop 1
	v_mov_b32_e32 v152, v160
	v_mov_b32_e32 v153, v161
	v_mov_b32_e32 v154, v162
	v_mov_b32_e32 v155, v163
	s_mov_b64 s[2:3], 0x10000
	s_mov_b32 s8, s52
	s_mov_b64 s[10:11], s[6:7]
	s_mov_b64 s[12:13], s[54:55]
	s_waitcnt lgkmcnt(0)
	v_lshlrev_b32_e32 v156, 16, v152
	v_and_b32_e32 v157, 0xffff0000, v152
	v_lshlrev_b32_e32 v152, 16, v153
	v_and_b32_e32 v153, 0xffff0000, v153
	v_lshlrev_b32_e32 v158, 16, v154
	v_and_b32_e32 v159, 0xffff0000, v154
	v_lshlrev_b32_e32 v154, 16, v155
	v_and_b32_e32 v155, 0xffff0000, v155
	v_pk_add_f32 v[126:127], v[126:127], v[152:153]
	v_pk_add_f32 v[124:125], v[124:125], v[156:157]
	v_pk_add_f32 v[152:153], v[122:123], v[154:155]
	v_pk_add_f32 v[122:123], v[120:121], v[158:159]
	v_cvt_pk_bf16_f32 v120, v124, v125
	v_cvt_pk_bf16_f32 v121, v126, v127
	v_cvt_pk_bf16_f32 v122, v122, v123
	v_cvt_pk_bf16_f32 v123, v152, v153
	global_store_dwordx4 v[144:145], v[120:123], off
	s_waitcnt vmcnt(15)
; DI unsigned pack2(float a, float b) { f32x2 v = {a, b}; hwbf16x2 r = __builtin_convertvector(v, hwbf16x2); return __builtin_bit_cast(unsigned, r); }
; DI float bflo(unsigned w) { return __uint_as_float(w << 16); }
; DI float bfhi(unsigned w) { return __uint_as_float(w & 0xffff0000u); }
;     DI void operator()(const f32x4 (&acc)[2][2][4][2], const Unit& u, int wr, int wc, int fr, int fq) const {
;     ...
;         for (int ai = 0; ai < 2; ++ai)
; #pragma unroll
;             for (int m = 0; m < 4; ++m) { const size_t ro = (size_t)(row0 + ai * HALF + m * 16) * D + col0;
; #pragma unroll
;                 for (int bj = 0; bj < 2; ++bj) {
;                     f32x4 x0, x1;
;                     if constexpr (IB) { const u32x4 w = *(const u32x4*)((const bf16_t*)Xin + ro + bj * HALF);
;                         x0 = (f32x4){bflo(w[0]), bfhi(w[0]), bflo(w[1]), bfhi(w[1])}; x1 = (f32x4){bflo(w[2]), bfhi(w[2]), bflo(w[3]), bfhi(w[3])}; }
;                     else { x0 = *(const f32x4*)((const float*)Xin + ro + bj * HALF); x1 = *(const f32x4*)((const float*)Xin + ro + bj * HALF + 4); }
;                     x0 += acc[ai][bj][m][0] * sc[bj][0]; x1 += acc[ai][bj][m][1] * sc[bj][1];
;                     if constexpr (OB) { u32x4 o; o[0] = pack2(x0[0], x0[1]); o[1] = pack2(x0[2], x0[3]); o[2] = pack2(x1[0], x1[1]); o[3] = pack2(x1[2], x1[3]);
;                         *(u32x4*)((bf16_t*)Xout + ro + bj * HALF) = o; }
;                     else { *(f32x4*)((float*)Xout + ro + bj * HALF) = x0; *(f32x4*)((float*)Xout + ro + bj * HALF + 4) = x1; } } }
	s_nop 1
	v_mov_b32_e32 v120, v164
	v_mov_b32_e32 v121, v165
	v_mov_b32_e32 v122, v166
	v_mov_b32_e32 v123, v167
	s_waitcnt lgkmcnt(0)
	v_lshlrev_b32_e32 v124, 16, v120
	v_and_b32_e32 v125, 0xffff0000, v120
	v_lshlrev_b32_e32 v120, 16, v121
	v_and_b32_e32 v121, 0xffff0000, v121
	v_lshlrev_b32_e32 v126, 16, v122
	v_and_b32_e32 v127, 0xffff0000, v122
	v_lshlrev_b32_e32 v122, 16, v123
	v_and_b32_e32 v123, 0xffff0000, v123
	v_pk_add_f32 v[116:117], v[116:117], v[124:125]
	v_pk_add_f32 v[118:119], v[118:119], v[120:121]
	v_pk_add_f32 v[120:121], v[114:115], v[122:123]
	v_pk_add_f32 v[114:115], v[112:113], v[126:127]
	v_cvt_pk_bf16_f32 v112, v116, v117
	v_lshl_add_u64 v[116:117], v[144:145], 0, s[2:3]
	s_mov_b32 s2, 0x10000
	v_cvt_pk_bf16_f32 v113, v118, v119
	v_add_co_u32_e32 v118, vcc, s2, v144
	v_cvt_pk_bf16_f32 v114, v114, v115
	v_cvt_pk_bf16_f32 v115, v120, v121
	v_addc_co_u32_e32 v119, vcc, 0, v145, vcc
	global_store_dwordx4 v[144:145], v[112:115], off offset:256
	s_waitcnt vmcnt(15)
	s_nop 1
	v_mov_b32_e32 v112, v168
	v_mov_b32_e32 v113, v169
	v_mov_b32_e32 v114, v170
	v_mov_b32_e32 v115, v171
	s_mov_b64 s[2:3], 0x20000
	s_waitcnt lgkmcnt(0)
	v_lshlrev_b32_e32 v120, 16, v112
	v_and_b32_e32 v121, 0xffff0000, v112
	v_lshlrev_b32_e32 v112, 16, v113
	v_and_b32_e32 v113, 0xffff0000, v113
	v_lshlrev_b32_e32 v122, 16, v114
	v_and_b32_e32 v123, 0xffff0000, v114
	v_lshlrev_b32_e32 v114, 16, v115
	v_and_b32_e32 v115, 0xffff0000, v115
	v_pk_add_f32 v[110:111], v[110:111], v[112:113]
	v_pk_add_f32 v[108:109], v[108:109], v[120:121]
	v_pk_add_f32 v[112:113], v[106:107], v[114:115]
	v_pk_add_f32 v[106:107], v[104:105], v[122:123]
	v_cvt_pk_bf16_f32 v104, v108, v109
	v_cvt_pk_bf16_f32 v105, v110, v111
	v_cvt_pk_bf16_f32 v106, v106, v107
	v_cvt_pk_bf16_f32 v107, v112, v113
	global_store_dwordx4 v[118:119], v[104:107], off
	s_waitcnt vmcnt(15)
	s_nop 1
	v_mov_b32_e32 v104, v172
	v_mov_b32_e32 v105, v173
	v_mov_b32_e32 v106, v174
	v_mov_b32_e32 v107, v175
	s_waitcnt lgkmcnt(0)
	v_lshlrev_b32_e32 v108, 16, v104
	v_and_b32_e32 v109, 0xffff0000, v104
	v_lshlrev_b32_e32 v104, 16, v105
	v_and_b32_e32 v105, 0xffff0000, v105
	v_lshlrev_b32_e32 v110, 16, v106
	v_and_b32_e32 v111, 0xffff0000, v106
	v_lshlrev_b32_e32 v106, 16, v107
	v_and_b32_e32 v107, 0xffff0000, v107
	v_pk_add_f32 v[100:101], v[100:101], v[108:109]
	v_pk_add_f32 v[102:103], v[102:103], v[104:105]
	v_pk_add_f32 v[104:105], v[98:99], v[106:107]
	v_pk_add_f32 v[98:99], v[96:97], v[110:111]
	v_cvt_pk_bf16_f32 v96, v100, v101
	v_lshl_add_u64 v[100:101], v[144:145], 0, s[2:3]
	s_mov_b32 s2, 0x20000
	v_cvt_pk_bf16_f32 v97, v102, v103
	v_add_co_u32_e32 v102, vcc, s2, v144
	v_cvt_pk_bf16_f32 v98, v98, v99
	v_cvt_pk_bf16_f32 v99, v104, v105
	v_addc_co_u32_e32 v103, vcc, 0, v145, vcc
	global_store_dwordx4 v[116:117], v[96:99], off offset:256
	s_waitcnt vmcnt(15)
	s_nop 1
	v_mov_b32_e32 v96, v176
	v_mov_b32_e32 v97, v177
	v_mov_b32_e32 v98, v178
	v_mov_b32_e32 v99, v179
	s_mov_b64 s[2:3], 0x30000
	s_waitcnt lgkmcnt(0)
	v_lshlrev_b32_e32 v104, 16, v96
	v_and_b32_e32 v105, 0xffff0000, v96
	v_lshlrev_b32_e32 v96, 16, v97
	v_and_b32_e32 v97, 0xffff0000, v97
	v_lshlrev_b32_e32 v106, 16, v98
	v_and_b32_e32 v107, 0xffff0000, v98
	v_lshlrev_b32_e32 v98, 16, v99
	v_and_b32_e32 v99, 0xffff0000, v99
	v_pk_add_f32 v[94:95], v[94:95], v[96:97]
	v_pk_add_f32 v[92:93], v[92:93], v[104:105]
	v_pk_add_f32 v[96:97], v[90:91], v[98:99]
	v_pk_add_f32 v[90:91], v[88:89], v[106:107]
	v_cvt_pk_bf16_f32 v88, v92, v93
	v_cvt_pk_bf16_f32 v89, v94, v95
	v_cvt_pk_bf16_f32 v90, v90, v91
	v_cvt_pk_bf16_f32 v91, v96, v97
	global_store_dwordx4 v[102:103], v[88:91], off
	s_waitcnt vmcnt(15)
	s_nop 1
	v_mov_b32_e32 v88, v180
	v_mov_b32_e32 v89, v181
	v_mov_b32_e32 v90, v182
	v_mov_b32_e32 v91, v183
	s_waitcnt lgkmcnt(0)
	v_lshlrev_b32_e32 v92, 16, v88
	v_and_b32_e32 v93, 0xffff0000, v88
	v_lshlrev_b32_e32 v88, 16, v89
	v_and_b32_e32 v89, 0xffff0000, v89
	v_lshlrev_b32_e32 v94, 16, v90
	v_and_b32_e32 v95, 0xffff0000, v90
	v_lshlrev_b32_e32 v90, 16, v91
	v_and_b32_e32 v91, 0xffff0000, v91
	v_pk_add_f32 v[86:87], v[86:87], v[88:89]
	v_pk_add_f32 v[84:85], v[84:85], v[92:93]
	v_pk_add_f32 v[88:89], v[82:83], v[90:91]
	v_pk_add_f32 v[82:83], v[80:81], v[94:95]
	v_cvt_pk_bf16_f32 v80, v84, v85
	v_cvt_pk_bf16_f32 v81, v86, v87
	v_cvt_pk_bf16_f32 v82, v82, v83
	v_cvt_pk_bf16_f32 v83, v88, v89
	global_store_dwordx4 v[100:101], v[80:83], off offset:256
	s_nop 1
	v_lshl_add_u64 v[80:81], v[144:145], 0, s[2:3]
	s_mov_b32 s2, 0x30000
	v_add_co_u32_e32 v86, vcc, s2, v144
	s_mov_b64 s[2:3], 0x80000
	s_nop 0
	v_addc_co_u32_e32 v87, vcc, 0, v145, vcc
	s_waitcnt vmcnt(15)
	s_nop 1
	v_mov_b32_e32 v82, v184
	v_mov_b32_e32 v83, v185
	v_mov_b32_e32 v84, v186
	v_mov_b32_e32 v85, v187
	s_waitcnt lgkmcnt(0)
	v_lshlrev_b32_e32 v88, 16, v82
	v_and_b32_e32 v89, 0xffff0000, v82
	v_lshlrev_b32_e32 v82, 16, v83
	v_and_b32_e32 v83, 0xffff0000, v83
	v_lshlrev_b32_e32 v90, 16, v84
	v_and_b32_e32 v91, 0xffff0000, v84
	v_lshlrev_b32_e32 v84, 16, v85
	v_and_b32_e32 v85, 0xffff0000, v85
	v_pk_add_f32 v[78:79], v[78:79], v[82:83]
	v_pk_add_f32 v[76:77], v[76:77], v[88:89]
	v_pk_add_f32 v[82:83], v[74:75], v[84:85]
	v_pk_add_f32 v[74:75], v[72:73], v[90:91]
	v_cvt_pk_bf16_f32 v72, v76, v77
	v_cvt_pk_bf16_f32 v73, v78, v79
	v_cvt_pk_bf16_f32 v74, v74, v75
	v_cvt_pk_bf16_f32 v75, v82, v83
	global_store_dwordx4 v[86:87], v[72:75], off
	s_waitcnt vmcnt(15)
	s_nop 1
	v_mov_b32_e32 v72, v188
	v_mov_b32_e32 v73, v189
	v_mov_b32_e32 v74, v190
	v_mov_b32_e32 v75, v191
	s_waitcnt lgkmcnt(0)
; DI unsigned pack2(float a, float b) { f32x2 v = {a, b}; hwbf16x2 r = __builtin_convertvector(v, hwbf16x2); return __builtin_bit_cast(unsigned, r); }
; DI float bflo(unsigned w) { return __uint_as_float(w << 16); }
; DI float bfhi(unsigned w) { return __uint_as_float(w & 0xffff0000u); }
;     DI void operator()(const f32x4 (&acc)[2][2][4][2], const Unit& u, int wr, int wc, int fr, int fq) const {
;     ...
;         for (int ai = 0; ai < 2; ++ai)
; #pragma unroll
;             for (int m = 0; m < 4; ++m) { const size_t ro = (size_t)(row0 + ai * HALF + m * 16) * D + col0;
; #pragma unroll
;                 for (int bj = 0; bj < 2; ++bj) {
;                     f32x4 x0, x1;
;                     if constexpr (IB) { const u32x4 w = *(const u32x4*)((const bf16_t*)Xin + ro + bj * HALF);
;                         x0 = (f32x4){bflo(w[0]), bfhi(w[0]), bflo(w[1]), bfhi(w[1])}; x1 = (f32x4){bflo(w[2]), bfhi(w[2]), bflo(w[3]), bfhi(w[3])}; }
;                     else { x0 = *(const f32x4*)((const float*)Xin + ro + bj * HALF); x1 = *(const f32x4*)((const float*)Xin + ro + bj * HALF + 4); }
;                     x0 += acc[ai][bj][m][0] * sc[bj][0]; x1 += acc[ai][bj][m][1] * sc[bj][1];
;                     if constexpr (OB) { u32x4 o; o[0] = pack2(x0[0], x0[1]); o[1] = pack2(x0[2], x0[3]); o[2] = pack2(x1[0], x1[1]); o[3] = pack2(x1[2], x1[3]);
;                         *(u32x4*)((bf16_t*)Xout + ro + bj * HALF) = o; }
;                     else { *(f32x4*)((float*)Xout + ro + bj * HALF) = x0; *(f32x4*)((float*)Xout + ro + bj * HALF + 4) = x1; } } }
	v_lshlrev_b32_e32 v76, 16, v72
	v_and_b32_e32 v77, 0xffff0000, v72
	v_lshlrev_b32_e32 v72, 16, v73
	v_and_b32_e32 v73, 0xffff0000, v73
	v_lshlrev_b32_e32 v78, 16, v74
	v_and_b32_e32 v79, 0xffff0000, v74
	v_lshlrev_b32_e32 v74, 16, v75
	v_and_b32_e32 v75, 0xffff0000, v75
	v_pk_add_f32 v[70:71], v[70:71], v[72:73]
	v_pk_add_f32 v[68:69], v[68:69], v[76:77]
	v_pk_add_f32 v[72:73], v[66:67], v[74:75]
	v_pk_add_f32 v[66:67], v[64:65], v[78:79]
	v_cvt_pk_bf16_f32 v64, v68, v69
	v_cvt_pk_bf16_f32 v65, v70, v71
	v_cvt_pk_bf16_f32 v66, v66, v67
	v_cvt_pk_bf16_f32 v67, v72, v73
	global_store_dwordx4 v[80:81], v[64:67], off offset:256
	s_nop 1
	v_lshl_add_u64 v[64:65], v[144:145], 0, s[2:3]
	s_mov_b32 s2, 0x80000
	v_add_co_u32_e32 v70, vcc, s2, v144
	s_mov_b64 s[2:3], 0x90000
	s_nop 0
	v_addc_co_u32_e32 v71, vcc, 0, v145, vcc
	s_waitcnt vmcnt(15)
	s_nop 1
	v_mov_b32_e32 v66, v192
	v_mov_b32_e32 v67, v193
	v_mov_b32_e32 v68, v194
	v_mov_b32_e32 v69, v195
	s_waitcnt lgkmcnt(0)
	v_lshlrev_b32_e32 v72, 16, v66
	v_and_b32_e32 v73, 0xffff0000, v66
	v_lshlrev_b32_e32 v66, 16, v67
	v_and_b32_e32 v67, 0xffff0000, v67
	v_lshlrev_b32_e32 v74, 16, v68
	v_and_b32_e32 v75, 0xffff0000, v68
	v_lshlrev_b32_e32 v68, 16, v69
	v_and_b32_e32 v69, 0xffff0000, v69
	v_pk_add_f32 v[62:63], v[62:63], v[66:67]
	v_pk_add_f32 v[60:61], v[60:61], v[72:73]
	v_pk_add_f32 v[66:67], v[58:59], v[68:69]
	v_pk_add_f32 v[58:59], v[56:57], v[74:75]
	v_cvt_pk_bf16_f32 v56, v60, v61
	v_cvt_pk_bf16_f32 v57, v62, v63
	v_cvt_pk_bf16_f32 v58, v58, v59
	v_cvt_pk_bf16_f32 v59, v66, v67
	global_store_dwordx4 v[70:71], v[56:59], off
	s_waitcnt vmcnt(15)
	s_nop 1
	v_mov_b32_e32 v56, v198
	v_mov_b32_e32 v57, v199
	v_mov_b32_e32 v58, v200
	v_mov_b32_e32 v59, v201
	s_waitcnt lgkmcnt(0)
	v_lshlrev_b32_e32 v60, 16, v56
	v_and_b32_e32 v61, 0xffff0000, v56
	v_lshlrev_b32_e32 v56, 16, v57
	v_and_b32_e32 v57, 0xffff0000, v57
	v_lshlrev_b32_e32 v62, 16, v58
	v_and_b32_e32 v63, 0xffff0000, v58
	v_lshlrev_b32_e32 v58, 16, v59
	v_and_b32_e32 v59, 0xffff0000, v59
	v_pk_add_f32 v[54:55], v[54:55], v[56:57]
	v_pk_add_f32 v[52:53], v[52:53], v[60:61]
	v_pk_add_f32 v[56:57], v[50:51], v[58:59]
	v_pk_add_f32 v[50:51], v[48:49], v[62:63]
	v_cvt_pk_bf16_f32 v48, v52, v53
	v_cvt_pk_bf16_f32 v49, v54, v55
	v_cvt_pk_bf16_f32 v50, v50, v51
	v_cvt_pk_bf16_f32 v51, v56, v57
	global_store_dwordx4 v[64:65], v[48:51], off offset:256
	s_nop 1
	v_lshl_add_u64 v[48:49], v[144:145], 0, s[2:3]
	s_mov_b32 s2, 0x90000
	v_add_co_u32_e32 v54, vcc, s2, v144
	s_mov_b64 s[2:3], 0xa0000
	s_nop 0
	v_addc_co_u32_e32 v55, vcc, 0, v145, vcc
	s_waitcnt vmcnt(15)
	s_nop 1
	v_mov_b32_e32 v50, v202
	v_mov_b32_e32 v51, v203
	v_mov_b32_e32 v52, v204
	v_mov_b32_e32 v53, v205
	s_waitcnt lgkmcnt(0)
	v_lshlrev_b32_e32 v56, 16, v50
	v_and_b32_e32 v57, 0xffff0000, v50
	v_lshlrev_b32_e32 v50, 16, v51
	v_and_b32_e32 v51, 0xffff0000, v51
	v_lshlrev_b32_e32 v58, 16, v52
	v_and_b32_e32 v59, 0xffff0000, v52
	v_lshlrev_b32_e32 v52, 16, v53
	v_and_b32_e32 v53, 0xffff0000, v53
	v_pk_add_f32 v[46:47], v[46:47], v[50:51]
	v_pk_add_f32 v[44:45], v[44:45], v[56:57]
	v_pk_add_f32 v[50:51], v[42:43], v[52:53]
	v_pk_add_f32 v[42:43], v[40:41], v[58:59]
	v_cvt_pk_bf16_f32 v40, v44, v45
	v_cvt_pk_bf16_f32 v41, v46, v47
	v_cvt_pk_bf16_f32 v42, v42, v43
	v_cvt_pk_bf16_f32 v43, v50, v51
	global_store_dwordx4 v[54:55], v[40:43], off
	s_waitcnt vmcnt(15)
	s_nop 1
	v_mov_b32_e32 v40, v206
	v_mov_b32_e32 v41, v207
	v_mov_b32_e32 v42, v208
	v_mov_b32_e32 v43, v209
	s_waitcnt lgkmcnt(0)
; DI unsigned pack2(float a, float b) { f32x2 v = {a, b}; hwbf16x2 r = __builtin_convertvector(v, hwbf16x2); return __builtin_bit_cast(unsigned, r); }
; DI float bflo(unsigned w) { return __uint_as_float(w << 16); }
; DI float bfhi(unsigned w) { return __uint_as_float(w & 0xffff0000u); }
;     DI const char* a(const Unit& u) const { return (const char*)(A + (size_t)u.pm * BM * lda); }
;     DI void operator()(const f32x4 (&acc)[2][2][4][2], const Unit& u, int wr, int wc, int fr, int fq) const {
;     ...
;         for (int ai = 0; ai < 2; ++ai)
; #pragma unroll
;             for (int m = 0; m < 4; ++m) { const size_t ro = (size_t)(row0 + ai * HALF + m * 16) * D + col0;
; #pragma unroll
;                 for (int bj = 0; bj < 2; ++bj) {
;                     f32x4 x0, x1;
;                     if constexpr (IB) { const u32x4 w = *(const u32x4*)((const bf16_t*)Xin + ro + bj * HALF);
;                         x0 = (f32x4){bflo(w[0]), bfhi(w[0]), bflo(w[1]), bfhi(w[1])}; x1 = (f32x4){bflo(w[2]), bfhi(w[2]), bflo(w[3]), bfhi(w[3])}; }
;                     else { x0 = *(const f32x4*)((const float*)Xin + ro + bj * HALF); x1 = *(const f32x4*)((const float*)Xin + ro + bj * HALF + 4); }
;                     x0 += acc[ai][bj][m][0] * sc[bj][0]; x1 += acc[ai][bj][m][1] * sc[bj][1];
;                     if constexpr (OB) { u32x4 o; o[0] = pack2(x0[0], x0[1]); o[1] = pack2(x0[2], x0[3]); o[2] = pack2(x1[0], x1[1]); o[3] = pack2(x1[2], x1[3]);
;                         *(u32x4*)((bf16_t*)Xout + ro + bj * HALF) = o; }
;                     else { *(f32x4*)((float*)Xout + ro + bj * HALF) = x0; *(f32x4*)((float*)Xout + ro + bj * HALF + 4) = x1; } } }
; template <class Map, class Epi>
; DI void gemm_phase(LAS unsigned char* lds, const Map& MP, const Epi& E, const int nM, const int nN, const int K, const int lda, const int ldb) {
;     ...
;         { int frr = fr, fqq = fq; asm volatile("" : "+v"(frr), "+v"(fqq)); E(acc, cur, wr, wc, frr, fqq); }
;         if (!has_next) break;
; #pragma unroll
;         for (int a = 0; a < 2; ++a)
; #pragma unroll
;             for (int b = 0; b < 2; ++b)
; #pragma unroll
;                 for (int m = 0; m < 4; ++m)
; #pragma unroll
;                     for (int n = 0; n < 2; ++n) acc[a][b][m][n] = (f32x4){0.f, 0.f, 0.f, 0.f};
;         cur = nxt; cA = nA; cB = nB; ++ui;
;     }
;     PG8_WAIT_V(0);
;     if (wr == 0) PG8_BAR;
;     PG8_BAR;
	v_lshlrev_b32_e32 v44, 16, v40
	v_and_b32_e32 v45, 0xffff0000, v40
	v_lshlrev_b32_e32 v40, 16, v41
	v_and_b32_e32 v41, 0xffff0000, v41
	v_lshlrev_b32_e32 v46, 16, v42
	v_and_b32_e32 v47, 0xffff0000, v42
	v_lshlrev_b32_e32 v42, 16, v43
	v_and_b32_e32 v43, 0xffff0000, v43
	v_pk_add_f32 v[38:39], v[38:39], v[40:41]
	v_pk_add_f32 v[36:37], v[36:37], v[44:45]
	v_pk_add_f32 v[40:41], v[34:35], v[42:43]
	v_pk_add_f32 v[34:35], v[32:33], v[46:47]
	v_cvt_pk_bf16_f32 v32, v36, v37
	v_cvt_pk_bf16_f32 v33, v38, v39
	v_cvt_pk_bf16_f32 v34, v34, v35
	v_cvt_pk_bf16_f32 v35, v40, v41
	global_store_dwordx4 v[48:49], v[32:35], off offset:256
	s_nop 1
	v_lshl_add_u64 v[32:33], v[144:145], 0, s[2:3]
	s_mov_b32 s2, 0xa0000
	v_add_co_u32_e32 v38, vcc, s2, v144
	s_mov_b64 s[2:3], 0xb0000
	s_nop 0
	v_addc_co_u32_e32 v39, vcc, 0, v145, vcc
	s_waitcnt vmcnt(15)
	s_nop 1
	v_mov_b32_e32 v34, v210
	v_mov_b32_e32 v35, v211
	v_mov_b32_e32 v36, v212
	v_mov_b32_e32 v37, v213
	s_waitcnt lgkmcnt(0)
	v_lshlrev_b32_e32 v40, 16, v34
	v_and_b32_e32 v41, 0xffff0000, v34
	v_lshlrev_b32_e32 v34, 16, v35
	v_and_b32_e32 v35, 0xffff0000, v35
	v_lshlrev_b32_e32 v42, 16, v36
	v_and_b32_e32 v43, 0xffff0000, v36
	v_lshlrev_b32_e32 v36, 16, v37
	v_and_b32_e32 v37, 0xffff0000, v37
	v_pk_add_f32 v[30:31], v[30:31], v[34:35]
	v_pk_add_f32 v[28:29], v[28:29], v[40:41]
	v_pk_add_f32 v[34:35], v[26:27], v[36:37]
	v_pk_add_f32 v[26:27], v[24:25], v[42:43]
	v_cvt_pk_bf16_f32 v24, v28, v29
	v_cvt_pk_bf16_f32 v25, v30, v31
	v_cvt_pk_bf16_f32 v26, v26, v27
	v_cvt_pk_bf16_f32 v27, v34, v35
	global_store_dwordx4 v[38:39], v[24:27], off
	s_waitcnt vmcnt(15)
	s_nop 1
	v_mov_b32_e32 v24, v214
	v_mov_b32_e32 v25, v215
	v_mov_b32_e32 v26, v216
	v_mov_b32_e32 v27, v217
	s_waitcnt lgkmcnt(0)
	v_lshlrev_b32_e32 v28, 16, v24
	v_and_b32_e32 v29, 0xffff0000, v24
	v_lshlrev_b32_e32 v24, 16, v25
	v_and_b32_e32 v25, 0xffff0000, v25
	v_lshlrev_b32_e32 v30, 16, v26
	v_and_b32_e32 v31, 0xffff0000, v26
	v_lshlrev_b32_e32 v26, 16, v27
	v_and_b32_e32 v27, 0xffff0000, v27
	v_pk_add_f32 v[22:23], v[22:23], v[24:25]
	v_pk_add_f32 v[20:21], v[20:21], v[28:29]
	v_pk_add_f32 v[24:25], v[18:19], v[26:27]
	v_pk_add_f32 v[18:19], v[16:17], v[30:31]
	v_cvt_pk_bf16_f32 v16, v20, v21
	v_cvt_pk_bf16_f32 v17, v22, v23
	v_cvt_pk_bf16_f32 v18, v18, v19
	v_cvt_pk_bf16_f32 v19, v24, v25
	global_store_dwordx4 v[32:33], v[16:19], off offset:256
	s_nop 1
	v_lshl_add_u64 v[16:17], v[144:145], 0, s[2:3]
	s_mov_b32 s2, 0xb0000
	v_add_co_u32_e32 v22, vcc, s2, v144
	s_mov_b32 s2, s46
	s_nop 0
	v_addc_co_u32_e32 v23, vcc, 0, v145, vcc
	s_waitcnt vmcnt(15)
	s_nop 1
	v_mov_b32_e32 v18, v248
	v_mov_b32_e32 v19, v249
	v_mov_b32_e32 v20, v250
	v_mov_b32_e32 v21, v251
	s_and_b64 vcc, exec, s[40:41]
	s_waitcnt lgkmcnt(0)
	v_lshlrev_b32_e32 v24, 16, v18
	v_and_b32_e32 v25, 0xffff0000, v18
	v_lshlrev_b32_e32 v18, 16, v19
	v_and_b32_e32 v19, 0xffff0000, v19
	v_lshlrev_b32_e32 v26, 16, v20
	v_and_b32_e32 v27, 0xffff0000, v20
	v_lshlrev_b32_e32 v20, 16, v21
	v_and_b32_e32 v21, 0xffff0000, v21
	v_pk_add_f32 v[14:15], v[14:15], v[18:19]
	v_pk_add_f32 v[12:13], v[12:13], v[24:25]
	v_pk_add_f32 v[18:19], v[10:11], v[20:21]
	v_pk_add_f32 v[10:11], v[8:9], v[26:27]
	v_cvt_pk_bf16_f32 v8, v12, v13
	v_cvt_pk_bf16_f32 v9, v14, v15
	v_cvt_pk_bf16_f32 v10, v10, v11
	v_cvt_pk_bf16_f32 v11, v18, v19
	global_store_dwordx4 v[22:23], v[8:11], off
	s_waitcnt vmcnt(15)
	s_nop 1
	v_mov_b32_e32 v8, v252
	v_mov_b32_e32 v9, v253
	v_mov_b32_e32 v10, v254
	v_mov_b32_e32 v11, v255
	s_waitcnt lgkmcnt(0)
	v_lshlrev_b32_e32 v12, 16, v8
	v_and_b32_e32 v13, 0xffff0000, v8
	v_lshlrev_b32_e32 v8, 16, v9
	v_and_b32_e32 v9, 0xffff0000, v9
	v_lshlrev_b32_e32 v14, 16, v10
	v_and_b32_e32 v15, 0xffff0000, v10
	v_lshlrev_b32_e32 v10, 16, v11
	v_and_b32_e32 v11, 0xffff0000, v11
	v_pk_add_f32 v[6:7], v[6:7], v[8:9]
	v_pk_add_f32 v[4:5], v[4:5], v[12:13]
	v_pk_add_f32 v[8:9], v[2:3], v[10:11]
	v_pk_add_f32 v[2:3], v[0:1], v[14:15]
	v_cvt_pk_bf16_f32 v0, v4, v5
	v_cvt_pk_bf16_f32 v1, v6, v7
	v_cvt_pk_bf16_f32 v2, v2, v3
	v_cvt_pk_bf16_f32 v3, v8, v9
	global_store_dwordx4 v[16:17], v[0:3], off offset:256
	s_cbranch_vccz .LBB1_922
	s_waitcnt vmcnt(0)
	s_cmpk_gt_u32 s17, 0xff
	s_cbranch_scc1 .LBB1_929
	s_barrier

; #define PG8_STAGE(bufoff, gbase, voff) do { _Pragma("unroll") for (int _i = 0; _i < 2; ++_i) \
;         __builtin_amdgcn_global_load_lds((const unsigned*)((const char*)(gbase) + (voff)[_i]), (LAS unsigned*)(lds + (bufoff) + ldsw + _i * 8192), 16, 0, 0); } while (0)
; #define PG8_LDA(dst, b, h) do { _Pragma("unroll") for (int m = 0; m < 4; ++m) _Pragma("unroll") for (int k = 0; k < 2; ++k) dst[m][k] = *(const LAS bf16x8*)(lds + PG8_SA(b, h) + aoff + m * 2048 + k * 1024); } while (0)
; #define PG8_LDB(dst, b, h) do { _Pragma("unroll") for (int n = 0; n < 2; ++n) _Pragma("unroll") for (int k = 0; k < 2; ++k) dst[n][k] = *(const LAS bf16x8*)(lds + PG8_SB(b, h) + boff + n * 2048 + k * 1024); } while (0)
; #define PG8_MMA(ai, bj, At, Bt) do { __builtin_amdgcn_s_setprio(1); _Pragma("unroll") for (int m = 0; m < 4; ++m) _Pragma("unroll") for (int n = 0; n < 2; ++n) _Pragma("unroll") for (int k = 0; k < 2; ++k) \
;         acc[ai][bj][m][n] = __builtin_amdgcn_mfma_f32_16x16x32_bf16(Bt[n][k], At[m][k], acc[ai][bj][m][n], 0, 0, 0); __builtin_amdgcn_s_setprio(0); } while (0)
; #define PG8_WAIT_V(n) asm volatile("s_waitcnt vmcnt(" #n ")" ::: "memory")
; #define PG8_WAIT_L(n) asm volatile("s_waitcnt lgkmcnt(" #n ")" ::: "memory")
; template <class Map, class Epi>
; DI void gemm_phase(LAS unsigned char* lds, const Map& MP, const Epi& E, const int nM, const int nN, const int K, const int lda, const int ldb) {
;     ...
;             const bool last = (t == nt - 2);
;             const char* a1 = cA + (size_t)(t + 1) * kstep;
;             const char* a2 = last ? nA : cA + (size_t)(t + 2) * kstep; const char* b2 = last ? nB : cB + (size_t)(t + 2) * kstep;
;             const char* a3 = a2 + kstep; const char* b3 = b2 + kstep;
;             PG8_LDB(B0, 0, 0); PG8_SCHED; PG8_LDA(At, 0, 0); PG8_STAGE(PG8_SA(1, 1), a1 + hstepA, voffA);
;             PG8_WAIT_L(8); PG8_BAR; PG8_WAIT_L(0); PG8_MMA(0, 0, At, B0); PG8_BAR; PG8_SCHED;
;             PG8_LDB(B1, 0, 1); PG8_STAGE(PG8_SB(0, 0), b2, voffB);
;             PG8_BAR; PG8_WAIT_L(0); PG8_MMA(0, 1, At, B1); PG8_BAR;
;             PG8_LDA(At, 0, 1); PG8_STAGE(PG8_SA(0, 0), a2, voffA);
;             PG8_BAR; PG8_WAIT_L(0); PG8_MMA(1, 0, At, B0); PG8_BAR; PG8_SCHED;
;             PG8_STAGE(PG8_SB(0, 1), b2 + hstepB, voffB);
;             PG8_WAIT_V(6); PG8_BAR; PG8_MMA(1, 1, At, B1); PG8_BAR;
.LBB1_1069:
	s_add_u32 s24, s42, 0xfff80080
	s_addc_u32 s25, s43, -1
	s_cmp_eq_u32 s3, 28
	s_cselect_b32 s47, s23, s25
	s_cselect_b32 s46, s58, s24
	s_cselect_b32 s25, s21, vcc_hi
	s_cselect_b32 s24, s59, vcc_lo
	s_add_i32 m0, s38, 0xc000
	ds_read_b128 v[96:99], v190
	ds_read_b128 v[100:103], v190 offset:1024
	ds_read_b128 v[108:111], v190 offset:2048
	ds_read_b128 v[112:115], v190 offset:3072
	ds_read_b128 v[160:163], v190 offset:4096
	ds_read_b128 v[164:167], v190 offset:5120
	ds_read_b128 v[198:201], v190 offset:6144
	ds_read_b128 v[202:205], v190 offset:7168
	global_load_lds_dwordx4 v178, s[42:43]
	s_add_i32 m0, s38, 0xe000
	s_nop 0
	global_load_lds_dwordx4 v176, s[42:43]
	s_waitcnt lgkmcnt(8)
	s_setprio 1
	s_barrier
	s_waitcnt lgkmcnt(7)
	v_mfma_f32_16x16x32_bf16 v[148:151], v[80:83], v[96:99], v[148:151]
	v_mfma_f32_16x16x32_bf16 v[144:147], v[88:91], v[96:99], v[144:147]
	s_waitcnt lgkmcnt(5)
	v_mfma_f32_16x16x32_bf16 v[136:139], v[80:83], v[108:111], v[136:139]
	v_mfma_f32_16x16x32_bf16 v[128:131], v[88:91], v[108:111], v[128:131]
	s_waitcnt lgkmcnt(3)
	v_mfma_f32_16x16x32_bf16 v[120:123], v[80:83], v[160:163], v[120:123]
	v_mfma_f32_16x16x32_bf16 v[104:107], v[88:91], v[160:163], v[104:107]
	s_waitcnt lgkmcnt(1)
	v_mfma_f32_16x16x32_bf16 v[76:79], v[80:83], v[198:201], v[76:79]
	v_mfma_f32_16x16x32_bf16 v[72:75], v[88:91], v[198:201], v[72:75]
	v_mfma_f32_16x16x32_bf16 v[148:151], v[84:87], v[100:103], v[148:151]
	s_add_i32 s68, s31, s66
	v_mfma_f32_16x16x32_bf16 v[144:147], v[92:95], v[100:103], v[144:147]
	v_lshl_add_u64 v[184:185], s[24:25], 0, v[172:173]
	v_mfma_f32_16x16x32_bf16 v[136:139], v[84:87], v[112:115], v[136:139]
	v_lshl_add_u64 v[194:195], s[24:25], 0, v[168:169]
	v_mfma_f32_16x16x32_bf16 v[128:131], v[92:95], v[112:115], v[128:131]
	v_mfma_f32_16x16x32_bf16 v[120:123], v[84:87], v[164:167], v[120:123]
	v_mfma_f32_16x16x32_bf16 v[104:107], v[92:95], v[164:167], v[104:107]
	s_waitcnt lgkmcnt(0)
	v_mfma_f32_16x16x32_bf16 v[76:79], v[84:87], v[202:205], v[76:79]
	v_mfma_f32_16x16x32_bf16 v[72:75], v[92:95], v[202:205], v[72:75]
	s_barrier
	s_setprio 0
	s_mov_b32 m0, s68
	ds_read_b128 v[206:209], v191
	ds_read_b128 v[210:213], v191 offset:1024
	ds_read_b128 v[214:217], v191 offset:2048
	ds_read_b128 v[218:221], v191 offset:3072
	global_load_lds_dwordx4 v[184:185], off
	s_add_i32 m0, s68, 0x2000
	s_nop 0
	global_load_lds_dwordx4 v[194:195], off
	s_setprio 1
	s_barrier
	s_waitcnt lgkmcnt(3)
	v_mfma_f32_16x16x32_bf16 v[156:159], v[206:209], v[96:99], v[156:159]
	s_waitcnt lgkmcnt(1)
	v_mfma_f32_16x16x32_bf16 v[96:99], v[214:217], v[96:99], v[152:155]
	v_mfma_f32_16x16x32_bf16 v[156:159], v[210:213], v[100:103], v[156:159]
	s_waitcnt lgkmcnt(0)
	v_mfma_f32_16x16x32_bf16 v[96:99], v[218:221], v[100:103], v[96:99]
	v_mfma_f32_16x16x32_bf16 v[100:103], v[206:209], v[108:111], v[140:143]
	v_mfma_f32_16x16x32_bf16 v[108:111], v[214:217], v[108:111], v[132:135]
	v_mfma_f32_16x16x32_bf16 v[116:119], v[214:217], v[160:163], v[116:119]
	v_mfma_f32_16x16x32_bf16 v[68:71], v[206:209], v[198:201], v[68:71]
	v_mfma_f32_16x16x32_bf16 v[64:67], v[214:217], v[198:201], v[64:67]
	v_lshl_add_u64 v[234:235], s[46:47], 0, v[170:171]
	s_mov_b32 m0, s38
	v_mfma_f32_16x16x32_bf16 v[100:103], v[210:213], v[112:115], v[100:103]
	v_lshl_add_u64 v[226:227], s[46:47], 0, v[174:175]
	v_mfma_f32_16x16x32_bf16 v[108:111], v[218:221], v[112:115], v[108:111]
	v_mfma_f32_16x16x32_bf16 v[112:115], v[206:209], v[160:163], v[124:127]
	v_mfma_f32_16x16x32_bf16 v[116:119], v[218:221], v[164:167], v[116:119]
	v_mfma_f32_16x16x32_bf16 v[68:71], v[210:213], v[202:205], v[68:71]
	v_mfma_f32_16x16x32_bf16 v[64:67], v[218:221], v[202:205], v[64:67]
	v_mfma_f32_16x16x32_bf16 v[112:115], v[210:213], v[164:167], v[112:115]
	s_barrier
	s_setprio 0
	ds_read_b128 v[124:127], v190 offset:16384
	ds_read_b128 v[132:135], v190 offset:17408
	ds_read_b128 v[140:143], v190 offset:18432
	ds_read_b128 v[152:155], v190 offset:19456
	ds_read_b128 v[160:163], v190 offset:20480
	ds_read_b128 v[164:167], v190 offset:21504
	ds_read_b128 v[198:201], v190 offset:22528
	ds_read_b128 v[202:205], v190 offset:23552
	global_load_lds_dwordx4 v[226:227], off
	s_mov_b32 m0, s39
	s_nop 0
	global_load_lds_dwordx4 v[234:235], off
	s_waitcnt vmcnt(10)
	s_setprio 1
	s_barrier
	s_waitcnt lgkmcnt(7)
	v_mfma_f32_16x16x32_bf16 v[60:63], v[80:83], v[124:127], v[60:63]
	v_mfma_f32_16x16x32_bf16 v[48:51], v[88:91], v[124:127], v[48:51]
	s_waitcnt lgkmcnt(5)
	v_mfma_f32_16x16x32_bf16 v[40:43], v[80:83], v[140:143], v[40:43]
	v_mfma_f32_16x16x32_bf16 v[32:35], v[88:91], v[140:143], v[32:35]
	s_waitcnt lgkmcnt(3)
	v_mfma_f32_16x16x32_bf16 v[24:27], v[80:83], v[160:163], v[24:27]
	v_mfma_f32_16x16x32_bf16 v[16:19], v[88:91], v[160:163], v[16:19]
	s_waitcnt lgkmcnt(1)
	v_mfma_f32_16x16x32_bf16 v[12:15], v[80:83], v[198:201], v[12:15]
	v_mfma_f32_16x16x32_bf16 v[8:11], v[88:91], v[198:201], v[8:11]
	v_mfma_f32_16x16x32_bf16 v[60:63], v[84:87], v[132:135], v[60:63]
	s_add_u32 s68, s24, 0x80000
	s_addc_u32 s69, s25, 0
	v_mfma_f32_16x16x32_bf16 v[48:51], v[92:95], v[132:135], v[48:51]
	s_add_i32 s70, s2, s66
	v_mfma_f32_16x16x32_bf16 v[40:43], v[84:87], v[152:155], v[40:43]
	v_mfma_f32_16x16x32_bf16 v[32:35], v[92:95], v[152:155], v[32:35]
	v_mfma_f32_16x16x32_bf16 v[24:27], v[84:87], v[164:167], v[24:27]
	v_mfma_f32_16x16x32_bf16 v[16:19], v[92:95], v[164:167], v[16:19]
	s_waitcnt lgkmcnt(0)
	v_mfma_f32_16x16x32_bf16 v[12:15], v[84:87], v[202:205], v[12:15]
	v_mfma_f32_16x16x32_bf16 v[8:11], v[92:95], v[202:205], v[8:11]
	s_barrier
; #define PG8_STAGE(bufoff, gbase, voff) do { _Pragma("unroll") for (int _i = 0; _i < 2; ++_i) \
;         __builtin_amdgcn_global_load_lds((const unsigned*)((const char*)(gbase) + (voff)[_i]), (LAS unsigned*)(lds + (bufoff) + ldsw + _i * 8192), 16, 0, 0); } while (0)
; #define PG8_LDA(dst, b, h) do { _Pragma("unroll") for (int m = 0; m < 4; ++m) _Pragma("unroll") for (int k = 0; k < 2; ++k) dst[m][k] = *(const LAS bf16x8*)(lds + PG8_SA(b, h) + aoff + m * 2048 + k * 1024); } while (0)
; #define PG8_LDB(dst, b, h) do { _Pragma("unroll") for (int n = 0; n < 2; ++n) _Pragma("unroll") for (int k = 0; k < 2; ++k) dst[n][k] = *(const LAS bf16x8*)(lds + PG8_SB(b, h) + boff + n * 2048 + k * 1024); } while (0)
; #define PG8_MMA(ai, bj, At, Bt) do { __builtin_amdgcn_s_setprio(1); _Pragma("unroll") for (int m = 0; m < 4; ++m) _Pragma("unroll") for (int n = 0; n < 2; ++n) _Pragma("unroll") for (int k = 0; k < 2; ++k) \
;         acc[ai][bj][m][n] = __builtin_amdgcn_mfma_f32_16x16x32_bf16(Bt[n][k], At[m][k], acc[ai][bj][m][n], 0, 0, 0); __builtin_amdgcn_s_setprio(0); } while (0)
; #define PG8_WAIT_V(n) asm volatile("s_waitcnt vmcnt(" #n ")" ::: "memory")
; #define PG8_WAIT_L(n) asm volatile("s_waitcnt lgkmcnt(" #n ")" ::: "memory")
; #define PG8_BAR __builtin_amdgcn_s_barrier()
; #define PG8_SCHED __builtin_amdgcn_sched_barrier(0)
; template <class Map, class Epi>
; DI void gemm_phase(LAS unsigned char* lds, const Map& MP, const Epi& E, const int nM, const int nN, const int K, const int lda, const int ldb) {
;     ...
;             PG8_WAIT_V(6); PG8_BAR; PG8_MMA(1, 1, At, B1); PG8_BAR;
;             PG8_LDB(B0, 1, 0); PG8_SCHED; PG8_LDA(At, 1, 0); PG8_STAGE(PG8_SA(0, 1), a2 + hstepA, voffA);
;             PG8_WAIT_L(8); PG8_BAR; PG8_WAIT_L(0); PG8_MMA(0, 0, At, B0); PG8_BAR; PG8_SCHED;
;             PG8_LDB(B1, 1, 1); PG8_STAGE(PG8_SB(1, 0), b3, voffB);
;             PG8_BAR; PG8_WAIT_L(0); PG8_MMA(0, 1, At, B1); PG8_BAR;
;             PG8_LDA(At, 1, 1); PG8_STAGE(PG8_SA(1, 0), a3, voffA);
;             PG8_BAR; PG8_WAIT_L(0); PG8_MMA(1, 0, At, B0); PG8_BAR; PG8_SCHED;
	s_setprio 0
	s_mov_b32 m0, s70
	s_nop 0
	global_load_lds_dwordx4 v172, s[68:69]
	s_add_i32 m0, s70, 0x2000
	s_nop 0
	global_load_lds_dwordx4 v168, s[68:69]
	s_waitcnt vmcnt(6)
	s_setprio 1
	s_barrier
	v_mfma_f32_16x16x32_bf16 v[56:59], v[206:209], v[124:127], v[56:59]
	v_mfma_f32_16x16x32_bf16 v[52:55], v[214:217], v[124:127], v[52:55]
	s_add_i32 s68, 0, 0x18000
	v_add_u32_e32 v92, s68, v188
	ds_read_b128 v[80:83], v92
	v_mfma_f32_16x16x32_bf16 v[44:47], v[206:209], v[140:143], v[44:47]
	v_mfma_f32_16x16x32_bf16 v[36:39], v[214:217], v[140:143], v[36:39]
	ds_read_b128 v[84:87], v92 offset:1024
	v_mfma_f32_16x16x32_bf16 v[28:31], v[206:209], v[160:163], v[28:31]
	v_mfma_f32_16x16x32_bf16 v[20:23], v[214:217], v[160:163], v[20:23]
	ds_read_b128 v[88:91], v92 offset:2048
	v_mfma_f32_16x16x32_bf16 v[4:7], v[206:209], v[198:201], v[4:7]
	v_mfma_f32_16x16x32_bf16 v[0:3], v[214:217], v[198:201], v[0:3]
	ds_read_b128 v[92:95], v92 offset:3072
	v_mfma_f32_16x16x32_bf16 v[56:59], v[210:213], v[132:135], v[56:59]
	s_add_u32 s46, s46, 0x80000
	s_addc_u32 s47, s47, 0
	v_mfma_f32_16x16x32_bf16 v[52:55], v[218:221], v[132:135], v[52:55]
	v_mfma_f32_16x16x32_bf16 v[44:47], v[210:213], v[152:155], v[44:47]
	v_mfma_f32_16x16x32_bf16 v[36:39], v[218:221], v[152:155], v[36:39]
	v_mfma_f32_16x16x32_bf16 v[28:31], v[210:213], v[164:167], v[28:31]
	v_mfma_f32_16x16x32_bf16 v[20:23], v[218:221], v[164:167], v[20:23]
	v_mfma_f32_16x16x32_bf16 v[4:7], v[210:213], v[202:205], v[4:7]
	v_mfma_f32_16x16x32_bf16 v[0:3], v[218:221], v[202:205], v[0:3]
	s_barrier
	s_setprio 0
	s_mov_b32 m0, s56
	ds_read_b128 v[124:127], v190 offset:32768
	ds_read_b128 v[132:135], v190 offset:33792
	ds_read_b128 v[160:163], v190 offset:34816
	ds_read_b128 v[164:167], v190 offset:35840
	ds_read_b128 v[198:201], v190 offset:36864
	ds_read_b128 v[202:205], v190 offset:37888
	ds_read_b128 v[206:209], v190 offset:38912
	ds_read_b128 v[210:213], v190 offset:39936
	global_load_lds_dwordx4 v174, s[46:47]
	s_mov_b32 m0, s57
	s_nop 0
	global_load_lds_dwordx4 v170, s[46:47]
	s_waitcnt lgkmcnt(8)
	s_setprio 1
	s_barrier
	s_waitcnt lgkmcnt(7)
	v_mfma_f32_16x16x32_bf16 v[140:143], v[80:83], v[124:127], v[148:151]
	s_waitcnt lgkmcnt(6)
	v_mfma_f32_16x16x32_bf16 v[148:151], v[84:87], v[132:135], v[140:143]
	v_mfma_f32_16x16x32_bf16 v[140:143], v[88:91], v[124:127], v[144:147]
	s_waitcnt lgkmcnt(5)
	v_mfma_f32_16x16x32_bf16 v[136:139], v[80:83], v[160:163], v[136:139]
	v_mfma_f32_16x16x32_bf16 v[128:131], v[88:91], v[160:163], v[128:131]
	s_waitcnt lgkmcnt(3)
	v_mfma_f32_16x16x32_bf16 v[120:123], v[80:83], v[198:201], v[120:123]
	v_mfma_f32_16x16x32_bf16 v[104:107], v[88:91], v[198:201], v[104:107]
	s_waitcnt lgkmcnt(1)
	v_mfma_f32_16x16x32_bf16 v[76:79], v[80:83], v[206:209], v[76:79]
	v_mfma_f32_16x16x32_bf16 v[72:75], v[88:91], v[206:209], v[72:75]
	s_add_i32 s46, 0, 0x1c000
	v_mfma_f32_16x16x32_bf16 v[144:147], v[92:95], v[132:135], v[140:143]
	v_add_u32_e32 v140, s46, v188
	v_mfma_f32_16x16x32_bf16 v[136:139], v[84:87], v[164:167], v[136:139]
	s_add_i32 s47, s68, s66
	v_mfma_f32_16x16x32_bf16 v[128:131], v[92:95], v[164:167], v[128:131]
	v_mfma_f32_16x16x32_bf16 v[120:123], v[84:87], v[202:205], v[120:123]
	v_mfma_f32_16x16x32_bf16 v[104:107], v[92:95], v[202:205], v[104:107]
	s_waitcnt lgkmcnt(0)
	v_mfma_f32_16x16x32_bf16 v[76:79], v[84:87], v[210:213], v[76:79]
	v_mfma_f32_16x16x32_bf16 v[72:75], v[92:95], v[210:213], v[72:75]
	s_barrier
	s_setprio 0
	ds_read_b128 v[214:217], v140
	ds_read_b128 v[218:221], v140 offset:1024
	ds_read_b128 v[222:225], v140 offset:2048
	ds_read_b128 v[230:233], v140 offset:3072
	v_lshl_add_u64 v[140:141], v[184:185], 0, s[14:15]
	s_mov_b32 m0, s47
	s_nop 0
	global_load_lds_dwordx4 v[140:141], off
	v_lshl_add_u64 v[140:141], v[194:195], 0, s[14:15]
	s_add_i32 m0, s47, 0x2000
	s_nop 0
	global_load_lds_dwordx4 v[140:141], off
	s_setprio 1
	s_barrier
	s_waitcnt lgkmcnt(1)
	v_mfma_f32_16x16x32_bf16 v[96:99], v[222:225], v[124:127], v[96:99]
	v_mfma_f32_16x16x32_bf16 v[140:143], v[214:217], v[124:127], v[156:159]
	s_waitcnt lgkmcnt(0)
	v_mfma_f32_16x16x32_bf16 v[152:155], v[230:233], v[132:135], v[96:99]
	v_mfma_f32_16x16x32_bf16 v[96:99], v[214:217], v[160:163], v[100:103]
	v_mfma_f32_16x16x32_bf16 v[156:159], v[218:221], v[132:135], v[140:143]
	v_mfma_f32_16x16x32_bf16 v[140:143], v[218:221], v[164:167], v[96:99]
	v_mfma_f32_16x16x32_bf16 v[96:99], v[222:225], v[160:163], v[108:111]
	v_mfma_f32_16x16x32_bf16 v[132:135], v[230:233], v[164:167], v[96:99]
	v_mfma_f32_16x16x32_bf16 v[96:99], v[214:217], v[198:201], v[112:115]
	s_mov_b32 m0, s63
	v_mfma_f32_16x16x32_bf16 v[124:127], v[218:221], v[202:205], v[96:99]
	v_lshl_add_u64 v[184:185], v[226:227], 0, s[14:15]
	v_mfma_f32_16x16x32_bf16 v[96:99], v[222:225], v[198:201], v[116:119]
	v_mfma_f32_16x16x32_bf16 v[68:71], v[214:217], v[206:209], v[68:71]
	v_mfma_f32_16x16x32_bf16 v[64:67], v[222:225], v[206:209], v[64:67]
	v_mfma_f32_16x16x32_bf16 v[116:119], v[230:233], v[202:205], v[96:99]
	v_mfma_f32_16x16x32_bf16 v[68:71], v[218:221], v[210:213], v[68:71]
	v_mfma_f32_16x16x32_bf16 v[64:67], v[230:233], v[210:213], v[64:67]
	s_barrier
	s_setprio 0
	ds_read_b128 v[96:99], v190 offset:49152
	ds_read_b128 v[100:103], v190 offset:50176
	ds_read_b128 v[108:111], v190 offset:51200
	ds_read_b128 v[112:115], v190 offset:52224
	ds_read_b128 v[160:163], v190 offset:53248
	ds_read_b128 v[164:167], v190 offset:54272
	ds_read_b128 v[198:201], v190 offset:55296
	ds_read_b128 v[202:205], v190 offset:56320
	global_load_lds_dwordx4 v[184:185], off
	v_lshl_add_u64 v[184:185], v[234:235], 0, s[14:15]
	s_mov_b32 m0, s4
	s_nop 0
	global_load_lds_dwordx4 v[184:185], off
	s_waitcnt vmcnt(10)
	s_setprio 1
	s_barrier
; #define PG8_STAGE(bufoff, gbase, voff) do { _Pragma("unroll") for (int _i = 0; _i < 2; ++_i) \
;         __builtin_amdgcn_global_load_lds((const unsigned*)((const char*)(gbase) + (voff)[_i]), (LAS unsigned*)(lds + (bufoff) + ldsw + _i * 8192), 16, 0, 0); } while (0)
; #define PG8_MMA(ai, bj, At, Bt) do { __builtin_amdgcn_s_setprio(1); _Pragma("unroll") for (int m = 0; m < 4; ++m) _Pragma("unroll") for (int n = 0; n < 2; ++n) _Pragma("unroll") for (int k = 0; k < 2; ++k) \
;         acc[ai][bj][m][n] = __builtin_amdgcn_mfma_f32_16x16x32_bf16(Bt[n][k], At[m][k], acc[ai][bj][m][n], 0, 0, 0); __builtin_amdgcn_s_setprio(0); } while (0)
; #define PG8_WAIT_V(n) asm volatile("s_waitcnt vmcnt(" #n ")" ::: "memory")
; #define PG8_BAR __builtin_amdgcn_s_barrier()
; template <class Map, class Epi>
; DI void gemm_phase(LAS unsigned char* lds, const Map& MP, const Epi& E, const int nM, const int nN, const int K, const int lda, const int ldb) {
;     ...
;             PG8_STAGE(PG8_SB(1, 1), b3 + hstepB, voffB);
;             PG8_WAIT_V(6); PG8_BAR; PG8_MMA(1, 1, At, B1); PG8_BAR;
	s_waitcnt lgkmcnt(7)
	v_mfma_f32_16x16x32_bf16 v[60:63], v[80:83], v[96:99], v[60:63]
	v_mfma_f32_16x16x32_bf16 v[48:51], v[88:91], v[96:99], v[48:51]
	s_waitcnt lgkmcnt(5)
	v_mfma_f32_16x16x32_bf16 v[40:43], v[80:83], v[108:111], v[40:43]
	v_mfma_f32_16x16x32_bf16 v[32:35], v[88:91], v[108:111], v[32:35]
	s_waitcnt lgkmcnt(3)
	v_mfma_f32_16x16x32_bf16 v[24:27], v[80:83], v[160:163], v[24:27]
	v_mfma_f32_16x16x32_bf16 v[16:19], v[88:91], v[160:163], v[16:19]
	s_waitcnt lgkmcnt(1)
	v_mfma_f32_16x16x32_bf16 v[12:15], v[80:83], v[198:201], v[12:15]
	v_mfma_f32_16x16x32_bf16 v[8:11], v[88:91], v[198:201], v[8:11]
	v_mfma_f32_16x16x32_bf16 v[60:63], v[84:87], v[100:103], v[60:63]
	s_add_u32 s24, s24, 0x80080
	s_addc_u32 s25, s25, 0
	v_mfma_f32_16x16x32_bf16 v[48:51], v[92:95], v[100:103], v[48:51]
	s_add_i32 s46, s46, s66
	v_mfma_f32_16x16x32_bf16 v[40:43], v[84:87], v[112:115], v[40:43]
	v_mfma_f32_16x16x32_bf16 v[32:35], v[92:95], v[112:115], v[32:35]
	v_mfma_f32_16x16x32_bf16 v[24:27], v[84:87], v[164:167], v[24:27]
	v_mfma_f32_16x16x32_bf16 v[16:19], v[92:95], v[164:167], v[16:19]
	s_waitcnt lgkmcnt(0)
	v_mfma_f32_16x16x32_bf16 v[12:15], v[84:87], v[202:205], v[12:15]
	v_mfma_f32_16x16x32_bf16 v[8:11], v[92:95], v[202:205], v[8:11]
	s_barrier
	s_setprio 0
	s_mov_b32 m0, s46
	s_nop 0
	global_load_lds_dwordx4 v172, s[24:25]
	s_add_i32 m0, s46, 0x2000
	s_nop 0
	global_load_lds_dwordx4 v168, s[24:25]
	s_waitcnt vmcnt(6)
	s_setprio 1
	s_barrier
	v_mfma_f32_16x16x32_bf16 v[56:59], v[214:217], v[96:99], v[56:59]
	v_mfma_f32_16x16x32_bf16 v[52:55], v[222:225], v[96:99], v[52:55]
	ds_read_b128 v[80:83], v189
	v_mfma_f32_16x16x32_bf16 v[44:47], v[214:217], v[108:111], v[44:47]
	v_mfma_f32_16x16x32_bf16 v[36:39], v[222:225], v[108:111], v[36:39]
	ds_read_b128 v[84:87], v189 offset:1024
	v_mfma_f32_16x16x32_bf16 v[28:31], v[214:217], v[160:163], v[28:31]
	v_mfma_f32_16x16x32_bf16 v[20:23], v[222:225], v[160:163], v[20:23]
	ds_read_b128 v[88:91], v189 offset:2048
	v_mfma_f32_16x16x32_bf16 v[4:7], v[214:217], v[198:201], v[4:7]
	v_mfma_f32_16x16x32_bf16 v[0:3], v[222:225], v[198:201], v[0:3]
	ds_read_b128 v[92:95], v189 offset:3072
	v_mfma_f32_16x16x32_bf16 v[56:59], v[218:221], v[100:103], v[56:59]
	s_add_i32 s3, s3, 2
	v_mfma_f32_16x16x32_bf16 v[52:55], v[230:233], v[100:103], v[52:55]
	s_add_u32 vcc_lo, vcc_lo, 0x100
	s_addc_u32 vcc_hi, vcc_hi, 0
	v_mfma_f32_16x16x32_bf16 v[44:47], v[218:221], v[112:115], v[44:47]
	s_add_u32 s42, s42, 0x100
	s_addc_u32 s43, s43, 0
	v_mfma_f32_16x16x32_bf16 v[36:39], v[230:233], v[112:115], v[36:39]
	s_cmp_gt_u32 s3, 29
	v_mfma_f32_16x16x32_bf16 v[28:31], v[218:221], v[164:167], v[28:31]
	v_mfma_f32_16x16x32_bf16 v[20:23], v[230:233], v[164:167], v[20:23]
	v_mfma_f32_16x16x32_bf16 v[4:7], v[218:221], v[202:205], v[4:7]
	v_mfma_f32_16x16x32_bf16 v[0:3], v[230:233], v[202:205], v[0:3]
	s_barrier
	s_setprio 0
	s_cbranch_scc0 .LBB1_1069
; DI float silu_mul(float g, float v) { return g * v * __builtin_amdgcn_rcpf(1.0f + __builtin_amdgcn_exp2f(-LOG2E * g)); }
;     DI void operator()(const f32x4 (&acc)[2][2][4][2], const Unit& u, int wr, int wc, int fr, int fq) const {
;         const int row0 = u.pm * BM + wr * 64 + fr, ch0 = u.pn * 128 + wc * 32 + 8 * fq;
;         f32x4 w0[2], w1[2], w2[2], bb[2];
; #pragma unroll
;         for (int n = 0; n < 2; ++n) { w0[n] = *(const f32x4*)(cw + ch0 + 4 * n); w1[n] = *(const f32x4*)(cw + DFF + ch0 + 4 * n); w2[n] = *(const f32x4*)(cw + 2 * DFF + ch0 + 4 * n); bb[n] = *(const f32x4*)(cb + ch0 + 4 * n); }
; #pragma unroll
;         for (int ai = 0; ai < 2; ++ai)
; #pragma unroll
;             for (int m = 0; m < 4; ++m) {
;                 const bool efirst = (m == 0) && (fr == 0), elast = (m == 3) && (fr == 15);
;                 const int row = row0 + ai * HALF + m * 16;
;                 f32x4 gc[2];
; #pragma unroll
;                 for (int n = 0; n < 2; ++n) {
;                     const f32x4 g = acc[ai][0][m][n];
;                     const f32x4 gprev = acc[ai][0][m > 0 ? m - 1 : 0][n], gnext = acc[ai][0][m < 3 ? m + 1 : 3][n];
;                     f32x4 up, dn;
; #pragma unroll
;                     for (int e = 0; e < 4; ++e) {
;                         const float pu = (m > 0 && fr == 15) ? gprev[e] : g[e];
;                         const float pd = (m < 3 && fr == 0) ? gnext[e] : g[e];
;                         up[e] = dpp_ror1(pu); dn[e] = dpp_ror15(pd);
;                     }
;                     if (efirst) up = (f32x4){0.f, 0.f, 0.f, 0.f};
;                     if (elast) dn = (f32x4){0.f, 0.f, 0.f, 0.f};
;                     gc[n] = w0[n] * up + w1[n] * g + w2[n] * dn + bb[n];
;                 }
;                 if (efirst || elast) {
;                     const size_t eo = (size_t)((row >> 6) * 2 + (elast ? 1 : 0)) * DFF + ch0;
; #pragma unroll
;                     for (int n = 0; n < 2; ++n) { *(f32x4*)(EP + eo + 4 * n) = gc[n]; *(f32x4*)(ER + eo + 4 * n) = acc[ai][0][m][n]; *(f32x4*)(EV + eo + 4 * n) = acc[ai][1][m][n]; }
;                 } else {
;                     const f32x4 v0 = acc[ai][1][m][0], v1 = acc[ai][1][m][1];
;                     u32x4 o;
;                     o[0] = pack2(silu_mul(gc[0][0], v0[0]), silu_mul(gc[0][1], v0[1])); o[1] = pack2(silu_mul(gc[0][2], v0[2]), silu_mul(gc[0][3], v0[3]));
	s_waitcnt lgkmcnt(0)
	s_lshl_b32 s21, s45, 7
	v_mov_b32_e32 v194, v186
	v_mov_b32_e32 v80, v187
	s_or_b32 s21, s21, s62
	v_lshl_add_u32 v184, v80, 3, s21
	v_ashrrev_i32_e32 v185, 31, v184
	v_lshlrev_b64 v[80:81], 2, v[184:185]
	v_lshl_add_u64 v[84:85], s[6:7], 0, v[80:81]
	v_lshl_add_u64 v[88:89], s[16:17], 0, v[80:81]
	v_lshl_add_u64 v[92:93], s[18:19], 0, v[80:81]
	v_lshl_add_u64 v[112:113], s[52:53], 0, v[80:81]
	global_load_dwordx4 v[80:83], v[84:85], off offset:16
	global_load_dwordx4 v[96:99], v[84:85], off
	s_nop 0
	global_load_dwordx4 v[84:87], v[88:89], off offset:16
	global_load_dwordx4 v[100:103], v[88:89], off
	s_nop 0
	global_load_dwordx4 v[88:91], v[92:93], off offset:16
	global_load_dwordx4 v[108:111], v[92:93], off
	s_nop 0
	global_load_dwordx4 v[92:95], v[112:113], off offset:16
	s_nop 0
	global_load_dwordx4 v[112:115], v[112:113], off
	v_cmp_eq_u32_e32 vcc, 0, v194
	s_nop 0
	s_nop 0
	v_cndmask_b32_e32 v161, v148, v136, vcc
	v_cndmask_b32_e32 v162, v149, v137, vcc
	v_cndmask_b32_e32 v163, v150, v138, vcc
	v_mov_b32_dpp v160, v161 row_ror:15 row_mask:0xf bank_mask:0xf
	s_nop 0
	s_nop 0
	v_mov_b32_dpp v161, v162 row_ror:15 row_mask:0xf bank_mask:0xf
	v_mov_b32_dpp v164, v150 row_ror:1 row_mask:0xf bank_mask:0xf
	v_cndmask_b32_e32 v165, v151, v139, vcc
	v_mov_b32_dpp v162, v163 row_ror:15 row_mask:0xf bank_mask:0xf
	v_mov_b32_dpp v195, v151 row_ror:1 row_mask:0xf bank_mask:0xf
	v_mov_b32_dpp v166, v148 row_ror:1 row_mask:0xf bank_mask:0xf
	v_mov_b32_dpp v167, v149 row_ror:1 row_mask:0xf bank_mask:0xf
	v_mov_b32_dpp v163, v165 row_ror:15 row_mask:0xf bank_mask:0xf
	v_cndmask_b32_e64 v165, v195, 0, vcc
	v_cndmask_b32_e64 v164, v164, 0, vcc
	v_cndmask_b32_e64 v167, v167, 0, vcc
	v_cndmask_b32_e64 v166, v166, 0, vcc
	s_nop 0
	s_nop 0
	v_mov_b32_dpp v195, v144 row_ror:1 row_mask:0xf bank_mask:0xf
	v_mov_b32_dpp v196, v145 row_ror:1 row_mask:0xf bank_mask:0xf
	v_mov_b32_dpp v198, v146 row_ror:1 row_mask:0xf bank_mask:0xf
	v_cndmask_b32_e32 v199, v147, v131, vcc
	v_mov_b32_dpp v200, v147 row_ror:1 row_mask:0xf bank_mask:0xf
	v_cndmask_b32_e64 v198, v198, 0, vcc
	v_cndmask_b32_e64 v201, v196, 0, vcc
	s_lshl_b32 s3, s44, 8
	s_add_i32 s3, s3, s49
	v_add_u32_e32 v193, s3, v194
	v_cmp_ne_u32_e64 s[46:47], 0, v194
	s_waitcnt vmcnt(0)
	v_pk_mul_f32 v[164:165], v[98:99], v[164:165]
	v_pk_mul_f32 v[166:167], v[96:97], v[166:167]
	v_pk_fma_f32 v[164:165], v[150:151], v[102:103], v[164:165]
	v_pk_fma_f32 v[166:167], v[148:149], v[100:101], v[166:167]
	v_pk_fma_f32 v[162:163], v[110:111], v[162:163], v[164:165]
	v_cndmask_b32_e32 v165, v144, v128, vcc
	v_pk_fma_f32 v[160:161], v[108:109], v[160:161], v[166:167]
	v_cndmask_b32_e32 v166, v145, v129, vcc
	v_mov_b32_dpp v164, v165 row_ror:15 row_mask:0xf bank_mask:0xf
	v_cndmask_b32_e32 v167, v146, v130, vcc
	v_pk_add_f32 v[162:163], v[114:115], v[162:163]
	v_mov_b32_dpp v165, v166 row_ror:15 row_mask:0xf bank_mask:0xf
	v_pk_add_f32 v[160:161], v[112:113], v[160:161]
	s_nop 0
	v_mov_b32_dpp v166, v167 row_ror:15 row_mask:0xf bank_mask:0xf
	s_nop 1
	v_mov_b32_dpp v167, v199 row_ror:15 row_mask:0xf bank_mask:0xf
	v_cndmask_b32_e64 v199, v200, 0, vcc
	v_cndmask_b32_e64 v200, v195, 0, vcc
	v_pk_mul_f32 v[200:201], v[80:81], v[200:201]
	v_pk_mul_f32 v[198:199], v[82:83], v[198:199]
	v_pk_fma_f32 v[200:201], v[144:145], v[84:85], v[200:201]
	v_pk_fma_f32 v[198:199], v[146:147], v[86:87], v[198:199]
	v_pk_fma_f32 v[164:165], v[88:89], v[164:165], v[200:201]
	v_pk_fma_f32 v[166:167], v[90:91], v[166:167], v[198:199]
	v_pk_add_f32 v[164:165], v[92:93], v[164:165]
	v_pk_add_f32 v[166:167], v[94:95], v[166:167]
	s_and_saveexec_b64 s[24:25], s[46:47]
	s_xor_b64 s[24:25], exec, s[24:25]
	s_cbranch_execz .LBB1_1072
	v_mul_f32_e32 v195, 0xbfb8aa3b, v160
	v_exp_f32_e32 v195, v195
	v_mul_f32_e32 v196, 0xbfb8aa3b, v161
	v_exp_f32_e32 v196, v196
	v_pk_mul_f32 v[160:161], v[156:157], v[160:161]
	v_add_f32_e32 v195, 1.0, v195
	v_rcp_f32_e32 v198, v195
	v_add_f32_e32 v196, 1.0, v196
	v_mul_f32_e32 v195, 0xbfb8aa3b, v162
	v_rcp_f32_e32 v199, v196
	v_exp_f32_e32 v195, v195
	v_mul_f32_e32 v196, 0xbfb8aa3b, v163
	v_exp_f32_e32 v196, v196
	v_pk_mul_f32 v[160:161], v[160:161], v[198:199]
	v_add_f32_e32 v195, 1.0, v195
	v_rcp_f32_e32 v200, v195
	v_add_f32_e32 v195, 1.0, v196
	v_rcp_f32_e32 v201, v195
	v_cvt_pk_bf16_f32 v160, v160, v161
	v_mul_f32_e32 v161, 0xbfb8aa3b, v164
	v_exp_f32_e32 v195, v161
	v_mul_f32_e32 v161, 0xbfb8aa3b, v165
	v_exp_f32_e32 v196, v161
	v_pk_mul_f32 v[162:163], v[158:159], v[162:163]
	v_pk_mul_f32 v[164:165], v[152:153], v[164:165]
	v_pk_mul_f32 v[162:163], v[162:163], v[200:201]
	s_nop 0
	v_cvt_pk_bf16_f32 v161, v162, v163
	v_add_f32_e32 v162, 1.0, v195
	v_mul_f32_e32 v195, 0xbfb8aa3b, v166
	v_add_f32_e32 v163, 1.0, v196
	v_exp_f32_e32 v195, v195
	v_mul_f32_e32 v196, 0xbfb8aa3b, v167
	v_exp_f32_e32 v196, v196
	v_rcp_f32_e32 v162, v162
	v_add_f32_e32 v195, 1.0, v195
	v_rcp_f32_e32 v198, v195
	v_add_f32_e32 v195, 1.0, v196
	v_rcp_f32_e32 v163, v163
	v_rcp_f32_e32 v199, v195
	v_pk_mul_f32 v[166:167], v[154:155], v[166:167]
	v_pk_mul_f32 v[162:163], v[164:165], v[162:163]
	v_pk_mul_f32 v[164:165], v[166:167], v[198:199]
	v_cvt_pk_bf16_f32 v162, v162, v163
	v_cvt_pk_bf16_f32 v163, v164, v165
	v_mov_b64_e32 v[164:165], s[54:55]
	v_mad_i64_i32 v[164:165], s[42:43], v193, s60, v[164:165]
	v_lshl_add_u64 v[164:165], v[184:185], 1, v[164:165]
	global_store_dwordx4 v[164:165], v[160:163], off

; #define PG8_STAGE(bufoff, gbase, voff) do { _Pragma("unroll") for (int _i = 0; _i < 2; ++_i) \
;         __builtin_amdgcn_global_load_lds((const unsigned*)((const char*)(gbase) + (voff)[_i]), (LAS unsigned*)(lds + (bufoff) + ldsw + _i * 8192), 16, 0, 0); } while (0)
; #define PG8_LDA(dst, b, h) do { _Pragma("unroll") for (int m = 0; m < 4; ++m) _Pragma("unroll") for (int k = 0; k < 2; ++k) dst[m][k] = *(const LAS bf16x8*)(lds + PG8_SA(b, h) + aoff + m * 2048 + k * 1024); } while (0)
; #define PG8_LDB(dst, b, h) do { _Pragma("unroll") for (int n = 0; n < 2; ++n) _Pragma("unroll") for (int k = 0; k < 2; ++k) dst[n][k] = *(const LAS bf16x8*)(lds + PG8_SB(b, h) + boff + n * 2048 + k * 1024); } while (0)
; #define PG8_MMA(ai, bj, At, Bt) do { __builtin_amdgcn_s_setprio(1); _Pragma("unroll") for (int m = 0; m < 4; ++m) _Pragma("unroll") for (int n = 0; n < 2; ++n) _Pragma("unroll") for (int k = 0; k < 2; ++k) \
;         acc[ai][bj][m][n] = __builtin_amdgcn_mfma_f32_16x16x32_bf16(Bt[n][k], At[m][k], acc[ai][bj][m][n], 0, 0, 0); __builtin_amdgcn_s_setprio(0); } while (0)
; #define PG8_WAIT_V(n) asm volatile("s_waitcnt vmcnt(" #n ")" ::: "memory")
; #define PG8_WAIT_L(n) asm volatile("s_waitcnt lgkmcnt(" #n ")" ::: "memory")
; template <class Map, class Epi>
; DI void gemm_phase(LAS unsigned char* lds, const Map& MP, const Epi& E, const int nM, const int nN, const int K, const int lda, const int ldb) {
;     ...
;             const bool last = (t == nt - 2);
;             const char* a1 = cA + (size_t)(t + 1) * kstep;
;             const char* a2 = last ? nA : cA + (size_t)(t + 2) * kstep; const char* b2 = last ? nB : cB + (size_t)(t + 2) * kstep;
;             const char* a3 = a2 + kstep; const char* b3 = b2 + kstep;
;             PG8_LDB(B0, 0, 0); PG8_SCHED; PG8_LDA(At, 0, 0); PG8_STAGE(PG8_SA(1, 1), a1 + hstepA, voffA);
;             PG8_WAIT_L(8); PG8_BAR; PG8_WAIT_L(0); PG8_MMA(0, 0, At, B0); PG8_BAR; PG8_SCHED;
;             PG8_LDB(B1, 0, 1); PG8_STAGE(PG8_SB(0, 0), b2, voffB);
;             PG8_BAR; PG8_WAIT_L(0); PG8_MMA(0, 1, At, B1); PG8_BAR;
;             PG8_LDA(At, 0, 1); PG8_STAGE(PG8_SA(0, 0), a2, voffA);
;             PG8_BAR; PG8_WAIT_L(0); PG8_MMA(1, 0, At, B0); PG8_BAR; PG8_SCHED;
;             PG8_STAGE(PG8_SB(0, 1), b2 + hstepB, voffB);
;             PG8_WAIT_V(6); PG8_BAR; PG8_MMA(1, 1, At, B1); PG8_BAR;
.LBB1_1239:
	s_add_u32 s10, s8, 0x100
	s_addc_u32 s11, s9, 0
	s_cmpk_eq_i32 s3, 0x54
	s_cselect_b32 s15, s43, s11
	s_cselect_b32 s14, s42, s10
	s_cselect_b32 s13, s7, s38
	s_cselect_b32 s12, s6, s5
	s_add_i32 m0, s24, 0xc000
	ds_read_b128 v[168:171], v150
	ds_read_b128 v[172:175], v150 offset:1024
	ds_read_b128 v[176:179], v150 offset:2048
	ds_read_b128 v[180:183], v150 offset:3072
	ds_read_b128 v[184:187], v150 offset:4096
	ds_read_b128 v[188:191], v150 offset:5120
	ds_read_b128 v[192:195], v150 offset:6144
	ds_read_b128 v[198:201], v150 offset:7168
	global_load_lds_dwordx4 v138, s[8:9]
	s_add_i32 m0, s24, 0xe000
	s_nop 0
	global_load_lds_dwordx4 v136, s[8:9]
	s_waitcnt lgkmcnt(8)
	s_setprio 1
	s_barrier
	s_waitcnt lgkmcnt(7)
	v_mfma_f32_16x16x32_bf16 v[124:127], v[152:155], v[168:171], v[124:127]
	v_mfma_f32_16x16x32_bf16 v[120:123], v[160:163], v[168:171], v[120:123]
	s_waitcnt lgkmcnt(5)
	v_mfma_f32_16x16x32_bf16 v[108:111], v[152:155], v[176:179], v[108:111]
	v_mfma_f32_16x16x32_bf16 v[104:107], v[160:163], v[176:179], v[104:107]
	s_waitcnt lgkmcnt(3)
	v_mfma_f32_16x16x32_bf16 v[92:95], v[152:155], v[184:187], v[92:95]
	v_mfma_f32_16x16x32_bf16 v[88:91], v[160:163], v[184:187], v[88:91]
	s_waitcnt lgkmcnt(1)
	v_mfma_f32_16x16x32_bf16 v[76:79], v[152:155], v[192:195], v[76:79]
	v_mfma_f32_16x16x32_bf16 v[72:75], v[160:163], v[192:195], v[72:75]
	v_mfma_f32_16x16x32_bf16 v[124:127], v[156:159], v[172:175], v[124:127]
	s_add_i32 s8, s35, s22
	v_mfma_f32_16x16x32_bf16 v[120:123], v[164:167], v[172:175], v[120:123]
	v_lshl_add_u64 v[144:145], s[12:13], 0, v[132:133]
	v_mfma_f32_16x16x32_bf16 v[108:111], v[156:159], v[180:183], v[108:111]
	v_lshl_add_u64 v[218:219], s[12:13], 0, v[128:129]
	v_mfma_f32_16x16x32_bf16 v[104:107], v[164:167], v[180:183], v[104:107]
	v_mfma_f32_16x16x32_bf16 v[92:95], v[156:159], v[188:191], v[92:95]
	v_mfma_f32_16x16x32_bf16 v[88:91], v[164:167], v[188:191], v[88:91]
	s_waitcnt lgkmcnt(0)
	v_mfma_f32_16x16x32_bf16 v[76:79], v[156:159], v[198:201], v[76:79]
	v_mfma_f32_16x16x32_bf16 v[72:75], v[164:167], v[198:201], v[72:75]
	s_barrier
	s_setprio 0
	s_mov_b32 m0, s8
	ds_read_b128 v[202:205], v151
	ds_read_b128 v[206:209], v151 offset:1024
	ds_read_b128 v[210:213], v151 offset:2048
	ds_read_b128 v[214:217], v151 offset:3072
	global_load_lds_dwordx4 v[144:145], off
	s_add_i32 m0, s8, 0x2000
	s_nop 0
	global_load_lds_dwordx4 v[218:219], off
	s_setprio 1
	s_barrier
	s_waitcnt lgkmcnt(3)
	v_mfma_f32_16x16x32_bf16 v[116:119], v[202:205], v[168:171], v[116:119]
	s_waitcnt lgkmcnt(1)
	v_mfma_f32_16x16x32_bf16 v[112:115], v[210:213], v[168:171], v[112:115]
	v_mfma_f32_16x16x32_bf16 v[100:103], v[202:205], v[176:179], v[100:103]
	v_mfma_f32_16x16x32_bf16 v[96:99], v[210:213], v[176:179], v[96:99]
	v_mfma_f32_16x16x32_bf16 v[84:87], v[202:205], v[184:187], v[84:87]
	v_mfma_f32_16x16x32_bf16 v[80:83], v[210:213], v[184:187], v[80:83]
	v_mfma_f32_16x16x32_bf16 v[68:71], v[202:205], v[192:195], v[68:71]
	v_mfma_f32_16x16x32_bf16 v[64:67], v[210:213], v[192:195], v[64:67]
	v_mfma_f32_16x16x32_bf16 v[116:119], v[206:209], v[172:175], v[116:119]
	v_lshl_add_u64 v[222:223], s[14:15], 0, v[130:131]
	s_mov_b32 m0, s24
	s_waitcnt lgkmcnt(0)
	v_mfma_f32_16x16x32_bf16 v[112:115], v[214:217], v[172:175], v[112:115]
	v_lshl_add_u64 v[220:221], s[14:15], 0, v[134:135]
	v_mfma_f32_16x16x32_bf16 v[100:103], v[206:209], v[180:183], v[100:103]
	v_mfma_f32_16x16x32_bf16 v[96:99], v[214:217], v[180:183], v[96:99]
	v_mfma_f32_16x16x32_bf16 v[84:87], v[206:209], v[188:191], v[84:87]
	v_mfma_f32_16x16x32_bf16 v[80:83], v[214:217], v[188:191], v[80:83]
	v_mfma_f32_16x16x32_bf16 v[68:71], v[206:209], v[198:201], v[68:71]
	v_mfma_f32_16x16x32_bf16 v[64:67], v[214:217], v[198:201], v[64:67]
	s_barrier
	s_setprio 0
	ds_read_b128 v[168:171], v150 offset:16384
	ds_read_b128 v[172:175], v150 offset:17408
	ds_read_b128 v[176:179], v150 offset:18432
	ds_read_b128 v[180:183], v150 offset:19456
	ds_read_b128 v[184:187], v150 offset:20480
	ds_read_b128 v[188:191], v150 offset:21504
	ds_read_b128 v[192:195], v150 offset:22528
	ds_read_b128 v[198:201], v150 offset:23552
	global_load_lds_dwordx4 v[220:221], off
	s_mov_b32 m0, s25
	s_nop 0
	global_load_lds_dwordx4 v[222:223], off
	s_waitcnt vmcnt(10)
	s_setprio 1
	s_barrier
	s_waitcnt lgkmcnt(7)
	v_mfma_f32_16x16x32_bf16 v[60:63], v[152:155], v[168:171], v[60:63]
	v_mfma_f32_16x16x32_bf16 v[56:59], v[160:163], v[168:171], v[56:59]
	s_waitcnt lgkmcnt(5)
	v_mfma_f32_16x16x32_bf16 v[44:47], v[152:155], v[176:179], v[44:47]
	v_mfma_f32_16x16x32_bf16 v[40:43], v[160:163], v[176:179], v[40:43]
	s_waitcnt lgkmcnt(3)
	v_mfma_f32_16x16x32_bf16 v[28:31], v[152:155], v[184:187], v[28:31]
	v_mfma_f32_16x16x32_bf16 v[24:27], v[160:163], v[184:187], v[24:27]
	s_waitcnt lgkmcnt(1)
	v_mfma_f32_16x16x32_bf16 v[12:15], v[152:155], v[192:195], v[12:15]
	v_mfma_f32_16x16x32_bf16 v[8:11], v[160:163], v[192:195], v[8:11]
	v_mfma_f32_16x16x32_bf16 v[60:63], v[156:159], v[172:175], v[60:63]
	s_add_u32 s8, s12, 0x160000
	s_addc_u32 s9, s13, 0
	v_mfma_f32_16x16x32_bf16 v[56:59], v[164:167], v[172:175], v[56:59]
	s_add_i32 s39, s36, s22
	v_mfma_f32_16x16x32_bf16 v[44:47], v[156:159], v[180:183], v[44:47]
	v_mfma_f32_16x16x32_bf16 v[40:43], v[164:167], v[180:183], v[40:43]
	v_mfma_f32_16x16x32_bf16 v[28:31], v[156:159], v[188:191], v[28:31]
	v_mfma_f32_16x16x32_bf16 v[24:27], v[164:167], v[188:191], v[24:27]
	s_waitcnt lgkmcnt(0)
	v_mfma_f32_16x16x32_bf16 v[12:15], v[156:159], v[198:201], v[12:15]
	v_mfma_f32_16x16x32_bf16 v[8:11], v[164:167], v[198:201], v[8:11]
	s_barrier
; #define PG8_STAGE(bufoff, gbase, voff) do { _Pragma("unroll") for (int _i = 0; _i < 2; ++_i) \
;         __builtin_amdgcn_global_load_lds((const unsigned*)((const char*)(gbase) + (voff)[_i]), (LAS unsigned*)(lds + (bufoff) + ldsw + _i * 8192), 16, 0, 0); } while (0)
; #define PG8_LDA(dst, b, h) do { _Pragma("unroll") for (int m = 0; m < 4; ++m) _Pragma("unroll") for (int k = 0; k < 2; ++k) dst[m][k] = *(const LAS bf16x8*)(lds + PG8_SA(b, h) + aoff + m * 2048 + k * 1024); } while (0)
; #define PG8_LDB(dst, b, h) do { _Pragma("unroll") for (int n = 0; n < 2; ++n) _Pragma("unroll") for (int k = 0; k < 2; ++k) dst[n][k] = *(const LAS bf16x8*)(lds + PG8_SB(b, h) + boff + n * 2048 + k * 1024); } while (0)
; #define PG8_MMA(ai, bj, At, Bt) do { __builtin_amdgcn_s_setprio(1); _Pragma("unroll") for (int m = 0; m < 4; ++m) _Pragma("unroll") for (int n = 0; n < 2; ++n) _Pragma("unroll") for (int k = 0; k < 2; ++k) \
;         acc[ai][bj][m][n] = __builtin_amdgcn_mfma_f32_16x16x32_bf16(Bt[n][k], At[m][k], acc[ai][bj][m][n], 0, 0, 0); __builtin_amdgcn_s_setprio(0); } while (0)
; #define PG8_WAIT_V(n) asm volatile("s_waitcnt vmcnt(" #n ")" ::: "memory")
; #define PG8_WAIT_L(n) asm volatile("s_waitcnt lgkmcnt(" #n ")" ::: "memory")
; #define PG8_BAR __builtin_amdgcn_s_barrier()
; #define PG8_SCHED __builtin_amdgcn_sched_barrier(0)
; template <class Map, class Epi>
; DI void gemm_phase(LAS unsigned char* lds, const Map& MP, const Epi& E, const int nM, const int nN, const int K, const int lda, const int ldb) {
;     ...
;             PG8_WAIT_V(6); PG8_BAR; PG8_MMA(1, 1, At, B1); PG8_BAR;
;             PG8_LDB(B0, 1, 0); PG8_SCHED; PG8_LDA(At, 1, 0); PG8_STAGE(PG8_SA(0, 1), a2 + hstepA, voffA);
;             PG8_WAIT_L(8); PG8_BAR; PG8_WAIT_L(0); PG8_MMA(0, 0, At, B0); PG8_BAR; PG8_SCHED;
;             PG8_LDB(B1, 1, 1); PG8_STAGE(PG8_SB(1, 0), b3, voffB);
;             PG8_BAR; PG8_WAIT_L(0); PG8_MMA(0, 1, At, B1); PG8_BAR;
;             PG8_LDA(At, 1, 1); PG8_STAGE(PG8_SA(1, 0), a3, voffA);
;             PG8_BAR; PG8_WAIT_L(0); PG8_MMA(1, 0, At, B0); PG8_BAR; PG8_SCHED;
	s_setprio 0
	s_mov_b32 m0, s39
	s_nop 0
	global_load_lds_dwordx4 v132, s[8:9]
	s_add_i32 m0, s39, 0x2000
	s_nop 0
	global_load_lds_dwordx4 v128, s[8:9]
	s_waitcnt vmcnt(6)
	s_setprio 1
	s_barrier
	v_mfma_f32_16x16x32_bf16 v[52:55], v[202:205], v[168:171], v[52:55]
	v_mfma_f32_16x16x32_bf16 v[48:51], v[210:213], v[168:171], v[48:51]
	s_add_i32 s39, 0, 0x18000
	v_add_u32_e32 v164, s39, v148
	ds_read_b128 v[152:155], v164
	v_mfma_f32_16x16x32_bf16 v[36:39], v[202:205], v[176:179], v[36:39]
	v_mfma_f32_16x16x32_bf16 v[32:35], v[210:213], v[176:179], v[32:35]
	ds_read_b128 v[156:159], v164 offset:1024
	v_mfma_f32_16x16x32_bf16 v[20:23], v[202:205], v[184:187], v[20:23]
	v_mfma_f32_16x16x32_bf16 v[16:19], v[210:213], v[184:187], v[16:19]
	ds_read_b128 v[160:163], v164 offset:2048
	v_mfma_f32_16x16x32_bf16 v[4:7], v[202:205], v[192:195], v[4:7]
	v_mfma_f32_16x16x32_bf16 v[0:3], v[210:213], v[192:195], v[0:3]
	ds_read_b128 v[164:167], v164 offset:3072
	v_mfma_f32_16x16x32_bf16 v[52:55], v[206:209], v[172:175], v[52:55]
	s_add_u32 s8, s14, 0x160000
	s_addc_u32 s9, s15, 0
	v_mfma_f32_16x16x32_bf16 v[48:51], v[214:217], v[172:175], v[48:51]
	v_mfma_f32_16x16x32_bf16 v[36:39], v[206:209], v[180:183], v[36:39]
	v_mfma_f32_16x16x32_bf16 v[32:35], v[214:217], v[180:183], v[32:35]
	v_mfma_f32_16x16x32_bf16 v[20:23], v[206:209], v[188:191], v[20:23]
	v_mfma_f32_16x16x32_bf16 v[16:19], v[214:217], v[188:191], v[16:19]
	v_mfma_f32_16x16x32_bf16 v[4:7], v[206:209], v[198:201], v[4:7]
	v_mfma_f32_16x16x32_bf16 v[0:3], v[214:217], v[198:201], v[0:3]
	s_barrier
	s_setprio 0
	s_mov_b32 m0, s26
	ds_read_b128 v[168:171], v150 offset:32768
	ds_read_b128 v[172:175], v150 offset:33792
	ds_read_b128 v[176:179], v150 offset:34816
	ds_read_b128 v[180:183], v150 offset:35840
	ds_read_b128 v[184:187], v150 offset:36864
	ds_read_b128 v[188:191], v150 offset:37888
	ds_read_b128 v[192:195], v150 offset:38912
	ds_read_b128 v[198:201], v150 offset:39936
	global_load_lds_dwordx4 v134, s[8:9]
	s_mov_b32 m0, s27
	s_nop 0
	global_load_lds_dwordx4 v130, s[8:9]
	s_waitcnt lgkmcnt(8)
	s_setprio 1
	s_barrier
	s_waitcnt lgkmcnt(7)
	v_mfma_f32_16x16x32_bf16 v[124:127], v[152:155], v[168:171], v[124:127]
	v_mfma_f32_16x16x32_bf16 v[120:123], v[160:163], v[168:171], v[120:123]
	s_waitcnt lgkmcnt(5)
	v_mfma_f32_16x16x32_bf16 v[108:111], v[152:155], v[176:179], v[108:111]
	v_mfma_f32_16x16x32_bf16 v[104:107], v[160:163], v[176:179], v[104:107]
	s_waitcnt lgkmcnt(3)
	v_mfma_f32_16x16x32_bf16 v[92:95], v[152:155], v[184:187], v[92:95]
	v_mfma_f32_16x16x32_bf16 v[88:91], v[160:163], v[184:187], v[88:91]
	s_waitcnt lgkmcnt(1)
	v_mfma_f32_16x16x32_bf16 v[76:79], v[152:155], v[192:195], v[76:79]
	v_mfma_f32_16x16x32_bf16 v[72:75], v[160:163], v[192:195], v[72:75]
	v_mfma_f32_16x16x32_bf16 v[124:127], v[156:159], v[172:175], v[124:127]
	s_add_i32 s14, 0, 0x1c000
	v_mfma_f32_16x16x32_bf16 v[120:123], v[164:167], v[172:175], v[120:123]
	s_add_i32 s8, s39, s22
	v_mfma_f32_16x16x32_bf16 v[108:111], v[156:159], v[180:183], v[108:111]
	v_add_u32_e32 v196, s14, v148
	v_mfma_f32_16x16x32_bf16 v[104:107], v[164:167], v[180:183], v[104:107]
	v_lshl_add_u64 v[144:145], v[144:145], 0, s[52:53]
	v_mfma_f32_16x16x32_bf16 v[92:95], v[156:159], v[188:191], v[92:95]
	v_mfma_f32_16x16x32_bf16 v[88:91], v[164:167], v[188:191], v[88:91]
	s_waitcnt lgkmcnt(0)
	v_mfma_f32_16x16x32_bf16 v[76:79], v[156:159], v[198:201], v[76:79]
	v_mfma_f32_16x16x32_bf16 v[72:75], v[164:167], v[198:201], v[72:75]
	s_barrier
	s_setprio 0
	s_mov_b32 m0, s8
	ds_read_b128 v[202:205], v196
	ds_read_b128 v[206:209], v196 offset:1024
	ds_read_b128 v[210:213], v196 offset:2048
	ds_read_b128 v[214:217], v196 offset:3072
	global_load_lds_dwordx4 v[144:145], off
	v_lshl_add_u64 v[144:145], v[218:219], 0, s[52:53]
	s_add_i32 m0, s8, 0x2000
	s_nop 0
	global_load_lds_dwordx4 v[144:145], off
	s_setprio 1
	s_barrier
	s_waitcnt lgkmcnt(3)
	v_mfma_f32_16x16x32_bf16 v[116:119], v[202:205], v[168:171], v[116:119]
	s_waitcnt lgkmcnt(1)
	v_mfma_f32_16x16x32_bf16 v[112:115], v[210:213], v[168:171], v[112:115]
	v_mfma_f32_16x16x32_bf16 v[100:103], v[202:205], v[176:179], v[100:103]
	v_mfma_f32_16x16x32_bf16 v[96:99], v[210:213], v[176:179], v[96:99]
	v_mfma_f32_16x16x32_bf16 v[84:87], v[202:205], v[184:187], v[84:87]
	v_mfma_f32_16x16x32_bf16 v[80:83], v[210:213], v[184:187], v[80:83]
	v_mfma_f32_16x16x32_bf16 v[68:71], v[202:205], v[192:195], v[68:71]
	v_mfma_f32_16x16x32_bf16 v[64:67], v[210:213], v[192:195], v[64:67]
	v_mfma_f32_16x16x32_bf16 v[116:119], v[206:209], v[172:175], v[116:119]
	s_mov_b32 m0, s30
	s_waitcnt lgkmcnt(0)
	v_mfma_f32_16x16x32_bf16 v[112:115], v[214:217], v[172:175], v[112:115]
	v_lshl_add_u64 v[144:145], v[220:221], 0, s[52:53]
	v_mfma_f32_16x16x32_bf16 v[100:103], v[206:209], v[180:183], v[100:103]
	v_mfma_f32_16x16x32_bf16 v[96:99], v[214:217], v[180:183], v[96:99]
	v_mfma_f32_16x16x32_bf16 v[84:87], v[206:209], v[188:191], v[84:87]
	v_mfma_f32_16x16x32_bf16 v[80:83], v[214:217], v[188:191], v[80:83]
	v_mfma_f32_16x16x32_bf16 v[68:71], v[206:209], v[198:201], v[68:71]
	v_mfma_f32_16x16x32_bf16 v[64:67], v[214:217], v[198:201], v[64:67]
	s_barrier
	s_setprio 0
	ds_read_b128 v[168:171], v150 offset:49152
	ds_read_b128 v[172:175], v150 offset:50176
	ds_read_b128 v[176:179], v150 offset:51200
	ds_read_b128 v[180:183], v150 offset:52224
	ds_read_b128 v[184:187], v150 offset:53248
	ds_read_b128 v[188:191], v150 offset:54272
	ds_read_b128 v[192:195], v150 offset:55296
	ds_read_b128 v[198:201], v150 offset:56320
	global_load_lds_dwordx4 v[144:145], off
	v_lshl_add_u64 v[144:145], v[222:223], 0, s[52:53]
	s_mov_b32 m0, s31
	s_nop 0
	global_load_lds_dwordx4 v[144:145], off
	s_waitcnt vmcnt(10)
	s_setprio 1
	s_barrier
; DI unsigned pack2(float a, float b) { f32x2 v = {a, b}; hwbf16x2 r = __builtin_convertvector(v, hwbf16x2); return __builtin_bit_cast(unsigned, r); }
; DI float bflo(unsigned w) { return __uint_as_float(w << 16); }
; DI float bfhi(unsigned w) { return __uint_as_float(w & 0xffff0000u); }
; #define PG8_WAIT_V(n) asm volatile("s_waitcnt vmcnt(" #n ")" ::: "memory")
; #define PG8_BAR __builtin_amdgcn_s_barrier()
;     DI void operator()(const f32x4 (&acc)[2][2][4][2], const Unit& u, int wr, int wc, int fr, int fq) const {
;         const int row0 = u.pm * BM + wr * 64 + fr, col0 = u.pn * BM + wc * 32 + 8 * fq;
;         f32x4 sc[2][2];
; #pragma unroll
;         for (int bj = 0; bj < 2; ++bj)
; #pragma unroll
;             for (int n = 0; n < 2; ++n) sc[bj][n] = scale ? *(const f32x4*)(scale + col0 + bj * HALF + 4 * n) : (f32x4){1.f, 1.f, 1.f, 1.f};
; #pragma unroll
;         for (int ai = 0; ai < 2; ++ai)
; #pragma unroll
;             for (int m = 0; m < 4; ++m) { const size_t ro = (size_t)(row0 + ai * HALF + m * 16) * D + col0;
; #pragma unroll
;                 for (int bj = 0; bj < 2; ++bj) {
;                     f32x4 x0, x1;
;                     if constexpr (IB) { const u32x4 w = *(const u32x4*)((const bf16_t*)Xin + ro + bj * HALF);
;                         x0 = (f32x4){bflo(w[0]), bfhi(w[0]), bflo(w[1]), bfhi(w[1])}; x1 = (f32x4){bflo(w[2]), bfhi(w[2]), bflo(w[3]), bfhi(w[3])}; }
;                     else { x0 = *(const f32x4*)((const float*)Xin + ro + bj * HALF); x1 = *(const f32x4*)((const float*)Xin + ro + bj * HALF + 4); }
;                     x0 += acc[ai][bj][m][0] * sc[bj][0]; x1 += acc[ai][bj][m][1] * sc[bj][1];
;                     if constexpr (OB) { u32x4 o; o[0] = pack2(x0[0], x0[1]); o[1] = pack2(x0[2], x0[3]); o[2] = pack2(x1[0], x1[1]); o[3] = pack2(x1[2], x1[3]);
;                         *(u32x4*)((bf16_t*)Xout + ro + bj * HALF) = o; }
;                     else { *(f32x4*)((float*)Xout + ro + bj * HALF) = x0; *(f32x4*)((float*)Xout + ro + bj * HALF + 4) = x1; } } }
; template <class Map, class Epi>
; DI void gemm_phase(LAS unsigned char* lds, const Map& MP, const Epi& E, const int nM, const int nN, const int K, const int lda, const int ldb) {
;     ...
;             PG8_STAGE(PG8_SB(1, 1), b3 + hstepB, voffB);
;             PG8_WAIT_V(6); PG8_BAR; PG8_MMA(1, 1, At, B1); PG8_BAR;
	s_waitcnt lgkmcnt(7)
	v_mfma_f32_16x16x32_bf16 v[60:63], v[152:155], v[168:171], v[60:63]
	v_mfma_f32_16x16x32_bf16 v[56:59], v[160:163], v[168:171], v[56:59]
	s_waitcnt lgkmcnt(5)
	v_mfma_f32_16x16x32_bf16 v[44:47], v[152:155], v[176:179], v[44:47]
	v_mfma_f32_16x16x32_bf16 v[40:43], v[160:163], v[176:179], v[40:43]
	s_waitcnt lgkmcnt(3)
	v_mfma_f32_16x16x32_bf16 v[28:31], v[152:155], v[184:187], v[28:31]
	v_mfma_f32_16x16x32_bf16 v[24:27], v[160:163], v[184:187], v[24:27]
	s_waitcnt lgkmcnt(1)
	v_mfma_f32_16x16x32_bf16 v[12:15], v[152:155], v[192:195], v[12:15]
	v_mfma_f32_16x16x32_bf16 v[8:11], v[160:163], v[192:195], v[8:11]
	v_mfma_f32_16x16x32_bf16 v[60:63], v[156:159], v[172:175], v[60:63]
	s_add_u32 s8, s12, 0x160080
	s_addc_u32 s9, s13, 0
	v_mfma_f32_16x16x32_bf16 v[56:59], v[164:167], v[172:175], v[56:59]
	s_add_i32 s12, s14, s22
	v_mfma_f32_16x16x32_bf16 v[44:47], v[156:159], v[180:183], v[44:47]
	v_mfma_f32_16x16x32_bf16 v[40:43], v[164:167], v[180:183], v[40:43]
	v_mfma_f32_16x16x32_bf16 v[28:31], v[156:159], v[188:191], v[28:31]
	v_mfma_f32_16x16x32_bf16 v[24:27], v[164:167], v[188:191], v[24:27]
	s_waitcnt lgkmcnt(0)
	v_mfma_f32_16x16x32_bf16 v[12:15], v[156:159], v[198:201], v[12:15]
	v_mfma_f32_16x16x32_bf16 v[8:11], v[164:167], v[198:201], v[8:11]
	s_barrier
	s_setprio 0
	s_mov_b32 m0, s12
	s_nop 0
	global_load_lds_dwordx4 v132, s[8:9]
	s_add_i32 m0, s12, 0x2000
	s_nop 0
	global_load_lds_dwordx4 v128, s[8:9]
	s_waitcnt vmcnt(6)
	s_setprio 1
	s_barrier
	v_mfma_f32_16x16x32_bf16 v[52:55], v[202:205], v[168:171], v[52:55]
	v_mfma_f32_16x16x32_bf16 v[48:51], v[210:213], v[168:171], v[48:51]
	ds_read_b128 v[152:155], v149
	v_mfma_f32_16x16x32_bf16 v[36:39], v[202:205], v[176:179], v[36:39]
	v_mfma_f32_16x16x32_bf16 v[32:35], v[210:213], v[176:179], v[32:35]
	ds_read_b128 v[156:159], v149 offset:1024
	v_mfma_f32_16x16x32_bf16 v[20:23], v[202:205], v[184:187], v[20:23]
	v_mfma_f32_16x16x32_bf16 v[16:19], v[210:213], v[184:187], v[16:19]
	ds_read_b128 v[160:163], v149 offset:2048
	v_mfma_f32_16x16x32_bf16 v[4:7], v[202:205], v[192:195], v[4:7]
	v_mfma_f32_16x16x32_bf16 v[0:3], v[210:213], v[192:195], v[0:3]
	ds_read_b128 v[164:167], v149 offset:3072
	v_mfma_f32_16x16x32_bf16 v[52:55], v[206:209], v[172:175], v[52:55]
	s_add_i32 s3, s3, 2
	v_mfma_f32_16x16x32_bf16 v[48:51], v[214:217], v[172:175], v[48:51]
	s_add_u32 s5, s5, 0x100
	s_addc_u32 s38, s38, 0
	v_mfma_f32_16x16x32_bf16 v[36:39], v[206:209], v[180:183], v[36:39]
	s_cmpk_gt_u32 s3, 0x55
	v_mfma_f32_16x16x32_bf16 v[32:35], v[214:217], v[180:183], v[32:35]
	s_mov_b64 s[8:9], s[10:11]
	v_mfma_f32_16x16x32_bf16 v[20:23], v[206:209], v[188:191], v[20:23]
	v_mfma_f32_16x16x32_bf16 v[16:19], v[214:217], v[188:191], v[16:19]
	v_mfma_f32_16x16x32_bf16 v[4:7], v[206:209], v[198:201], v[4:7]
	v_mfma_f32_16x16x32_bf16 v[0:3], v[214:217], v[198:201], v[0:3]
	s_barrier
	s_setprio 0
	s_cbranch_scc0 .LBB1_1239
	s_waitcnt lgkmcnt(0)
	v_mov_b32_e32 v152, v147
	v_mov_b32_e32 v144, v146
	s_lshl_b32 s2, s2, 8
	s_add_i32 s2, s2, s29
	s_lshl_b32 s3, s4, 8
	v_add_u32_e32 v152, s2, v152
	s_or_b32 s3, s3, s54
	v_ashrrev_i32_e32 v153, 31, v152
	v_lshl_add_u32 v144, v144, 3, s3
	v_lshlrev_b64 v[152:153], 12, v[152:153]
	v_ashrrev_i32_e32 v145, 31, v144
	v_lshl_add_u64 v[152:153], s[46:47], 0, v[152:153]
	v_lshl_add_u64 v[144:145], v[144:145], 1, v[152:153]
	global_load_dwordx4 v[160:163], v[144:145], off
	global_load_dwordx4 v[164:167], v[144:145], off offset:256
	s_mov_b64 s[98:99], 0x10000
	v_lshl_add_u64 v[154:155], v[144:145], 0, s[98:99]
	global_load_dwordx4 v[168:171], v[154:155], off
	global_load_dwordx4 v[172:175], v[154:155], off offset:256
	s_mov_b64 s[98:99], 0x20000
	v_lshl_add_u64 v[154:155], v[144:145], 0, s[98:99]
	global_load_dwordx4 v[176:179], v[154:155], off
	global_load_dwordx4 v[180:183], v[154:155], off offset:256
	s_mov_b64 s[98:99], 0x30000
	v_lshl_add_u64 v[154:155], v[144:145], 0, s[98:99]
	global_load_dwordx4 v[184:187], v[154:155], off
	global_load_dwordx4 v[188:191], v[154:155], off offset:256
	s_mov_b64 s[98:99], 0x80000
	v_lshl_add_u64 v[154:155], v[144:145], 0, s[98:99]
	global_load_dwordx4 v[192:195], v[154:155], off
	global_load_dwordx4 v[198:201], v[154:155], off offset:256
	s_mov_b64 s[98:99], 0x90000
	v_lshl_add_u64 v[154:155], v[144:145], 0, s[98:99]
	global_load_dwordx4 v[202:205], v[154:155], off
	global_load_dwordx4 v[206:209], v[154:155], off offset:256
	s_mov_b64 s[98:99], 0xa0000
	v_lshl_add_u64 v[154:155], v[144:145], 0, s[98:99]
	global_load_dwordx4 v[210:213], v[154:155], off
	global_load_dwordx4 v[214:217], v[154:155], off offset:256
	s_mov_b64 s[98:99], 0xb0000
	v_lshl_add_u64 v[154:155], v[144:145], 0, s[98:99]
	global_load_dwordx4 v[248:251], v[154:155], off
	global_load_dwordx4 v[252:255], v[154:155], off offset:256
	s_waitcnt vmcnt(15)
	s_nop 1
	v_mov_b32_e32 v152, v160
	v_mov_b32_e32 v153, v161
	v_mov_b32_e32 v154, v162
	v_mov_b32_e32 v155, v163
	s_mov_b64 s[2:3], 0x10000
	s_mov_b32 s4, s37
	s_mov_b64 s[10:11], s[6:7]
	s_mov_b64 s[8:9], s[42:43]
	s_waitcnt lgkmcnt(0)
	v_lshlrev_b32_e32 v156, 16, v152
	v_and_b32_e32 v157, 0xffff0000, v152
	v_lshlrev_b32_e32 v152, 16, v153
	v_and_b32_e32 v153, 0xffff0000, v153
	v_lshlrev_b32_e32 v158, 16, v154
	v_and_b32_e32 v159, 0xffff0000, v154
	v_lshlrev_b32_e32 v154, 16, v155
	v_and_b32_e32 v155, 0xffff0000, v155
	v_pk_add_f32 v[126:127], v[126:127], v[152:153]
	v_pk_add_f32 v[124:125], v[124:125], v[156:157]
	v_pk_add_f32 v[152:153], v[122:123], v[154:155]
	v_pk_add_f32 v[122:123], v[120:121], v[158:159]
	v_cvt_pk_bf16_f32 v120, v124, v125
	v_cvt_pk_bf16_f32 v121, v126, v127
	v_cvt_pk_bf16_f32 v122, v122, v123
	v_cvt_pk_bf16_f32 v123, v152, v153
	global_store_dwordx4 v[144:145], v[120:123], off
	s_waitcnt vmcnt(15)
; DI unsigned pack2(float a, float b) { f32x2 v = {a, b}; hwbf16x2 r = __builtin_convertvector(v, hwbf16x2); return __builtin_bit_cast(unsigned, r); }
; DI float bflo(unsigned w) { return __uint_as_float(w << 16); }
; DI float bfhi(unsigned w) { return __uint_as_float(w & 0xffff0000u); }
;     DI void operator()(const f32x4 (&acc)[2][2][4][2], const Unit& u, int wr, int wc, int fr, int fq) const {
;     ...
;         for (int ai = 0; ai < 2; ++ai)
; #pragma unroll
;             for (int m = 0; m < 4; ++m) { const size_t ro = (size_t)(row0 + ai * HALF + m * 16) * D + col0;
; #pragma unroll
;                 for (int bj = 0; bj < 2; ++bj) {
;                     f32x4 x0, x1;
;                     if constexpr (IB) { const u32x4 w = *(const u32x4*)((const bf16_t*)Xin + ro + bj * HALF);
;                         x0 = (f32x4){bflo(w[0]), bfhi(w[0]), bflo(w[1]), bfhi(w[1])}; x1 = (f32x4){bflo(w[2]), bfhi(w[2]), bflo(w[3]), bfhi(w[3])}; }
;                     else { x0 = *(const f32x4*)((const float*)Xin + ro + bj * HALF); x1 = *(const f32x4*)((const float*)Xin + ro + bj * HALF + 4); }
;                     x0 += acc[ai][bj][m][0] * sc[bj][0]; x1 += acc[ai][bj][m][1] * sc[bj][1];
;                     if constexpr (OB) { u32x4 o; o[0] = pack2(x0[0], x0[1]); o[1] = pack2(x0[2], x0[3]); o[2] = pack2(x1[0], x1[1]); o[3] = pack2(x1[2], x1[3]);
;                         *(u32x4*)((bf16_t*)Xout + ro + bj * HALF) = o; }
;                     else { *(f32x4*)((float*)Xout + ro + bj * HALF) = x0; *(f32x4*)((float*)Xout + ro + bj * HALF + 4) = x1; } } }
	s_nop 1
	v_mov_b32_e32 v120, v164
	v_mov_b32_e32 v121, v165
	v_mov_b32_e32 v122, v166
	v_mov_b32_e32 v123, v167
	s_waitcnt lgkmcnt(0)
	v_lshlrev_b32_e32 v124, 16, v120
	v_and_b32_e32 v125, 0xffff0000, v120
	v_lshlrev_b32_e32 v120, 16, v121
	v_and_b32_e32 v121, 0xffff0000, v121
	v_lshlrev_b32_e32 v126, 16, v122
	v_and_b32_e32 v127, 0xffff0000, v122
	v_lshlrev_b32_e32 v122, 16, v123
	v_and_b32_e32 v123, 0xffff0000, v123
	v_pk_add_f32 v[116:117], v[116:117], v[124:125]
	v_pk_add_f32 v[118:119], v[118:119], v[120:121]
	v_pk_add_f32 v[120:121], v[114:115], v[122:123]
	v_pk_add_f32 v[114:115], v[112:113], v[126:127]
	v_cvt_pk_bf16_f32 v112, v116, v117
	v_lshl_add_u64 v[116:117], v[144:145], 0, s[2:3]
	s_mov_b32 s2, 0x10000
	v_cvt_pk_bf16_f32 v113, v118, v119
	v_add_co_u32_e32 v118, vcc, s2, v144
	v_cvt_pk_bf16_f32 v114, v114, v115
	v_cvt_pk_bf16_f32 v115, v120, v121
	v_addc_co_u32_e32 v119, vcc, 0, v145, vcc
	global_store_dwordx4 v[144:145], v[112:115], off offset:256
	s_waitcnt vmcnt(15)
	s_nop 1
	v_mov_b32_e32 v112, v168
	v_mov_b32_e32 v113, v169
	v_mov_b32_e32 v114, v170
	v_mov_b32_e32 v115, v171
	s_mov_b64 s[2:3], 0x20000
	s_waitcnt lgkmcnt(0)
	v_lshlrev_b32_e32 v120, 16, v112
	v_and_b32_e32 v121, 0xffff0000, v112
	v_lshlrev_b32_e32 v112, 16, v113
	v_and_b32_e32 v113, 0xffff0000, v113
	v_lshlrev_b32_e32 v122, 16, v114
	v_and_b32_e32 v123, 0xffff0000, v114
	v_lshlrev_b32_e32 v114, 16, v115
	v_and_b32_e32 v115, 0xffff0000, v115
	v_pk_add_f32 v[110:111], v[110:111], v[112:113]
	v_pk_add_f32 v[108:109], v[108:109], v[120:121]
	v_pk_add_f32 v[112:113], v[106:107], v[114:115]
	v_pk_add_f32 v[106:107], v[104:105], v[122:123]
	v_cvt_pk_bf16_f32 v104, v108, v109
	v_cvt_pk_bf16_f32 v105, v110, v111
	v_cvt_pk_bf16_f32 v106, v106, v107
	v_cvt_pk_bf16_f32 v107, v112, v113
	global_store_dwordx4 v[118:119], v[104:107], off
	s_waitcnt vmcnt(15)
	s_nop 1
	v_mov_b32_e32 v104, v172
	v_mov_b32_e32 v105, v173
	v_mov_b32_e32 v106, v174
	v_mov_b32_e32 v107, v175
	s_waitcnt lgkmcnt(0)
	v_lshlrev_b32_e32 v108, 16, v104
	v_and_b32_e32 v109, 0xffff0000, v104
	v_lshlrev_b32_e32 v104, 16, v105
	v_and_b32_e32 v105, 0xffff0000, v105
	v_lshlrev_b32_e32 v110, 16, v106
	v_and_b32_e32 v111, 0xffff0000, v106
	v_lshlrev_b32_e32 v106, 16, v107
	v_and_b32_e32 v107, 0xffff0000, v107
	v_pk_add_f32 v[100:101], v[100:101], v[108:109]
	v_pk_add_f32 v[102:103], v[102:103], v[104:105]
	v_pk_add_f32 v[104:105], v[98:99], v[106:107]
	v_pk_add_f32 v[98:99], v[96:97], v[110:111]
	v_cvt_pk_bf16_f32 v96, v100, v101
	v_lshl_add_u64 v[100:101], v[144:145], 0, s[2:3]
	s_mov_b32 s2, 0x20000
	v_cvt_pk_bf16_f32 v97, v102, v103
	v_add_co_u32_e32 v102, vcc, s2, v144
	v_cvt_pk_bf16_f32 v98, v98, v99
	v_cvt_pk_bf16_f32 v99, v104, v105
	v_addc_co_u32_e32 v103, vcc, 0, v145, vcc
	global_store_dwordx4 v[116:117], v[96:99], off offset:256
	s_waitcnt vmcnt(15)
	s_nop 1
	v_mov_b32_e32 v96, v176
	v_mov_b32_e32 v97, v177
	v_mov_b32_e32 v98, v178
	v_mov_b32_e32 v99, v179
	s_mov_b64 s[2:3], 0x30000
	s_waitcnt lgkmcnt(0)
	v_lshlrev_b32_e32 v104, 16, v96
	v_and_b32_e32 v105, 0xffff0000, v96
	v_lshlrev_b32_e32 v96, 16, v97
	v_and_b32_e32 v97, 0xffff0000, v97
	v_lshlrev_b32_e32 v106, 16, v98
	v_and_b32_e32 v107, 0xffff0000, v98
	v_lshlrev_b32_e32 v98, 16, v99
	v_and_b32_e32 v99, 0xffff0000, v99
	v_pk_add_f32 v[94:95], v[94:95], v[96:97]
	v_pk_add_f32 v[92:93], v[92:93], v[104:105]
	v_pk_add_f32 v[96:97], v[90:91], v[98:99]
	v_pk_add_f32 v[90:91], v[88:89], v[106:107]
	v_cvt_pk_bf16_f32 v88, v92, v93
	v_cvt_pk_bf16_f32 v89, v94, v95
	v_cvt_pk_bf16_f32 v90, v90, v91
	v_cvt_pk_bf16_f32 v91, v96, v97
	global_store_dwordx4 v[102:103], v[88:91], off
	s_waitcnt vmcnt(15)
	s_nop 1
	v_mov_b32_e32 v88, v180
	v_mov_b32_e32 v89, v181
	v_mov_b32_e32 v90, v182
	v_mov_b32_e32 v91, v183
	s_waitcnt lgkmcnt(0)
	v_lshlrev_b32_e32 v92, 16, v88
	v_and_b32_e32 v93, 0xffff0000, v88
	v_lshlrev_b32_e32 v88, 16, v89
	v_and_b32_e32 v89, 0xffff0000, v89
	v_lshlrev_b32_e32 v94, 16, v90
	v_and_b32_e32 v95, 0xffff0000, v90
	v_lshlrev_b32_e32 v90, 16, v91
	v_and_b32_e32 v91, 0xffff0000, v91
	v_pk_add_f32 v[86:87], v[86:87], v[88:89]
	v_pk_add_f32 v[84:85], v[84:85], v[92:93]
	v_pk_add_f32 v[88:89], v[82:83], v[90:91]
	v_pk_add_f32 v[82:83], v[80:81], v[94:95]
	v_cvt_pk_bf16_f32 v80, v84, v85
	v_cvt_pk_bf16_f32 v81, v86, v87
	v_cvt_pk_bf16_f32 v82, v82, v83
	v_cvt_pk_bf16_f32 v83, v88, v89
	global_store_dwordx4 v[100:101], v[80:83], off offset:256
	s_nop 1
	v_lshl_add_u64 v[80:81], v[144:145], 0, s[2:3]
	s_mov_b32 s2, 0x30000
	v_add_co_u32_e32 v86, vcc, s2, v144
	s_mov_b64 s[2:3], 0x80000
	s_nop 0
	v_addc_co_u32_e32 v87, vcc, 0, v145, vcc
	s_waitcnt vmcnt(15)
	s_nop 1
	v_mov_b32_e32 v82, v184
	v_mov_b32_e32 v83, v185
	v_mov_b32_e32 v84, v186
	v_mov_b32_e32 v85, v187
	s_waitcnt lgkmcnt(0)
	v_lshlrev_b32_e32 v88, 16, v82
	v_and_b32_e32 v89, 0xffff0000, v82
	v_lshlrev_b32_e32 v82, 16, v83
	v_and_b32_e32 v83, 0xffff0000, v83
	v_lshlrev_b32_e32 v90, 16, v84
	v_and_b32_e32 v91, 0xffff0000, v84
	v_lshlrev_b32_e32 v84, 16, v85
	v_and_b32_e32 v85, 0xffff0000, v85
	v_pk_add_f32 v[78:79], v[78:79], v[82:83]
	v_pk_add_f32 v[76:77], v[76:77], v[88:89]
	v_pk_add_f32 v[82:83], v[74:75], v[84:85]
	v_pk_add_f32 v[74:75], v[72:73], v[90:91]
	v_cvt_pk_bf16_f32 v72, v76, v77
	v_cvt_pk_bf16_f32 v73, v78, v79
	v_cvt_pk_bf16_f32 v74, v74, v75
	v_cvt_pk_bf16_f32 v75, v82, v83
	global_store_dwordx4 v[86:87], v[72:75], off
	s_waitcnt vmcnt(15)
	s_nop 1
	v_mov_b32_e32 v72, v188
	v_mov_b32_e32 v73, v189
	v_mov_b32_e32 v74, v190
	v_mov_b32_e32 v75, v191
	s_waitcnt lgkmcnt(0)
; DI unsigned pack2(float a, float b) { f32x2 v = {a, b}; hwbf16x2 r = __builtin_convertvector(v, hwbf16x2); return __builtin_bit_cast(unsigned, r); }
; DI float bflo(unsigned w) { return __uint_as_float(w << 16); }
; DI float bfhi(unsigned w) { return __uint_as_float(w & 0xffff0000u); }
;     DI void operator()(const f32x4 (&acc)[2][2][4][2], const Unit& u, int wr, int wc, int fr, int fq) const {
;     ...
;         for (int ai = 0; ai < 2; ++ai)
; #pragma unroll
;             for (int m = 0; m < 4; ++m) { const size_t ro = (size_t)(row0 + ai * HALF + m * 16) * D + col0;
; #pragma unroll
;                 for (int bj = 0; bj < 2; ++bj) {
;                     f32x4 x0, x1;
;                     if constexpr (IB) { const u32x4 w = *(const u32x4*)((const bf16_t*)Xin + ro + bj * HALF);
;                         x0 = (f32x4){bflo(w[0]), bfhi(w[0]), bflo(w[1]), bfhi(w[1])}; x1 = (f32x4){bflo(w[2]), bfhi(w[2]), bflo(w[3]), bfhi(w[3])}; }
;                     else { x0 = *(const f32x4*)((const float*)Xin + ro + bj * HALF); x1 = *(const f32x4*)((const float*)Xin + ro + bj * HALF + 4); }
;                     x0 += acc[ai][bj][m][0] * sc[bj][0]; x1 += acc[ai][bj][m][1] * sc[bj][1];
;                     if constexpr (OB) { u32x4 o; o[0] = pack2(x0[0], x0[1]); o[1] = pack2(x0[2], x0[3]); o[2] = pack2(x1[0], x1[1]); o[3] = pack2(x1[2], x1[3]);
;                         *(u32x4*)((bf16_t*)Xout + ro + bj * HALF) = o; }
;                     else { *(f32x4*)((float*)Xout + ro + bj * HALF) = x0; *(f32x4*)((float*)Xout + ro + bj * HALF + 4) = x1; } } }
	v_lshlrev_b32_e32 v76, 16, v72
	v_and_b32_e32 v77, 0xffff0000, v72
	v_lshlrev_b32_e32 v72, 16, v73
	v_and_b32_e32 v73, 0xffff0000, v73
	v_lshlrev_b32_e32 v78, 16, v74
	v_and_b32_e32 v79, 0xffff0000, v74
	v_lshlrev_b32_e32 v74, 16, v75
	v_and_b32_e32 v75, 0xffff0000, v75
	v_pk_add_f32 v[70:71], v[70:71], v[72:73]
	v_pk_add_f32 v[68:69], v[68:69], v[76:77]
	v_pk_add_f32 v[72:73], v[66:67], v[74:75]
	v_pk_add_f32 v[66:67], v[64:65], v[78:79]
	v_cvt_pk_bf16_f32 v64, v68, v69
	v_cvt_pk_bf16_f32 v65, v70, v71
	v_cvt_pk_bf16_f32 v66, v66, v67
	v_cvt_pk_bf16_f32 v67, v72, v73
	global_store_dwordx4 v[80:81], v[64:67], off offset:256
	s_nop 1
	v_lshl_add_u64 v[64:65], v[144:145], 0, s[2:3]
	s_mov_b32 s2, 0x80000
	v_add_co_u32_e32 v70, vcc, s2, v144
	s_mov_b64 s[2:3], 0x90000
	s_nop 0
	v_addc_co_u32_e32 v71, vcc, 0, v145, vcc
	s_waitcnt vmcnt(15)
	s_nop 1
	v_mov_b32_e32 v66, v192
	v_mov_b32_e32 v67, v193
	v_mov_b32_e32 v68, v194
	v_mov_b32_e32 v69, v195
	s_waitcnt lgkmcnt(0)
	v_lshlrev_b32_e32 v72, 16, v66
	v_and_b32_e32 v73, 0xffff0000, v66
	v_lshlrev_b32_e32 v66, 16, v67
	v_and_b32_e32 v67, 0xffff0000, v67
	v_lshlrev_b32_e32 v74, 16, v68
	v_and_b32_e32 v75, 0xffff0000, v68
	v_lshlrev_b32_e32 v68, 16, v69
	v_and_b32_e32 v69, 0xffff0000, v69
	v_pk_add_f32 v[62:63], v[62:63], v[66:67]
	v_pk_add_f32 v[60:61], v[60:61], v[72:73]
	v_pk_add_f32 v[66:67], v[58:59], v[68:69]
	v_pk_add_f32 v[58:59], v[56:57], v[74:75]
	v_cvt_pk_bf16_f32 v56, v60, v61
	v_cvt_pk_bf16_f32 v57, v62, v63
	v_cvt_pk_bf16_f32 v58, v58, v59
	v_cvt_pk_bf16_f32 v59, v66, v67
	global_store_dwordx4 v[70:71], v[56:59], off
	s_waitcnt vmcnt(15)
	s_nop 1
	v_mov_b32_e32 v56, v198
	v_mov_b32_e32 v57, v199
	v_mov_b32_e32 v58, v200
	v_mov_b32_e32 v59, v201
	s_waitcnt lgkmcnt(0)
	v_lshlrev_b32_e32 v60, 16, v56
	v_and_b32_e32 v61, 0xffff0000, v56
	v_lshlrev_b32_e32 v56, 16, v57
	v_and_b32_e32 v57, 0xffff0000, v57
	v_lshlrev_b32_e32 v62, 16, v58
	v_and_b32_e32 v63, 0xffff0000, v58
	v_lshlrev_b32_e32 v58, 16, v59
	v_and_b32_e32 v59, 0xffff0000, v59
	v_pk_add_f32 v[54:55], v[54:55], v[56:57]
	v_pk_add_f32 v[52:53], v[52:53], v[60:61]
	v_pk_add_f32 v[56:57], v[50:51], v[58:59]
	v_pk_add_f32 v[50:51], v[48:49], v[62:63]
	v_cvt_pk_bf16_f32 v48, v52, v53
	v_cvt_pk_bf16_f32 v49, v54, v55
	v_cvt_pk_bf16_f32 v50, v50, v51
	v_cvt_pk_bf16_f32 v51, v56, v57
	global_store_dwordx4 v[64:65], v[48:51], off offset:256
	s_nop 1
	v_lshl_add_u64 v[48:49], v[144:145], 0, s[2:3]
	s_mov_b32 s2, 0x90000
	v_add_co_u32_e32 v54, vcc, s2, v144
	s_mov_b64 s[2:3], 0xa0000
	s_nop 0
	v_addc_co_u32_e32 v55, vcc, 0, v145, vcc
	s_waitcnt vmcnt(15)
	s_nop 1
	v_mov_b32_e32 v50, v202
	v_mov_b32_e32 v51, v203
	v_mov_b32_e32 v52, v204
	v_mov_b32_e32 v53, v205
	s_waitcnt lgkmcnt(0)
	v_lshlrev_b32_e32 v56, 16, v50
	v_and_b32_e32 v57, 0xffff0000, v50
	v_lshlrev_b32_e32 v50, 16, v51
	v_and_b32_e32 v51, 0xffff0000, v51
	v_lshlrev_b32_e32 v58, 16, v52
	v_and_b32_e32 v59, 0xffff0000, v52
	v_lshlrev_b32_e32 v52, 16, v53
	v_and_b32_e32 v53, 0xffff0000, v53
	v_pk_add_f32 v[46:47], v[46:47], v[50:51]
	v_pk_add_f32 v[44:45], v[44:45], v[56:57]
	v_pk_add_f32 v[50:51], v[42:43], v[52:53]
	v_pk_add_f32 v[42:43], v[40:41], v[58:59]
	v_cvt_pk_bf16_f32 v40, v44, v45
	v_cvt_pk_bf16_f32 v41, v46, v47
	v_cvt_pk_bf16_f32 v42, v42, v43
	v_cvt_pk_bf16_f32 v43, v50, v51
	global_store_dwordx4 v[54:55], v[40:43], off
	s_waitcnt vmcnt(15)
	s_nop 1
	v_mov_b32_e32 v40, v206
	v_mov_b32_e32 v41, v207
	v_mov_b32_e32 v42, v208
	v_mov_b32_e32 v43, v209
	s_waitcnt lgkmcnt(0)
; DI unsigned pack2(float a, float b) { f32x2 v = {a, b}; hwbf16x2 r = __builtin_convertvector(v, hwbf16x2); return __builtin_bit_cast(unsigned, r); }
; DI float bflo(unsigned w) { return __uint_as_float(w << 16); }
; DI float bfhi(unsigned w) { return __uint_as_float(w & 0xffff0000u); }
; #define PG8_WAIT_V(n) asm volatile("s_waitcnt vmcnt(" #n ")" ::: "memory")
; #define PG8_BAR __builtin_amdgcn_s_barrier()
;     DI void operator()(const f32x4 (&acc)[2][2][4][2], const Unit& u, int wr, int wc, int fr, int fq) const {
;     ...
;             for (int m = 0; m < 4; ++m) { const size_t ro = (size_t)(row0 + ai * HALF + m * 16) * D + col0;
; #pragma unroll
;                 for (int bj = 0; bj < 2; ++bj) {
;                     f32x4 x0, x1;
;                     if constexpr (IB) { const u32x4 w = *(const u32x4*)((const bf16_t*)Xin + ro + bj * HALF);
;                         x0 = (f32x4){bflo(w[0]), bfhi(w[0]), bflo(w[1]), bfhi(w[1])}; x1 = (f32x4){bflo(w[2]), bfhi(w[2]), bflo(w[3]), bfhi(w[3])}; }
;                     else { x0 = *(const f32x4*)((const float*)Xin + ro + bj * HALF); x1 = *(const f32x4*)((const float*)Xin + ro + bj * HALF + 4); }
;                     x0 += acc[ai][bj][m][0] * sc[bj][0]; x1 += acc[ai][bj][m][1] * sc[bj][1];
;                     if constexpr (OB) { u32x4 o; o[0] = pack2(x0[0], x0[1]); o[1] = pack2(x0[2], x0[3]); o[2] = pack2(x1[0], x1[1]); o[3] = pack2(x1[2], x1[3]);
;                         *(u32x4*)((bf16_t*)Xout + ro + bj * HALF) = o; }
;                     else { *(f32x4*)((float*)Xout + ro + bj * HALF) = x0; *(f32x4*)((float*)Xout + ro + bj * HALF + 4) = x1; } } }
; template <class Map, class Epi>
; DI void gemm_phase(LAS unsigned char* lds, const Map& MP, const Epi& E, const int nM, const int nN, const int K, const int lda, const int ldb) {
;     ...
;     PG8_WAIT_V(0);
;     if (wr == 0) PG8_BAR;
;     PG8_BAR;
	v_lshlrev_b32_e32 v44, 16, v40
	v_and_b32_e32 v45, 0xffff0000, v40
	v_lshlrev_b32_e32 v40, 16, v41
	v_and_b32_e32 v41, 0xffff0000, v41
	v_lshlrev_b32_e32 v46, 16, v42
	v_and_b32_e32 v47, 0xffff0000, v42
	v_lshlrev_b32_e32 v42, 16, v43
	v_and_b32_e32 v43, 0xffff0000, v43
	v_pk_add_f32 v[38:39], v[38:39], v[40:41]
	v_pk_add_f32 v[36:37], v[36:37], v[44:45]
	v_pk_add_f32 v[40:41], v[34:35], v[42:43]
	v_pk_add_f32 v[34:35], v[32:33], v[46:47]
	v_cvt_pk_bf16_f32 v32, v36, v37
	v_cvt_pk_bf16_f32 v33, v38, v39
	v_cvt_pk_bf16_f32 v34, v34, v35
	v_cvt_pk_bf16_f32 v35, v40, v41
	global_store_dwordx4 v[48:49], v[32:35], off offset:256
	s_nop 1
	v_lshl_add_u64 v[32:33], v[144:145], 0, s[2:3]
	s_mov_b32 s2, 0xa0000
	v_add_co_u32_e32 v38, vcc, s2, v144
	s_mov_b64 s[2:3], 0xb0000
	s_nop 0
	v_addc_co_u32_e32 v39, vcc, 0, v145, vcc
	s_waitcnt vmcnt(15)
	s_nop 1
	v_mov_b32_e32 v34, v210
	v_mov_b32_e32 v35, v211
	v_mov_b32_e32 v36, v212
	v_mov_b32_e32 v37, v213
	s_waitcnt lgkmcnt(0)
	v_lshlrev_b32_e32 v40, 16, v34
	v_and_b32_e32 v41, 0xffff0000, v34
	v_lshlrev_b32_e32 v34, 16, v35
	v_and_b32_e32 v35, 0xffff0000, v35
	v_lshlrev_b32_e32 v42, 16, v36
	v_and_b32_e32 v43, 0xffff0000, v36
	v_lshlrev_b32_e32 v36, 16, v37
	v_and_b32_e32 v37, 0xffff0000, v37
	v_pk_add_f32 v[30:31], v[30:31], v[34:35]
	v_pk_add_f32 v[28:29], v[28:29], v[40:41]
	v_pk_add_f32 v[34:35], v[26:27], v[36:37]
	v_pk_add_f32 v[26:27], v[24:25], v[42:43]
	v_cvt_pk_bf16_f32 v24, v28, v29
	v_cvt_pk_bf16_f32 v25, v30, v31
	v_cvt_pk_bf16_f32 v26, v26, v27
	v_cvt_pk_bf16_f32 v27, v34, v35
	global_store_dwordx4 v[38:39], v[24:27], off
	s_waitcnt vmcnt(15)
	s_nop 1
	v_mov_b32_e32 v24, v214
	v_mov_b32_e32 v25, v215
	v_mov_b32_e32 v26, v216
	v_mov_b32_e32 v27, v217
	s_waitcnt lgkmcnt(0)
	v_lshlrev_b32_e32 v28, 16, v24
	v_and_b32_e32 v29, 0xffff0000, v24
	v_lshlrev_b32_e32 v24, 16, v25
	v_and_b32_e32 v25, 0xffff0000, v25
	v_lshlrev_b32_e32 v30, 16, v26
	v_and_b32_e32 v31, 0xffff0000, v26
	v_lshlrev_b32_e32 v26, 16, v27
	v_and_b32_e32 v27, 0xffff0000, v27
	v_pk_add_f32 v[22:23], v[22:23], v[24:25]
	v_pk_add_f32 v[20:21], v[20:21], v[28:29]
	v_pk_add_f32 v[24:25], v[18:19], v[26:27]
	v_pk_add_f32 v[18:19], v[16:17], v[30:31]
	v_cvt_pk_bf16_f32 v16, v20, v21
	v_cvt_pk_bf16_f32 v17, v22, v23
	v_cvt_pk_bf16_f32 v18, v18, v19
	v_cvt_pk_bf16_f32 v19, v24, v25
	global_store_dwordx4 v[32:33], v[16:19], off offset:256
	s_nop 1
	v_lshl_add_u64 v[16:17], v[144:145], 0, s[2:3]
	s_mov_b32 s2, 0xb0000
	v_add_co_u32_e32 v22, vcc, s2, v144
	s_mov_b32 s2, s55
	s_nop 0
	v_addc_co_u32_e32 v23, vcc, 0, v145, vcc
	s_waitcnt vmcnt(15)
	s_nop 1
	v_mov_b32_e32 v18, v248
	v_mov_b32_e32 v19, v249
	v_mov_b32_e32 v20, v250
	v_mov_b32_e32 v21, v251
	s_and_b64 vcc, exec, s[40:41]
	s_waitcnt lgkmcnt(0)
	v_lshlrev_b32_e32 v24, 16, v18
	v_and_b32_e32 v25, 0xffff0000, v18
	v_lshlrev_b32_e32 v18, 16, v19
	v_and_b32_e32 v19, 0xffff0000, v19
	v_lshlrev_b32_e32 v26, 16, v20
	v_and_b32_e32 v27, 0xffff0000, v20
	v_lshlrev_b32_e32 v20, 16, v21
	v_and_b32_e32 v21, 0xffff0000, v21
	v_pk_add_f32 v[14:15], v[14:15], v[18:19]
	v_pk_add_f32 v[12:13], v[12:13], v[24:25]
	v_pk_add_f32 v[18:19], v[10:11], v[20:21]
	v_pk_add_f32 v[10:11], v[8:9], v[26:27]
	v_cvt_pk_bf16_f32 v8, v12, v13
	v_cvt_pk_bf16_f32 v9, v14, v15
	v_cvt_pk_bf16_f32 v10, v10, v11
	v_cvt_pk_bf16_f32 v11, v18, v19
	global_store_dwordx4 v[22:23], v[8:11], off
	s_waitcnt vmcnt(15)
	s_nop 1
	v_mov_b32_e32 v8, v252
	v_mov_b32_e32 v9, v253
	v_mov_b32_e32 v10, v254
	v_mov_b32_e32 v11, v255
	s_waitcnt lgkmcnt(0)
	v_lshlrev_b32_e32 v12, 16, v8
	v_and_b32_e32 v13, 0xffff0000, v8
	v_lshlrev_b32_e32 v8, 16, v9
	v_and_b32_e32 v9, 0xffff0000, v9
	v_lshlrev_b32_e32 v14, 16, v10
	v_and_b32_e32 v15, 0xffff0000, v10
	v_lshlrev_b32_e32 v10, 16, v11
	v_and_b32_e32 v11, 0xffff0000, v11
	v_pk_add_f32 v[6:7], v[6:7], v[8:9]
	v_pk_add_f32 v[4:5], v[4:5], v[12:13]
	v_pk_add_f32 v[8:9], v[2:3], v[10:11]
	v_pk_add_f32 v[2:3], v[0:1], v[14:15]
	v_cvt_pk_bf16_f32 v0, v4, v5
	v_cvt_pk_bf16_f32 v1, v6, v7
	v_cvt_pk_bf16_f32 v2, v2, v3
	v_cvt_pk_bf16_f32 v3, v8, v9
	global_store_dwordx4 v[16:17], v[0:3], off offset:256
	s_cbranch_vccz .LBB1_1232
	s_waitcnt vmcnt(0)
	s_cmpk_gt_u32 s17, 0xff
	s_cbranch_scc1 .LBB1_1243
	s_barrier

; #define PG8_STAGE(bufoff, gbase, voff) do { _Pragma("unroll") for (int _i = 0; _i < 2; ++_i) \
;         __builtin_amdgcn_global_load_lds((const unsigned*)((const char*)(gbase) + (voff)[_i]), (LAS unsigned*)(lds + (bufoff) + ldsw + _i * 8192), 16, 0, 0); } while (0)
; #define PG8_LDA(dst, b, h) do { _Pragma("unroll") for (int m = 0; m < 4; ++m) _Pragma("unroll") for (int k = 0; k < 2; ++k) dst[m][k] = *(const LAS bf16x8*)(lds + PG8_SA(b, h) + aoff + m * 2048 + k * 1024); } while (0)
; #define PG8_LDB(dst, b, h) do { _Pragma("unroll") for (int n = 0; n < 2; ++n) _Pragma("unroll") for (int k = 0; k < 2; ++k) dst[n][k] = *(const LAS bf16x8*)(lds + PG8_SB(b, h) + boff + n * 2048 + k * 1024); } while (0)
; #define PG8_MMA(ai, bj, At, Bt) do { __builtin_amdgcn_s_setprio(1); _Pragma("unroll") for (int m = 0; m < 4; ++m) _Pragma("unroll") for (int n = 0; n < 2; ++n) _Pragma("unroll") for (int k = 0; k < 2; ++k) \
;         acc[ai][bj][m][n] = __builtin_amdgcn_mfma_f32_16x16x32_bf16(Bt[n][k], At[m][k], acc[ai][bj][m][n], 0, 0, 0); __builtin_amdgcn_s_setprio(0); } while (0)
; #define PG8_WAIT_V(n) asm volatile("s_waitcnt vmcnt(" #n ")" ::: "memory")
; #define PG8_WAIT_L(n) asm volatile("s_waitcnt lgkmcnt(" #n ")" ::: "memory")
; template <class Map, class Epi>
; DI void gemm_phase(LAS unsigned char* lds, const Map& MP, const Epi& E, const int nM, const int nN, const int K, const int lda, const int ldb) {
;     ...
;         for (int t = 0; t < nt; t += 2) {
;             const bool last = (t == nt - 2);
;             const char* a1 = cA + (size_t)(t + 1) * kstep;
;             const char* a2 = last ? nA : cA + (size_t)(t + 2) * kstep; const char* b2 = last ? nB : cB + (size_t)(t + 2) * kstep;
;             const char* a3 = a2 + kstep; const char* b3 = b2 + kstep;
;             PG8_LDB(B0, 0, 0); PG8_SCHED; PG8_LDA(At, 0, 0); PG8_STAGE(PG8_SA(1, 1), a1 + hstepA, voffA);
;             PG8_WAIT_L(8); PG8_BAR; PG8_WAIT_L(0); PG8_MMA(0, 0, At, B0); PG8_BAR; PG8_SCHED;
;             PG8_LDB(B1, 0, 1); PG8_STAGE(PG8_SB(0, 0), b2, voffB);
;             PG8_BAR; PG8_WAIT_L(0); PG8_MMA(0, 1, At, B1); PG8_BAR;
;             PG8_LDA(At, 0, 1); PG8_STAGE(PG8_SA(0, 0), a2, voffA);
;             PG8_BAR; PG8_WAIT_L(0); PG8_MMA(1, 0, At, B0); PG8_BAR; PG8_SCHED;
;             PG8_STAGE(PG8_SB(0, 1), b2 + hstepB, voffB);
;             PG8_WAIT_V(6); PG8_BAR; PG8_MMA(1, 1, At, B1); PG8_BAR;
.LBB1_1382:
	s_add_u32 s22, s20, 0xfff80080
	s_addc_u32 s23, s21, -1
	s_cmp_eq_u32 s3, 28
	s_cselect_b32 s25, s15, s23
	s_cselect_b32 s24, s48, s22
	s_cselect_b32 s23, s13, s53
	s_cselect_b32 s22, s49, s52
	s_add_i32 m0, s31, 0xc000
	ds_read_b128 v[166:169], v148
	ds_read_b128 v[170:173], v148 offset:1024
	ds_read_b128 v[174:177], v148 offset:2048
	ds_read_b128 v[178:181], v148 offset:3072
	ds_read_b128 v[182:185], v148 offset:4096
	ds_read_b128 v[186:189], v148 offset:5120
	ds_read_b128 v[190:193], v148 offset:6144
	ds_read_b128 v[198:201], v148 offset:7168
	global_load_lds_dwordx4 v138, s[20:21]
	s_add_i32 m0, s31, 0xe000
	s_nop 0
	global_load_lds_dwordx4 v136, s[20:21]
	s_waitcnt lgkmcnt(8)
	s_setprio 1
	s_barrier
	s_waitcnt lgkmcnt(7)
	v_mfma_f32_16x16x32_bf16 v[124:127], v[150:153], v[166:169], v[124:127]
	v_mfma_f32_16x16x32_bf16 v[120:123], v[158:161], v[166:169], v[120:123]
	s_waitcnt lgkmcnt(5)
	v_mfma_f32_16x16x32_bf16 v[116:119], v[150:153], v[174:177], v[116:119]
	v_mfma_f32_16x16x32_bf16 v[112:115], v[158:161], v[174:177], v[112:115]
	s_waitcnt lgkmcnt(3)
	v_mfma_f32_16x16x32_bf16 v[100:103], v[150:153], v[182:185], v[100:103]
	v_mfma_f32_16x16x32_bf16 v[96:99], v[158:161], v[182:185], v[96:99]
	s_waitcnt lgkmcnt(1)
	v_mfma_f32_16x16x32_bf16 v[84:87], v[150:153], v[190:193], v[84:87]
	v_mfma_f32_16x16x32_bf16 v[80:83], v[158:161], v[190:193], v[80:83]
	v_mfma_f32_16x16x32_bf16 v[124:127], v[154:157], v[170:173], v[124:127]
	s_add_i32 s54, s44, s29
	v_mfma_f32_16x16x32_bf16 v[120:123], v[162:165], v[170:173], v[120:123]
	v_lshl_add_u64 v[194:195], s[22:23], 0, v[132:133]
	v_mfma_f32_16x16x32_bf16 v[116:119], v[154:157], v[178:181], v[116:119]
	v_lshl_add_u64 v[218:219], s[22:23], 0, v[128:129]
	v_mfma_f32_16x16x32_bf16 v[112:115], v[162:165], v[178:181], v[112:115]
	v_mfma_f32_16x16x32_bf16 v[100:103], v[154:157], v[186:189], v[100:103]
	v_mfma_f32_16x16x32_bf16 v[96:99], v[162:165], v[186:189], v[96:99]
	s_waitcnt lgkmcnt(0)
	v_mfma_f32_16x16x32_bf16 v[84:87], v[154:157], v[198:201], v[84:87]
	v_mfma_f32_16x16x32_bf16 v[80:83], v[162:165], v[198:201], v[80:83]
	s_barrier
	s_setprio 0
	s_mov_b32 m0, s54
	ds_read_b128 v[202:205], v149
	ds_read_b128 v[206:209], v149 offset:1024
	ds_read_b128 v[210:213], v149 offset:2048
	ds_read_b128 v[214:217], v149 offset:3072
	global_load_lds_dwordx4 v[194:195], off
	s_add_i32 m0, s54, 0x2000
	s_nop 0
	global_load_lds_dwordx4 v[218:219], off
	s_setprio 1
	s_barrier
	s_waitcnt lgkmcnt(3)
	v_mfma_f32_16x16x32_bf16 v[108:111], v[202:205], v[166:169], v[108:111]
	s_waitcnt lgkmcnt(1)
	v_mfma_f32_16x16x32_bf16 v[104:107], v[210:213], v[166:169], v[104:107]
	v_mfma_f32_16x16x32_bf16 v[92:95], v[202:205], v[174:177], v[92:95]
	v_mfma_f32_16x16x32_bf16 v[88:91], v[210:213], v[174:177], v[88:91]
	v_mfma_f32_16x16x32_bf16 v[76:79], v[202:205], v[182:185], v[76:79]
	v_mfma_f32_16x16x32_bf16 v[72:75], v[210:213], v[182:185], v[72:75]
	v_mfma_f32_16x16x32_bf16 v[68:71], v[202:205], v[190:193], v[68:71]
	v_mfma_f32_16x16x32_bf16 v[64:67], v[210:213], v[190:193], v[64:67]
	v_mfma_f32_16x16x32_bf16 v[108:111], v[206:209], v[170:173], v[108:111]
	v_lshl_add_u64 v[222:223], s[24:25], 0, v[130:131]
	s_mov_b32 m0, s31
	s_waitcnt lgkmcnt(0)
	v_mfma_f32_16x16x32_bf16 v[104:107], v[214:217], v[170:173], v[104:107]
	v_lshl_add_u64 v[220:221], s[24:25], 0, v[134:135]
	v_mfma_f32_16x16x32_bf16 v[92:95], v[206:209], v[178:181], v[92:95]
	v_mfma_f32_16x16x32_bf16 v[88:91], v[214:217], v[178:181], v[88:91]
	v_mfma_f32_16x16x32_bf16 v[76:79], v[206:209], v[186:189], v[76:79]
	v_mfma_f32_16x16x32_bf16 v[72:75], v[214:217], v[186:189], v[72:75]
	v_mfma_f32_16x16x32_bf16 v[68:71], v[206:209], v[198:201], v[68:71]
	v_mfma_f32_16x16x32_bf16 v[64:67], v[214:217], v[198:201], v[64:67]
	s_barrier
	s_setprio 0
	ds_read_b128 v[166:169], v148 offset:16384
	ds_read_b128 v[170:173], v148 offset:17408
	ds_read_b128 v[174:177], v148 offset:18432
	ds_read_b128 v[178:181], v148 offset:19456
	ds_read_b128 v[182:185], v148 offset:20480
	ds_read_b128 v[186:189], v148 offset:21504
	ds_read_b128 v[190:193], v148 offset:22528
	ds_read_b128 v[198:201], v148 offset:23552
	global_load_lds_dwordx4 v[220:221], off
	s_mov_b32 m0, s11
	s_nop 0
	global_load_lds_dwordx4 v[222:223], off
	s_waitcnt vmcnt(10)
	s_setprio 1
	s_barrier
	s_waitcnt lgkmcnt(7)
	v_mfma_f32_16x16x32_bf16 v[60:63], v[150:153], v[166:169], v[60:63]
	v_mfma_f32_16x16x32_bf16 v[56:59], v[158:161], v[166:169], v[56:59]
	s_waitcnt lgkmcnt(5)
	v_mfma_f32_16x16x32_bf16 v[52:55], v[150:153], v[174:177], v[52:55]
	v_mfma_f32_16x16x32_bf16 v[48:51], v[158:161], v[174:177], v[48:51]
	s_waitcnt lgkmcnt(3)
	v_mfma_f32_16x16x32_bf16 v[36:39], v[150:153], v[182:185], v[36:39]
	v_mfma_f32_16x16x32_bf16 v[32:35], v[158:161], v[182:185], v[32:35]
	s_waitcnt lgkmcnt(1)
	v_mfma_f32_16x16x32_bf16 v[20:23], v[150:153], v[190:193], v[20:23]
	v_mfma_f32_16x16x32_bf16 v[16:19], v[158:161], v[190:193], v[16:19]
	v_mfma_f32_16x16x32_bf16 v[60:63], v[154:157], v[170:173], v[60:63]
	s_add_u32 s54, s22, 0x80000
	s_addc_u32 s55, s23, 0
	v_mfma_f32_16x16x32_bf16 v[56:59], v[162:165], v[170:173], v[56:59]
	s_add_i32 s56, s45, s29
	v_mfma_f32_16x16x32_bf16 v[52:55], v[154:157], v[178:181], v[52:55]
	v_mfma_f32_16x16x32_bf16 v[48:51], v[162:165], v[178:181], v[48:51]
	v_mfma_f32_16x16x32_bf16 v[36:39], v[154:157], v[186:189], v[36:39]
	v_mfma_f32_16x16x32_bf16 v[32:35], v[162:165], v[186:189], v[32:35]
	s_waitcnt lgkmcnt(0)
	v_mfma_f32_16x16x32_bf16 v[20:23], v[154:157], v[198:201], v[20:23]
	v_mfma_f32_16x16x32_bf16 v[16:19], v[162:165], v[198:201], v[16:19]
	s_barrier
; #define PG8_STAGE(bufoff, gbase, voff) do { _Pragma("unroll") for (int _i = 0; _i < 2; ++_i) \
;         __builtin_amdgcn_global_load_lds((const unsigned*)((const char*)(gbase) + (voff)[_i]), (LAS unsigned*)(lds + (bufoff) + ldsw + _i * 8192), 16, 0, 0); } while (0)
; #define PG8_LDA(dst, b, h) do { _Pragma("unroll") for (int m = 0; m < 4; ++m) _Pragma("unroll") for (int k = 0; k < 2; ++k) dst[m][k] = *(const LAS bf16x8*)(lds + PG8_SA(b, h) + aoff + m * 2048 + k * 1024); } while (0)
; #define PG8_LDB(dst, b, h) do { _Pragma("unroll") for (int n = 0; n < 2; ++n) _Pragma("unroll") for (int k = 0; k < 2; ++k) dst[n][k] = *(const LAS bf16x8*)(lds + PG8_SB(b, h) + boff + n * 2048 + k * 1024); } while (0)
; #define PG8_MMA(ai, bj, At, Bt) do { __builtin_amdgcn_s_setprio(1); _Pragma("unroll") for (int m = 0; m < 4; ++m) _Pragma("unroll") for (int n = 0; n < 2; ++n) _Pragma("unroll") for (int k = 0; k < 2; ++k) \
;         acc[ai][bj][m][n] = __builtin_amdgcn_mfma_f32_16x16x32_bf16(Bt[n][k], At[m][k], acc[ai][bj][m][n], 0, 0, 0); __builtin_amdgcn_s_setprio(0); } while (0)
; #define PG8_WAIT_V(n) asm volatile("s_waitcnt vmcnt(" #n ")" ::: "memory")
; #define PG8_WAIT_L(n) asm volatile("s_waitcnt lgkmcnt(" #n ")" ::: "memory")
; #define PG8_BAR __builtin_amdgcn_s_barrier()
; #define PG8_SCHED __builtin_amdgcn_sched_barrier(0)
; template <class Map, class Epi>
; DI void gemm_phase(LAS unsigned char* lds, const Map& MP, const Epi& E, const int nM, const int nN, const int K, const int lda, const int ldb) {
;     ...
;             PG8_STAGE(PG8_SB(0, 1), b2 + hstepB, voffB);
;             PG8_WAIT_V(6); PG8_BAR; PG8_MMA(1, 1, At, B1); PG8_BAR;
;             PG8_LDB(B0, 1, 0); PG8_SCHED; PG8_LDA(At, 1, 0); PG8_STAGE(PG8_SA(0, 1), a2 + hstepA, voffA);
;             PG8_WAIT_L(8); PG8_BAR; PG8_WAIT_L(0); PG8_MMA(0, 0, At, B0); PG8_BAR; PG8_SCHED;
;             PG8_LDB(B1, 1, 1); PG8_STAGE(PG8_SB(1, 0), b3, voffB);
;             PG8_BAR; PG8_WAIT_L(0); PG8_MMA(0, 1, At, B1); PG8_BAR;
;             PG8_LDA(At, 1, 1); PG8_STAGE(PG8_SA(1, 0), a3, voffA);
;             PG8_BAR; PG8_WAIT_L(0); PG8_MMA(1, 0, At, B0); PG8_BAR; PG8_SCHED;
;             PG8_STAGE(PG8_SB(1, 1), b3 + hstepB, voffB);
	s_setprio 0
	s_mov_b32 m0, s56
	s_nop 0
	global_load_lds_dwordx4 v132, s[54:55]
	s_add_i32 m0, s56, 0x2000
	s_nop 0
	global_load_lds_dwordx4 v128, s[54:55]
	s_waitcnt vmcnt(6)
	s_setprio 1
	s_barrier
	v_mfma_f32_16x16x32_bf16 v[44:47], v[202:205], v[166:169], v[44:47]
	v_mfma_f32_16x16x32_bf16 v[40:43], v[210:213], v[166:169], v[40:43]
	s_add_i32 s54, 0, 0x18000
	v_add_u32_e32 v162, s54, v146
	ds_read_b128 v[150:153], v162
	v_mfma_f32_16x16x32_bf16 v[28:31], v[202:205], v[174:177], v[28:31]
	v_mfma_f32_16x16x32_bf16 v[24:27], v[210:213], v[174:177], v[24:27]
	ds_read_b128 v[154:157], v162 offset:1024
	v_mfma_f32_16x16x32_bf16 v[12:15], v[202:205], v[182:185], v[12:15]
	v_mfma_f32_16x16x32_bf16 v[8:11], v[210:213], v[182:185], v[8:11]
	ds_read_b128 v[158:161], v162 offset:2048
	v_mfma_f32_16x16x32_bf16 v[4:7], v[202:205], v[190:193], v[4:7]
	v_mfma_f32_16x16x32_bf16 v[0:3], v[210:213], v[190:193], v[0:3]
	ds_read_b128 v[162:165], v162 offset:3072
	v_mfma_f32_16x16x32_bf16 v[44:47], v[206:209], v[170:173], v[44:47]
	s_add_u32 s24, s24, 0x80000
	s_addc_u32 s25, s25, 0
	v_mfma_f32_16x16x32_bf16 v[40:43], v[214:217], v[170:173], v[40:43]
	v_mfma_f32_16x16x32_bf16 v[28:31], v[206:209], v[178:181], v[28:31]
	v_mfma_f32_16x16x32_bf16 v[24:27], v[214:217], v[178:181], v[24:27]
	v_mfma_f32_16x16x32_bf16 v[12:15], v[206:209], v[186:189], v[12:15]
	v_mfma_f32_16x16x32_bf16 v[8:11], v[214:217], v[186:189], v[8:11]
	v_mfma_f32_16x16x32_bf16 v[4:7], v[206:209], v[198:201], v[4:7]
	v_mfma_f32_16x16x32_bf16 v[0:3], v[214:217], v[198:201], v[0:3]
	s_barrier
	s_setprio 0
	s_mov_b32 m0, s34
	ds_read_b128 v[166:169], v148 offset:32768
	ds_read_b128 v[170:173], v148 offset:33792
	ds_read_b128 v[174:177], v148 offset:34816
	ds_read_b128 v[178:181], v148 offset:35840
	ds_read_b128 v[182:185], v148 offset:36864
	ds_read_b128 v[186:189], v148 offset:37888
	ds_read_b128 v[190:193], v148 offset:38912
	ds_read_b128 v[198:201], v148 offset:39936
	global_load_lds_dwordx4 v134, s[24:25]
	s_mov_b32 m0, s35
	s_nop 0
	global_load_lds_dwordx4 v130, s[24:25]
	s_waitcnt lgkmcnt(8)
	s_setprio 1
	s_barrier
	s_waitcnt lgkmcnt(7)
	v_mfma_f32_16x16x32_bf16 v[124:127], v[150:153], v[166:169], v[124:127]
	v_mfma_f32_16x16x32_bf16 v[120:123], v[158:161], v[166:169], v[120:123]
	s_waitcnt lgkmcnt(5)
	v_mfma_f32_16x16x32_bf16 v[116:119], v[150:153], v[174:177], v[116:119]
	v_mfma_f32_16x16x32_bf16 v[112:115], v[158:161], v[174:177], v[112:115]
	s_waitcnt lgkmcnt(3)
	v_mfma_f32_16x16x32_bf16 v[100:103], v[150:153], v[182:185], v[100:103]
	v_mfma_f32_16x16x32_bf16 v[96:99], v[158:161], v[182:185], v[96:99]
	s_waitcnt lgkmcnt(1)
	v_mfma_f32_16x16x32_bf16 v[84:87], v[150:153], v[190:193], v[84:87]
	v_mfma_f32_16x16x32_bf16 v[80:83], v[158:161], v[190:193], v[80:83]
	v_mfma_f32_16x16x32_bf16 v[124:127], v[154:157], v[170:173], v[124:127]
	s_add_i32 s24, 0, 0x1c000
	v_mfma_f32_16x16x32_bf16 v[120:123], v[162:165], v[170:173], v[120:123]
	s_add_i32 s25, s54, s29
	v_mfma_f32_16x16x32_bf16 v[116:119], v[154:157], v[178:181], v[116:119]
	v_add_u32_e32 v196, s24, v146
	v_mfma_f32_16x16x32_bf16 v[112:115], v[162:165], v[178:181], v[112:115]
	v_lshl_add_u64 v[194:195], v[194:195], 0, s[8:9]
	v_mfma_f32_16x16x32_bf16 v[100:103], v[154:157], v[186:189], v[100:103]
	v_mfma_f32_16x16x32_bf16 v[96:99], v[162:165], v[186:189], v[96:99]
	s_waitcnt lgkmcnt(0)
	v_mfma_f32_16x16x32_bf16 v[84:87], v[154:157], v[198:201], v[84:87]
	v_mfma_f32_16x16x32_bf16 v[80:83], v[162:165], v[198:201], v[80:83]
	s_barrier
	s_setprio 0
	s_mov_b32 m0, s25
	ds_read_b128 v[202:205], v196
	ds_read_b128 v[206:209], v196 offset:1024
	ds_read_b128 v[210:213], v196 offset:2048
	ds_read_b128 v[214:217], v196 offset:3072
	global_load_lds_dwordx4 v[194:195], off
	v_lshl_add_u64 v[194:195], v[218:219], 0, s[8:9]
	s_add_i32 m0, s25, 0x2000
	s_nop 0
	global_load_lds_dwordx4 v[194:195], off
	s_setprio 1
	s_barrier
	s_waitcnt lgkmcnt(3)
	v_mfma_f32_16x16x32_bf16 v[108:111], v[202:205], v[166:169], v[108:111]
	s_waitcnt lgkmcnt(1)
	v_mfma_f32_16x16x32_bf16 v[104:107], v[210:213], v[166:169], v[104:107]
	v_mfma_f32_16x16x32_bf16 v[92:95], v[202:205], v[174:177], v[92:95]
	v_mfma_f32_16x16x32_bf16 v[88:91], v[210:213], v[174:177], v[88:91]
	v_mfma_f32_16x16x32_bf16 v[76:79], v[202:205], v[182:185], v[76:79]
	v_mfma_f32_16x16x32_bf16 v[72:75], v[210:213], v[182:185], v[72:75]
	v_mfma_f32_16x16x32_bf16 v[68:71], v[202:205], v[190:193], v[68:71]
	v_mfma_f32_16x16x32_bf16 v[64:67], v[210:213], v[190:193], v[64:67]
	v_mfma_f32_16x16x32_bf16 v[108:111], v[206:209], v[170:173], v[108:111]
	s_mov_b32 m0, s39
	s_waitcnt lgkmcnt(0)
	v_mfma_f32_16x16x32_bf16 v[104:107], v[214:217], v[170:173], v[104:107]
	v_lshl_add_u64 v[194:195], v[220:221], 0, s[8:9]
	v_mfma_f32_16x16x32_bf16 v[92:95], v[206:209], v[178:181], v[92:95]
	v_mfma_f32_16x16x32_bf16 v[88:91], v[214:217], v[178:181], v[88:91]
	v_mfma_f32_16x16x32_bf16 v[76:79], v[206:209], v[186:189], v[76:79]
	v_mfma_f32_16x16x32_bf16 v[72:75], v[214:217], v[186:189], v[72:75]
	v_mfma_f32_16x16x32_bf16 v[68:71], v[206:209], v[198:201], v[68:71]
	v_mfma_f32_16x16x32_bf16 v[64:67], v[214:217], v[198:201], v[64:67]
	s_barrier
	s_setprio 0
	ds_read_b128 v[166:169], v148 offset:49152
	ds_read_b128 v[170:173], v148 offset:50176
	ds_read_b128 v[174:177], v148 offset:51200
	ds_read_b128 v[178:181], v148 offset:52224
	ds_read_b128 v[182:185], v148 offset:53248
	ds_read_b128 v[186:189], v148 offset:54272
	ds_read_b128 v[190:193], v148 offset:55296
	ds_read_b128 v[198:201], v148 offset:56320
	global_load_lds_dwordx4 v[194:195], off
	v_lshl_add_u64 v[194:195], v[222:223], 0, s[8:9]
	s_mov_b32 m0, s42
	s_nop 0
	global_load_lds_dwordx4 v[194:195], off
	s_waitcnt vmcnt(10)
	s_setprio 1
	s_barrier
; #define PG8_STAGE(bufoff, gbase, voff) do { _Pragma("unroll") for (int _i = 0; _i < 2; ++_i) \
;         __builtin_amdgcn_global_load_lds((const unsigned*)((const char*)(gbase) + (voff)[_i]), (LAS unsigned*)(lds + (bufoff) + ldsw + _i * 8192), 16, 0, 0); } while (0)
; #define PG8_LDA(dst, b, h) do { _Pragma("unroll") for (int m = 0; m < 4; ++m) _Pragma("unroll") for (int k = 0; k < 2; ++k) dst[m][k] = *(const LAS bf16x8*)(lds + PG8_SA(b, h) + aoff + m * 2048 + k * 1024); } while (0)
; #define PG8_MMA(ai, bj, At, Bt) do { __builtin_amdgcn_s_setprio(1); _Pragma("unroll") for (int m = 0; m < 4; ++m) _Pragma("unroll") for (int n = 0; n < 2; ++n) _Pragma("unroll") for (int k = 0; k < 2; ++k) \
;         acc[ai][bj][m][n] = __builtin_amdgcn_mfma_f32_16x16x32_bf16(Bt[n][k], At[m][k], acc[ai][bj][m][n], 0, 0, 0); __builtin_amdgcn_s_setprio(0); } while (0)
; #define PG8_WAIT_V(n) asm volatile("s_waitcnt vmcnt(" #n ")" ::: "memory")
; #define PG8_WAIT_L(n) asm volatile("s_waitcnt lgkmcnt(" #n ")" ::: "memory")
; #define PG8_BAR __builtin_amdgcn_s_barrier()
; #define PG8_SCHED __builtin_amdgcn_sched_barrier(0)
; template <class Map, class Epi>
; DI void gemm_phase(LAS unsigned char* lds, const Map& MP, const Epi& E, const int nM, const int nN, const int K, const int lda, const int ldb) {
;     ...
;             PG8_LDA(At, 1, 1); PG8_STAGE(PG8_SA(1, 0), a3, voffA);
;             PG8_BAR; PG8_WAIT_L(0); PG8_MMA(1, 0, At, B0); PG8_BAR; PG8_SCHED;
;             PG8_STAGE(PG8_SB(1, 1), b3 + hstepB, voffB);
;             PG8_WAIT_V(6); PG8_BAR; PG8_MMA(1, 1, At, B1); PG8_BAR;
;         }
	s_waitcnt lgkmcnt(7)
	v_mfma_f32_16x16x32_bf16 v[60:63], v[150:153], v[166:169], v[60:63]
	v_mfma_f32_16x16x32_bf16 v[56:59], v[158:161], v[166:169], v[56:59]
	s_waitcnt lgkmcnt(5)
	v_mfma_f32_16x16x32_bf16 v[52:55], v[150:153], v[174:177], v[52:55]
	v_mfma_f32_16x16x32_bf16 v[48:51], v[158:161], v[174:177], v[48:51]
	s_waitcnt lgkmcnt(3)
	v_mfma_f32_16x16x32_bf16 v[36:39], v[150:153], v[182:185], v[36:39]
	v_mfma_f32_16x16x32_bf16 v[32:35], v[158:161], v[182:185], v[32:35]
	s_waitcnt lgkmcnt(1)
	v_mfma_f32_16x16x32_bf16 v[20:23], v[150:153], v[190:193], v[20:23]
	v_mfma_f32_16x16x32_bf16 v[16:19], v[158:161], v[190:193], v[16:19]
	v_mfma_f32_16x16x32_bf16 v[60:63], v[154:157], v[170:173], v[60:63]
	s_add_u32 s22, s22, 0x80080
	s_addc_u32 s23, s23, 0
	v_mfma_f32_16x16x32_bf16 v[56:59], v[162:165], v[170:173], v[56:59]
	s_add_i32 s24, s24, s29
	v_mfma_f32_16x16x32_bf16 v[52:55], v[154:157], v[178:181], v[52:55]
	v_mfma_f32_16x16x32_bf16 v[48:51], v[162:165], v[178:181], v[48:51]
	v_mfma_f32_16x16x32_bf16 v[36:39], v[154:157], v[186:189], v[36:39]
	v_mfma_f32_16x16x32_bf16 v[32:35], v[162:165], v[186:189], v[32:35]
	s_waitcnt lgkmcnt(0)
	v_mfma_f32_16x16x32_bf16 v[20:23], v[154:157], v[198:201], v[20:23]
	v_mfma_f32_16x16x32_bf16 v[16:19], v[162:165], v[198:201], v[16:19]
	s_barrier
	s_setprio 0
	s_mov_b32 m0, s24
	s_nop 0
	global_load_lds_dwordx4 v132, s[22:23]
	s_add_i32 m0, s24, 0x2000
	s_nop 0
	global_load_lds_dwordx4 v128, s[22:23]
	s_waitcnt vmcnt(6)
	s_setprio 1
	s_barrier
	v_mfma_f32_16x16x32_bf16 v[44:47], v[202:205], v[166:169], v[44:47]
	v_mfma_f32_16x16x32_bf16 v[40:43], v[210:213], v[166:169], v[40:43]
	ds_read_b128 v[150:153], v147
	v_mfma_f32_16x16x32_bf16 v[28:31], v[202:205], v[174:177], v[28:31]
	v_mfma_f32_16x16x32_bf16 v[24:27], v[210:213], v[174:177], v[24:27]
	ds_read_b128 v[154:157], v147 offset:1024
	v_mfma_f32_16x16x32_bf16 v[12:15], v[202:205], v[182:185], v[12:15]
	v_mfma_f32_16x16x32_bf16 v[8:11], v[210:213], v[182:185], v[8:11]
	ds_read_b128 v[158:161], v147 offset:2048
	v_mfma_f32_16x16x32_bf16 v[4:7], v[202:205], v[190:193], v[4:7]
	v_mfma_f32_16x16x32_bf16 v[0:3], v[210:213], v[190:193], v[0:3]
	ds_read_b128 v[162:165], v147 offset:3072
	v_mfma_f32_16x16x32_bf16 v[44:47], v[206:209], v[170:173], v[44:47]
	s_add_i32 s3, s3, 2
	v_mfma_f32_16x16x32_bf16 v[40:43], v[214:217], v[170:173], v[40:43]
	s_add_u32 s52, s52, 0x100
	s_addc_u32 s53, s53, 0
	v_mfma_f32_16x16x32_bf16 v[28:31], v[206:209], v[178:181], v[28:31]
	s_add_u32 s20, s20, 0x100
	s_addc_u32 s21, s21, 0
	v_mfma_f32_16x16x32_bf16 v[24:27], v[214:217], v[178:181], v[24:27]
	s_cmp_gt_u32 s3, 29
	v_mfma_f32_16x16x32_bf16 v[12:15], v[206:209], v[186:189], v[12:15]
	v_mfma_f32_16x16x32_bf16 v[8:11], v[214:217], v[186:189], v[8:11]
	v_mfma_f32_16x16x32_bf16 v[4:7], v[206:209], v[198:201], v[4:7]
	v_mfma_f32_16x16x32_bf16 v[0:3], v[214:217], v[198:201], v[0:3]
	s_barrier
	s_setprio 0
	s_cbranch_scc0 .LBB1_1382
; DI unsigned pack2(float a, float b) { f32x2 v = {a, b}; hwbf16x2 r = __builtin_convertvector(v, hwbf16x2); return __builtin_bit_cast(unsigned, r); }
;     DI const char* a(const Unit& u) const { return (const char*)(A + (size_t)u.pm * BM * lda); }
;     DI const char* a(const Unit& u) const { return (const char*)(A + (size_t)u.pm * BM * 2048 + (u.pn >> 1) * 512); }
;     DI const char* a(const Unit& u) const { return (const char*)((u.pn < 12 ? A1 : A2) + (size_t)u.pm * BM * 512); }
; #define PG8_WAIT_V(n) asm volatile("s_waitcnt vmcnt(" #n ")" ::: "memory")
; #define PG8_BAR __builtin_amdgcn_s_barrier()
;     DI void operator()(const f32x4 (&acc)[2][2][4][2], const Unit& u, int wr, int wc, int fr, int fq) const {
;         bf16_t* O = O1; int ldc = ldc1, pn = u.pn; if (pn >= split) { O = O2; ldc = ldc2; pn -= split; }
;         const int row0 = u.pm * BM + wr * 64 + fr, col0 = pn * BM + wc * 32 + 8 * fq;
; #pragma unroll
;         for (int ai = 0; ai < 2; ++ai)
; #pragma unroll
;             for (int m = 0; m < 4; ++m) { bf16_t* rowp = O + (size_t)(row0 + ai * HALF + m * 16) * ldc + col0;
; #pragma unroll
;                 for (int bj = 0; bj < 2; ++bj) { const f32x4 v0 = acc[ai][bj][m][0], v1 = acc[ai][bj][m][1];
;                     u32x4 o; o[0] = pack2(v0[0], v0[1]); o[1] = pack2(v0[2], v0[3]); o[2] = pack2(v1[0], v1[1]); o[3] = pack2(v1[2], v1[3]);
;                     *(u32x4*)(rowp + bj * HALF) = o; } }
;     }
; template <class Map, class Epi>
; DI void gemm_phase(LAS unsigned char* lds, const Map& MP, const Epi& E, const int nM, const int nN, const int K, const int lda, const int ldb) {
;     ...
;         { int frr = fr, fqq = fq; asm volatile("" : "+v"(frr), "+v"(fqq)); E(acc, cur, wr, wc, frr, fqq); }
;         if (!has_next) break;
; #pragma unroll
;         for (int a = 0; a < 2; ++a)
; #pragma unroll
;             for (int b = 0; b < 2; ++b)
; #pragma unroll
;                 for (int m = 0; m < 4; ++m)
; #pragma unroll
;                     for (int n = 0; n < 2; ++n) acc[a][b][m][n] = (f32x4){0.f, 0.f, 0.f, 0.f};
;         cur = nxt; cA = nA; cB = nB; ++ui;
;     }
;     PG8_WAIT_V(0);
;     if (wr == 0) PG8_BAR;
;     PG8_BAR;
	s_waitcnt lgkmcnt(0)
	s_lshl_b32 s3, s10, 8
	v_mov_b32_e32 v150, v144
	v_mov_b32_e32 v151, v145
	s_add_i32 s3, s3, s37
	v_cvt_pk_bf16_f32 v68, v68, v69
	v_add_u32_e32 v154, s3, v150
	s_lshl_b32 s3, s47, 8
	s_or_b32 s3, s3, s38
	v_lshl_add_u32 v150, v151, 3, s3
	v_ashrrev_i32_e32 v151, 31, v150
	v_lshl_add_u64 v[150:151], v[150:151], 1, s[6:7]
	v_cvt_pk_bf16_f32 v69, v70, v71
	v_cvt_pk_bf16_f32 v70, v64, v65
	v_add_u32_e32 v64, 0x80, v154
	v_mad_i64_i32 v[152:153], s[20:21], v154, s46, v[150:151]
	v_cvt_pk_bf16_f32 v108, v108, v109
	v_cvt_pk_bf16_f32 v109, v110, v111
	v_cvt_pk_bf16_f32 v110, v104, v105
	v_cvt_pk_bf16_f32 v111, v106, v107
	v_add_u32_e32 v104, 16, v154
	v_mad_i64_i32 v[64:65], s[20:21], v64, s46, v[150:151]
	v_cvt_pk_bf16_f32 v44, v44, v45
	v_cvt_pk_bf16_f32 v45, v46, v47
	v_cvt_pk_bf16_f32 v46, v40, v41
	v_cvt_pk_bf16_f32 v47, v42, v43
	v_add_u32_e32 v40, 0x90, v154
	global_store_dwordx4 v[152:153], v[108:111], off offset:256
	v_cvt_pk_bf16_f32 v92, v92, v93
	v_cvt_pk_bf16_f32 v93, v94, v95
	v_mad_i64_i32 v[108:109], s[20:21], v104, s46, v[150:151]
	v_cvt_pk_bf16_f32 v94, v88, v89
	v_cvt_pk_bf16_f32 v95, v90, v91
	v_add_u32_e32 v88, 32, v154
	global_store_dwordx4 v[64:65], v[44:47], off offset:256
	v_cvt_pk_bf16_f32 v28, v28, v29
	v_cvt_pk_bf16_f32 v29, v30, v31
	v_mad_i64_i32 v[44:45], s[20:21], v40, s46, v[150:151]
	v_cvt_pk_bf16_f32 v30, v24, v25
	v_cvt_pk_bf16_f32 v31, v26, v27
	v_add_u32_e32 v24, 0xa0, v154
	global_store_dwordx4 v[108:109], v[92:95], off offset:256
	v_cvt_pk_bf16_f32 v76, v76, v77
	v_cvt_pk_bf16_f32 v77, v78, v79
	v_mad_i64_i32 v[92:93], s[20:21], v88, s46, v[150:151]
	v_cvt_pk_bf16_f32 v78, v72, v73
	v_cvt_pk_bf16_f32 v79, v74, v75
	v_add_u32_e32 v72, 48, v154
	global_store_dwordx4 v[44:45], v[28:31], off offset:256
	v_cvt_pk_bf16_f32 v12, v12, v13
	v_cvt_pk_bf16_f32 v13, v14, v15
	v_mad_i64_i32 v[28:29], s[20:21], v24, s46, v[150:151]
	v_cvt_pk_bf16_f32 v14, v8, v9
	v_cvt_pk_bf16_f32 v15, v10, v11
	v_add_u32_e32 v8, 0xb0, v154
	global_store_dwordx4 v[92:93], v[76:79], off offset:256
	global_store_dwordx4 v[28:29], v[12:15], off offset:256
	v_cvt_pk_bf16_f32 v124, v124, v125
	v_mad_i64_i32 v[76:77], s[20:21], v72, s46, v[150:151]
	v_mad_i64_i32 v[12:13], s[20:21], v8, s46, v[150:151]
	v_cvt_pk_bf16_f32 v125, v126, v127
	v_cvt_pk_bf16_f32 v126, v120, v121
	v_cvt_pk_bf16_f32 v127, v122, v123
	v_cvt_pk_bf16_f32 v104, v116, v117
	v_cvt_pk_bf16_f32 v105, v118, v119
	v_cvt_pk_bf16_f32 v106, v112, v113
	v_cvt_pk_bf16_f32 v107, v114, v115
	v_cvt_pk_bf16_f32 v88, v100, v101
	v_cvt_pk_bf16_f32 v89, v102, v103
	v_cvt_pk_bf16_f32 v90, v96, v97
	v_cvt_pk_bf16_f32 v91, v98, v99
	v_cvt_pk_bf16_f32 v72, v84, v85
	v_cvt_pk_bf16_f32 v73, v86, v87
	v_cvt_pk_bf16_f32 v74, v80, v81
	v_cvt_pk_bf16_f32 v75, v82, v83
	v_cvt_pk_bf16_f32 v71, v66, v67
	v_cvt_pk_bf16_f32 v60, v60, v61
	v_cvt_pk_bf16_f32 v61, v62, v63
	v_cvt_pk_bf16_f32 v62, v56, v57
	v_cvt_pk_bf16_f32 v63, v58, v59
	v_cvt_pk_bf16_f32 v40, v52, v53
	v_cvt_pk_bf16_f32 v41, v54, v55
	v_cvt_pk_bf16_f32 v42, v48, v49
	v_cvt_pk_bf16_f32 v43, v50, v51
	v_cvt_pk_bf16_f32 v24, v36, v37
	v_cvt_pk_bf16_f32 v25, v38, v39
	v_cvt_pk_bf16_f32 v26, v32, v33
	v_cvt_pk_bf16_f32 v27, v34, v35
	v_cvt_pk_bf16_f32 v8, v20, v21
	v_cvt_pk_bf16_f32 v9, v22, v23
	v_cvt_pk_bf16_f32 v10, v16, v17
	v_cvt_pk_bf16_f32 v11, v18, v19
	v_cvt_pk_bf16_f32 v4, v4, v5
	v_cvt_pk_bf16_f32 v5, v6, v7
	v_cvt_pk_bf16_f32 v6, v0, v1
	v_cvt_pk_bf16_f32 v7, v2, v3
	s_and_b64 vcc, exec, s[40:41]
	s_mov_b32 s47, s12
	s_mov_b32 s10, s14
	s_mov_b64 s[20:21], s[18:19]
	s_mov_b64 s[22:23], s[16:17]
	global_store_dwordx4 v[152:153], v[124:127], off
	global_store_dwordx4 v[108:109], v[104:107], off
	global_store_dwordx4 v[92:93], v[88:91], off
	global_store_dwordx4 v[76:77], v[72:75], off
	global_store_dwordx4 v[76:77], v[68:71], off offset:256
	global_store_dwordx4 v[64:65], v[60:63], off
	global_store_dwordx4 v[44:45], v[40:43], off
	global_store_dwordx4 v[28:29], v[24:27], off
	global_store_dwordx4 v[12:13], v[8:11], off
	global_store_dwordx4 v[12:13], v[4:7], off offset:256
	s_cbranch_vccz .LBB1_1379
	s_waitcnt vmcnt(0)
	s_cmpk_gt_u32 s4, 0xff
	s_cbranch_scc1 .LBB1_1386
	s_barrier

; #define PG8_STAGE(bufoff, gbase, voff) do { _Pragma("unroll") for (int _i = 0; _i < 2; ++_i) \
;         __builtin_amdgcn_global_load_lds((const unsigned*)((const char*)(gbase) + (voff)[_i]), (LAS unsigned*)(lds + (bufoff) + ldsw + _i * 8192), 16, 0, 0); } while (0)
; #define PG8_LDA(dst, b, h) do { _Pragma("unroll") for (int m = 0; m < 4; ++m) _Pragma("unroll") for (int k = 0; k < 2; ++k) dst[m][k] = *(const LAS bf16x8*)(lds + PG8_SA(b, h) + aoff + m * 2048 + k * 1024); } while (0)
; #define PG8_LDB(dst, b, h) do { _Pragma("unroll") for (int n = 0; n < 2; ++n) _Pragma("unroll") for (int k = 0; k < 2; ++k) dst[n][k] = *(const LAS bf16x8*)(lds + PG8_SB(b, h) + boff + n * 2048 + k * 1024); } while (0)
; #define PG8_MMA(ai, bj, At, Bt) do { __builtin_amdgcn_s_setprio(1); _Pragma("unroll") for (int m = 0; m < 4; ++m) _Pragma("unroll") for (int n = 0; n < 2; ++n) _Pragma("unroll") for (int k = 0; k < 2; ++k) \
;         acc[ai][bj][m][n] = __builtin_amdgcn_mfma_f32_16x16x32_bf16(Bt[n][k], At[m][k], acc[ai][bj][m][n], 0, 0, 0); __builtin_amdgcn_s_setprio(0); } while (0)
; #define PG8_WAIT_V(n) asm volatile("s_waitcnt vmcnt(" #n ")" ::: "memory")
; #define PG8_WAIT_L(n) asm volatile("s_waitcnt lgkmcnt(" #n ")" ::: "memory")
; template <class Map, class Epi>
; DI void gemm_phase(LAS unsigned char* lds, const Map& MP, const Epi& E, const int nM, const int nN, const int K, const int lda, const int ldb) {
;     ...
;         for (int t = 0; t < nt; t += 2) {
;             const bool last = (t == nt - 2);
;             const char* a1 = cA + (size_t)(t + 1) * kstep;
;             const char* a2 = last ? nA : cA + (size_t)(t + 2) * kstep; const char* b2 = last ? nB : cB + (size_t)(t + 2) * kstep;
;             const char* a3 = a2 + kstep; const char* b3 = b2 + kstep;
;             PG8_LDB(B0, 0, 0); PG8_SCHED; PG8_LDA(At, 0, 0); PG8_STAGE(PG8_SA(1, 1), a1 + hstepA, voffA);
;             PG8_WAIT_L(8); PG8_BAR; PG8_WAIT_L(0); PG8_MMA(0, 0, At, B0); PG8_BAR; PG8_SCHED;
;             PG8_LDB(B1, 0, 1); PG8_STAGE(PG8_SB(0, 0), b2, voffB);
;             PG8_BAR; PG8_WAIT_L(0); PG8_MMA(0, 1, At, B1); PG8_BAR;
;             PG8_LDA(At, 0, 1); PG8_STAGE(PG8_SA(0, 0), a2, voffA);
;             PG8_BAR; PG8_WAIT_L(0); PG8_MMA(1, 0, At, B0); PG8_BAR; PG8_SCHED;
;             PG8_STAGE(PG8_SB(0, 1), b2 + hstepB, voffB);
;             PG8_WAIT_V(6); PG8_BAR; PG8_MMA(1, 1, At, B1); PG8_BAR;
.LBB1_1529:
	s_add_u32 s20, s18, 0xfffe0080
	s_addc_u32 s21, s19, -1
	s_cmp_eq_u32 s3, 4
	s_cselect_b32 s23, s13, s21
	s_cselect_b32 s22, s52, s20
	s_cselect_b32 s21, s53, s56
	s_cselect_b32 s20, s54, s55
	s_add_i32 m0, s11, 0xc000
	ds_read_b128 v[166:169], v148
	ds_read_b128 v[170:173], v148 offset:1024
	ds_read_b128 v[174:177], v148 offset:2048
	ds_read_b128 v[178:181], v148 offset:3072
	ds_read_b128 v[182:185], v148 offset:4096
	ds_read_b128 v[186:189], v148 offset:5120
	ds_read_b128 v[190:193], v148 offset:6144
	ds_read_b128 v[198:201], v148 offset:7168
	global_load_lds_dwordx4 v138, s[18:19]
	s_add_i32 m0, s11, 0xe000
	s_nop 0
	global_load_lds_dwordx4 v136, s[18:19]
	s_waitcnt lgkmcnt(8)
	s_setprio 1
	s_barrier
	s_waitcnt lgkmcnt(7)
	v_mfma_f32_16x16x32_bf16 v[124:127], v[150:153], v[166:169], v[124:127]
	v_mfma_f32_16x16x32_bf16 v[120:123], v[158:161], v[166:169], v[120:123]
	s_waitcnt lgkmcnt(5)
	v_mfma_f32_16x16x32_bf16 v[116:119], v[150:153], v[174:177], v[116:119]
	v_mfma_f32_16x16x32_bf16 v[112:115], v[158:161], v[174:177], v[112:115]
	s_waitcnt lgkmcnt(3)
	v_mfma_f32_16x16x32_bf16 v[100:103], v[150:153], v[182:185], v[100:103]
	v_mfma_f32_16x16x32_bf16 v[96:99], v[158:161], v[182:185], v[96:99]
	s_waitcnt lgkmcnt(1)
	v_mfma_f32_16x16x32_bf16 v[84:87], v[150:153], v[190:193], v[84:87]
	v_mfma_f32_16x16x32_bf16 v[80:83], v[158:161], v[190:193], v[80:83]
	v_mfma_f32_16x16x32_bf16 v[124:127], v[154:157], v[170:173], v[124:127]
	s_add_i32 s57, s47, s31
	v_mfma_f32_16x16x32_bf16 v[120:123], v[162:165], v[170:173], v[120:123]
	v_lshl_add_u64 v[194:195], s[20:21], 0, v[132:133]
	v_mfma_f32_16x16x32_bf16 v[116:119], v[154:157], v[178:181], v[116:119]
	v_lshl_add_u64 v[218:219], s[20:21], 0, v[128:129]
	v_mfma_f32_16x16x32_bf16 v[112:115], v[162:165], v[178:181], v[112:115]
	v_mfma_f32_16x16x32_bf16 v[100:103], v[154:157], v[186:189], v[100:103]
	v_mfma_f32_16x16x32_bf16 v[96:99], v[162:165], v[186:189], v[96:99]
	s_waitcnt lgkmcnt(0)
	v_mfma_f32_16x16x32_bf16 v[84:87], v[154:157], v[198:201], v[84:87]
	v_mfma_f32_16x16x32_bf16 v[80:83], v[162:165], v[198:201], v[80:83]
	s_barrier
	s_setprio 0
	s_mov_b32 m0, s57
	ds_read_b128 v[202:205], v149
	ds_read_b128 v[206:209], v149 offset:1024
	ds_read_b128 v[210:213], v149 offset:2048
	ds_read_b128 v[214:217], v149 offset:3072
	global_load_lds_dwordx4 v[194:195], off
	s_add_i32 m0, s57, 0x2000
	s_nop 0
	global_load_lds_dwordx4 v[218:219], off
	s_setprio 1
	s_barrier
	s_waitcnt lgkmcnt(3)
	v_mfma_f32_16x16x32_bf16 v[108:111], v[202:205], v[166:169], v[108:111]
	s_waitcnt lgkmcnt(1)
	v_mfma_f32_16x16x32_bf16 v[104:107], v[210:213], v[166:169], v[104:107]
	v_mfma_f32_16x16x32_bf16 v[92:95], v[202:205], v[174:177], v[92:95]
	v_mfma_f32_16x16x32_bf16 v[88:91], v[210:213], v[174:177], v[88:91]
	v_mfma_f32_16x16x32_bf16 v[76:79], v[202:205], v[182:185], v[76:79]
	v_mfma_f32_16x16x32_bf16 v[72:75], v[210:213], v[182:185], v[72:75]
	v_mfma_f32_16x16x32_bf16 v[68:71], v[202:205], v[190:193], v[68:71]
	v_mfma_f32_16x16x32_bf16 v[64:67], v[210:213], v[190:193], v[64:67]
	v_mfma_f32_16x16x32_bf16 v[108:111], v[206:209], v[170:173], v[108:111]
	v_lshl_add_u64 v[222:223], s[22:23], 0, v[130:131]
	s_mov_b32 m0, s11
	s_waitcnt lgkmcnt(0)
	v_mfma_f32_16x16x32_bf16 v[104:107], v[214:217], v[170:173], v[104:107]
	v_lshl_add_u64 v[220:221], s[22:23], 0, v[134:135]
	v_mfma_f32_16x16x32_bf16 v[92:95], v[206:209], v[178:181], v[92:95]
	v_mfma_f32_16x16x32_bf16 v[88:91], v[214:217], v[178:181], v[88:91]
	v_mfma_f32_16x16x32_bf16 v[76:79], v[206:209], v[186:189], v[76:79]
	v_mfma_f32_16x16x32_bf16 v[72:75], v[214:217], v[186:189], v[72:75]
	v_mfma_f32_16x16x32_bf16 v[68:71], v[206:209], v[198:201], v[68:71]
	v_mfma_f32_16x16x32_bf16 v[64:67], v[214:217], v[198:201], v[64:67]
	s_barrier
	s_setprio 0
	ds_read_b128 v[166:169], v148 offset:16384
	ds_read_b128 v[170:173], v148 offset:17408
	ds_read_b128 v[174:177], v148 offset:18432
	ds_read_b128 v[178:181], v148 offset:19456
	ds_read_b128 v[182:185], v148 offset:20480
	ds_read_b128 v[186:189], v148 offset:21504
	ds_read_b128 v[190:193], v148 offset:22528
	ds_read_b128 v[198:201], v148 offset:23552
	global_load_lds_dwordx4 v[220:221], off
	s_mov_b32 m0, s35
	s_nop 0
	global_load_lds_dwordx4 v[222:223], off
	s_waitcnt vmcnt(10)
	s_setprio 1
	s_barrier
	s_waitcnt lgkmcnt(7)
	v_mfma_f32_16x16x32_bf16 v[60:63], v[150:153], v[166:169], v[60:63]
	v_mfma_f32_16x16x32_bf16 v[56:59], v[158:161], v[166:169], v[56:59]
	s_waitcnt lgkmcnt(5)
	v_mfma_f32_16x16x32_bf16 v[52:55], v[150:153], v[174:177], v[52:55]
	v_mfma_f32_16x16x32_bf16 v[48:51], v[158:161], v[174:177], v[48:51]
	s_waitcnt lgkmcnt(3)
	v_mfma_f32_16x16x32_bf16 v[36:39], v[150:153], v[182:185], v[36:39]
	v_mfma_f32_16x16x32_bf16 v[32:35], v[158:161], v[182:185], v[32:35]
	s_waitcnt lgkmcnt(1)
	v_mfma_f32_16x16x32_bf16 v[20:23], v[150:153], v[190:193], v[20:23]
	v_mfma_f32_16x16x32_bf16 v[16:19], v[158:161], v[190:193], v[16:19]
	v_mfma_f32_16x16x32_bf16 v[60:63], v[154:157], v[170:173], v[60:63]
	s_add_u32 s58, s20, 0x20000
	s_addc_u32 s59, s21, 0
	v_mfma_f32_16x16x32_bf16 v[56:59], v[162:165], v[170:173], v[56:59]
	s_add_i32 s57, s48, s31
	v_mfma_f32_16x16x32_bf16 v[52:55], v[154:157], v[178:181], v[52:55]
	v_mfma_f32_16x16x32_bf16 v[48:51], v[162:165], v[178:181], v[48:51]
	v_mfma_f32_16x16x32_bf16 v[36:39], v[154:157], v[186:189], v[36:39]
	v_mfma_f32_16x16x32_bf16 v[32:35], v[162:165], v[186:189], v[32:35]
	s_waitcnt lgkmcnt(0)
	v_mfma_f32_16x16x32_bf16 v[20:23], v[154:157], v[198:201], v[20:23]
	v_mfma_f32_16x16x32_bf16 v[16:19], v[162:165], v[198:201], v[16:19]
	s_barrier
; #define PG8_STAGE(bufoff, gbase, voff) do { _Pragma("unroll") for (int _i = 0; _i < 2; ++_i) \
;         __builtin_amdgcn_global_load_lds((const unsigned*)((const char*)(gbase) + (voff)[_i]), (LAS unsigned*)(lds + (bufoff) + ldsw + _i * 8192), 16, 0, 0); } while (0)
; #define PG8_LDA(dst, b, h) do { _Pragma("unroll") for (int m = 0; m < 4; ++m) _Pragma("unroll") for (int k = 0; k < 2; ++k) dst[m][k] = *(const LAS bf16x8*)(lds + PG8_SA(b, h) + aoff + m * 2048 + k * 1024); } while (0)
; #define PG8_LDB(dst, b, h) do { _Pragma("unroll") for (int n = 0; n < 2; ++n) _Pragma("unroll") for (int k = 0; k < 2; ++k) dst[n][k] = *(const LAS bf16x8*)(lds + PG8_SB(b, h) + boff + n * 2048 + k * 1024); } while (0)
; #define PG8_MMA(ai, bj, At, Bt) do { __builtin_amdgcn_s_setprio(1); _Pragma("unroll") for (int m = 0; m < 4; ++m) _Pragma("unroll") for (int n = 0; n < 2; ++n) _Pragma("unroll") for (int k = 0; k < 2; ++k) \
;         acc[ai][bj][m][n] = __builtin_amdgcn_mfma_f32_16x16x32_bf16(Bt[n][k], At[m][k], acc[ai][bj][m][n], 0, 0, 0); __builtin_amdgcn_s_setprio(0); } while (0)
; #define PG8_WAIT_V(n) asm volatile("s_waitcnt vmcnt(" #n ")" ::: "memory")
; #define PG8_WAIT_L(n) asm volatile("s_waitcnt lgkmcnt(" #n ")" ::: "memory")
; #define PG8_BAR __builtin_amdgcn_s_barrier()
; #define PG8_SCHED __builtin_amdgcn_sched_barrier(0)
; template <class Map, class Epi>
; DI void gemm_phase(LAS unsigned char* lds, const Map& MP, const Epi& E, const int nM, const int nN, const int K, const int lda, const int ldb) {
;     ...
;             PG8_STAGE(PG8_SB(0, 1), b2 + hstepB, voffB);
;             PG8_WAIT_V(6); PG8_BAR; PG8_MMA(1, 1, At, B1); PG8_BAR;
;             PG8_LDB(B0, 1, 0); PG8_SCHED; PG8_LDA(At, 1, 0); PG8_STAGE(PG8_SA(0, 1), a2 + hstepA, voffA);
;             PG8_WAIT_L(8); PG8_BAR; PG8_WAIT_L(0); PG8_MMA(0, 0, At, B0); PG8_BAR; PG8_SCHED;
;             PG8_LDB(B1, 1, 1); PG8_STAGE(PG8_SB(1, 0), b3, voffB);
;             PG8_BAR; PG8_WAIT_L(0); PG8_MMA(0, 1, At, B1); PG8_BAR;
;             PG8_LDA(At, 1, 1); PG8_STAGE(PG8_SA(1, 0), a3, voffA);
;             PG8_BAR; PG8_WAIT_L(0); PG8_MMA(1, 0, At, B0); PG8_BAR; PG8_SCHED;
;             PG8_STAGE(PG8_SB(1, 1), b3 + hstepB, voffB);
	s_setprio 0
	s_mov_b32 m0, s57
	s_nop 0
	global_load_lds_dwordx4 v132, s[58:59]
	s_add_i32 m0, s57, 0x2000
	s_nop 0
	global_load_lds_dwordx4 v128, s[58:59]
	s_waitcnt vmcnt(6)
	s_setprio 1
	s_barrier
	v_mfma_f32_16x16x32_bf16 v[44:47], v[202:205], v[166:169], v[44:47]
	v_mfma_f32_16x16x32_bf16 v[40:43], v[210:213], v[166:169], v[40:43]
	s_add_i32 s57, 0, 0x18000
	v_add_u32_e32 v162, s57, v146
	ds_read_b128 v[150:153], v162
	v_mfma_f32_16x16x32_bf16 v[28:31], v[202:205], v[174:177], v[28:31]
	v_mfma_f32_16x16x32_bf16 v[24:27], v[210:213], v[174:177], v[24:27]
	ds_read_b128 v[154:157], v162 offset:1024
	v_mfma_f32_16x16x32_bf16 v[12:15], v[202:205], v[182:185], v[12:15]
	v_mfma_f32_16x16x32_bf16 v[8:11], v[210:213], v[182:185], v[8:11]
	ds_read_b128 v[158:161], v162 offset:2048
	v_mfma_f32_16x16x32_bf16 v[4:7], v[202:205], v[190:193], v[4:7]
	v_mfma_f32_16x16x32_bf16 v[0:3], v[210:213], v[190:193], v[0:3]
	ds_read_b128 v[162:165], v162 offset:3072
	v_mfma_f32_16x16x32_bf16 v[44:47], v[206:209], v[170:173], v[44:47]
	s_add_u32 s22, s22, 0x20000
	s_addc_u32 s23, s23, 0
	v_mfma_f32_16x16x32_bf16 v[40:43], v[214:217], v[170:173], v[40:43]
	v_mfma_f32_16x16x32_bf16 v[28:31], v[206:209], v[178:181], v[28:31]
	v_mfma_f32_16x16x32_bf16 v[24:27], v[214:217], v[178:181], v[24:27]
	v_mfma_f32_16x16x32_bf16 v[12:15], v[206:209], v[186:189], v[12:15]
	v_mfma_f32_16x16x32_bf16 v[8:11], v[214:217], v[186:189], v[8:11]
	v_mfma_f32_16x16x32_bf16 v[4:7], v[206:209], v[198:201], v[4:7]
	v_mfma_f32_16x16x32_bf16 v[0:3], v[214:217], v[198:201], v[0:3]
	s_barrier
	s_setprio 0
	s_mov_b32 m0, s36
	ds_read_b128 v[166:169], v148 offset:32768
	ds_read_b128 v[170:173], v148 offset:33792
	ds_read_b128 v[174:177], v148 offset:34816
	ds_read_b128 v[178:181], v148 offset:35840
	ds_read_b128 v[182:185], v148 offset:36864
	ds_read_b128 v[186:189], v148 offset:37888
	ds_read_b128 v[190:193], v148 offset:38912
	ds_read_b128 v[198:201], v148 offset:39936
	global_load_lds_dwordx4 v134, s[22:23]
	s_mov_b32 m0, s37
	s_nop 0
	global_load_lds_dwordx4 v130, s[22:23]
	s_waitcnt lgkmcnt(8)
	s_setprio 1
	s_barrier
	s_waitcnt lgkmcnt(7)
	v_mfma_f32_16x16x32_bf16 v[124:127], v[150:153], v[166:169], v[124:127]
	v_mfma_f32_16x16x32_bf16 v[120:123], v[158:161], v[166:169], v[120:123]
	s_waitcnt lgkmcnt(5)
	v_mfma_f32_16x16x32_bf16 v[116:119], v[150:153], v[174:177], v[116:119]
	v_mfma_f32_16x16x32_bf16 v[112:115], v[158:161], v[174:177], v[112:115]
	s_waitcnt lgkmcnt(3)
	v_mfma_f32_16x16x32_bf16 v[100:103], v[150:153], v[182:185], v[100:103]
	v_mfma_f32_16x16x32_bf16 v[96:99], v[158:161], v[182:185], v[96:99]
	s_waitcnt lgkmcnt(1)
	v_mfma_f32_16x16x32_bf16 v[84:87], v[150:153], v[190:193], v[84:87]
	v_mfma_f32_16x16x32_bf16 v[80:83], v[158:161], v[190:193], v[80:83]
	v_mfma_f32_16x16x32_bf16 v[124:127], v[154:157], v[170:173], v[124:127]
	s_add_i32 s22, 0, 0x1c000
	v_mfma_f32_16x16x32_bf16 v[120:123], v[162:165], v[170:173], v[120:123]
	s_add_i32 s23, s57, s31
	v_mfma_f32_16x16x32_bf16 v[116:119], v[154:157], v[178:181], v[116:119]
	v_add_u32_e32 v196, s22, v146
	v_mfma_f32_16x16x32_bf16 v[112:115], v[162:165], v[178:181], v[112:115]
	v_lshl_add_u64 v[194:195], v[194:195], 0, s[8:9]
	v_mfma_f32_16x16x32_bf16 v[100:103], v[154:157], v[186:189], v[100:103]
	v_mfma_f32_16x16x32_bf16 v[96:99], v[162:165], v[186:189], v[96:99]
	s_waitcnt lgkmcnt(0)
	v_mfma_f32_16x16x32_bf16 v[84:87], v[154:157], v[198:201], v[84:87]
	v_mfma_f32_16x16x32_bf16 v[80:83], v[162:165], v[198:201], v[80:83]
	s_barrier
	s_setprio 0
	s_mov_b32 m0, s23
	ds_read_b128 v[202:205], v196
	ds_read_b128 v[206:209], v196 offset:1024
	ds_read_b128 v[210:213], v196 offset:2048
	ds_read_b128 v[214:217], v196 offset:3072
	global_load_lds_dwordx4 v[194:195], off
	v_lshl_add_u64 v[194:195], v[218:219], 0, s[8:9]
	s_add_i32 m0, s23, 0x2000
	s_nop 0
	global_load_lds_dwordx4 v[194:195], off
	s_setprio 1
	s_barrier
	s_waitcnt lgkmcnt(3)
	v_mfma_f32_16x16x32_bf16 v[108:111], v[202:205], v[166:169], v[108:111]
	s_waitcnt lgkmcnt(1)
	v_mfma_f32_16x16x32_bf16 v[104:107], v[210:213], v[166:169], v[104:107]
	v_mfma_f32_16x16x32_bf16 v[92:95], v[202:205], v[174:177], v[92:95]
	v_mfma_f32_16x16x32_bf16 v[88:91], v[210:213], v[174:177], v[88:91]
	v_mfma_f32_16x16x32_bf16 v[76:79], v[202:205], v[182:185], v[76:79]
	v_mfma_f32_16x16x32_bf16 v[72:75], v[210:213], v[182:185], v[72:75]
	v_mfma_f32_16x16x32_bf16 v[68:71], v[202:205], v[190:193], v[68:71]
	v_mfma_f32_16x16x32_bf16 v[64:67], v[210:213], v[190:193], v[64:67]
	v_mfma_f32_16x16x32_bf16 v[108:111], v[206:209], v[170:173], v[108:111]
	s_mov_b32 m0, s43
	s_waitcnt lgkmcnt(0)
	v_mfma_f32_16x16x32_bf16 v[104:107], v[214:217], v[170:173], v[104:107]
	v_lshl_add_u64 v[194:195], v[220:221], 0, s[8:9]
	v_mfma_f32_16x16x32_bf16 v[92:95], v[206:209], v[178:181], v[92:95]
	v_mfma_f32_16x16x32_bf16 v[88:91], v[214:217], v[178:181], v[88:91]
	v_mfma_f32_16x16x32_bf16 v[76:79], v[206:209], v[186:189], v[76:79]
	v_mfma_f32_16x16x32_bf16 v[72:75], v[214:217], v[186:189], v[72:75]
	v_mfma_f32_16x16x32_bf16 v[68:71], v[206:209], v[198:201], v[68:71]
	v_mfma_f32_16x16x32_bf16 v[64:67], v[214:217], v[198:201], v[64:67]
	s_barrier
	s_setprio 0
	ds_read_b128 v[166:169], v148 offset:49152
	ds_read_b128 v[170:173], v148 offset:50176
	ds_read_b128 v[174:177], v148 offset:51200
	ds_read_b128 v[178:181], v148 offset:52224
	ds_read_b128 v[182:185], v148 offset:53248
	ds_read_b128 v[186:189], v148 offset:54272
	ds_read_b128 v[190:193], v148 offset:55296
	ds_read_b128 v[198:201], v148 offset:56320
	global_load_lds_dwordx4 v[194:195], off
	v_lshl_add_u64 v[194:195], v[222:223], 0, s[8:9]
	s_mov_b32 m0, s44
	s_nop 0
	global_load_lds_dwordx4 v[194:195], off
	s_waitcnt vmcnt(10)
	s_setprio 1
	s_barrier
; #define PG8_STAGE(bufoff, gbase, voff) do { _Pragma("unroll") for (int _i = 0; _i < 2; ++_i) \
;         __builtin_amdgcn_global_load_lds((const unsigned*)((const char*)(gbase) + (voff)[_i]), (LAS unsigned*)(lds + (bufoff) + ldsw + _i * 8192), 16, 0, 0); } while (0)
; #define PG8_LDA(dst, b, h) do { _Pragma("unroll") for (int m = 0; m < 4; ++m) _Pragma("unroll") for (int k = 0; k < 2; ++k) dst[m][k] = *(const LAS bf16x8*)(lds + PG8_SA(b, h) + aoff + m * 2048 + k * 1024); } while (0)
; #define PG8_MMA(ai, bj, At, Bt) do { __builtin_amdgcn_s_setprio(1); _Pragma("unroll") for (int m = 0; m < 4; ++m) _Pragma("unroll") for (int n = 0; n < 2; ++n) _Pragma("unroll") for (int k = 0; k < 2; ++k) \
;         acc[ai][bj][m][n] = __builtin_amdgcn_mfma_f32_16x16x32_bf16(Bt[n][k], At[m][k], acc[ai][bj][m][n], 0, 0, 0); __builtin_amdgcn_s_setprio(0); } while (0)
; #define PG8_WAIT_V(n) asm volatile("s_waitcnt vmcnt(" #n ")" ::: "memory")
; #define PG8_WAIT_L(n) asm volatile("s_waitcnt lgkmcnt(" #n ")" ::: "memory")
; #define PG8_BAR __builtin_amdgcn_s_barrier()
; #define PG8_SCHED __builtin_amdgcn_sched_barrier(0)
; template <class Map, class Epi>
; DI void gemm_phase(LAS unsigned char* lds, const Map& MP, const Epi& E, const int nM, const int nN, const int K, const int lda, const int ldb) {
;     ...
;             PG8_LDA(At, 1, 1); PG8_STAGE(PG8_SA(1, 0), a3, voffA);
;             PG8_BAR; PG8_WAIT_L(0); PG8_MMA(1, 0, At, B0); PG8_BAR; PG8_SCHED;
;             PG8_STAGE(PG8_SB(1, 1), b3 + hstepB, voffB);
;             PG8_WAIT_V(6); PG8_BAR; PG8_MMA(1, 1, At, B1); PG8_BAR;
;         }
	s_waitcnt lgkmcnt(7)
	v_mfma_f32_16x16x32_bf16 v[60:63], v[150:153], v[166:169], v[60:63]
	v_mfma_f32_16x16x32_bf16 v[56:59], v[158:161], v[166:169], v[56:59]
	s_waitcnt lgkmcnt(5)
	v_mfma_f32_16x16x32_bf16 v[52:55], v[150:153], v[174:177], v[52:55]
	v_mfma_f32_16x16x32_bf16 v[48:51], v[158:161], v[174:177], v[48:51]
	s_waitcnt lgkmcnt(3)
	v_mfma_f32_16x16x32_bf16 v[36:39], v[150:153], v[182:185], v[36:39]
	v_mfma_f32_16x16x32_bf16 v[32:35], v[158:161], v[182:185], v[32:35]
	s_waitcnt lgkmcnt(1)
	v_mfma_f32_16x16x32_bf16 v[20:23], v[150:153], v[190:193], v[20:23]
	v_mfma_f32_16x16x32_bf16 v[16:19], v[158:161], v[190:193], v[16:19]
	v_mfma_f32_16x16x32_bf16 v[60:63], v[154:157], v[170:173], v[60:63]
	s_add_u32 s20, s20, 0x20080
	s_addc_u32 s21, s21, 0
	v_mfma_f32_16x16x32_bf16 v[56:59], v[162:165], v[170:173], v[56:59]
	s_add_i32 s22, s22, s31
	v_mfma_f32_16x16x32_bf16 v[52:55], v[154:157], v[178:181], v[52:55]
	v_mfma_f32_16x16x32_bf16 v[48:51], v[162:165], v[178:181], v[48:51]
	v_mfma_f32_16x16x32_bf16 v[36:39], v[154:157], v[186:189], v[36:39]
	v_mfma_f32_16x16x32_bf16 v[32:35], v[162:165], v[186:189], v[32:35]
	s_waitcnt lgkmcnt(0)
	v_mfma_f32_16x16x32_bf16 v[20:23], v[154:157], v[198:201], v[20:23]
	v_mfma_f32_16x16x32_bf16 v[16:19], v[162:165], v[198:201], v[16:19]
	s_barrier
	s_setprio 0
	s_mov_b32 m0, s22
	s_nop 0
	global_load_lds_dwordx4 v132, s[20:21]
	s_add_i32 m0, s22, 0x2000
	s_nop 0
	global_load_lds_dwordx4 v128, s[20:21]
	s_waitcnt vmcnt(6)
	s_setprio 1
	s_barrier
	v_mfma_f32_16x16x32_bf16 v[44:47], v[202:205], v[166:169], v[44:47]
	v_mfma_f32_16x16x32_bf16 v[40:43], v[210:213], v[166:169], v[40:43]
	ds_read_b128 v[150:153], v147
	v_mfma_f32_16x16x32_bf16 v[28:31], v[202:205], v[174:177], v[28:31]
	v_mfma_f32_16x16x32_bf16 v[24:27], v[210:213], v[174:177], v[24:27]
	ds_read_b128 v[154:157], v147 offset:1024
	v_mfma_f32_16x16x32_bf16 v[12:15], v[202:205], v[182:185], v[12:15]
	v_mfma_f32_16x16x32_bf16 v[8:11], v[210:213], v[182:185], v[8:11]
	ds_read_b128 v[158:161], v147 offset:2048
	v_mfma_f32_16x16x32_bf16 v[4:7], v[202:205], v[190:193], v[4:7]
	v_mfma_f32_16x16x32_bf16 v[0:3], v[210:213], v[190:193], v[0:3]
	ds_read_b128 v[162:165], v147 offset:3072
	v_mfma_f32_16x16x32_bf16 v[44:47], v[206:209], v[170:173], v[44:47]
	s_add_i32 s3, s3, 2
	v_mfma_f32_16x16x32_bf16 v[40:43], v[214:217], v[170:173], v[40:43]
	s_add_u32 s55, s55, 0x100
	s_addc_u32 s56, s56, 0
	v_mfma_f32_16x16x32_bf16 v[28:31], v[206:209], v[178:181], v[28:31]
	s_add_u32 s18, s18, 0x100
	s_addc_u32 s19, s19, 0
	v_mfma_f32_16x16x32_bf16 v[24:27], v[214:217], v[178:181], v[24:27]
	s_cmp_gt_u32 s3, 5
	v_mfma_f32_16x16x32_bf16 v[12:15], v[206:209], v[186:189], v[12:15]
	v_mfma_f32_16x16x32_bf16 v[8:11], v[214:217], v[186:189], v[8:11]
	v_mfma_f32_16x16x32_bf16 v[4:7], v[206:209], v[198:201], v[4:7]
	v_mfma_f32_16x16x32_bf16 v[0:3], v[214:217], v[198:201], v[0:3]
	s_barrier
	s_setprio 0
	s_cbranch_scc0 .LBB1_1529
; DI unsigned pack2(float a, float b) { f32x2 v = {a, b}; hwbf16x2 r = __builtin_convertvector(v, hwbf16x2); return __builtin_bit_cast(unsigned, r); }
;     DI void operator()(const f32x4 (&acc)[2][2][4][2], const Unit& u, int wr, int wc, int fr, int fq) const {
;         bf16_t* O = O1; int ldc = ldc1, pn = u.pn; if (pn >= split) { O = O2; ldc = ldc2; pn -= split; }
;         const int row0 = u.pm * BM + wr * 64 + fr, col0 = pn * BM + wc * 32 + 8 * fq;
; #pragma unroll
;         for (int ai = 0; ai < 2; ++ai)
; #pragma unroll
;             for (int m = 0; m < 4; ++m) { bf16_t* rowp = O + (size_t)(row0 + ai * HALF + m * 16) * ldc + col0;
; #pragma unroll
;                 for (int bj = 0; bj < 2; ++bj) { const f32x4 v0 = acc[ai][bj][m][0], v1 = acc[ai][bj][m][1];
;                     u32x4 o; o[0] = pack2(v0[0], v0[1]); o[1] = pack2(v0[2], v0[3]); o[2] = pack2(v1[0], v1[1]); o[3] = pack2(v1[2], v1[3]);
;                     *(u32x4*)(rowp + bj * HALF) = o; } }
;     }
	s_waitcnt lgkmcnt(0)
	s_cmp_lt_i32 s45, 12
	s_cselect_b32 s3, 0, -12
	s_mov_b32 s13, 0x1e510000
	s_movk_i32 s18, 0xc00
	s_cselect_b32 s13, s13, 0x2a510000
	s_cselect_b32 s20, s18, 0x1000
	s_add_i32 s3, s3, s45
	s_add_u32 s18, s6, s13
	v_mov_b32_e32 v150, v144
	v_mov_b32_e32 v151, v145
	s_addc_u32 s19, s7, 0
	s_lshl_b32 s10, s10, 8
	s_lshl_b32 s3, s3, 8
	s_add_i32 s10, s10, s39
	s_or_b32 s3, s3, s42
	v_add_u32_e32 v154, s10, v150
	v_lshl_add_u32 v150, v151, 3, s3
	v_ashrrev_i32_e32 v151, 31, v150
	v_lshl_add_u64 v[150:151], v[150:151], 1, s[18:19]
	v_mad_i64_i32 v[152:153], s[18:19], s20, v154, 0
	v_cvt_pk_bf16_f32 v108, v108, v109
	v_cvt_pk_bf16_f32 v109, v110, v111
	v_cvt_pk_bf16_f32 v110, v104, v105
	v_add_u32_e32 v104, 16, v154
	v_lshl_add_u64 v[152:153], v[152:153], 1, v[150:151]
	v_cvt_pk_bf16_f32 v111, v106, v107
	v_mad_i64_i32 v[104:105], s[18:19], s20, v104, 0
	v_cvt_pk_bf16_f32 v92, v92, v93
	v_cvt_pk_bf16_f32 v93, v94, v95
	v_cvt_pk_bf16_f32 v94, v88, v89
	v_add_u32_e32 v88, 32, v154
	v_cvt_pk_bf16_f32 v124, v124, v125
	v_cvt_pk_bf16_f32 v125, v126, v127
	v_cvt_pk_bf16_f32 v126, v120, v121
	v_cvt_pk_bf16_f32 v127, v122, v123
	global_store_dwordx4 v[152:153], v[108:111], off offset:256
	v_cvt_pk_bf16_f32 v95, v90, v91
	v_mad_i64_i32 v[88:89], s[18:19], s20, v88, 0
	v_lshl_add_u64 v[108:109], v[104:105], 1, v[150:151]
	v_cvt_pk_bf16_f32 v76, v76, v77
	v_cvt_pk_bf16_f32 v77, v78, v79
	v_cvt_pk_bf16_f32 v78, v72, v73
	v_add_u32_e32 v72, 48, v154
	v_cvt_pk_bf16_f32 v68, v68, v69
	v_cvt_pk_bf16_f32 v69, v70, v71
	v_cvt_pk_bf16_f32 v70, v64, v65
	v_add_u32_e32 v64, 0x80, v154
	global_store_dwordx4 v[152:153], v[124:127], off
	v_cvt_pk_bf16_f32 v104, v116, v117
	v_cvt_pk_bf16_f32 v105, v118, v119
	v_cvt_pk_bf16_f32 v106, v112, v113
	v_cvt_pk_bf16_f32 v107, v114, v115
	global_store_dwordx4 v[108:109], v[92:95], off offset:256
	v_cvt_pk_bf16_f32 v79, v74, v75
	v_mad_i64_i32 v[72:73], s[18:19], s20, v72, 0
	v_lshl_add_u64 v[92:93], v[88:89], 1, v[150:151]
	v_mad_i64_i32 v[64:65], s[18:19], s20, v64, 0
	v_cvt_pk_bf16_f32 v44, v44, v45
	v_cvt_pk_bf16_f32 v45, v46, v47
	v_cvt_pk_bf16_f32 v46, v40, v41
	v_add_u32_e32 v40, 0x90, v154
	global_store_dwordx4 v[108:109], v[104:107], off
	v_cvt_pk_bf16_f32 v88, v100, v101
	v_cvt_pk_bf16_f32 v89, v102, v103
	v_cvt_pk_bf16_f32 v90, v96, v97
	v_cvt_pk_bf16_f32 v91, v98, v99
	global_store_dwordx4 v[92:93], v[76:79], off offset:256
	v_cvt_pk_bf16_f32 v74, v80, v81
	v_cvt_pk_bf16_f32 v75, v82, v83
	v_lshl_add_u64 v[76:77], v[72:73], 1, v[150:151]
	v_cvt_pk_bf16_f32 v72, v84, v85
	v_cvt_pk_bf16_f32 v73, v86, v87
	v_cvt_pk_bf16_f32 v71, v66, v67
	v_lshl_add_u64 v[64:65], v[64:65], 1, v[150:151]
	v_cvt_pk_bf16_f32 v47, v42, v43
	v_mad_i64_i32 v[40:41], s[18:19], s20, v40, 0
	v_cvt_pk_bf16_f32 v28, v28, v29
	v_cvt_pk_bf16_f32 v29, v30, v31
	v_cvt_pk_bf16_f32 v30, v24, v25
	v_add_u32_e32 v24, 0xa0, v154
	global_store_dwordx4 v[92:93], v[88:91], off
	global_store_dwordx4 v[76:77], v[72:75], off
	global_store_dwordx4 v[76:77], v[68:71], off offset:256
	v_cvt_pk_bf16_f32 v60, v60, v61
	v_cvt_pk_bf16_f32 v61, v62, v63
	v_cvt_pk_bf16_f32 v62, v56, v57
	v_cvt_pk_bf16_f32 v63, v58, v59
	global_store_dwordx4 v[64:65], v[44:47], off offset:256
	v_cvt_pk_bf16_f32 v31, v26, v27
	v_mad_i64_i32 v[24:25], s[18:19], s20, v24, 0
	v_lshl_add_u64 v[44:45], v[40:41], 1, v[150:151]
	v_cvt_pk_bf16_f32 v12, v12, v13
	v_cvt_pk_bf16_f32 v13, v14, v15
	v_cvt_pk_bf16_f32 v14, v8, v9
	v_add_u32_e32 v8, 0xb0, v154
	global_store_dwordx4 v[64:65], v[60:63], off
	v_cvt_pk_bf16_f32 v40, v52, v53
	v_cvt_pk_bf16_f32 v41, v54, v55
	v_cvt_pk_bf16_f32 v42, v48, v49
	v_cvt_pk_bf16_f32 v43, v50, v51
	global_store_dwordx4 v[44:45], v[28:31], off offset:256
	v_cvt_pk_bf16_f32 v15, v10, v11
	v_mad_i64_i32 v[8:9], s[18:19], s20, v8, 0
	v_lshl_add_u64 v[28:29], v[24:25], 1, v[150:151]
	global_store_dwordx4 v[44:45], v[40:43], off
	v_cvt_pk_bf16_f32 v24, v36, v37
	v_cvt_pk_bf16_f32 v25, v38, v39
	v_cvt_pk_bf16_f32 v26, v32, v33
	v_cvt_pk_bf16_f32 v27, v34, v35
	global_store_dwordx4 v[28:29], v[12:15], off offset:256
	v_cvt_pk_bf16_f32 v10, v16, v17
	v_cvt_pk_bf16_f32 v11, v18, v19
	v_lshl_add_u64 v[12:13], v[8:9], 1, v[150:151]
	v_cvt_pk_bf16_f32 v8, v20, v21
	v_cvt_pk_bf16_f32 v9, v22, v23
	v_cvt_pk_bf16_f32 v4, v4, v5
	v_cvt_pk_bf16_f32 v5, v6, v7
	v_cvt_pk_bf16_f32 v6, v0, v1
	v_cvt_pk_bf16_f32 v7, v2, v3
	s_and_b64 vcc, exec, s[40:41]
	s_mov_b32 s45, s49
	s_mov_b32 s10, s12
	s_mov_b64 s[18:19], s[16:17]
	s_mov_b64 s[20:21], s[14:15]
	global_store_dwordx4 v[28:29], v[24:27], off
	global_store_dwordx4 v[12:13], v[8:11], off
	global_store_dwordx4 v[12:13], v[4:7], off offset:256
	s_cbranch_vccz .LBB1_1526
	s_waitcnt vmcnt(0)
	s_cmpk_gt_u32 s4, 0xff
	s_cbranch_scc1 .LBB1_1533
	s_barrier

; #define PG8_STAGE(bufoff, gbase, voff) do { _Pragma("unroll") for (int _i = 0; _i < 2; ++_i) \
;         __builtin_amdgcn_global_load_lds((const unsigned*)((const char*)(gbase) + (voff)[_i]), (LAS unsigned*)(lds + (bufoff) + ldsw + _i * 8192), 16, 0, 0); } while (0)
; #define PG8_LDA(dst, b, h) do { _Pragma("unroll") for (int m = 0; m < 4; ++m) _Pragma("unroll") for (int k = 0; k < 2; ++k) dst[m][k] = *(const LAS bf16x8*)(lds + PG8_SA(b, h) + aoff + m * 2048 + k * 1024); } while (0)
; #define PG8_LDB(dst, b, h) do { _Pragma("unroll") for (int n = 0; n < 2; ++n) _Pragma("unroll") for (int k = 0; k < 2; ++k) dst[n][k] = *(const LAS bf16x8*)(lds + PG8_SB(b, h) + boff + n * 2048 + k * 1024); } while (0)
; #define PG8_MMA(ai, bj, At, Bt) do { __builtin_amdgcn_s_setprio(1); _Pragma("unroll") for (int m = 0; m < 4; ++m) _Pragma("unroll") for (int n = 0; n < 2; ++n) _Pragma("unroll") for (int k = 0; k < 2; ++k) \
;         acc[ai][bj][m][n] = __builtin_amdgcn_mfma_f32_16x16x32_bf16(Bt[n][k], At[m][k], acc[ai][bj][m][n], 0, 0, 0); __builtin_amdgcn_s_setprio(0); } while (0)
; #define PG8_WAIT_V(n) asm volatile("s_waitcnt vmcnt(" #n ")" ::: "memory")
; #define PG8_WAIT_L(n) asm volatile("s_waitcnt lgkmcnt(" #n ")" ::: "memory")
; template <class Map, class Epi>
; DI void gemm_phase(LAS unsigned char* lds, const Map& MP, const Epi& E, const int nM, const int nN, const int K, const int lda, const int ldb) {
;     ...
;         for (int t = 0; t < nt; t += 2) {
;             const bool last = (t == nt - 2);
;             const char* a1 = cA + (size_t)(t + 1) * kstep;
;             const char* a2 = last ? nA : cA + (size_t)(t + 2) * kstep; const char* b2 = last ? nB : cB + (size_t)(t + 2) * kstep;
;             const char* a3 = a2 + kstep; const char* b3 = b2 + kstep;
;             PG8_LDB(B0, 0, 0); PG8_SCHED; PG8_LDA(At, 0, 0); PG8_STAGE(PG8_SA(1, 1), a1 + hstepA, voffA);
;             PG8_WAIT_L(8); PG8_BAR; PG8_WAIT_L(0); PG8_MMA(0, 0, At, B0); PG8_BAR; PG8_SCHED;
;             PG8_LDB(B1, 0, 1); PG8_STAGE(PG8_SB(0, 0), b2, voffB);
;             PG8_BAR; PG8_WAIT_L(0); PG8_MMA(0, 1, At, B1); PG8_BAR;
;             PG8_LDA(At, 0, 1); PG8_STAGE(PG8_SA(0, 0), a2, voffA);
;             PG8_BAR; PG8_WAIT_L(0); PG8_MMA(1, 0, At, B0); PG8_BAR; PG8_SCHED;
;             PG8_STAGE(PG8_SB(0, 1), b2 + hstepB, voffB);
;             PG8_WAIT_V(6); PG8_BAR; PG8_MMA(1, 1, At, B1); PG8_BAR;
.LBB1_1764:
	s_add_u32 s12, s10, 0xfff80080
	s_addc_u32 s13, s11, -1
	s_cmp_eq_u32 s3, 28
	s_cselect_b32 s15, s37, s13
	s_cselect_b32 s14, s38, s12
	s_cselect_b32 s13, s39, s48
	s_cselect_b32 s12, s45, s47
	s_add_i32 m0, s24, 0xc000
	ds_read_b128 v[168:171], v150
	ds_read_b128 v[172:175], v150 offset:1024
	ds_read_b128 v[176:179], v150 offset:2048
	ds_read_b128 v[180:183], v150 offset:3072
	ds_read_b128 v[184:187], v150 offset:4096
	ds_read_b128 v[188:191], v150 offset:5120
	ds_read_b128 v[192:195], v150 offset:6144
	ds_read_b128 v[198:201], v150 offset:7168
	global_load_lds_dwordx4 v138, s[10:11]
	s_add_i32 m0, s24, 0xe000
	s_nop 0
	global_load_lds_dwordx4 v136, s[10:11]
	s_waitcnt lgkmcnt(8)
	s_setprio 1
	s_barrier
	s_waitcnt lgkmcnt(7)
	v_mfma_f32_16x16x32_bf16 v[124:127], v[152:155], v[168:171], v[124:127]
	v_mfma_f32_16x16x32_bf16 v[120:123], v[160:163], v[168:171], v[120:123]
	s_waitcnt lgkmcnt(5)
	v_mfma_f32_16x16x32_bf16 v[108:111], v[152:155], v[176:179], v[108:111]
	v_mfma_f32_16x16x32_bf16 v[104:107], v[160:163], v[176:179], v[104:107]
	s_waitcnt lgkmcnt(3)
	v_mfma_f32_16x16x32_bf16 v[92:95], v[152:155], v[184:187], v[92:95]
	v_mfma_f32_16x16x32_bf16 v[88:91], v[160:163], v[184:187], v[88:91]
	s_waitcnt lgkmcnt(1)
	v_mfma_f32_16x16x32_bf16 v[76:79], v[152:155], v[192:195], v[76:79]
	v_mfma_f32_16x16x32_bf16 v[72:75], v[160:163], v[192:195], v[72:75]
	v_mfma_f32_16x16x32_bf16 v[124:127], v[156:159], v[172:175], v[124:127]
	s_add_i32 s49, s35, s22
	v_mfma_f32_16x16x32_bf16 v[120:123], v[164:167], v[172:175], v[120:123]
	v_lshl_add_u64 v[144:145], s[12:13], 0, v[132:133]
	v_mfma_f32_16x16x32_bf16 v[108:111], v[156:159], v[180:183], v[108:111]
	v_lshl_add_u64 v[218:219], s[12:13], 0, v[128:129]
	v_mfma_f32_16x16x32_bf16 v[104:107], v[164:167], v[180:183], v[104:107]
	v_mfma_f32_16x16x32_bf16 v[92:95], v[156:159], v[188:191], v[92:95]
	v_mfma_f32_16x16x32_bf16 v[88:91], v[164:167], v[188:191], v[88:91]
	s_waitcnt lgkmcnt(0)
	v_mfma_f32_16x16x32_bf16 v[76:79], v[156:159], v[198:201], v[76:79]
	v_mfma_f32_16x16x32_bf16 v[72:75], v[164:167], v[198:201], v[72:75]
	s_barrier
	s_setprio 0
	s_mov_b32 m0, s49
	ds_read_b128 v[202:205], v151
	ds_read_b128 v[206:209], v151 offset:1024
	ds_read_b128 v[210:213], v151 offset:2048
	ds_read_b128 v[214:217], v151 offset:3072
	global_load_lds_dwordx4 v[144:145], off
	s_add_i32 m0, s49, 0x2000
	s_nop 0
	global_load_lds_dwordx4 v[218:219], off
	s_setprio 1
	s_barrier
	s_waitcnt lgkmcnt(3)
	v_mfma_f32_16x16x32_bf16 v[116:119], v[202:205], v[168:171], v[116:119]
	s_waitcnt lgkmcnt(1)
	v_mfma_f32_16x16x32_bf16 v[112:115], v[210:213], v[168:171], v[112:115]
	v_mfma_f32_16x16x32_bf16 v[100:103], v[202:205], v[176:179], v[100:103]
	v_mfma_f32_16x16x32_bf16 v[96:99], v[210:213], v[176:179], v[96:99]
	v_mfma_f32_16x16x32_bf16 v[84:87], v[202:205], v[184:187], v[84:87]
	v_mfma_f32_16x16x32_bf16 v[80:83], v[210:213], v[184:187], v[80:83]
	v_mfma_f32_16x16x32_bf16 v[68:71], v[202:205], v[192:195], v[68:71]
	v_mfma_f32_16x16x32_bf16 v[64:67], v[210:213], v[192:195], v[64:67]
	v_mfma_f32_16x16x32_bf16 v[116:119], v[206:209], v[172:175], v[116:119]
	v_lshl_add_u64 v[222:223], s[14:15], 0, v[130:131]
	s_mov_b32 m0, s24
	s_waitcnt lgkmcnt(0)
	v_mfma_f32_16x16x32_bf16 v[112:115], v[214:217], v[172:175], v[112:115]
	v_lshl_add_u64 v[220:221], s[14:15], 0, v[134:135]
	v_mfma_f32_16x16x32_bf16 v[100:103], v[206:209], v[180:183], v[100:103]
	v_mfma_f32_16x16x32_bf16 v[96:99], v[214:217], v[180:183], v[96:99]
	v_mfma_f32_16x16x32_bf16 v[84:87], v[206:209], v[188:191], v[84:87]
	v_mfma_f32_16x16x32_bf16 v[80:83], v[214:217], v[188:191], v[80:83]
	v_mfma_f32_16x16x32_bf16 v[68:71], v[206:209], v[198:201], v[68:71]
	v_mfma_f32_16x16x32_bf16 v[64:67], v[214:217], v[198:201], v[64:67]
	s_barrier
	s_setprio 0
	ds_read_b128 v[168:171], v150 offset:16384
	ds_read_b128 v[172:175], v150 offset:17408
	ds_read_b128 v[176:179], v150 offset:18432
	ds_read_b128 v[180:183], v150 offset:19456
	ds_read_b128 v[184:187], v150 offset:20480
	ds_read_b128 v[188:191], v150 offset:21504
	ds_read_b128 v[192:195], v150 offset:22528
	ds_read_b128 v[198:201], v150 offset:23552
	global_load_lds_dwordx4 v[220:221], off
	s_mov_b32 m0, s9
	s_nop 0
	global_load_lds_dwordx4 v[222:223], off
	s_waitcnt vmcnt(10)
	s_setprio 1
	s_barrier
	s_waitcnt lgkmcnt(7)
	v_mfma_f32_16x16x32_bf16 v[60:63], v[152:155], v[168:171], v[60:63]
	v_mfma_f32_16x16x32_bf16 v[56:59], v[160:163], v[168:171], v[56:59]
	s_waitcnt lgkmcnt(5)
	v_mfma_f32_16x16x32_bf16 v[44:47], v[152:155], v[176:179], v[44:47]
	v_mfma_f32_16x16x32_bf16 v[40:43], v[160:163], v[176:179], v[40:43]
	s_waitcnt lgkmcnt(3)
	v_mfma_f32_16x16x32_bf16 v[28:31], v[152:155], v[184:187], v[28:31]
	v_mfma_f32_16x16x32_bf16 v[24:27], v[160:163], v[184:187], v[24:27]
	s_waitcnt lgkmcnt(1)
	v_mfma_f32_16x16x32_bf16 v[12:15], v[152:155], v[192:195], v[12:15]
	v_mfma_f32_16x16x32_bf16 v[8:11], v[160:163], v[192:195], v[8:11]
	v_mfma_f32_16x16x32_bf16 v[60:63], v[156:159], v[172:175], v[60:63]
	s_add_u32 s54, s12, 0x80000
	s_addc_u32 s55, s13, 0
	v_mfma_f32_16x16x32_bf16 v[56:59], v[164:167], v[172:175], v[56:59]
	s_add_i32 s49, s36, s22
	v_mfma_f32_16x16x32_bf16 v[44:47], v[156:159], v[180:183], v[44:47]
	v_mfma_f32_16x16x32_bf16 v[40:43], v[164:167], v[180:183], v[40:43]
	v_mfma_f32_16x16x32_bf16 v[28:31], v[156:159], v[188:191], v[28:31]
	v_mfma_f32_16x16x32_bf16 v[24:27], v[164:167], v[188:191], v[24:27]
	s_waitcnt lgkmcnt(0)
	v_mfma_f32_16x16x32_bf16 v[12:15], v[156:159], v[198:201], v[12:15]
	v_mfma_f32_16x16x32_bf16 v[8:11], v[164:167], v[198:201], v[8:11]
	s_barrier
; #define PG8_STAGE(bufoff, gbase, voff) do { _Pragma("unroll") for (int _i = 0; _i < 2; ++_i) \
;         __builtin_amdgcn_global_load_lds((const unsigned*)((const char*)(gbase) + (voff)[_i]), (LAS unsigned*)(lds + (bufoff) + ldsw + _i * 8192), 16, 0, 0); } while (0)
; #define PG8_LDA(dst, b, h) do { _Pragma("unroll") for (int m = 0; m < 4; ++m) _Pragma("unroll") for (int k = 0; k < 2; ++k) dst[m][k] = *(const LAS bf16x8*)(lds + PG8_SA(b, h) + aoff + m * 2048 + k * 1024); } while (0)
; #define PG8_LDB(dst, b, h) do { _Pragma("unroll") for (int n = 0; n < 2; ++n) _Pragma("unroll") for (int k = 0; k < 2; ++k) dst[n][k] = *(const LAS bf16x8*)(lds + PG8_SB(b, h) + boff + n * 2048 + k * 1024); } while (0)
; #define PG8_MMA(ai, bj, At, Bt) do { __builtin_amdgcn_s_setprio(1); _Pragma("unroll") for (int m = 0; m < 4; ++m) _Pragma("unroll") for (int n = 0; n < 2; ++n) _Pragma("unroll") for (int k = 0; k < 2; ++k) \
;         acc[ai][bj][m][n] = __builtin_amdgcn_mfma_f32_16x16x32_bf16(Bt[n][k], At[m][k], acc[ai][bj][m][n], 0, 0, 0); __builtin_amdgcn_s_setprio(0); } while (0)
; #define PG8_WAIT_V(n) asm volatile("s_waitcnt vmcnt(" #n ")" ::: "memory")
; #define PG8_WAIT_L(n) asm volatile("s_waitcnt lgkmcnt(" #n ")" ::: "memory")
; #define PG8_BAR __builtin_amdgcn_s_barrier()
; #define PG8_SCHED __builtin_amdgcn_sched_barrier(0)
; template <class Map, class Epi>
; DI void gemm_phase(LAS unsigned char* lds, const Map& MP, const Epi& E, const int nM, const int nN, const int K, const int lda, const int ldb) {
;     ...
;             PG8_STAGE(PG8_SB(0, 1), b2 + hstepB, voffB);
;             PG8_WAIT_V(6); PG8_BAR; PG8_MMA(1, 1, At, B1); PG8_BAR;
;             PG8_LDB(B0, 1, 0); PG8_SCHED; PG8_LDA(At, 1, 0); PG8_STAGE(PG8_SA(0, 1), a2 + hstepA, voffA);
;             PG8_WAIT_L(8); PG8_BAR; PG8_WAIT_L(0); PG8_MMA(0, 0, At, B0); PG8_BAR; PG8_SCHED;
;             PG8_LDB(B1, 1, 1); PG8_STAGE(PG8_SB(1, 0), b3, voffB);
;             PG8_BAR; PG8_WAIT_L(0); PG8_MMA(0, 1, At, B1); PG8_BAR;
;             PG8_LDA(At, 1, 1); PG8_STAGE(PG8_SA(1, 0), a3, voffA);
;             PG8_BAR; PG8_WAIT_L(0); PG8_MMA(1, 0, At, B0); PG8_BAR; PG8_SCHED;
;             PG8_STAGE(PG8_SB(1, 1), b3 + hstepB, voffB);
	s_setprio 0
	s_mov_b32 m0, s49
	s_nop 0
	global_load_lds_dwordx4 v132, s[54:55]
	s_add_i32 m0, s49, 0x2000
	s_nop 0
	global_load_lds_dwordx4 v128, s[54:55]
	s_waitcnt vmcnt(6)
	s_setprio 1
	s_barrier
	v_mfma_f32_16x16x32_bf16 v[52:55], v[202:205], v[168:171], v[52:55]
	v_mfma_f32_16x16x32_bf16 v[48:51], v[210:213], v[168:171], v[48:51]
	s_add_i32 s49, 0, 0x18000
	v_add_u32_e32 v164, s49, v148
	ds_read_b128 v[152:155], v164
	v_mfma_f32_16x16x32_bf16 v[36:39], v[202:205], v[176:179], v[36:39]
	v_mfma_f32_16x16x32_bf16 v[32:35], v[210:213], v[176:179], v[32:35]
	ds_read_b128 v[156:159], v164 offset:1024
	v_mfma_f32_16x16x32_bf16 v[20:23], v[202:205], v[184:187], v[20:23]
	v_mfma_f32_16x16x32_bf16 v[16:19], v[210:213], v[184:187], v[16:19]
	ds_read_b128 v[160:163], v164 offset:2048
	v_mfma_f32_16x16x32_bf16 v[4:7], v[202:205], v[192:195], v[4:7]
	v_mfma_f32_16x16x32_bf16 v[0:3], v[210:213], v[192:195], v[0:3]
	ds_read_b128 v[164:167], v164 offset:3072
	v_mfma_f32_16x16x32_bf16 v[52:55], v[206:209], v[172:175], v[52:55]
	s_add_u32 s14, s14, 0x80000
	s_addc_u32 s15, s15, 0
	v_mfma_f32_16x16x32_bf16 v[48:51], v[214:217], v[172:175], v[48:51]
	v_mfma_f32_16x16x32_bf16 v[36:39], v[206:209], v[180:183], v[36:39]
	v_mfma_f32_16x16x32_bf16 v[32:35], v[214:217], v[180:183], v[32:35]
	v_mfma_f32_16x16x32_bf16 v[20:23], v[206:209], v[188:191], v[20:23]
	v_mfma_f32_16x16x32_bf16 v[16:19], v[214:217], v[188:191], v[16:19]
	v_mfma_f32_16x16x32_bf16 v[4:7], v[206:209], v[198:201], v[4:7]
	v_mfma_f32_16x16x32_bf16 v[0:3], v[214:217], v[198:201], v[0:3]
	s_barrier
	s_setprio 0
	s_mov_b32 m0, s25
	ds_read_b128 v[168:171], v150 offset:32768
	ds_read_b128 v[172:175], v150 offset:33792
	ds_read_b128 v[176:179], v150 offset:34816
	ds_read_b128 v[180:183], v150 offset:35840
	ds_read_b128 v[184:187], v150 offset:36864
	ds_read_b128 v[188:191], v150 offset:37888
	ds_read_b128 v[192:195], v150 offset:38912
	ds_read_b128 v[198:201], v150 offset:39936
	global_load_lds_dwordx4 v134, s[14:15]
	s_mov_b32 m0, s26
	s_nop 0
	global_load_lds_dwordx4 v130, s[14:15]
	s_waitcnt lgkmcnt(8)
	s_setprio 1
	s_barrier
	s_waitcnt lgkmcnt(7)
	v_mfma_f32_16x16x32_bf16 v[124:127], v[152:155], v[168:171], v[124:127]
	v_mfma_f32_16x16x32_bf16 v[120:123], v[160:163], v[168:171], v[120:123]
	s_waitcnt lgkmcnt(5)
	v_mfma_f32_16x16x32_bf16 v[108:111], v[152:155], v[176:179], v[108:111]
	v_mfma_f32_16x16x32_bf16 v[104:107], v[160:163], v[176:179], v[104:107]
	s_waitcnt lgkmcnt(3)
	v_mfma_f32_16x16x32_bf16 v[92:95], v[152:155], v[184:187], v[92:95]
	v_mfma_f32_16x16x32_bf16 v[88:91], v[160:163], v[184:187], v[88:91]
	s_waitcnt lgkmcnt(1)
	v_mfma_f32_16x16x32_bf16 v[76:79], v[152:155], v[192:195], v[76:79]
	v_mfma_f32_16x16x32_bf16 v[72:75], v[160:163], v[192:195], v[72:75]
	v_mfma_f32_16x16x32_bf16 v[124:127], v[156:159], v[172:175], v[124:127]
	s_add_i32 s14, 0, 0x1c000
	v_mfma_f32_16x16x32_bf16 v[120:123], v[164:167], v[172:175], v[120:123]
	s_add_i32 s15, s49, s22
	v_mfma_f32_16x16x32_bf16 v[108:111], v[156:159], v[180:183], v[108:111]
	v_add_u32_e32 v196, s14, v148
	v_mfma_f32_16x16x32_bf16 v[104:107], v[164:167], v[180:183], v[104:107]
	v_lshl_add_u64 v[144:145], v[144:145], 0, s[42:43]
	v_mfma_f32_16x16x32_bf16 v[92:95], v[156:159], v[188:191], v[92:95]
	v_mfma_f32_16x16x32_bf16 v[88:91], v[164:167], v[188:191], v[88:91]
	s_waitcnt lgkmcnt(0)
	v_mfma_f32_16x16x32_bf16 v[76:79], v[156:159], v[198:201], v[76:79]
	v_mfma_f32_16x16x32_bf16 v[72:75], v[164:167], v[198:201], v[72:75]
	s_barrier
	s_setprio 0
	s_mov_b32 m0, s15
	ds_read_b128 v[202:205], v196
	ds_read_b128 v[206:209], v196 offset:1024
	ds_read_b128 v[210:213], v196 offset:2048
	ds_read_b128 v[214:217], v196 offset:3072
	global_load_lds_dwordx4 v[144:145], off
	v_lshl_add_u64 v[144:145], v[218:219], 0, s[42:43]
	s_add_i32 m0, s15, 0x2000
	s_nop 0
	global_load_lds_dwordx4 v[144:145], off
	s_setprio 1
	s_barrier
	s_waitcnt lgkmcnt(3)
	v_mfma_f32_16x16x32_bf16 v[116:119], v[202:205], v[168:171], v[116:119]
	s_waitcnt lgkmcnt(1)
	v_mfma_f32_16x16x32_bf16 v[112:115], v[210:213], v[168:171], v[112:115]
	v_mfma_f32_16x16x32_bf16 v[100:103], v[202:205], v[176:179], v[100:103]
	v_mfma_f32_16x16x32_bf16 v[96:99], v[210:213], v[176:179], v[96:99]
	v_mfma_f32_16x16x32_bf16 v[84:87], v[202:205], v[184:187], v[84:87]
	v_mfma_f32_16x16x32_bf16 v[80:83], v[210:213], v[184:187], v[80:83]
	v_mfma_f32_16x16x32_bf16 v[68:71], v[202:205], v[192:195], v[68:71]
	v_mfma_f32_16x16x32_bf16 v[64:67], v[210:213], v[192:195], v[64:67]
	v_mfma_f32_16x16x32_bf16 v[116:119], v[206:209], v[172:175], v[116:119]
	s_mov_b32 m0, s30
	s_waitcnt lgkmcnt(0)
	v_mfma_f32_16x16x32_bf16 v[112:115], v[214:217], v[172:175], v[112:115]
	v_lshl_add_u64 v[144:145], v[220:221], 0, s[42:43]
	v_mfma_f32_16x16x32_bf16 v[100:103], v[206:209], v[180:183], v[100:103]
	v_mfma_f32_16x16x32_bf16 v[96:99], v[214:217], v[180:183], v[96:99]
	v_mfma_f32_16x16x32_bf16 v[84:87], v[206:209], v[188:191], v[84:87]
	v_mfma_f32_16x16x32_bf16 v[80:83], v[214:217], v[188:191], v[80:83]
	v_mfma_f32_16x16x32_bf16 v[68:71], v[206:209], v[198:201], v[68:71]
	v_mfma_f32_16x16x32_bf16 v[64:67], v[214:217], v[198:201], v[64:67]
	s_barrier
	s_setprio 0
	ds_read_b128 v[168:171], v150 offset:49152
	ds_read_b128 v[172:175], v150 offset:50176
	ds_read_b128 v[176:179], v150 offset:51200
	ds_read_b128 v[180:183], v150 offset:52224
	ds_read_b128 v[184:187], v150 offset:53248
	ds_read_b128 v[188:191], v150 offset:54272
	ds_read_b128 v[192:195], v150 offset:55296
	ds_read_b128 v[198:201], v150 offset:56320
	global_load_lds_dwordx4 v[144:145], off
	v_lshl_add_u64 v[144:145], v[222:223], 0, s[42:43]
	s_mov_b32 m0, s31
	s_nop 0
	global_load_lds_dwordx4 v[144:145], off
	s_waitcnt vmcnt(10)
	s_setprio 1
	s_barrier
; DI unsigned pack2(float a, float b) { f32x2 v = {a, b}; hwbf16x2 r = __builtin_convertvector(v, hwbf16x2); return __builtin_bit_cast(unsigned, r); }
; DI float bflo(unsigned w) { return __uint_as_float(w << 16); }
; DI float bfhi(unsigned w) { return __uint_as_float(w & 0xffff0000u); }
; #define PG8_STAGE(bufoff, gbase, voff) do { _Pragma("unroll") for (int _i = 0; _i < 2; ++_i) \
;         __builtin_amdgcn_global_load_lds((const unsigned*)((const char*)(gbase) + (voff)[_i]), (LAS unsigned*)(lds + (bufoff) + ldsw + _i * 8192), 16, 0, 0); } while (0)
; #define PG8_LDA(dst, b, h) do { _Pragma("unroll") for (int m = 0; m < 4; ++m) _Pragma("unroll") for (int k = 0; k < 2; ++k) dst[m][k] = *(const LAS bf16x8*)(lds + PG8_SA(b, h) + aoff + m * 2048 + k * 1024); } while (0)
; #define PG8_BAR __builtin_amdgcn_s_barrier()
;     DI void operator()(const f32x4 (&acc)[2][2][4][2], const Unit& u, int wr, int wc, int fr, int fq) const {
;     ...
;             for (int m = 0; m < 4; ++m) { const size_t ro = (size_t)(row0 + ai * HALF + m * 16) * D + col0;
; #pragma unroll
;                 for (int bj = 0; bj < 2; ++bj) {
;                     f32x4 x0, x1;
;                     if constexpr (IB) { const u32x4 w = *(const u32x4*)((const bf16_t*)Xin + ro + bj * HALF);
;                         x0 = (f32x4){bflo(w[0]), bfhi(w[0]), bflo(w[1]), bfhi(w[1])}; x1 = (f32x4){bflo(w[2]), bfhi(w[2]), bflo(w[3]), bfhi(w[3])}; }
;                     else { x0 = *(const f32x4*)((const float*)Xin + ro + bj * HALF); x1 = *(const f32x4*)((const float*)Xin + ro + bj * HALF + 4); }
;                     x0 += acc[ai][bj][m][0] * sc[bj][0]; x1 += acc[ai][bj][m][1] * sc[bj][1];
;                     if constexpr (OB) { u32x4 o; o[0] = pack2(x0[0], x0[1]); o[1] = pack2(x0[2], x0[3]); o[2] = pack2(x1[0], x1[1]); o[3] = pack2(x1[2], x1[3]);
;                         *(u32x4*)((bf16_t*)Xout + ro + bj * HALF) = o; }
; template <class Map, class Epi>
; DI void gemm_phase(LAS unsigned char* lds, const Map& MP, const Epi& E, const int nM, const int nN, const int K, const int lda, const int ldb) {
;     ...
;             PG8_LDA(At, 1, 1); PG8_STAGE(PG8_SA(1, 0), a3, voffA);
;             PG8_BAR; PG8_WAIT_L(0); PG8_MMA(1, 0, At, B0); PG8_BAR; PG8_SCHED;
;             PG8_STAGE(PG8_SB(1, 1), b3 + hstepB, voffB);
;             PG8_WAIT_V(6); PG8_BAR; PG8_MMA(1, 1, At, B1); PG8_BAR;
;         }
	s_waitcnt lgkmcnt(7)
	v_mfma_f32_16x16x32_bf16 v[60:63], v[152:155], v[168:171], v[60:63]
	v_mfma_f32_16x16x32_bf16 v[56:59], v[160:163], v[168:171], v[56:59]
	s_waitcnt lgkmcnt(5)
	v_mfma_f32_16x16x32_bf16 v[44:47], v[152:155], v[176:179], v[44:47]
	v_mfma_f32_16x16x32_bf16 v[40:43], v[160:163], v[176:179], v[40:43]
	s_waitcnt lgkmcnt(3)
	v_mfma_f32_16x16x32_bf16 v[28:31], v[152:155], v[184:187], v[28:31]
	v_mfma_f32_16x16x32_bf16 v[24:27], v[160:163], v[184:187], v[24:27]
	s_waitcnt lgkmcnt(1)
	v_mfma_f32_16x16x32_bf16 v[12:15], v[152:155], v[192:195], v[12:15]
	v_mfma_f32_16x16x32_bf16 v[8:11], v[160:163], v[192:195], v[8:11]
	v_mfma_f32_16x16x32_bf16 v[60:63], v[156:159], v[172:175], v[60:63]
	s_add_u32 s12, s12, 0x80080
	s_addc_u32 s13, s13, 0
	v_mfma_f32_16x16x32_bf16 v[56:59], v[164:167], v[172:175], v[56:59]
	s_add_i32 s14, s14, s22
	v_mfma_f32_16x16x32_bf16 v[44:47], v[156:159], v[180:183], v[44:47]
	v_mfma_f32_16x16x32_bf16 v[40:43], v[164:167], v[180:183], v[40:43]
	v_mfma_f32_16x16x32_bf16 v[28:31], v[156:159], v[188:191], v[28:31]
	v_mfma_f32_16x16x32_bf16 v[24:27], v[164:167], v[188:191], v[24:27]
	s_waitcnt lgkmcnt(0)
	v_mfma_f32_16x16x32_bf16 v[12:15], v[156:159], v[198:201], v[12:15]
	v_mfma_f32_16x16x32_bf16 v[8:11], v[164:167], v[198:201], v[8:11]
	s_barrier
	s_setprio 0
	s_mov_b32 m0, s14
	s_nop 0
	global_load_lds_dwordx4 v132, s[12:13]
	s_add_i32 m0, s14, 0x2000
	s_nop 0
	global_load_lds_dwordx4 v128, s[12:13]
	s_waitcnt vmcnt(6)
	s_setprio 1
	s_barrier
	v_mfma_f32_16x16x32_bf16 v[52:55], v[202:205], v[168:171], v[52:55]
	v_mfma_f32_16x16x32_bf16 v[48:51], v[210:213], v[168:171], v[48:51]
	ds_read_b128 v[152:155], v149
	v_mfma_f32_16x16x32_bf16 v[36:39], v[202:205], v[176:179], v[36:39]
	v_mfma_f32_16x16x32_bf16 v[32:35], v[210:213], v[176:179], v[32:35]
	ds_read_b128 v[156:159], v149 offset:1024
	v_mfma_f32_16x16x32_bf16 v[20:23], v[202:205], v[184:187], v[20:23]
	v_mfma_f32_16x16x32_bf16 v[16:19], v[210:213], v[184:187], v[16:19]
	ds_read_b128 v[160:163], v149 offset:2048
	v_mfma_f32_16x16x32_bf16 v[4:7], v[202:205], v[192:195], v[4:7]
	v_mfma_f32_16x16x32_bf16 v[0:3], v[210:213], v[192:195], v[0:3]
	ds_read_b128 v[164:167], v149 offset:3072
	v_mfma_f32_16x16x32_bf16 v[52:55], v[206:209], v[172:175], v[52:55]
	s_add_i32 s3, s3, 2
	v_mfma_f32_16x16x32_bf16 v[48:51], v[214:217], v[172:175], v[48:51]
	s_add_u32 s47, s47, 0x100
	s_addc_u32 s48, s48, 0
	v_mfma_f32_16x16x32_bf16 v[36:39], v[206:209], v[180:183], v[36:39]
	s_add_u32 s10, s10, 0x100
	s_addc_u32 s11, s11, 0
	v_mfma_f32_16x16x32_bf16 v[32:35], v[214:217], v[180:183], v[32:35]
	s_cmp_gt_u32 s3, 29
	v_mfma_f32_16x16x32_bf16 v[20:23], v[206:209], v[188:191], v[20:23]
	v_mfma_f32_16x16x32_bf16 v[16:19], v[214:217], v[188:191], v[16:19]
	v_mfma_f32_16x16x32_bf16 v[4:7], v[206:209], v[198:201], v[4:7]
	v_mfma_f32_16x16x32_bf16 v[0:3], v[214:217], v[198:201], v[0:3]
	s_barrier
	s_setprio 0
	s_cbranch_scc0 .LBB1_1764
	s_waitcnt lgkmcnt(0)
	v_mov_b32_e32 v152, v147
	v_mov_b32_e32 v144, v146
	s_lshl_b32 s2, s2, 8
	s_or_b32 s2, s2, s29
	v_lshl_add_u32 v144, v144, 3, s2
	s_lshl_b32 s2, s8, 8
	s_add_i32 s2, s2, s28
	v_add_u32_e32 v152, s2, v152
	v_ashrrev_i32_e32 v153, 31, v152
	v_lshlrev_b64 v[152:153], 12, v[152:153]
	v_ashrrev_i32_e32 v145, 31, v144
	v_lshl_add_u64 v[152:153], s[4:5], 0, v[152:153]
	v_lshl_add_u64 v[144:145], v[144:145], 1, v[152:153]
	global_load_dwordx4 v[160:163], v[144:145], off
	global_load_dwordx4 v[164:167], v[144:145], off offset:256
	s_mov_b64 s[98:99], 0x10000
	v_lshl_add_u64 v[154:155], v[144:145], 0, s[98:99]
	global_load_dwordx4 v[168:171], v[154:155], off
	global_load_dwordx4 v[172:175], v[154:155], off offset:256
	s_mov_b64 s[98:99], 0x20000
	v_lshl_add_u64 v[154:155], v[144:145], 0, s[98:99]
	global_load_dwordx4 v[176:179], v[154:155], off
	global_load_dwordx4 v[180:183], v[154:155], off offset:256
	s_mov_b64 s[98:99], 0x30000
	v_lshl_add_u64 v[154:155], v[144:145], 0, s[98:99]
	global_load_dwordx4 v[184:187], v[154:155], off
	global_load_dwordx4 v[188:191], v[154:155], off offset:256
	s_mov_b64 s[98:99], 0x80000
	v_lshl_add_u64 v[154:155], v[144:145], 0, s[98:99]
	global_load_dwordx4 v[192:195], v[154:155], off
	global_load_dwordx4 v[198:201], v[154:155], off offset:256
	s_mov_b64 s[98:99], 0x90000
	v_lshl_add_u64 v[154:155], v[144:145], 0, s[98:99]
	global_load_dwordx4 v[202:205], v[154:155], off
	global_load_dwordx4 v[206:209], v[154:155], off offset:256
	s_mov_b64 s[98:99], 0xa0000
	v_lshl_add_u64 v[154:155], v[144:145], 0, s[98:99]
	global_load_dwordx4 v[210:213], v[154:155], off
	global_load_dwordx4 v[214:217], v[154:155], off offset:256
	s_mov_b64 s[98:99], 0xb0000
	v_lshl_add_u64 v[154:155], v[144:145], 0, s[98:99]
	global_load_dwordx4 v[248:251], v[154:155], off
	global_load_dwordx4 v[252:255], v[154:155], off offset:256
	s_waitcnt vmcnt(15)
	s_nop 1
	v_mov_b32_e32 v152, v160
	v_mov_b32_e32 v153, v161
	v_mov_b32_e32 v154, v162
	v_mov_b32_e32 v155, v163
	s_mov_b64 s[2:3], 0x10000
	s_mov_b32 s8, s46
	s_mov_b64 s[10:11], s[6:7]
	s_mov_b64 s[12:13], s[52:53]
	s_waitcnt lgkmcnt(0)
	v_lshlrev_b32_e32 v156, 16, v152
	v_and_b32_e32 v157, 0xffff0000, v152
	v_lshlrev_b32_e32 v152, 16, v153
	v_and_b32_e32 v153, 0xffff0000, v153
	v_lshlrev_b32_e32 v158, 16, v154
	v_and_b32_e32 v159, 0xffff0000, v154
	v_lshlrev_b32_e32 v154, 16, v155
	v_and_b32_e32 v155, 0xffff0000, v155
	v_pk_add_f32 v[126:127], v[126:127], v[152:153]
	v_pk_add_f32 v[124:125], v[124:125], v[156:157]
	v_pk_add_f32 v[152:153], v[122:123], v[154:155]
	v_pk_add_f32 v[122:123], v[120:121], v[158:159]
	v_cvt_pk_bf16_f32 v120, v124, v125
	v_cvt_pk_bf16_f32 v121, v126, v127
	v_cvt_pk_bf16_f32 v122, v122, v123
	v_cvt_pk_bf16_f32 v123, v152, v153
	global_store_dwordx4 v[144:145], v[120:123], off
	s_waitcnt vmcnt(15)
; DI unsigned pack2(float a, float b) { f32x2 v = {a, b}; hwbf16x2 r = __builtin_convertvector(v, hwbf16x2); return __builtin_bit_cast(unsigned, r); }
; DI float bflo(unsigned w) { return __uint_as_float(w << 16); }
; DI float bfhi(unsigned w) { return __uint_as_float(w & 0xffff0000u); }
;     DI void operator()(const f32x4 (&acc)[2][2][4][2], const Unit& u, int wr, int wc, int fr, int fq) const {
;     ...
;             for (int m = 0; m < 4; ++m) { const size_t ro = (size_t)(row0 + ai * HALF + m * 16) * D + col0;
; #pragma unroll
;                 for (int bj = 0; bj < 2; ++bj) {
;                     f32x4 x0, x1;
;                     if constexpr (IB) { const u32x4 w = *(const u32x4*)((const bf16_t*)Xin + ro + bj * HALF);
;                         x0 = (f32x4){bflo(w[0]), bfhi(w[0]), bflo(w[1]), bfhi(w[1])}; x1 = (f32x4){bflo(w[2]), bfhi(w[2]), bflo(w[3]), bfhi(w[3])}; }
;                     else { x0 = *(const f32x4*)((const float*)Xin + ro + bj * HALF); x1 = *(const f32x4*)((const float*)Xin + ro + bj * HALF + 4); }
;                     x0 += acc[ai][bj][m][0] * sc[bj][0]; x1 += acc[ai][bj][m][1] * sc[bj][1];
;                     if constexpr (OB) { u32x4 o; o[0] = pack2(x0[0], x0[1]); o[1] = pack2(x0[2], x0[3]); o[2] = pack2(x1[0], x1[1]); o[3] = pack2(x1[2], x1[3]);
;                         *(u32x4*)((bf16_t*)Xout + ro + bj * HALF) = o; }
;                     else { *(f32x4*)((float*)Xout + ro + bj * HALF) = x0; *(f32x4*)((float*)Xout + ro + bj * HALF + 4) = x1; } } }
	s_nop 1
	v_mov_b32_e32 v120, v164
	v_mov_b32_e32 v121, v165
	v_mov_b32_e32 v122, v166
	v_mov_b32_e32 v123, v167
	s_waitcnt lgkmcnt(0)
	v_lshlrev_b32_e32 v124, 16, v120
	v_and_b32_e32 v125, 0xffff0000, v120
	v_lshlrev_b32_e32 v120, 16, v121
	v_and_b32_e32 v121, 0xffff0000, v121
	v_lshlrev_b32_e32 v126, 16, v122
	v_and_b32_e32 v127, 0xffff0000, v122
	v_lshlrev_b32_e32 v122, 16, v123
	v_and_b32_e32 v123, 0xffff0000, v123
	v_pk_add_f32 v[116:117], v[116:117], v[124:125]
	v_pk_add_f32 v[118:119], v[118:119], v[120:121]
	v_pk_add_f32 v[120:121], v[114:115], v[122:123]
	v_pk_add_f32 v[114:115], v[112:113], v[126:127]
	v_cvt_pk_bf16_f32 v112, v116, v117
	v_lshl_add_u64 v[116:117], v[144:145], 0, s[2:3]
	s_mov_b32 s2, 0x10000
	v_cvt_pk_bf16_f32 v113, v118, v119
	v_add_co_u32_e32 v118, vcc, s2, v144
	v_cvt_pk_bf16_f32 v114, v114, v115
	v_cvt_pk_bf16_f32 v115, v120, v121
	v_addc_co_u32_e32 v119, vcc, 0, v145, vcc
	global_store_dwordx4 v[144:145], v[112:115], off offset:256
	s_waitcnt vmcnt(15)
	s_nop 1
	v_mov_b32_e32 v112, v168
	v_mov_b32_e32 v113, v169
	v_mov_b32_e32 v114, v170
	v_mov_b32_e32 v115, v171
	s_mov_b64 s[2:3], 0x20000
	s_waitcnt lgkmcnt(0)
	v_lshlrev_b32_e32 v120, 16, v112
	v_and_b32_e32 v121, 0xffff0000, v112
	v_lshlrev_b32_e32 v112, 16, v113
	v_and_b32_e32 v113, 0xffff0000, v113
	v_lshlrev_b32_e32 v122, 16, v114
	v_and_b32_e32 v123, 0xffff0000, v114
	v_lshlrev_b32_e32 v114, 16, v115
	v_and_b32_e32 v115, 0xffff0000, v115
	v_pk_add_f32 v[110:111], v[110:111], v[112:113]
	v_pk_add_f32 v[108:109], v[108:109], v[120:121]
	v_pk_add_f32 v[112:113], v[106:107], v[114:115]
	v_pk_add_f32 v[106:107], v[104:105], v[122:123]
	v_cvt_pk_bf16_f32 v104, v108, v109
	v_cvt_pk_bf16_f32 v105, v110, v111
	v_cvt_pk_bf16_f32 v106, v106, v107
	v_cvt_pk_bf16_f32 v107, v112, v113
	global_store_dwordx4 v[118:119], v[104:107], off
	s_waitcnt vmcnt(15)
	s_nop 1
	v_mov_b32_e32 v104, v172
	v_mov_b32_e32 v105, v173
	v_mov_b32_e32 v106, v174
	v_mov_b32_e32 v107, v175
	s_waitcnt lgkmcnt(0)
	v_lshlrev_b32_e32 v108, 16, v104
	v_and_b32_e32 v109, 0xffff0000, v104
	v_lshlrev_b32_e32 v104, 16, v105
	v_and_b32_e32 v105, 0xffff0000, v105
	v_lshlrev_b32_e32 v110, 16, v106
	v_and_b32_e32 v111, 0xffff0000, v106
	v_lshlrev_b32_e32 v106, 16, v107
	v_and_b32_e32 v107, 0xffff0000, v107
	v_pk_add_f32 v[100:101], v[100:101], v[108:109]
	v_pk_add_f32 v[102:103], v[102:103], v[104:105]
	v_pk_add_f32 v[104:105], v[98:99], v[106:107]
	v_pk_add_f32 v[98:99], v[96:97], v[110:111]
	v_cvt_pk_bf16_f32 v96, v100, v101
	v_lshl_add_u64 v[100:101], v[144:145], 0, s[2:3]
	s_mov_b32 s2, 0x20000
	v_cvt_pk_bf16_f32 v97, v102, v103
	v_add_co_u32_e32 v102, vcc, s2, v144
	v_cvt_pk_bf16_f32 v98, v98, v99
	v_cvt_pk_bf16_f32 v99, v104, v105
	v_addc_co_u32_e32 v103, vcc, 0, v145, vcc
	global_store_dwordx4 v[116:117], v[96:99], off offset:256
	s_waitcnt vmcnt(15)
	s_nop 1
	v_mov_b32_e32 v96, v176
	v_mov_b32_e32 v97, v177
	v_mov_b32_e32 v98, v178
	v_mov_b32_e32 v99, v179
	s_mov_b64 s[2:3], 0x30000
	s_waitcnt lgkmcnt(0)
	v_lshlrev_b32_e32 v104, 16, v96
	v_and_b32_e32 v105, 0xffff0000, v96
	v_lshlrev_b32_e32 v96, 16, v97
	v_and_b32_e32 v97, 0xffff0000, v97
	v_lshlrev_b32_e32 v106, 16, v98
	v_and_b32_e32 v107, 0xffff0000, v98
	v_lshlrev_b32_e32 v98, 16, v99
	v_and_b32_e32 v99, 0xffff0000, v99
	v_pk_add_f32 v[94:95], v[94:95], v[96:97]
	v_pk_add_f32 v[92:93], v[92:93], v[104:105]
	v_pk_add_f32 v[96:97], v[90:91], v[98:99]
	v_pk_add_f32 v[90:91], v[88:89], v[106:107]
	v_cvt_pk_bf16_f32 v88, v92, v93
	v_cvt_pk_bf16_f32 v89, v94, v95
	v_cvt_pk_bf16_f32 v90, v90, v91
	v_cvt_pk_bf16_f32 v91, v96, v97
	global_store_dwordx4 v[102:103], v[88:91], off
	s_waitcnt vmcnt(15)
	s_nop 1
	v_mov_b32_e32 v88, v180
	v_mov_b32_e32 v89, v181
	v_mov_b32_e32 v90, v182
	v_mov_b32_e32 v91, v183
	s_waitcnt lgkmcnt(0)
	v_lshlrev_b32_e32 v92, 16, v88
	v_and_b32_e32 v93, 0xffff0000, v88
	v_lshlrev_b32_e32 v88, 16, v89
	v_and_b32_e32 v89, 0xffff0000, v89
	v_lshlrev_b32_e32 v94, 16, v90
	v_and_b32_e32 v95, 0xffff0000, v90
	v_lshlrev_b32_e32 v90, 16, v91
	v_and_b32_e32 v91, 0xffff0000, v91
	v_pk_add_f32 v[86:87], v[86:87], v[88:89]
	v_pk_add_f32 v[84:85], v[84:85], v[92:93]
	v_pk_add_f32 v[88:89], v[82:83], v[90:91]
	v_pk_add_f32 v[82:83], v[80:81], v[94:95]
	v_cvt_pk_bf16_f32 v80, v84, v85
	v_cvt_pk_bf16_f32 v81, v86, v87
	v_cvt_pk_bf16_f32 v82, v82, v83
	v_cvt_pk_bf16_f32 v83, v88, v89
	global_store_dwordx4 v[100:101], v[80:83], off offset:256
	s_nop 1
	v_lshl_add_u64 v[80:81], v[144:145], 0, s[2:3]
	s_mov_b32 s2, 0x30000
	v_add_co_u32_e32 v86, vcc, s2, v144
	s_mov_b64 s[2:3], 0x80000
	s_nop 0
	v_addc_co_u32_e32 v87, vcc, 0, v145, vcc
	s_waitcnt vmcnt(15)
	s_nop 1
	v_mov_b32_e32 v82, v184
	v_mov_b32_e32 v83, v185
	v_mov_b32_e32 v84, v186
	v_mov_b32_e32 v85, v187
	s_waitcnt lgkmcnt(0)
	v_lshlrev_b32_e32 v88, 16, v82
	v_and_b32_e32 v89, 0xffff0000, v82
	v_lshlrev_b32_e32 v82, 16, v83
	v_and_b32_e32 v83, 0xffff0000, v83
	v_lshlrev_b32_e32 v90, 16, v84
	v_and_b32_e32 v91, 0xffff0000, v84
	v_lshlrev_b32_e32 v84, 16, v85
	v_and_b32_e32 v85, 0xffff0000, v85
	v_pk_add_f32 v[78:79], v[78:79], v[82:83]
	v_pk_add_f32 v[76:77], v[76:77], v[88:89]
	v_pk_add_f32 v[82:83], v[74:75], v[84:85]
	v_pk_add_f32 v[74:75], v[72:73], v[90:91]
	v_cvt_pk_bf16_f32 v72, v76, v77
	v_cvt_pk_bf16_f32 v73, v78, v79
	v_cvt_pk_bf16_f32 v74, v74, v75
	v_cvt_pk_bf16_f32 v75, v82, v83
	global_store_dwordx4 v[86:87], v[72:75], off
	s_waitcnt vmcnt(15)
	s_nop 1
	v_mov_b32_e32 v72, v188
	v_mov_b32_e32 v73, v189
	v_mov_b32_e32 v74, v190
	v_mov_b32_e32 v75, v191
	s_waitcnt lgkmcnt(0)
; DI unsigned pack2(float a, float b) { f32x2 v = {a, b}; hwbf16x2 r = __builtin_convertvector(v, hwbf16x2); return __builtin_bit_cast(unsigned, r); }
; DI float bflo(unsigned w) { return __uint_as_float(w << 16); }
; DI float bfhi(unsigned w) { return __uint_as_float(w & 0xffff0000u); }
;     DI void operator()(const f32x4 (&acc)[2][2][4][2], const Unit& u, int wr, int wc, int fr, int fq) const {
;     ...
;             for (int m = 0; m < 4; ++m) { const size_t ro = (size_t)(row0 + ai * HALF + m * 16) * D + col0;
; #pragma unroll
;                 for (int bj = 0; bj < 2; ++bj) {
;                     f32x4 x0, x1;
;                     if constexpr (IB) { const u32x4 w = *(const u32x4*)((const bf16_t*)Xin + ro + bj * HALF);
;                         x0 = (f32x4){bflo(w[0]), bfhi(w[0]), bflo(w[1]), bfhi(w[1])}; x1 = (f32x4){bflo(w[2]), bfhi(w[2]), bflo(w[3]), bfhi(w[3])}; }
;                     else { x0 = *(const f32x4*)((const float*)Xin + ro + bj * HALF); x1 = *(const f32x4*)((const float*)Xin + ro + bj * HALF + 4); }
;                     x0 += acc[ai][bj][m][0] * sc[bj][0]; x1 += acc[ai][bj][m][1] * sc[bj][1];
;                     if constexpr (OB) { u32x4 o; o[0] = pack2(x0[0], x0[1]); o[1] = pack2(x0[2], x0[3]); o[2] = pack2(x1[0], x1[1]); o[3] = pack2(x1[2], x1[3]);
;                         *(u32x4*)((bf16_t*)Xout + ro + bj * HALF) = o; }
;                     else { *(f32x4*)((float*)Xout + ro + bj * HALF) = x0; *(f32x4*)((float*)Xout + ro + bj * HALF + 4) = x1; } } }
	v_lshlrev_b32_e32 v76, 16, v72
	v_and_b32_e32 v77, 0xffff0000, v72
	v_lshlrev_b32_e32 v72, 16, v73
	v_and_b32_e32 v73, 0xffff0000, v73
	v_lshlrev_b32_e32 v78, 16, v74
	v_and_b32_e32 v79, 0xffff0000, v74
	v_lshlrev_b32_e32 v74, 16, v75
	v_and_b32_e32 v75, 0xffff0000, v75
	v_pk_add_f32 v[70:71], v[70:71], v[72:73]
	v_pk_add_f32 v[68:69], v[68:69], v[76:77]
	v_pk_add_f32 v[72:73], v[66:67], v[74:75]
	v_pk_add_f32 v[66:67], v[64:65], v[78:79]
	v_cvt_pk_bf16_f32 v64, v68, v69
	v_cvt_pk_bf16_f32 v65, v70, v71
	v_cvt_pk_bf16_f32 v66, v66, v67
	v_cvt_pk_bf16_f32 v67, v72, v73
	global_store_dwordx4 v[80:81], v[64:67], off offset:256
	s_nop 1
	v_lshl_add_u64 v[64:65], v[144:145], 0, s[2:3]
	s_mov_b32 s2, 0x80000
	v_add_co_u32_e32 v70, vcc, s2, v144
	s_mov_b64 s[2:3], 0x90000
	s_nop 0
	v_addc_co_u32_e32 v71, vcc, 0, v145, vcc
	s_waitcnt vmcnt(15)
	s_nop 1
	v_mov_b32_e32 v66, v192
	v_mov_b32_e32 v67, v193
	v_mov_b32_e32 v68, v194
	v_mov_b32_e32 v69, v195
	s_waitcnt lgkmcnt(0)
	v_lshlrev_b32_e32 v72, 16, v66
	v_and_b32_e32 v73, 0xffff0000, v66
	v_lshlrev_b32_e32 v66, 16, v67
	v_and_b32_e32 v67, 0xffff0000, v67
	v_lshlrev_b32_e32 v74, 16, v68
	v_and_b32_e32 v75, 0xffff0000, v68
	v_lshlrev_b32_e32 v68, 16, v69
	v_and_b32_e32 v69, 0xffff0000, v69
	v_pk_add_f32 v[62:63], v[62:63], v[66:67]
	v_pk_add_f32 v[60:61], v[60:61], v[72:73]
	v_pk_add_f32 v[66:67], v[58:59], v[68:69]
	v_pk_add_f32 v[58:59], v[56:57], v[74:75]
	v_cvt_pk_bf16_f32 v56, v60, v61
	v_cvt_pk_bf16_f32 v57, v62, v63
	v_cvt_pk_bf16_f32 v58, v58, v59
	v_cvt_pk_bf16_f32 v59, v66, v67
	global_store_dwordx4 v[70:71], v[56:59], off
	s_waitcnt vmcnt(15)
	s_nop 1
	v_mov_b32_e32 v56, v198
	v_mov_b32_e32 v57, v199
	v_mov_b32_e32 v58, v200
	v_mov_b32_e32 v59, v201
	s_waitcnt lgkmcnt(0)
	v_lshlrev_b32_e32 v60, 16, v56
	v_and_b32_e32 v61, 0xffff0000, v56
	v_lshlrev_b32_e32 v56, 16, v57
	v_and_b32_e32 v57, 0xffff0000, v57
	v_lshlrev_b32_e32 v62, 16, v58
	v_and_b32_e32 v63, 0xffff0000, v58
	v_lshlrev_b32_e32 v58, 16, v59
	v_and_b32_e32 v59, 0xffff0000, v59
	v_pk_add_f32 v[54:55], v[54:55], v[56:57]
	v_pk_add_f32 v[52:53], v[52:53], v[60:61]
	v_pk_add_f32 v[56:57], v[50:51], v[58:59]
	v_pk_add_f32 v[50:51], v[48:49], v[62:63]
	v_cvt_pk_bf16_f32 v48, v52, v53
	v_cvt_pk_bf16_f32 v49, v54, v55
	v_cvt_pk_bf16_f32 v50, v50, v51
	v_cvt_pk_bf16_f32 v51, v56, v57
	global_store_dwordx4 v[64:65], v[48:51], off offset:256
	s_nop 1
	v_lshl_add_u64 v[48:49], v[144:145], 0, s[2:3]
	s_mov_b32 s2, 0x90000
	v_add_co_u32_e32 v54, vcc, s2, v144
	s_mov_b64 s[2:3], 0xa0000
	s_nop 0
	v_addc_co_u32_e32 v55, vcc, 0, v145, vcc
	s_waitcnt vmcnt(15)
	s_nop 1
	v_mov_b32_e32 v50, v202
	v_mov_b32_e32 v51, v203
	v_mov_b32_e32 v52, v204
	v_mov_b32_e32 v53, v205
	s_waitcnt lgkmcnt(0)
	v_lshlrev_b32_e32 v56, 16, v50
	v_and_b32_e32 v57, 0xffff0000, v50
	v_lshlrev_b32_e32 v50, 16, v51
	v_and_b32_e32 v51, 0xffff0000, v51
	v_lshlrev_b32_e32 v58, 16, v52
	v_and_b32_e32 v59, 0xffff0000, v52
	v_lshlrev_b32_e32 v52, 16, v53
	v_and_b32_e32 v53, 0xffff0000, v53
	v_pk_add_f32 v[46:47], v[46:47], v[50:51]
	v_pk_add_f32 v[44:45], v[44:45], v[56:57]
	v_pk_add_f32 v[50:51], v[42:43], v[52:53]
	v_pk_add_f32 v[42:43], v[40:41], v[58:59]
	v_cvt_pk_bf16_f32 v40, v44, v45
	v_cvt_pk_bf16_f32 v41, v46, v47
	v_cvt_pk_bf16_f32 v42, v42, v43
	v_cvt_pk_bf16_f32 v43, v50, v51
	global_store_dwordx4 v[54:55], v[40:43], off
	s_waitcnt vmcnt(15)
	s_nop 1
	v_mov_b32_e32 v40, v206
	v_mov_b32_e32 v41, v207
	v_mov_b32_e32 v42, v208
	v_mov_b32_e32 v43, v209
	s_waitcnt lgkmcnt(0)
; DI unsigned pack2(float a, float b) { f32x2 v = {a, b}; hwbf16x2 r = __builtin_convertvector(v, hwbf16x2); return __builtin_bit_cast(unsigned, r); }
; DI float bflo(unsigned w) { return __uint_as_float(w << 16); }
; DI float bfhi(unsigned w) { return __uint_as_float(w & 0xffff0000u); }
; #define PG8_WAIT_V(n) asm volatile("s_waitcnt vmcnt(" #n ")" ::: "memory")
; #define PG8_BAR __builtin_amdgcn_s_barrier()
;     DI void operator()(const f32x4 (&acc)[2][2][4][2], const Unit& u, int wr, int wc, int fr, int fq) const {
;     ...
;             for (int m = 0; m < 4; ++m) { const size_t ro = (size_t)(row0 + ai * HALF + m * 16) * D + col0;
; #pragma unroll
;                 for (int bj = 0; bj < 2; ++bj) {
;                     f32x4 x0, x1;
;                     if constexpr (IB) { const u32x4 w = *(const u32x4*)((const bf16_t*)Xin + ro + bj * HALF);
;                         x0 = (f32x4){bflo(w[0]), bfhi(w[0]), bflo(w[1]), bfhi(w[1])}; x1 = (f32x4){bflo(w[2]), bfhi(w[2]), bflo(w[3]), bfhi(w[3])}; }
;                     else { x0 = *(const f32x4*)((const float*)Xin + ro + bj * HALF); x1 = *(const f32x4*)((const float*)Xin + ro + bj * HALF + 4); }
;                     x0 += acc[ai][bj][m][0] * sc[bj][0]; x1 += acc[ai][bj][m][1] * sc[bj][1];
;                     if constexpr (OB) { u32x4 o; o[0] = pack2(x0[0], x0[1]); o[1] = pack2(x0[2], x0[3]); o[2] = pack2(x1[0], x1[1]); o[3] = pack2(x1[2], x1[3]);
;                         *(u32x4*)((bf16_t*)Xout + ro + bj * HALF) = o; }
;                     else { *(f32x4*)((float*)Xout + ro + bj * HALF) = x0; *(f32x4*)((float*)Xout + ro + bj * HALF + 4) = x1; } } }
; template <class Map, class Epi>
; DI void gemm_phase(LAS unsigned char* lds, const Map& MP, const Epi& E, const int nM, const int nN, const int K, const int lda, const int ldb) {
;     ...
;     PG8_WAIT_V(0);
;     if (wr == 0) PG8_BAR;
;     PG8_BAR;
	v_lshlrev_b32_e32 v44, 16, v40
	v_and_b32_e32 v45, 0xffff0000, v40
	v_lshlrev_b32_e32 v40, 16, v41
	v_and_b32_e32 v41, 0xffff0000, v41
	v_lshlrev_b32_e32 v46, 16, v42
	v_and_b32_e32 v47, 0xffff0000, v42
	v_lshlrev_b32_e32 v42, 16, v43
	v_and_b32_e32 v43, 0xffff0000, v43
	v_pk_add_f32 v[38:39], v[38:39], v[40:41]
	v_pk_add_f32 v[36:37], v[36:37], v[44:45]
	v_pk_add_f32 v[40:41], v[34:35], v[42:43]
	v_pk_add_f32 v[34:35], v[32:33], v[46:47]
	v_cvt_pk_bf16_f32 v32, v36, v37
	v_cvt_pk_bf16_f32 v33, v38, v39
	v_cvt_pk_bf16_f32 v34, v34, v35
	v_cvt_pk_bf16_f32 v35, v40, v41
	global_store_dwordx4 v[48:49], v[32:35], off offset:256
	s_nop 1
	v_lshl_add_u64 v[32:33], v[144:145], 0, s[2:3]
	s_mov_b32 s2, 0xa0000
	v_add_co_u32_e32 v38, vcc, s2, v144
	s_mov_b64 s[2:3], 0xb0000
	s_nop 0
	v_addc_co_u32_e32 v39, vcc, 0, v145, vcc
	s_waitcnt vmcnt(15)
	s_nop 1
	v_mov_b32_e32 v34, v210
	v_mov_b32_e32 v35, v211
	v_mov_b32_e32 v36, v212
	v_mov_b32_e32 v37, v213
	s_waitcnt lgkmcnt(0)
	v_lshlrev_b32_e32 v40, 16, v34
	v_and_b32_e32 v41, 0xffff0000, v34
	v_lshlrev_b32_e32 v34, 16, v35
	v_and_b32_e32 v35, 0xffff0000, v35
	v_lshlrev_b32_e32 v42, 16, v36
	v_and_b32_e32 v43, 0xffff0000, v36
	v_lshlrev_b32_e32 v36, 16, v37
	v_and_b32_e32 v37, 0xffff0000, v37
	v_pk_add_f32 v[30:31], v[30:31], v[34:35]
	v_pk_add_f32 v[28:29], v[28:29], v[40:41]
	v_pk_add_f32 v[34:35], v[26:27], v[36:37]
	v_pk_add_f32 v[26:27], v[24:25], v[42:43]
	v_cvt_pk_bf16_f32 v24, v28, v29
	v_cvt_pk_bf16_f32 v25, v30, v31
	v_cvt_pk_bf16_f32 v26, v26, v27
	v_cvt_pk_bf16_f32 v27, v34, v35
	global_store_dwordx4 v[38:39], v[24:27], off
	s_waitcnt vmcnt(15)
	s_nop 1
	v_mov_b32_e32 v24, v214
	v_mov_b32_e32 v25, v215
	v_mov_b32_e32 v26, v216
	v_mov_b32_e32 v27, v217
	s_waitcnt lgkmcnt(0)
	v_lshlrev_b32_e32 v28, 16, v24
	v_and_b32_e32 v29, 0xffff0000, v24
	v_lshlrev_b32_e32 v24, 16, v25
	v_and_b32_e32 v25, 0xffff0000, v25
	v_lshlrev_b32_e32 v30, 16, v26
	v_and_b32_e32 v31, 0xffff0000, v26
	v_lshlrev_b32_e32 v26, 16, v27
	v_and_b32_e32 v27, 0xffff0000, v27
	v_pk_add_f32 v[22:23], v[22:23], v[24:25]
	v_pk_add_f32 v[20:21], v[20:21], v[28:29]
	v_pk_add_f32 v[24:25], v[18:19], v[26:27]
	v_pk_add_f32 v[18:19], v[16:17], v[30:31]
	v_cvt_pk_bf16_f32 v16, v20, v21
	v_cvt_pk_bf16_f32 v17, v22, v23
	v_cvt_pk_bf16_f32 v18, v18, v19
	v_cvt_pk_bf16_f32 v19, v24, v25
	global_store_dwordx4 v[32:33], v[16:19], off offset:256
	s_nop 1
	v_lshl_add_u64 v[16:17], v[144:145], 0, s[2:3]
	s_mov_b32 s2, 0xb0000
	v_add_co_u32_e32 v22, vcc, s2, v144
	s_mov_b32 s2, s44
	s_nop 0
	v_addc_co_u32_e32 v23, vcc, 0, v145, vcc
	s_waitcnt vmcnt(15)
	s_nop 1
	v_mov_b32_e32 v18, v248
	v_mov_b32_e32 v19, v249
	v_mov_b32_e32 v20, v250
	v_mov_b32_e32 v21, v251
	s_and_b64 vcc, exec, s[40:41]
	s_waitcnt lgkmcnt(0)
	v_lshlrev_b32_e32 v24, 16, v18
	v_and_b32_e32 v25, 0xffff0000, v18
	v_lshlrev_b32_e32 v18, 16, v19
	v_and_b32_e32 v19, 0xffff0000, v19
	v_lshlrev_b32_e32 v26, 16, v20
	v_and_b32_e32 v27, 0xffff0000, v20
	v_lshlrev_b32_e32 v20, 16, v21
	v_and_b32_e32 v21, 0xffff0000, v21
	v_pk_add_f32 v[14:15], v[14:15], v[18:19]
	v_pk_add_f32 v[12:13], v[12:13], v[24:25]
	v_pk_add_f32 v[18:19], v[10:11], v[20:21]
	v_pk_add_f32 v[10:11], v[8:9], v[26:27]
	v_cvt_pk_bf16_f32 v8, v12, v13
	v_cvt_pk_bf16_f32 v9, v14, v15
	v_cvt_pk_bf16_f32 v10, v10, v11
	v_cvt_pk_bf16_f32 v11, v18, v19
	global_store_dwordx4 v[22:23], v[8:11], off
	s_waitcnt vmcnt(15)
	s_nop 1
	v_mov_b32_e32 v8, v252
	v_mov_b32_e32 v9, v253
	v_mov_b32_e32 v10, v254
	v_mov_b32_e32 v11, v255
	s_waitcnt lgkmcnt(0)
	v_lshlrev_b32_e32 v12, 16, v8
	v_and_b32_e32 v13, 0xffff0000, v8
	v_lshlrev_b32_e32 v8, 16, v9
	v_and_b32_e32 v9, 0xffff0000, v9
	v_lshlrev_b32_e32 v14, 16, v10
	v_and_b32_e32 v15, 0xffff0000, v10
	v_lshlrev_b32_e32 v10, 16, v11
	v_and_b32_e32 v11, 0xffff0000, v11
	v_pk_add_f32 v[6:7], v[6:7], v[8:9]
	v_pk_add_f32 v[4:5], v[4:5], v[12:13]
	v_pk_add_f32 v[8:9], v[2:3], v[10:11]
	v_pk_add_f32 v[2:3], v[0:1], v[14:15]
	v_cvt_pk_bf16_f32 v0, v4, v5
	v_cvt_pk_bf16_f32 v1, v6, v7
	v_cvt_pk_bf16_f32 v2, v2, v3
	v_cvt_pk_bf16_f32 v3, v8, v9
	global_store_dwordx4 v[16:17], v[0:3], off offset:256
	s_cbranch_vccz .LBB1_1761
	s_waitcnt vmcnt(0)
	s_cmpk_gt_u32 s17, 0xff
	s_cbranch_scc1 .LBB1_1768
	s_barrier

; #define PG8_STAGE(bufoff, gbase, voff) do { _Pragma("unroll") for (int _i = 0; _i < 2; ++_i) \
;         __builtin_amdgcn_global_load_lds((const unsigned*)((const char*)(gbase) + (voff)[_i]), (LAS unsigned*)(lds + (bufoff) + ldsw + _i * 8192), 16, 0, 0); } while (0)
; #define PG8_LDA(dst, b, h) do { _Pragma("unroll") for (int m = 0; m < 4; ++m) _Pragma("unroll") for (int k = 0; k < 2; ++k) dst[m][k] = *(const LAS bf16x8*)(lds + PG8_SA(b, h) + aoff + m * 2048 + k * 1024); } while (0)
; #define PG8_LDB(dst, b, h) do { _Pragma("unroll") for (int n = 0; n < 2; ++n) _Pragma("unroll") for (int k = 0; k < 2; ++k) dst[n][k] = *(const LAS bf16x8*)(lds + PG8_SB(b, h) + boff + n * 2048 + k * 1024); } while (0)
; #define PG8_MMA(ai, bj, At, Bt) do { __builtin_amdgcn_s_setprio(1); _Pragma("unroll") for (int m = 0; m < 4; ++m) _Pragma("unroll") for (int n = 0; n < 2; ++n) _Pragma("unroll") for (int k = 0; k < 2; ++k) \
;         acc[ai][bj][m][n] = __builtin_amdgcn_mfma_f32_16x16x32_bf16(Bt[n][k], At[m][k], acc[ai][bj][m][n], 0, 0, 0); __builtin_amdgcn_s_setprio(0); } while (0)
; #define PG8_WAIT_V(n) asm volatile("s_waitcnt vmcnt(" #n ")" ::: "memory")
; #define PG8_WAIT_L(n) asm volatile("s_waitcnt lgkmcnt(" #n ")" ::: "memory")
; template <class Map, class Epi>
; DI void gemm_phase(LAS unsigned char* lds, const Map& MP, const Epi& E, const int nM, const int nN, const int K, const int lda, const int ldb) {
;     ...
;         for (int t = 0; t < nt; t += 2) {
;             const bool last = (t == nt - 2);
;             const char* a1 = cA + (size_t)(t + 1) * kstep;
;             const char* a2 = last ? nA : cA + (size_t)(t + 2) * kstep; const char* b2 = last ? nB : cB + (size_t)(t + 2) * kstep;
;             const char* a3 = a2 + kstep; const char* b3 = b2 + kstep;
;             PG8_LDB(B0, 0, 0); PG8_SCHED; PG8_LDA(At, 0, 0); PG8_STAGE(PG8_SA(1, 1), a1 + hstepA, voffA);
;             PG8_WAIT_L(8); PG8_BAR; PG8_WAIT_L(0); PG8_MMA(0, 0, At, B0); PG8_BAR; PG8_SCHED;
;             PG8_LDB(B1, 0, 1); PG8_STAGE(PG8_SB(0, 0), b2, voffB);
;             PG8_BAR; PG8_WAIT_L(0); PG8_MMA(0, 1, At, B1); PG8_BAR;
;             PG8_LDA(At, 0, 1); PG8_STAGE(PG8_SA(0, 0), a2, voffA);
;             PG8_BAR; PG8_WAIT_L(0); PG8_MMA(1, 0, At, B0); PG8_BAR; PG8_SCHED;
;             PG8_STAGE(PG8_SB(0, 1), b2 + hstepB, voffB);
;             PG8_WAIT_V(6); PG8_BAR; PG8_MMA(1, 1, At, B1); PG8_BAR;
.LBB1_1908:
	s_add_u32 s28, s42, 0xfff80080
	s_addc_u32 s29, s43, -1
	s_cmp_eq_u32 s3, 28
	s_cselect_b32 s47, s23, s29
	s_cselect_b32 s46, s58, s28
	s_cselect_b32 s29, s21, vcc_hi
	s_cselect_b32 s28, s59, vcc_lo
	s_add_i32 m0, s38, 0xc000
	ds_read_b128 v[96:99], v190
	ds_read_b128 v[100:103], v190 offset:1024
	ds_read_b128 v[108:111], v190 offset:2048
	ds_read_b128 v[112:115], v190 offset:3072
	ds_read_b128 v[160:163], v190 offset:4096
	ds_read_b128 v[164:167], v190 offset:5120
	ds_read_b128 v[198:201], v190 offset:6144
	ds_read_b128 v[202:205], v190 offset:7168
	global_load_lds_dwordx4 v178, s[42:43]
	s_add_i32 m0, s38, 0xe000
	s_nop 0
	global_load_lds_dwordx4 v176, s[42:43]
	s_waitcnt lgkmcnt(8)
	s_setprio 1
	s_barrier
	s_waitcnt lgkmcnt(7)
	v_mfma_f32_16x16x32_bf16 v[148:151], v[80:83], v[96:99], v[148:151]
	v_mfma_f32_16x16x32_bf16 v[144:147], v[88:91], v[96:99], v[144:147]
	s_waitcnt lgkmcnt(5)
	v_mfma_f32_16x16x32_bf16 v[136:139], v[80:83], v[108:111], v[136:139]
	v_mfma_f32_16x16x32_bf16 v[128:131], v[88:91], v[108:111], v[128:131]
	s_waitcnt lgkmcnt(3)
	v_mfma_f32_16x16x32_bf16 v[120:123], v[80:83], v[160:163], v[120:123]
	v_mfma_f32_16x16x32_bf16 v[104:107], v[88:91], v[160:163], v[104:107]
	s_waitcnt lgkmcnt(1)
	v_mfma_f32_16x16x32_bf16 v[76:79], v[80:83], v[198:201], v[76:79]
	v_mfma_f32_16x16x32_bf16 v[72:75], v[88:91], v[198:201], v[72:75]
	v_mfma_f32_16x16x32_bf16 v[148:151], v[84:87], v[100:103], v[148:151]
	s_add_i32 s68, s2, s54
	v_mfma_f32_16x16x32_bf16 v[144:147], v[92:95], v[100:103], v[144:147]
	v_lshl_add_u64 v[184:185], s[28:29], 0, v[172:173]
	v_mfma_f32_16x16x32_bf16 v[136:139], v[84:87], v[112:115], v[136:139]
	v_lshl_add_u64 v[194:195], s[28:29], 0, v[168:169]
	v_mfma_f32_16x16x32_bf16 v[128:131], v[92:95], v[112:115], v[128:131]
	v_mfma_f32_16x16x32_bf16 v[120:123], v[84:87], v[164:167], v[120:123]
	v_mfma_f32_16x16x32_bf16 v[104:107], v[92:95], v[164:167], v[104:107]
	s_waitcnt lgkmcnt(0)
	v_mfma_f32_16x16x32_bf16 v[76:79], v[84:87], v[202:205], v[76:79]
	v_mfma_f32_16x16x32_bf16 v[72:75], v[92:95], v[202:205], v[72:75]
	s_barrier
	s_setprio 0
	s_mov_b32 m0, s68
	ds_read_b128 v[206:209], v191
	ds_read_b128 v[210:213], v191 offset:1024
	ds_read_b128 v[214:217], v191 offset:2048
	ds_read_b128 v[218:221], v191 offset:3072
	global_load_lds_dwordx4 v[184:185], off
	s_add_i32 m0, s68, 0x2000
	s_nop 0
	global_load_lds_dwordx4 v[194:195], off
	s_setprio 1
	s_barrier
	s_waitcnt lgkmcnt(3)
	v_mfma_f32_16x16x32_bf16 v[156:159], v[206:209], v[96:99], v[156:159]
	s_waitcnt lgkmcnt(1)
	v_mfma_f32_16x16x32_bf16 v[96:99], v[214:217], v[96:99], v[152:155]
	v_mfma_f32_16x16x32_bf16 v[156:159], v[210:213], v[100:103], v[156:159]
	s_waitcnt lgkmcnt(0)
	v_mfma_f32_16x16x32_bf16 v[96:99], v[218:221], v[100:103], v[96:99]
	v_mfma_f32_16x16x32_bf16 v[100:103], v[206:209], v[108:111], v[140:143]
	v_mfma_f32_16x16x32_bf16 v[108:111], v[214:217], v[108:111], v[132:135]
	v_mfma_f32_16x16x32_bf16 v[116:119], v[214:217], v[160:163], v[116:119]
	v_mfma_f32_16x16x32_bf16 v[68:71], v[206:209], v[198:201], v[68:71]
	v_mfma_f32_16x16x32_bf16 v[64:67], v[214:217], v[198:201], v[64:67]
	v_lshl_add_u64 v[234:235], s[46:47], 0, v[170:171]
	s_mov_b32 m0, s38
	v_mfma_f32_16x16x32_bf16 v[100:103], v[210:213], v[112:115], v[100:103]
	v_lshl_add_u64 v[226:227], s[46:47], 0, v[174:175]
	v_mfma_f32_16x16x32_bf16 v[108:111], v[218:221], v[112:115], v[108:111]
	v_mfma_f32_16x16x32_bf16 v[112:115], v[206:209], v[160:163], v[124:127]
	v_mfma_f32_16x16x32_bf16 v[116:119], v[218:221], v[164:167], v[116:119]
	v_mfma_f32_16x16x32_bf16 v[68:71], v[210:213], v[202:205], v[68:71]
	v_mfma_f32_16x16x32_bf16 v[64:67], v[218:221], v[202:205], v[64:67]
	v_mfma_f32_16x16x32_bf16 v[112:115], v[210:213], v[164:167], v[112:115]
	s_barrier
	s_setprio 0
	ds_read_b128 v[124:127], v190 offset:16384
	ds_read_b128 v[132:135], v190 offset:17408
	ds_read_b128 v[140:143], v190 offset:18432
	ds_read_b128 v[152:155], v190 offset:19456
	ds_read_b128 v[160:163], v190 offset:20480
	ds_read_b128 v[164:167], v190 offset:21504
	ds_read_b128 v[198:201], v190 offset:22528
	ds_read_b128 v[202:205], v190 offset:23552
	global_load_lds_dwordx4 v[226:227], off
	s_mov_b32 m0, s39
	s_nop 0
	global_load_lds_dwordx4 v[234:235], off
	s_waitcnt vmcnt(10)
	s_setprio 1
	s_barrier
	s_waitcnt lgkmcnt(7)
	v_mfma_f32_16x16x32_bf16 v[60:63], v[80:83], v[124:127], v[60:63]
	v_mfma_f32_16x16x32_bf16 v[48:51], v[88:91], v[124:127], v[48:51]
	s_waitcnt lgkmcnt(5)
	v_mfma_f32_16x16x32_bf16 v[40:43], v[80:83], v[140:143], v[40:43]
	v_mfma_f32_16x16x32_bf16 v[32:35], v[88:91], v[140:143], v[32:35]
	s_waitcnt lgkmcnt(3)
	v_mfma_f32_16x16x32_bf16 v[24:27], v[80:83], v[160:163], v[24:27]
	v_mfma_f32_16x16x32_bf16 v[16:19], v[88:91], v[160:163], v[16:19]
	s_waitcnt lgkmcnt(1)
	v_mfma_f32_16x16x32_bf16 v[12:15], v[80:83], v[198:201], v[12:15]
	v_mfma_f32_16x16x32_bf16 v[8:11], v[88:91], v[198:201], v[8:11]
	v_mfma_f32_16x16x32_bf16 v[60:63], v[84:87], v[132:135], v[60:63]
	s_add_u32 s68, s28, 0x80000
	s_addc_u32 s69, s29, 0
	v_mfma_f32_16x16x32_bf16 v[48:51], v[92:95], v[132:135], v[48:51]
	s_add_i32 s70, s31, s54
	v_mfma_f32_16x16x32_bf16 v[40:43], v[84:87], v[152:155], v[40:43]
	v_mfma_f32_16x16x32_bf16 v[32:35], v[92:95], v[152:155], v[32:35]
	v_mfma_f32_16x16x32_bf16 v[24:27], v[84:87], v[164:167], v[24:27]
	v_mfma_f32_16x16x32_bf16 v[16:19], v[92:95], v[164:167], v[16:19]
	s_waitcnt lgkmcnt(0)
	v_mfma_f32_16x16x32_bf16 v[12:15], v[84:87], v[202:205], v[12:15]
	v_mfma_f32_16x16x32_bf16 v[8:11], v[92:95], v[202:205], v[8:11]
	s_barrier
; #define PG8_STAGE(bufoff, gbase, voff) do { _Pragma("unroll") for (int _i = 0; _i < 2; ++_i) \
;         __builtin_amdgcn_global_load_lds((const unsigned*)((const char*)(gbase) + (voff)[_i]), (LAS unsigned*)(lds + (bufoff) + ldsw + _i * 8192), 16, 0, 0); } while (0)
; #define PG8_LDA(dst, b, h) do { _Pragma("unroll") for (int m = 0; m < 4; ++m) _Pragma("unroll") for (int k = 0; k < 2; ++k) dst[m][k] = *(const LAS bf16x8*)(lds + PG8_SA(b, h) + aoff + m * 2048 + k * 1024); } while (0)
; #define PG8_LDB(dst, b, h) do { _Pragma("unroll") for (int n = 0; n < 2; ++n) _Pragma("unroll") for (int k = 0; k < 2; ++k) dst[n][k] = *(const LAS bf16x8*)(lds + PG8_SB(b, h) + boff + n * 2048 + k * 1024); } while (0)
; #define PG8_MMA(ai, bj, At, Bt) do { __builtin_amdgcn_s_setprio(1); _Pragma("unroll") for (int m = 0; m < 4; ++m) _Pragma("unroll") for (int n = 0; n < 2; ++n) _Pragma("unroll") for (int k = 0; k < 2; ++k) \
;         acc[ai][bj][m][n] = __builtin_amdgcn_mfma_f32_16x16x32_bf16(Bt[n][k], At[m][k], acc[ai][bj][m][n], 0, 0, 0); __builtin_amdgcn_s_setprio(0); } while (0)
; #define PG8_WAIT_V(n) asm volatile("s_waitcnt vmcnt(" #n ")" ::: "memory")
; #define PG8_WAIT_L(n) asm volatile("s_waitcnt lgkmcnt(" #n ")" ::: "memory")
; #define PG8_BAR __builtin_amdgcn_s_barrier()
; #define PG8_SCHED __builtin_amdgcn_sched_barrier(0)
; template <class Map, class Epi>
; DI void gemm_phase(LAS unsigned char* lds, const Map& MP, const Epi& E, const int nM, const int nN, const int K, const int lda, const int ldb) {
;     ...
;             PG8_STAGE(PG8_SB(0, 1), b2 + hstepB, voffB);
;             PG8_WAIT_V(6); PG8_BAR; PG8_MMA(1, 1, At, B1); PG8_BAR;
;             PG8_LDB(B0, 1, 0); PG8_SCHED; PG8_LDA(At, 1, 0); PG8_STAGE(PG8_SA(0, 1), a2 + hstepA, voffA);
;             PG8_WAIT_L(8); PG8_BAR; PG8_WAIT_L(0); PG8_MMA(0, 0, At, B0); PG8_BAR; PG8_SCHED;
;             PG8_LDB(B1, 1, 1); PG8_STAGE(PG8_SB(1, 0), b3, voffB);
;             PG8_BAR; PG8_WAIT_L(0); PG8_MMA(0, 1, At, B1); PG8_BAR;
;             PG8_LDA(At, 1, 1); PG8_STAGE(PG8_SA(1, 0), a3, voffA);
;             PG8_BAR; PG8_WAIT_L(0); PG8_MMA(1, 0, At, B0); PG8_BAR; PG8_SCHED;
;             PG8_STAGE(PG8_SB(1, 1), b3 + hstepB, voffB);
	s_setprio 0
	s_mov_b32 m0, s70
	s_nop 0
	global_load_lds_dwordx4 v172, s[68:69]
	s_add_i32 m0, s70, 0x2000
	s_nop 0
	global_load_lds_dwordx4 v168, s[68:69]
	s_waitcnt vmcnt(6)
	s_setprio 1
	s_barrier
	v_mfma_f32_16x16x32_bf16 v[56:59], v[206:209], v[124:127], v[56:59]
	v_mfma_f32_16x16x32_bf16 v[52:55], v[214:217], v[124:127], v[52:55]
	s_add_i32 s68, 0, 0x18000
	v_add_u32_e32 v92, s68, v188
	ds_read_b128 v[80:83], v92
	v_mfma_f32_16x16x32_bf16 v[44:47], v[206:209], v[140:143], v[44:47]
	v_mfma_f32_16x16x32_bf16 v[36:39], v[214:217], v[140:143], v[36:39]
	ds_read_b128 v[84:87], v92 offset:1024
	v_mfma_f32_16x16x32_bf16 v[28:31], v[206:209], v[160:163], v[28:31]
	v_mfma_f32_16x16x32_bf16 v[20:23], v[214:217], v[160:163], v[20:23]
	ds_read_b128 v[88:91], v92 offset:2048
	v_mfma_f32_16x16x32_bf16 v[4:7], v[206:209], v[198:201], v[4:7]
	v_mfma_f32_16x16x32_bf16 v[0:3], v[214:217], v[198:201], v[0:3]
	ds_read_b128 v[92:95], v92 offset:3072
	v_mfma_f32_16x16x32_bf16 v[56:59], v[210:213], v[132:135], v[56:59]
	s_add_u32 s46, s46, 0x80000
	s_addc_u32 s47, s47, 0
	v_mfma_f32_16x16x32_bf16 v[52:55], v[218:221], v[132:135], v[52:55]
	v_mfma_f32_16x16x32_bf16 v[44:47], v[210:213], v[152:155], v[44:47]
	v_mfma_f32_16x16x32_bf16 v[36:39], v[218:221], v[152:155], v[36:39]
	v_mfma_f32_16x16x32_bf16 v[28:31], v[210:213], v[164:167], v[28:31]
	v_mfma_f32_16x16x32_bf16 v[20:23], v[218:221], v[164:167], v[20:23]
	v_mfma_f32_16x16x32_bf16 v[4:7], v[210:213], v[202:205], v[4:7]
	v_mfma_f32_16x16x32_bf16 v[0:3], v[218:221], v[202:205], v[0:3]
	s_barrier
	s_setprio 0
	s_mov_b32 m0, s56
	ds_read_b128 v[124:127], v190 offset:32768
	ds_read_b128 v[132:135], v190 offset:33792
	ds_read_b128 v[160:163], v190 offset:34816
	ds_read_b128 v[164:167], v190 offset:35840
	ds_read_b128 v[198:201], v190 offset:36864
	ds_read_b128 v[202:205], v190 offset:37888
	ds_read_b128 v[206:209], v190 offset:38912
	ds_read_b128 v[210:213], v190 offset:39936
	global_load_lds_dwordx4 v174, s[46:47]
	s_mov_b32 m0, s57
	s_nop 0
	global_load_lds_dwordx4 v170, s[46:47]
	s_waitcnt lgkmcnt(8)
	s_setprio 1
	s_barrier
	s_waitcnt lgkmcnt(7)
	v_mfma_f32_16x16x32_bf16 v[140:143], v[80:83], v[124:127], v[148:151]
	s_waitcnt lgkmcnt(6)
	v_mfma_f32_16x16x32_bf16 v[148:151], v[84:87], v[132:135], v[140:143]
	v_mfma_f32_16x16x32_bf16 v[140:143], v[88:91], v[124:127], v[144:147]
	s_waitcnt lgkmcnt(5)
	v_mfma_f32_16x16x32_bf16 v[136:139], v[80:83], v[160:163], v[136:139]
	v_mfma_f32_16x16x32_bf16 v[128:131], v[88:91], v[160:163], v[128:131]
	s_waitcnt lgkmcnt(3)
	v_mfma_f32_16x16x32_bf16 v[120:123], v[80:83], v[198:201], v[120:123]
	v_mfma_f32_16x16x32_bf16 v[104:107], v[88:91], v[198:201], v[104:107]
	s_waitcnt lgkmcnt(1)
	v_mfma_f32_16x16x32_bf16 v[76:79], v[80:83], v[206:209], v[76:79]
	v_mfma_f32_16x16x32_bf16 v[72:75], v[88:91], v[206:209], v[72:75]
	s_add_i32 s46, 0, 0x1c000
	v_mfma_f32_16x16x32_bf16 v[144:147], v[92:95], v[132:135], v[140:143]
	v_add_u32_e32 v140, s46, v188
	v_mfma_f32_16x16x32_bf16 v[136:139], v[84:87], v[164:167], v[136:139]
	s_add_i32 s47, s68, s54
	v_mfma_f32_16x16x32_bf16 v[128:131], v[92:95], v[164:167], v[128:131]
	v_mfma_f32_16x16x32_bf16 v[120:123], v[84:87], v[202:205], v[120:123]
	v_mfma_f32_16x16x32_bf16 v[104:107], v[92:95], v[202:205], v[104:107]
	s_waitcnt lgkmcnt(0)
	v_mfma_f32_16x16x32_bf16 v[76:79], v[84:87], v[210:213], v[76:79]
	v_mfma_f32_16x16x32_bf16 v[72:75], v[92:95], v[210:213], v[72:75]
	s_barrier
	s_setprio 0
	ds_read_b128 v[214:217], v140
	ds_read_b128 v[218:221], v140 offset:1024
	ds_read_b128 v[222:225], v140 offset:2048
	ds_read_b128 v[230:233], v140 offset:3072
	v_lshl_add_u64 v[140:141], v[184:185], 0, s[14:15]
	s_mov_b32 m0, s47
	s_nop 0
	global_load_lds_dwordx4 v[140:141], off
	v_lshl_add_u64 v[140:141], v[194:195], 0, s[14:15]
	s_add_i32 m0, s47, 0x2000
	s_nop 0
	global_load_lds_dwordx4 v[140:141], off
	s_setprio 1
	s_barrier
	s_waitcnt lgkmcnt(1)
	v_mfma_f32_16x16x32_bf16 v[96:99], v[222:225], v[124:127], v[96:99]
	v_mfma_f32_16x16x32_bf16 v[140:143], v[214:217], v[124:127], v[156:159]
	s_waitcnt lgkmcnt(0)
	v_mfma_f32_16x16x32_bf16 v[152:155], v[230:233], v[132:135], v[96:99]
	v_mfma_f32_16x16x32_bf16 v[96:99], v[214:217], v[160:163], v[100:103]
	v_mfma_f32_16x16x32_bf16 v[156:159], v[218:221], v[132:135], v[140:143]
	v_mfma_f32_16x16x32_bf16 v[140:143], v[218:221], v[164:167], v[96:99]
	v_mfma_f32_16x16x32_bf16 v[96:99], v[222:225], v[160:163], v[108:111]
	v_mfma_f32_16x16x32_bf16 v[132:135], v[230:233], v[164:167], v[96:99]
	v_mfma_f32_16x16x32_bf16 v[96:99], v[214:217], v[198:201], v[112:115]
	s_mov_b32 m0, s63
	v_mfma_f32_16x16x32_bf16 v[124:127], v[218:221], v[202:205], v[96:99]
	v_lshl_add_u64 v[184:185], v[226:227], 0, s[14:15]
	v_mfma_f32_16x16x32_bf16 v[96:99], v[222:225], v[198:201], v[116:119]
	v_mfma_f32_16x16x32_bf16 v[68:71], v[214:217], v[206:209], v[68:71]
	v_mfma_f32_16x16x32_bf16 v[64:67], v[222:225], v[206:209], v[64:67]
	v_mfma_f32_16x16x32_bf16 v[116:119], v[230:233], v[202:205], v[96:99]
	v_mfma_f32_16x16x32_bf16 v[68:71], v[218:221], v[210:213], v[68:71]
	v_mfma_f32_16x16x32_bf16 v[64:67], v[230:233], v[210:213], v[64:67]
	s_barrier
	s_setprio 0
	ds_read_b128 v[96:99], v190 offset:49152
	ds_read_b128 v[100:103], v190 offset:50176
	ds_read_b128 v[108:111], v190 offset:51200
	ds_read_b128 v[112:115], v190 offset:52224
	ds_read_b128 v[160:163], v190 offset:53248
	ds_read_b128 v[164:167], v190 offset:54272
	ds_read_b128 v[198:201], v190 offset:55296
	ds_read_b128 v[202:205], v190 offset:56320
	global_load_lds_dwordx4 v[184:185], off
	v_lshl_add_u64 v[184:185], v[234:235], 0, s[14:15]
	s_mov_b32 m0, s66
	s_nop 0
	global_load_lds_dwordx4 v[184:185], off
	s_waitcnt vmcnt(10)
	s_setprio 1
	s_barrier
; #define PG8_STAGE(bufoff, gbase, voff) do { _Pragma("unroll") for (int _i = 0; _i < 2; ++_i) \
;         __builtin_amdgcn_global_load_lds((const unsigned*)((const char*)(gbase) + (voff)[_i]), (LAS unsigned*)(lds + (bufoff) + ldsw + _i * 8192), 16, 0, 0); } while (0)
; #define PG8_LDA(dst, b, h) do { _Pragma("unroll") for (int m = 0; m < 4; ++m) _Pragma("unroll") for (int k = 0; k < 2; ++k) dst[m][k] = *(const LAS bf16x8*)(lds + PG8_SA(b, h) + aoff + m * 2048 + k * 1024); } while (0)
; #define PG8_MMA(ai, bj, At, Bt) do { __builtin_amdgcn_s_setprio(1); _Pragma("unroll") for (int m = 0; m < 4; ++m) _Pragma("unroll") for (int n = 0; n < 2; ++n) _Pragma("unroll") for (int k = 0; k < 2; ++k) \
;         acc[ai][bj][m][n] = __builtin_amdgcn_mfma_f32_16x16x32_bf16(Bt[n][k], At[m][k], acc[ai][bj][m][n], 0, 0, 0); __builtin_amdgcn_s_setprio(0); } while (0)
; #define PG8_WAIT_V(n) asm volatile("s_waitcnt vmcnt(" #n ")" ::: "memory")
; #define PG8_WAIT_L(n) asm volatile("s_waitcnt lgkmcnt(" #n ")" ::: "memory")
; #define PG8_BAR __builtin_amdgcn_s_barrier()
; #define PG8_SCHED __builtin_amdgcn_sched_barrier(0)
; template <class Map, class Epi>
; DI void gemm_phase(LAS unsigned char* lds, const Map& MP, const Epi& E, const int nM, const int nN, const int K, const int lda, const int ldb) {
;     ...
;             PG8_LDA(At, 1, 1); PG8_STAGE(PG8_SA(1, 0), a3, voffA);
;             PG8_BAR; PG8_WAIT_L(0); PG8_MMA(1, 0, At, B0); PG8_BAR; PG8_SCHED;
;             PG8_STAGE(PG8_SB(1, 1), b3 + hstepB, voffB);
;             PG8_WAIT_V(6); PG8_BAR; PG8_MMA(1, 1, At, B1); PG8_BAR;
;         }
	s_waitcnt lgkmcnt(7)
	v_mfma_f32_16x16x32_bf16 v[60:63], v[80:83], v[96:99], v[60:63]
	v_mfma_f32_16x16x32_bf16 v[48:51], v[88:91], v[96:99], v[48:51]
	s_waitcnt lgkmcnt(5)
	v_mfma_f32_16x16x32_bf16 v[40:43], v[80:83], v[108:111], v[40:43]
	v_mfma_f32_16x16x32_bf16 v[32:35], v[88:91], v[108:111], v[32:35]
	s_waitcnt lgkmcnt(3)
	v_mfma_f32_16x16x32_bf16 v[24:27], v[80:83], v[160:163], v[24:27]
	v_mfma_f32_16x16x32_bf16 v[16:19], v[88:91], v[160:163], v[16:19]
	s_waitcnt lgkmcnt(1)
	v_mfma_f32_16x16x32_bf16 v[12:15], v[80:83], v[198:201], v[12:15]
	v_mfma_f32_16x16x32_bf16 v[8:11], v[88:91], v[198:201], v[8:11]
	v_mfma_f32_16x16x32_bf16 v[60:63], v[84:87], v[100:103], v[60:63]
	s_add_u32 s28, s28, 0x80080
	s_addc_u32 s29, s29, 0
	v_mfma_f32_16x16x32_bf16 v[48:51], v[92:95], v[100:103], v[48:51]
	s_add_i32 s46, s46, s54
	v_mfma_f32_16x16x32_bf16 v[40:43], v[84:87], v[112:115], v[40:43]
	v_mfma_f32_16x16x32_bf16 v[32:35], v[92:95], v[112:115], v[32:35]
	v_mfma_f32_16x16x32_bf16 v[24:27], v[84:87], v[164:167], v[24:27]
	v_mfma_f32_16x16x32_bf16 v[16:19], v[92:95], v[164:167], v[16:19]
	s_waitcnt lgkmcnt(0)
	v_mfma_f32_16x16x32_bf16 v[12:15], v[84:87], v[202:205], v[12:15]
	v_mfma_f32_16x16x32_bf16 v[8:11], v[92:95], v[202:205], v[8:11]
	s_barrier
	s_setprio 0
	s_mov_b32 m0, s46
	s_nop 0
	global_load_lds_dwordx4 v172, s[28:29]
	s_add_i32 m0, s46, 0x2000
	s_nop 0
	global_load_lds_dwordx4 v168, s[28:29]
	s_waitcnt vmcnt(6)
	s_setprio 1
	s_barrier
	v_mfma_f32_16x16x32_bf16 v[56:59], v[214:217], v[96:99], v[56:59]
	v_mfma_f32_16x16x32_bf16 v[52:55], v[222:225], v[96:99], v[52:55]
	ds_read_b128 v[80:83], v189
	v_mfma_f32_16x16x32_bf16 v[44:47], v[214:217], v[108:111], v[44:47]
	v_mfma_f32_16x16x32_bf16 v[36:39], v[222:225], v[108:111], v[36:39]
	ds_read_b128 v[84:87], v189 offset:1024
	v_mfma_f32_16x16x32_bf16 v[28:31], v[214:217], v[160:163], v[28:31]
	v_mfma_f32_16x16x32_bf16 v[20:23], v[222:225], v[160:163], v[20:23]
	ds_read_b128 v[88:91], v189 offset:2048
	v_mfma_f32_16x16x32_bf16 v[4:7], v[214:217], v[198:201], v[4:7]
	v_mfma_f32_16x16x32_bf16 v[0:3], v[222:225], v[198:201], v[0:3]
	ds_read_b128 v[92:95], v189 offset:3072
	v_mfma_f32_16x16x32_bf16 v[56:59], v[218:221], v[100:103], v[56:59]
	s_add_i32 s3, s3, 2
	v_mfma_f32_16x16x32_bf16 v[52:55], v[230:233], v[100:103], v[52:55]
	s_add_u32 vcc_lo, vcc_lo, 0x100
	s_addc_u32 vcc_hi, vcc_hi, 0
	v_mfma_f32_16x16x32_bf16 v[44:47], v[218:221], v[112:115], v[44:47]
	s_add_u32 s42, s42, 0x100
	s_addc_u32 s43, s43, 0
	v_mfma_f32_16x16x32_bf16 v[36:39], v[230:233], v[112:115], v[36:39]
	s_cmp_gt_u32 s3, 29
	v_mfma_f32_16x16x32_bf16 v[28:31], v[218:221], v[164:167], v[28:31]
	v_mfma_f32_16x16x32_bf16 v[20:23], v[230:233], v[164:167], v[20:23]
	v_mfma_f32_16x16x32_bf16 v[4:7], v[218:221], v[202:205], v[4:7]
	v_mfma_f32_16x16x32_bf16 v[0:3], v[230:233], v[202:205], v[0:3]
	s_barrier
	s_setprio 0
	s_cbranch_scc0 .LBB1_1908
; DI float silu_mul(float g, float v) { return g * v * __builtin_amdgcn_rcpf(1.0f + __builtin_amdgcn_exp2f(-LOG2E * g)); }
;     DI void operator()(const f32x4 (&acc)[2][2][4][2], const Unit& u, int wr, int wc, int fr, int fq) const {
;         const int row0 = u.pm * BM + wr * 64 + fr, ch0 = u.pn * 128 + wc * 32 + 8 * fq;
;         f32x4 w0[2], w1[2], w2[2], bb[2];
; #pragma unroll
;         for (int n = 0; n < 2; ++n) { w0[n] = *(const f32x4*)(cw + ch0 + 4 * n); w1[n] = *(const f32x4*)(cw + DFF + ch0 + 4 * n); w2[n] = *(const f32x4*)(cw + 2 * DFF + ch0 + 4 * n); bb[n] = *(const f32x4*)(cb + ch0 + 4 * n); }
; #pragma unroll
;         for (int ai = 0; ai < 2; ++ai)
; #pragma unroll
;             for (int m = 0; m < 4; ++m) {
;                 const bool efirst = (m == 0) && (fr == 0), elast = (m == 3) && (fr == 15);
;                 const int row = row0 + ai * HALF + m * 16;
;                 f32x4 gc[2];
; #pragma unroll
;                 for (int n = 0; n < 2; ++n) {
;                     const f32x4 g = acc[ai][0][m][n];
;                     const f32x4 gprev = acc[ai][0][m > 0 ? m - 1 : 0][n], gnext = acc[ai][0][m < 3 ? m + 1 : 3][n];
;                     f32x4 up, dn;
; #pragma unroll
;                     for (int e = 0; e < 4; ++e) {
;                         const float pu = (m > 0 && fr == 15) ? gprev[e] : g[e];
;                         const float pd = (m < 3 && fr == 0) ? gnext[e] : g[e];
;                         up[e] = dpp_ror1(pu); dn[e] = dpp_ror15(pd);
;                     }
;                     if (efirst) up = (f32x4){0.f, 0.f, 0.f, 0.f};
;                     if (elast) dn = (f32x4){0.f, 0.f, 0.f, 0.f};
;                     gc[n] = w0[n] * up + w1[n] * g + w2[n] * dn + bb[n];
;                 }
;                 if (efirst || elast) {
;                     const size_t eo = (size_t)((row >> 6) * 2 + (elast ? 1 : 0)) * DFF + ch0;
; #pragma unroll
;                     for (int n = 0; n < 2; ++n) { *(f32x4*)(EP + eo + 4 * n) = gc[n]; *(f32x4*)(ER + eo + 4 * n) = acc[ai][0][m][n]; *(f32x4*)(EV + eo + 4 * n) = acc[ai][1][m][n]; }
;                 } else {
;                     const f32x4 v0 = acc[ai][1][m][0], v1 = acc[ai][1][m][1];
;                     u32x4 o;
;                     o[0] = pack2(silu_mul(gc[0][0], v0[0]), silu_mul(gc[0][1], v0[1])); o[1] = pack2(silu_mul(gc[0][2], v0[2]), silu_mul(gc[0][3], v0[3]));
	s_waitcnt lgkmcnt(0)
	s_lshl_b32 s21, s45, 7
	v_mov_b32_e32 v194, v186
	v_mov_b32_e32 v80, v187
	s_or_b32 s21, s21, s62
	v_lshl_add_u32 v184, v80, 3, s21
	v_ashrrev_i32_e32 v185, 31, v184
	v_lshlrev_b64 v[80:81], 2, v[184:185]
	v_lshl_add_u64 v[84:85], s[4:5], 0, v[80:81]
	v_lshl_add_u64 v[88:89], s[16:17], 0, v[80:81]
	v_lshl_add_u64 v[92:93], s[18:19], 0, v[80:81]
	v_lshl_add_u64 v[112:113], s[6:7], 0, v[80:81]
	global_load_dwordx4 v[80:83], v[84:85], off offset:16
	global_load_dwordx4 v[96:99], v[84:85], off
	s_nop 0
	global_load_dwordx4 v[84:87], v[88:89], off offset:16
	global_load_dwordx4 v[100:103], v[88:89], off
	s_nop 0
	global_load_dwordx4 v[88:91], v[92:93], off offset:16
	global_load_dwordx4 v[108:111], v[92:93], off
	s_nop 0
	global_load_dwordx4 v[92:95], v[112:113], off offset:16
	s_nop 0
	global_load_dwordx4 v[112:115], v[112:113], off
	v_cmp_eq_u32_e32 vcc, 0, v194
	s_nop 0
	s_nop 0
	v_cndmask_b32_e32 v161, v148, v136, vcc
	v_cndmask_b32_e32 v162, v149, v137, vcc
	v_cndmask_b32_e32 v163, v150, v138, vcc
	v_mov_b32_dpp v160, v161 row_ror:15 row_mask:0xf bank_mask:0xf
	s_nop 0
	s_nop 0
	v_mov_b32_dpp v161, v162 row_ror:15 row_mask:0xf bank_mask:0xf
	v_mov_b32_dpp v164, v150 row_ror:1 row_mask:0xf bank_mask:0xf
	v_cndmask_b32_e32 v165, v151, v139, vcc
	v_mov_b32_dpp v162, v163 row_ror:15 row_mask:0xf bank_mask:0xf
	v_mov_b32_dpp v195, v151 row_ror:1 row_mask:0xf bank_mask:0xf
	v_mov_b32_dpp v166, v148 row_ror:1 row_mask:0xf bank_mask:0xf
	v_mov_b32_dpp v167, v149 row_ror:1 row_mask:0xf bank_mask:0xf
	v_mov_b32_dpp v163, v165 row_ror:15 row_mask:0xf bank_mask:0xf
	v_cndmask_b32_e64 v165, v195, 0, vcc
	v_cndmask_b32_e64 v164, v164, 0, vcc
	v_cndmask_b32_e64 v167, v167, 0, vcc
	v_cndmask_b32_e64 v166, v166, 0, vcc
	s_nop 0
	s_nop 0
	v_mov_b32_dpp v195, v144 row_ror:1 row_mask:0xf bank_mask:0xf
	v_mov_b32_dpp v196, v145 row_ror:1 row_mask:0xf bank_mask:0xf
	v_mov_b32_dpp v198, v146 row_ror:1 row_mask:0xf bank_mask:0xf
	v_cndmask_b32_e32 v199, v147, v131, vcc
	v_mov_b32_dpp v200, v147 row_ror:1 row_mask:0xf bank_mask:0xf
	v_cndmask_b32_e64 v198, v198, 0, vcc
	v_cndmask_b32_e64 v201, v196, 0, vcc
	s_lshl_b32 s3, s44, 8
	s_add_i32 s3, s3, s49
	v_add_u32_e32 v193, s3, v194
	v_cmp_ne_u32_e64 s[46:47], 0, v194
	s_waitcnt vmcnt(0)
	v_pk_mul_f32 v[164:165], v[98:99], v[164:165]
	v_pk_mul_f32 v[166:167], v[96:97], v[166:167]
	v_pk_fma_f32 v[164:165], v[150:151], v[102:103], v[164:165]
	v_pk_fma_f32 v[166:167], v[148:149], v[100:101], v[166:167]
	v_pk_fma_f32 v[162:163], v[110:111], v[162:163], v[164:165]
	v_cndmask_b32_e32 v165, v144, v128, vcc
	v_pk_fma_f32 v[160:161], v[108:109], v[160:161], v[166:167]
	v_cndmask_b32_e32 v166, v145, v129, vcc
	v_mov_b32_dpp v164, v165 row_ror:15 row_mask:0xf bank_mask:0xf
	v_cndmask_b32_e32 v167, v146, v130, vcc
	v_pk_add_f32 v[162:163], v[114:115], v[162:163]
	v_mov_b32_dpp v165, v166 row_ror:15 row_mask:0xf bank_mask:0xf
	v_pk_add_f32 v[160:161], v[112:113], v[160:161]
	s_nop 0
	v_mov_b32_dpp v166, v167 row_ror:15 row_mask:0xf bank_mask:0xf
	s_nop 1
	v_mov_b32_dpp v167, v199 row_ror:15 row_mask:0xf bank_mask:0xf
	v_cndmask_b32_e64 v199, v200, 0, vcc
	v_cndmask_b32_e64 v200, v195, 0, vcc
	v_pk_mul_f32 v[200:201], v[80:81], v[200:201]
	v_pk_mul_f32 v[198:199], v[82:83], v[198:199]
	v_pk_fma_f32 v[200:201], v[144:145], v[84:85], v[200:201]
	v_pk_fma_f32 v[198:199], v[146:147], v[86:87], v[198:199]
	v_pk_fma_f32 v[164:165], v[88:89], v[164:165], v[200:201]
	v_pk_fma_f32 v[166:167], v[90:91], v[166:167], v[198:199]
	v_pk_add_f32 v[164:165], v[92:93], v[164:165]
	v_pk_add_f32 v[166:167], v[94:95], v[166:167]
	s_and_saveexec_b64 s[28:29], s[46:47]
	s_xor_b64 s[28:29], exec, s[28:29]
	s_cbranch_execz .LBB1_1911
	v_mul_f32_e32 v195, 0xbfb8aa3b, v160
	v_exp_f32_e32 v195, v195
	v_mul_f32_e32 v196, 0xbfb8aa3b, v161
	v_exp_f32_e32 v196, v196
	v_pk_mul_f32 v[160:161], v[156:157], v[160:161]
	v_add_f32_e32 v195, 1.0, v195
	v_rcp_f32_e32 v198, v195
	v_add_f32_e32 v196, 1.0, v196
	v_mul_f32_e32 v195, 0xbfb8aa3b, v162
	v_rcp_f32_e32 v199, v196
	v_exp_f32_e32 v195, v195
	v_mul_f32_e32 v196, 0xbfb8aa3b, v163
	v_exp_f32_e32 v196, v196
	v_pk_mul_f32 v[160:161], v[160:161], v[198:199]
	v_add_f32_e32 v195, 1.0, v195
	v_rcp_f32_e32 v200, v195
	v_add_f32_e32 v195, 1.0, v196
	v_rcp_f32_e32 v201, v195
	v_cvt_pk_bf16_f32 v160, v160, v161
	v_mul_f32_e32 v161, 0xbfb8aa3b, v164
	v_exp_f32_e32 v195, v161
	v_mul_f32_e32 v161, 0xbfb8aa3b, v165
	v_exp_f32_e32 v196, v161
	v_pk_mul_f32 v[162:163], v[158:159], v[162:163]
	v_pk_mul_f32 v[164:165], v[152:153], v[164:165]
	v_pk_mul_f32 v[162:163], v[162:163], v[200:201]
	s_nop 0
	v_cvt_pk_bf16_f32 v161, v162, v163
	v_add_f32_e32 v162, 1.0, v195
	v_mul_f32_e32 v195, 0xbfb8aa3b, v166
	v_add_f32_e32 v163, 1.0, v196
	v_exp_f32_e32 v195, v195
	v_mul_f32_e32 v196, 0xbfb8aa3b, v167
	v_exp_f32_e32 v196, v196
	v_rcp_f32_e32 v162, v162
	v_add_f32_e32 v195, 1.0, v195
	v_rcp_f32_e32 v198, v195
	v_add_f32_e32 v195, 1.0, v196
	v_rcp_f32_e32 v163, v163
	v_rcp_f32_e32 v199, v195
	v_pk_mul_f32 v[166:167], v[154:155], v[166:167]
	v_pk_mul_f32 v[162:163], v[164:165], v[162:163]
	v_pk_mul_f32 v[164:165], v[166:167], v[198:199]
	v_cvt_pk_bf16_f32 v162, v162, v163
	v_cvt_pk_bf16_f32 v163, v164, v165
	v_mov_b64_e32 v[164:165], s[52:53]
	v_mad_i64_i32 v[164:165], s[42:43], v193, s60, v[164:165]
	v_lshl_add_u64 v[164:165], v[184:185], 1, v[164:165]
	global_store_dwordx4 v[164:165], v[160:163], off

; #define PG8_STAGE(bufoff, gbase, voff) do { _Pragma("unroll") for (int _i = 0; _i < 2; ++_i) \
;         __builtin_amdgcn_global_load_lds((const unsigned*)((const char*)(gbase) + (voff)[_i]), (LAS unsigned*)(lds + (bufoff) + ldsw + _i * 8192), 16, 0, 0); } while (0)
; #define PG8_LDA(dst, b, h) do { _Pragma("unroll") for (int m = 0; m < 4; ++m) _Pragma("unroll") for (int k = 0; k < 2; ++k) dst[m][k] = *(const LAS bf16x8*)(lds + PG8_SA(b, h) + aoff + m * 2048 + k * 1024); } while (0)
; #define PG8_LDB(dst, b, h) do { _Pragma("unroll") for (int n = 0; n < 2; ++n) _Pragma("unroll") for (int k = 0; k < 2; ++k) dst[n][k] = *(const LAS bf16x8*)(lds + PG8_SB(b, h) + boff + n * 2048 + k * 1024); } while (0)
; #define PG8_MMA(ai, bj, At, Bt) do { __builtin_amdgcn_s_setprio(1); _Pragma("unroll") for (int m = 0; m < 4; ++m) _Pragma("unroll") for (int n = 0; n < 2; ++n) _Pragma("unroll") for (int k = 0; k < 2; ++k) \
;         acc[ai][bj][m][n] = __builtin_amdgcn_mfma_f32_16x16x32_bf16(Bt[n][k], At[m][k], acc[ai][bj][m][n], 0, 0, 0); __builtin_amdgcn_s_setprio(0); } while (0)
; #define PG8_WAIT_V(n) asm volatile("s_waitcnt vmcnt(" #n ")" ::: "memory")
; #define PG8_WAIT_L(n) asm volatile("s_waitcnt lgkmcnt(" #n ")" ::: "memory")
; template <class Map, class Epi>
; DI void gemm_phase(LAS unsigned char* lds, const Map& MP, const Epi& E, const int nM, const int nN, const int K, const int lda, const int ldb) {
;     ...
;         for (int t = 0; t < nt; t += 2) {
;             const bool last = (t == nt - 2);
;             const char* a1 = cA + (size_t)(t + 1) * kstep;
;             const char* a2 = last ? nA : cA + (size_t)(t + 2) * kstep; const char* b2 = last ? nB : cB + (size_t)(t + 2) * kstep;
;             const char* a3 = a2 + kstep; const char* b3 = b2 + kstep;
;             PG8_LDB(B0, 0, 0); PG8_SCHED; PG8_LDA(At, 0, 0); PG8_STAGE(PG8_SA(1, 1), a1 + hstepA, voffA);
;             PG8_WAIT_L(8); PG8_BAR; PG8_WAIT_L(0); PG8_MMA(0, 0, At, B0); PG8_BAR; PG8_SCHED;
;             PG8_LDB(B1, 0, 1); PG8_STAGE(PG8_SB(0, 0), b2, voffB);
;             PG8_BAR; PG8_WAIT_L(0); PG8_MMA(0, 1, At, B1); PG8_BAR;
;             PG8_LDA(At, 0, 1); PG8_STAGE(PG8_SA(0, 0), a2, voffA);
;             PG8_BAR; PG8_WAIT_L(0); PG8_MMA(1, 0, At, B0); PG8_BAR; PG8_SCHED;
;             PG8_STAGE(PG8_SB(0, 1), b2 + hstepB, voffB);
;             PG8_WAIT_V(6); PG8_BAR; PG8_MMA(1, 1, At, B1); PG8_BAR;
.LBB1_2078:
	s_add_u32 s10, s8, 0x100
	s_addc_u32 s11, s9, 0
	s_cmpk_eq_i32 s3, 0x54
	s_cselect_b32 s15, s43, s11
	s_cselect_b32 s14, s42, s10
	s_cselect_b32 s13, s7, s44
	s_cselect_b32 s12, s6, s39
	s_add_i32 m0, s24, 0xc000
	ds_read_b128 v[168:171], v150
	ds_read_b128 v[172:175], v150 offset:1024
	ds_read_b128 v[176:179], v150 offset:2048
	ds_read_b128 v[180:183], v150 offset:3072
	ds_read_b128 v[184:187], v150 offset:4096
	ds_read_b128 v[188:191], v150 offset:5120
	ds_read_b128 v[192:195], v150 offset:6144
	ds_read_b128 v[198:201], v150 offset:7168
	global_load_lds_dwordx4 v138, s[8:9]
	s_add_i32 m0, s24, 0xe000
	s_nop 0
	global_load_lds_dwordx4 v136, s[8:9]
	s_waitcnt lgkmcnt(8)
	s_setprio 1
	s_barrier
	s_waitcnt lgkmcnt(7)
	v_mfma_f32_16x16x32_bf16 v[124:127], v[152:155], v[168:171], v[124:127]
	v_mfma_f32_16x16x32_bf16 v[120:123], v[160:163], v[168:171], v[120:123]
	s_waitcnt lgkmcnt(5)
	v_mfma_f32_16x16x32_bf16 v[108:111], v[152:155], v[176:179], v[108:111]
	v_mfma_f32_16x16x32_bf16 v[104:107], v[160:163], v[176:179], v[104:107]
	s_waitcnt lgkmcnt(3)
	v_mfma_f32_16x16x32_bf16 v[92:95], v[152:155], v[184:187], v[92:95]
	v_mfma_f32_16x16x32_bf16 v[88:91], v[160:163], v[184:187], v[88:91]
	s_waitcnt lgkmcnt(1)
	v_mfma_f32_16x16x32_bf16 v[76:79], v[152:155], v[192:195], v[76:79]
	v_mfma_f32_16x16x32_bf16 v[72:75], v[160:163], v[192:195], v[72:75]
	v_mfma_f32_16x16x32_bf16 v[124:127], v[156:159], v[172:175], v[124:127]
	s_add_i32 s8, s35, s22
	v_mfma_f32_16x16x32_bf16 v[120:123], v[164:167], v[172:175], v[120:123]
	v_lshl_add_u64 v[144:145], s[12:13], 0, v[132:133]
	v_mfma_f32_16x16x32_bf16 v[108:111], v[156:159], v[180:183], v[108:111]
	v_lshl_add_u64 v[218:219], s[12:13], 0, v[128:129]
	v_mfma_f32_16x16x32_bf16 v[104:107], v[164:167], v[180:183], v[104:107]
	v_mfma_f32_16x16x32_bf16 v[92:95], v[156:159], v[188:191], v[92:95]
	v_mfma_f32_16x16x32_bf16 v[88:91], v[164:167], v[188:191], v[88:91]
	s_waitcnt lgkmcnt(0)
	v_mfma_f32_16x16x32_bf16 v[76:79], v[156:159], v[198:201], v[76:79]
	v_mfma_f32_16x16x32_bf16 v[72:75], v[164:167], v[198:201], v[72:75]
	s_barrier
	s_setprio 0
	s_mov_b32 m0, s8
	ds_read_b128 v[202:205], v151
	ds_read_b128 v[206:209], v151 offset:1024
	ds_read_b128 v[210:213], v151 offset:2048
	ds_read_b128 v[214:217], v151 offset:3072
	global_load_lds_dwordx4 v[144:145], off
	s_add_i32 m0, s8, 0x2000
	s_nop 0
	global_load_lds_dwordx4 v[218:219], off
	s_setprio 1
	s_barrier
	s_waitcnt lgkmcnt(3)
	v_mfma_f32_16x16x32_bf16 v[116:119], v[202:205], v[168:171], v[116:119]
	s_waitcnt lgkmcnt(1)
	v_mfma_f32_16x16x32_bf16 v[112:115], v[210:213], v[168:171], v[112:115]
	v_mfma_f32_16x16x32_bf16 v[100:103], v[202:205], v[176:179], v[100:103]
	v_mfma_f32_16x16x32_bf16 v[96:99], v[210:213], v[176:179], v[96:99]
	v_mfma_f32_16x16x32_bf16 v[84:87], v[202:205], v[184:187], v[84:87]
	v_mfma_f32_16x16x32_bf16 v[80:83], v[210:213], v[184:187], v[80:83]
	v_mfma_f32_16x16x32_bf16 v[68:71], v[202:205], v[192:195], v[68:71]
	v_mfma_f32_16x16x32_bf16 v[64:67], v[210:213], v[192:195], v[64:67]
	v_mfma_f32_16x16x32_bf16 v[116:119], v[206:209], v[172:175], v[116:119]
	v_lshl_add_u64 v[222:223], s[14:15], 0, v[130:131]
	s_mov_b32 m0, s24
	s_waitcnt lgkmcnt(0)
	v_mfma_f32_16x16x32_bf16 v[112:115], v[214:217], v[172:175], v[112:115]
	v_lshl_add_u64 v[220:221], s[14:15], 0, v[134:135]
	v_mfma_f32_16x16x32_bf16 v[100:103], v[206:209], v[180:183], v[100:103]
	v_mfma_f32_16x16x32_bf16 v[96:99], v[214:217], v[180:183], v[96:99]
	v_mfma_f32_16x16x32_bf16 v[84:87], v[206:209], v[188:191], v[84:87]
	v_mfma_f32_16x16x32_bf16 v[80:83], v[214:217], v[188:191], v[80:83]
	v_mfma_f32_16x16x32_bf16 v[68:71], v[206:209], v[198:201], v[68:71]
	v_mfma_f32_16x16x32_bf16 v[64:67], v[214:217], v[198:201], v[64:67]
	s_barrier
	s_setprio 0
	ds_read_b128 v[168:171], v150 offset:16384
	ds_read_b128 v[172:175], v150 offset:17408
	ds_read_b128 v[176:179], v150 offset:18432
	ds_read_b128 v[180:183], v150 offset:19456
	ds_read_b128 v[184:187], v150 offset:20480
	ds_read_b128 v[188:191], v150 offset:21504
	ds_read_b128 v[192:195], v150 offset:22528
	ds_read_b128 v[198:201], v150 offset:23552
	global_load_lds_dwordx4 v[220:221], off
	s_mov_b32 m0, s25
	s_nop 0
	global_load_lds_dwordx4 v[222:223], off
	s_waitcnt vmcnt(10)
	s_setprio 1
	s_barrier
	s_waitcnt lgkmcnt(7)
	v_mfma_f32_16x16x32_bf16 v[60:63], v[152:155], v[168:171], v[60:63]
	v_mfma_f32_16x16x32_bf16 v[56:59], v[160:163], v[168:171], v[56:59]
	s_waitcnt lgkmcnt(5)
	v_mfma_f32_16x16x32_bf16 v[44:47], v[152:155], v[176:179], v[44:47]
	v_mfma_f32_16x16x32_bf16 v[40:43], v[160:163], v[176:179], v[40:43]
	s_waitcnt lgkmcnt(3)
	v_mfma_f32_16x16x32_bf16 v[28:31], v[152:155], v[184:187], v[28:31]
	v_mfma_f32_16x16x32_bf16 v[24:27], v[160:163], v[184:187], v[24:27]
	s_waitcnt lgkmcnt(1)
	v_mfma_f32_16x16x32_bf16 v[12:15], v[152:155], v[192:195], v[12:15]
	v_mfma_f32_16x16x32_bf16 v[8:11], v[160:163], v[192:195], v[8:11]
	v_mfma_f32_16x16x32_bf16 v[60:63], v[156:159], v[172:175], v[60:63]
	s_add_u32 s8, s12, 0x160000
	s_addc_u32 s9, s13, 0
	v_mfma_f32_16x16x32_bf16 v[56:59], v[164:167], v[172:175], v[56:59]
	s_add_i32 s45, s36, s22
	v_mfma_f32_16x16x32_bf16 v[44:47], v[156:159], v[180:183], v[44:47]
	v_mfma_f32_16x16x32_bf16 v[40:43], v[164:167], v[180:183], v[40:43]
	v_mfma_f32_16x16x32_bf16 v[28:31], v[156:159], v[188:191], v[28:31]
	v_mfma_f32_16x16x32_bf16 v[24:27], v[164:167], v[188:191], v[24:27]
	s_waitcnt lgkmcnt(0)
	v_mfma_f32_16x16x32_bf16 v[12:15], v[156:159], v[198:201], v[12:15]
	v_mfma_f32_16x16x32_bf16 v[8:11], v[164:167], v[198:201], v[8:11]
	s_barrier
; #define PG8_STAGE(bufoff, gbase, voff) do { _Pragma("unroll") for (int _i = 0; _i < 2; ++_i) \
;         __builtin_amdgcn_global_load_lds((const unsigned*)((const char*)(gbase) + (voff)[_i]), (LAS unsigned*)(lds + (bufoff) + ldsw + _i * 8192), 16, 0, 0); } while (0)
; #define PG8_LDA(dst, b, h) do { _Pragma("unroll") for (int m = 0; m < 4; ++m) _Pragma("unroll") for (int k = 0; k < 2; ++k) dst[m][k] = *(const LAS bf16x8*)(lds + PG8_SA(b, h) + aoff + m * 2048 + k * 1024); } while (0)
; #define PG8_LDB(dst, b, h) do { _Pragma("unroll") for (int n = 0; n < 2; ++n) _Pragma("unroll") for (int k = 0; k < 2; ++k) dst[n][k] = *(const LAS bf16x8*)(lds + PG8_SB(b, h) + boff + n * 2048 + k * 1024); } while (0)
; #define PG8_MMA(ai, bj, At, Bt) do { __builtin_amdgcn_s_setprio(1); _Pragma("unroll") for (int m = 0; m < 4; ++m) _Pragma("unroll") for (int n = 0; n < 2; ++n) _Pragma("unroll") for (int k = 0; k < 2; ++k) \
;         acc[ai][bj][m][n] = __builtin_amdgcn_mfma_f32_16x16x32_bf16(Bt[n][k], At[m][k], acc[ai][bj][m][n], 0, 0, 0); __builtin_amdgcn_s_setprio(0); } while (0)
; #define PG8_WAIT_V(n) asm volatile("s_waitcnt vmcnt(" #n ")" ::: "memory")
; #define PG8_WAIT_L(n) asm volatile("s_waitcnt lgkmcnt(" #n ")" ::: "memory")
; #define PG8_BAR __builtin_amdgcn_s_barrier()
; #define PG8_SCHED __builtin_amdgcn_sched_barrier(0)
; template <class Map, class Epi>
; DI void gemm_phase(LAS unsigned char* lds, const Map& MP, const Epi& E, const int nM, const int nN, const int K, const int lda, const int ldb) {
;     ...
;             PG8_STAGE(PG8_SB(0, 1), b2 + hstepB, voffB);
;             PG8_WAIT_V(6); PG8_BAR; PG8_MMA(1, 1, At, B1); PG8_BAR;
;             PG8_LDB(B0, 1, 0); PG8_SCHED; PG8_LDA(At, 1, 0); PG8_STAGE(PG8_SA(0, 1), a2 + hstepA, voffA);
;             PG8_WAIT_L(8); PG8_BAR; PG8_WAIT_L(0); PG8_MMA(0, 0, At, B0); PG8_BAR; PG8_SCHED;
;             PG8_LDB(B1, 1, 1); PG8_STAGE(PG8_SB(1, 0), b3, voffB);
;             PG8_BAR; PG8_WAIT_L(0); PG8_MMA(0, 1, At, B1); PG8_BAR;
;             PG8_LDA(At, 1, 1); PG8_STAGE(PG8_SA(1, 0), a3, voffA);
;             PG8_BAR; PG8_WAIT_L(0); PG8_MMA(1, 0, At, B0); PG8_BAR; PG8_SCHED;
;             PG8_STAGE(PG8_SB(1, 1), b3 + hstepB, voffB);
	s_setprio 0
	s_mov_b32 m0, s45
	s_nop 0
	global_load_lds_dwordx4 v132, s[8:9]
	s_add_i32 m0, s45, 0x2000
	s_nop 0
	global_load_lds_dwordx4 v128, s[8:9]
	s_waitcnt vmcnt(6)
	s_setprio 1
	s_barrier
	v_mfma_f32_16x16x32_bf16 v[52:55], v[202:205], v[168:171], v[52:55]
	v_mfma_f32_16x16x32_bf16 v[48:51], v[210:213], v[168:171], v[48:51]
	s_add_i32 s45, 0, 0x18000
	v_add_u32_e32 v164, s45, v148
	ds_read_b128 v[152:155], v164
	v_mfma_f32_16x16x32_bf16 v[36:39], v[202:205], v[176:179], v[36:39]
	v_mfma_f32_16x16x32_bf16 v[32:35], v[210:213], v[176:179], v[32:35]
	ds_read_b128 v[156:159], v164 offset:1024
	v_mfma_f32_16x16x32_bf16 v[20:23], v[202:205], v[184:187], v[20:23]
	v_mfma_f32_16x16x32_bf16 v[16:19], v[210:213], v[184:187], v[16:19]
	ds_read_b128 v[160:163], v164 offset:2048
	v_mfma_f32_16x16x32_bf16 v[4:7], v[202:205], v[192:195], v[4:7]
	v_mfma_f32_16x16x32_bf16 v[0:3], v[210:213], v[192:195], v[0:3]
	ds_read_b128 v[164:167], v164 offset:3072
	v_mfma_f32_16x16x32_bf16 v[52:55], v[206:209], v[172:175], v[52:55]
	s_add_u32 s8, s14, 0x160000
	s_addc_u32 s9, s15, 0
	v_mfma_f32_16x16x32_bf16 v[48:51], v[214:217], v[172:175], v[48:51]
	v_mfma_f32_16x16x32_bf16 v[36:39], v[206:209], v[180:183], v[36:39]
	v_mfma_f32_16x16x32_bf16 v[32:35], v[214:217], v[180:183], v[32:35]
	v_mfma_f32_16x16x32_bf16 v[20:23], v[206:209], v[188:191], v[20:23]
	v_mfma_f32_16x16x32_bf16 v[16:19], v[214:217], v[188:191], v[16:19]
	v_mfma_f32_16x16x32_bf16 v[4:7], v[206:209], v[198:201], v[4:7]
	v_mfma_f32_16x16x32_bf16 v[0:3], v[214:217], v[198:201], v[0:3]
	s_barrier
	s_setprio 0
	s_mov_b32 m0, s26
	ds_read_b128 v[168:171], v150 offset:32768
	ds_read_b128 v[172:175], v150 offset:33792
	ds_read_b128 v[176:179], v150 offset:34816
	ds_read_b128 v[180:183], v150 offset:35840
	ds_read_b128 v[184:187], v150 offset:36864
	ds_read_b128 v[188:191], v150 offset:37888
	ds_read_b128 v[192:195], v150 offset:38912
	ds_read_b128 v[198:201], v150 offset:39936
	global_load_lds_dwordx4 v134, s[8:9]
	s_mov_b32 m0, s27
	s_nop 0
	global_load_lds_dwordx4 v130, s[8:9]
	s_waitcnt lgkmcnt(8)
	s_setprio 1
	s_barrier
	s_waitcnt lgkmcnt(7)
	v_mfma_f32_16x16x32_bf16 v[124:127], v[152:155], v[168:171], v[124:127]
	v_mfma_f32_16x16x32_bf16 v[120:123], v[160:163], v[168:171], v[120:123]
	s_waitcnt lgkmcnt(5)
	v_mfma_f32_16x16x32_bf16 v[108:111], v[152:155], v[176:179], v[108:111]
	v_mfma_f32_16x16x32_bf16 v[104:107], v[160:163], v[176:179], v[104:107]
	s_waitcnt lgkmcnt(3)
	v_mfma_f32_16x16x32_bf16 v[92:95], v[152:155], v[184:187], v[92:95]
	v_mfma_f32_16x16x32_bf16 v[88:91], v[160:163], v[184:187], v[88:91]
	s_waitcnt lgkmcnt(1)
	v_mfma_f32_16x16x32_bf16 v[76:79], v[152:155], v[192:195], v[76:79]
	v_mfma_f32_16x16x32_bf16 v[72:75], v[160:163], v[192:195], v[72:75]
	v_mfma_f32_16x16x32_bf16 v[124:127], v[156:159], v[172:175], v[124:127]
	s_add_i32 s14, 0, 0x1c000
	v_mfma_f32_16x16x32_bf16 v[120:123], v[164:167], v[172:175], v[120:123]
	s_add_i32 s8, s45, s22
	v_mfma_f32_16x16x32_bf16 v[108:111], v[156:159], v[180:183], v[108:111]
	v_add_u32_e32 v196, s14, v148
	v_mfma_f32_16x16x32_bf16 v[104:107], v[164:167], v[180:183], v[104:107]
	v_lshl_add_u64 v[144:145], v[144:145], 0, s[46:47]
	v_mfma_f32_16x16x32_bf16 v[92:95], v[156:159], v[188:191], v[92:95]
	v_mfma_f32_16x16x32_bf16 v[88:91], v[164:167], v[188:191], v[88:91]
	s_waitcnt lgkmcnt(0)
	v_mfma_f32_16x16x32_bf16 v[76:79], v[156:159], v[198:201], v[76:79]
	v_mfma_f32_16x16x32_bf16 v[72:75], v[164:167], v[198:201], v[72:75]
	s_barrier
	s_setprio 0
	s_mov_b32 m0, s8
	ds_read_b128 v[202:205], v196
	ds_read_b128 v[206:209], v196 offset:1024
	ds_read_b128 v[210:213], v196 offset:2048
	ds_read_b128 v[214:217], v196 offset:3072
	global_load_lds_dwordx4 v[144:145], off
	v_lshl_add_u64 v[144:145], v[218:219], 0, s[46:47]
	s_add_i32 m0, s8, 0x2000
	s_nop 0
	global_load_lds_dwordx4 v[144:145], off
	s_setprio 1
	s_barrier
	s_waitcnt lgkmcnt(3)
	v_mfma_f32_16x16x32_bf16 v[116:119], v[202:205], v[168:171], v[116:119]
	s_waitcnt lgkmcnt(1)
	v_mfma_f32_16x16x32_bf16 v[112:115], v[210:213], v[168:171], v[112:115]
	v_mfma_f32_16x16x32_bf16 v[100:103], v[202:205], v[176:179], v[100:103]
	v_mfma_f32_16x16x32_bf16 v[96:99], v[210:213], v[176:179], v[96:99]
	v_mfma_f32_16x16x32_bf16 v[84:87], v[202:205], v[184:187], v[84:87]
	v_mfma_f32_16x16x32_bf16 v[80:83], v[210:213], v[184:187], v[80:83]
	v_mfma_f32_16x16x32_bf16 v[68:71], v[202:205], v[192:195], v[68:71]
	v_mfma_f32_16x16x32_bf16 v[64:67], v[210:213], v[192:195], v[64:67]
	v_mfma_f32_16x16x32_bf16 v[116:119], v[206:209], v[172:175], v[116:119]
	s_mov_b32 m0, s30
	s_waitcnt lgkmcnt(0)
	v_mfma_f32_16x16x32_bf16 v[112:115], v[214:217], v[172:175], v[112:115]
	v_lshl_add_u64 v[144:145], v[220:221], 0, s[46:47]
	v_mfma_f32_16x16x32_bf16 v[100:103], v[206:209], v[180:183], v[100:103]
	v_mfma_f32_16x16x32_bf16 v[96:99], v[214:217], v[180:183], v[96:99]
	v_mfma_f32_16x16x32_bf16 v[84:87], v[206:209], v[188:191], v[84:87]
	v_mfma_f32_16x16x32_bf16 v[80:83], v[214:217], v[188:191], v[80:83]
	v_mfma_f32_16x16x32_bf16 v[68:71], v[206:209], v[198:201], v[68:71]
	v_mfma_f32_16x16x32_bf16 v[64:67], v[214:217], v[198:201], v[64:67]
	s_barrier
	s_setprio 0
	ds_read_b128 v[168:171], v150 offset:49152
	ds_read_b128 v[172:175], v150 offset:50176
	ds_read_b128 v[176:179], v150 offset:51200
	ds_read_b128 v[180:183], v150 offset:52224
	ds_read_b128 v[184:187], v150 offset:53248
	ds_read_b128 v[188:191], v150 offset:54272
	ds_read_b128 v[192:195], v150 offset:55296
	ds_read_b128 v[198:201], v150 offset:56320
	global_load_lds_dwordx4 v[144:145], off
	v_lshl_add_u64 v[144:145], v[222:223], 0, s[46:47]
	s_mov_b32 m0, s31
	s_nop 0
	global_load_lds_dwordx4 v[144:145], off
	s_waitcnt vmcnt(10)
	s_setprio 1
	s_barrier
; DI unsigned pack2(float a, float b) { f32x2 v = {a, b}; hwbf16x2 r = __builtin_convertvector(v, hwbf16x2); return __builtin_bit_cast(unsigned, r); }
; DI float bflo(unsigned w) { return __uint_as_float(w << 16); }
; DI float bfhi(unsigned w) { return __uint_as_float(w & 0xffff0000u); }
; #define PG8_STAGE(bufoff, gbase, voff) do { _Pragma("unroll") for (int _i = 0; _i < 2; ++_i) \
;         __builtin_amdgcn_global_load_lds((const unsigned*)((const char*)(gbase) + (voff)[_i]), (LAS unsigned*)(lds + (bufoff) + ldsw + _i * 8192), 16, 0, 0); } while (0)
; #define PG8_LDA(dst, b, h) do { _Pragma("unroll") for (int m = 0; m < 4; ++m) _Pragma("unroll") for (int k = 0; k < 2; ++k) dst[m][k] = *(const LAS bf16x8*)(lds + PG8_SA(b, h) + aoff + m * 2048 + k * 1024); } while (0)
; #define PG8_BAR __builtin_amdgcn_s_barrier()
;     DI void operator()(const f32x4 (&acc)[2][2][4][2], const Unit& u, int wr, int wc, int fr, int fq) const {
;     ...
;             for (int m = 0; m < 4; ++m) { const size_t ro = (size_t)(row0 + ai * HALF + m * 16) * D + col0;
; #pragma unroll
;                 for (int bj = 0; bj < 2; ++bj) {
;                     f32x4 x0, x1;
;                     if constexpr (IB) { const u32x4 w = *(const u32x4*)((const bf16_t*)Xin + ro + bj * HALF);
;                         x0 = (f32x4){bflo(w[0]), bfhi(w[0]), bflo(w[1]), bfhi(w[1])}; x1 = (f32x4){bflo(w[2]), bfhi(w[2]), bflo(w[3]), bfhi(w[3])}; }
;                     else { x0 = *(const f32x4*)((const float*)Xin + ro + bj * HALF); x1 = *(const f32x4*)((const float*)Xin + ro + bj * HALF + 4); }
;                     x0 += acc[ai][bj][m][0] * sc[bj][0]; x1 += acc[ai][bj][m][1] * sc[bj][1];
;                     if constexpr (OB) { u32x4 o; o[0] = pack2(x0[0], x0[1]); o[1] = pack2(x0[2], x0[3]); o[2] = pack2(x1[0], x1[1]); o[3] = pack2(x1[2], x1[3]);
;                         *(u32x4*)((bf16_t*)Xout + ro + bj * HALF) = o; }
; template <class Map, class Epi>
; DI void gemm_phase(LAS unsigned char* lds, const Map& MP, const Epi& E, const int nM, const int nN, const int K, const int lda, const int ldb) {
;     ...
;             PG8_LDA(At, 1, 1); PG8_STAGE(PG8_SA(1, 0), a3, voffA);
;             PG8_BAR; PG8_WAIT_L(0); PG8_MMA(1, 0, At, B0); PG8_BAR; PG8_SCHED;
;             PG8_STAGE(PG8_SB(1, 1), b3 + hstepB, voffB);
;             PG8_WAIT_V(6); PG8_BAR; PG8_MMA(1, 1, At, B1); PG8_BAR;
;         }
	s_waitcnt lgkmcnt(7)
	v_mfma_f32_16x16x32_bf16 v[60:63], v[152:155], v[168:171], v[60:63]
	v_mfma_f32_16x16x32_bf16 v[56:59], v[160:163], v[168:171], v[56:59]
	s_waitcnt lgkmcnt(5)
	v_mfma_f32_16x16x32_bf16 v[44:47], v[152:155], v[176:179], v[44:47]
	v_mfma_f32_16x16x32_bf16 v[40:43], v[160:163], v[176:179], v[40:43]
	s_waitcnt lgkmcnt(3)
	v_mfma_f32_16x16x32_bf16 v[28:31], v[152:155], v[184:187], v[28:31]
	v_mfma_f32_16x16x32_bf16 v[24:27], v[160:163], v[184:187], v[24:27]
	s_waitcnt lgkmcnt(1)
	v_mfma_f32_16x16x32_bf16 v[12:15], v[152:155], v[192:195], v[12:15]
	v_mfma_f32_16x16x32_bf16 v[8:11], v[160:163], v[192:195], v[8:11]
	v_mfma_f32_16x16x32_bf16 v[60:63], v[156:159], v[172:175], v[60:63]
	s_add_u32 s8, s12, 0x160080
	s_addc_u32 s9, s13, 0
	v_mfma_f32_16x16x32_bf16 v[56:59], v[164:167], v[172:175], v[56:59]
	s_add_i32 s12, s14, s22
	v_mfma_f32_16x16x32_bf16 v[44:47], v[156:159], v[180:183], v[44:47]
	v_mfma_f32_16x16x32_bf16 v[40:43], v[164:167], v[180:183], v[40:43]
	v_mfma_f32_16x16x32_bf16 v[28:31], v[156:159], v[188:191], v[28:31]
	v_mfma_f32_16x16x32_bf16 v[24:27], v[164:167], v[188:191], v[24:27]
	s_waitcnt lgkmcnt(0)
	v_mfma_f32_16x16x32_bf16 v[12:15], v[156:159], v[198:201], v[12:15]
	v_mfma_f32_16x16x32_bf16 v[8:11], v[164:167], v[198:201], v[8:11]
	s_barrier
	s_setprio 0
	s_mov_b32 m0, s12
	s_nop 0
	global_load_lds_dwordx4 v132, s[8:9]
	s_add_i32 m0, s12, 0x2000
	s_nop 0
	global_load_lds_dwordx4 v128, s[8:9]
	s_waitcnt vmcnt(6)
	s_setprio 1
	s_barrier
	v_mfma_f32_16x16x32_bf16 v[52:55], v[202:205], v[168:171], v[52:55]
	v_mfma_f32_16x16x32_bf16 v[48:51], v[210:213], v[168:171], v[48:51]
	ds_read_b128 v[152:155], v149
	v_mfma_f32_16x16x32_bf16 v[36:39], v[202:205], v[176:179], v[36:39]
	v_mfma_f32_16x16x32_bf16 v[32:35], v[210:213], v[176:179], v[32:35]
	ds_read_b128 v[156:159], v149 offset:1024
	v_mfma_f32_16x16x32_bf16 v[20:23], v[202:205], v[184:187], v[20:23]
	v_mfma_f32_16x16x32_bf16 v[16:19], v[210:213], v[184:187], v[16:19]
	ds_read_b128 v[160:163], v149 offset:2048
	v_mfma_f32_16x16x32_bf16 v[4:7], v[202:205], v[192:195], v[4:7]
	v_mfma_f32_16x16x32_bf16 v[0:3], v[210:213], v[192:195], v[0:3]
	ds_read_b128 v[164:167], v149 offset:3072
	v_mfma_f32_16x16x32_bf16 v[52:55], v[206:209], v[172:175], v[52:55]
	s_add_i32 s3, s3, 2
	v_mfma_f32_16x16x32_bf16 v[48:51], v[214:217], v[172:175], v[48:51]
	s_add_u32 s39, s39, 0x100
	s_addc_u32 s44, s44, 0
	v_mfma_f32_16x16x32_bf16 v[36:39], v[206:209], v[180:183], v[36:39]
	s_cmpk_gt_u32 s3, 0x55
	v_mfma_f32_16x16x32_bf16 v[32:35], v[214:217], v[180:183], v[32:35]
	s_mov_b64 s[8:9], s[10:11]
	v_mfma_f32_16x16x32_bf16 v[20:23], v[206:209], v[188:191], v[20:23]
	v_mfma_f32_16x16x32_bf16 v[16:19], v[214:217], v[188:191], v[16:19]
	v_mfma_f32_16x16x32_bf16 v[4:7], v[206:209], v[198:201], v[4:7]
	v_mfma_f32_16x16x32_bf16 v[0:3], v[214:217], v[198:201], v[0:3]
	s_barrier
	s_setprio 0
	s_cbranch_scc0 .LBB1_2078
	s_waitcnt lgkmcnt(0)
	v_mov_b32_e32 v152, v147
	v_mov_b32_e32 v144, v146
	s_lshl_b32 s2, s2, 8
	s_add_i32 s2, s2, s29
	s_lshl_b32 s3, s38, 8
	v_add_u32_e32 v152, s2, v152
	s_or_b32 s3, s3, s52
	v_ashrrev_i32_e32 v153, 31, v152
	v_lshl_add_u32 v144, v144, 3, s3
	v_lshlrev_b64 v[152:153], 12, v[152:153]
	v_ashrrev_i32_e32 v145, 31, v144
	v_lshl_add_u64 v[152:153], s[4:5], 0, v[152:153]
	v_lshl_add_u64 v[144:145], v[144:145], 1, v[152:153]
	global_load_dwordx4 v[160:163], v[144:145], off
	global_load_dwordx4 v[164:167], v[144:145], off offset:256
	s_mov_b64 s[98:99], 0x10000
	v_lshl_add_u64 v[154:155], v[144:145], 0, s[98:99]
	global_load_dwordx4 v[168:171], v[154:155], off
	global_load_dwordx4 v[172:175], v[154:155], off offset:256
	s_mov_b64 s[98:99], 0x20000
	v_lshl_add_u64 v[154:155], v[144:145], 0, s[98:99]
	global_load_dwordx4 v[176:179], v[154:155], off
	global_load_dwordx4 v[180:183], v[154:155], off offset:256
	s_mov_b64 s[98:99], 0x30000
	v_lshl_add_u64 v[154:155], v[144:145], 0, s[98:99]
	global_load_dwordx4 v[184:187], v[154:155], off
	global_load_dwordx4 v[188:191], v[154:155], off offset:256
	s_mov_b64 s[98:99], 0x80000
	v_lshl_add_u64 v[154:155], v[144:145], 0, s[98:99]
	global_load_dwordx4 v[192:195], v[154:155], off
	global_load_dwordx4 v[198:201], v[154:155], off offset:256
	s_mov_b64 s[98:99], 0x90000
	v_lshl_add_u64 v[154:155], v[144:145], 0, s[98:99]
	global_load_dwordx4 v[202:205], v[154:155], off
	global_load_dwordx4 v[206:209], v[154:155], off offset:256
	s_mov_b64 s[98:99], 0xa0000
	v_lshl_add_u64 v[154:155], v[144:145], 0, s[98:99]
	global_load_dwordx4 v[210:213], v[154:155], off
	global_load_dwordx4 v[214:217], v[154:155], off offset:256
	s_mov_b64 s[98:99], 0xb0000
	v_lshl_add_u64 v[154:155], v[144:145], 0, s[98:99]
	global_load_dwordx4 v[248:251], v[154:155], off
	global_load_dwordx4 v[252:255], v[154:155], off offset:256
	s_waitcnt vmcnt(15)
	s_nop 1
	v_mov_b32_e32 v152, v160
	v_mov_b32_e32 v153, v161
	v_mov_b32_e32 v154, v162
	v_mov_b32_e32 v155, v163
	s_mov_b64 s[2:3], 0x10000
	s_mov_b32 s38, s37
	s_mov_b64 s[10:11], s[6:7]
	s_mov_b64 s[8:9], s[42:43]
	s_waitcnt lgkmcnt(0)
	v_lshlrev_b32_e32 v156, 16, v152
	v_and_b32_e32 v157, 0xffff0000, v152
	v_lshlrev_b32_e32 v152, 16, v153
	v_and_b32_e32 v153, 0xffff0000, v153
	v_lshlrev_b32_e32 v158, 16, v154
	v_and_b32_e32 v159, 0xffff0000, v154
	v_lshlrev_b32_e32 v154, 16, v155
	v_and_b32_e32 v155, 0xffff0000, v155
	v_pk_add_f32 v[126:127], v[126:127], v[152:153]
	v_pk_add_f32 v[124:125], v[124:125], v[156:157]
	v_pk_add_f32 v[152:153], v[122:123], v[154:155]
	v_pk_add_f32 v[122:123], v[120:121], v[158:159]
	v_cvt_pk_bf16_f32 v120, v124, v125
	v_cvt_pk_bf16_f32 v121, v126, v127
	v_cvt_pk_bf16_f32 v122, v122, v123
	v_cvt_pk_bf16_f32 v123, v152, v153
	global_store_dwordx4 v[144:145], v[120:123], off
	s_waitcnt vmcnt(15)
; DI unsigned pack2(float a, float b) { f32x2 v = {a, b}; hwbf16x2 r = __builtin_convertvector(v, hwbf16x2); return __builtin_bit_cast(unsigned, r); }
; DI float bflo(unsigned w) { return __uint_as_float(w << 16); }
; DI float bfhi(unsigned w) { return __uint_as_float(w & 0xffff0000u); }
;     DI void operator()(const f32x4 (&acc)[2][2][4][2], const Unit& u, int wr, int wc, int fr, int fq) const {
;     ...
;             for (int m = 0; m < 4; ++m) { const size_t ro = (size_t)(row0 + ai * HALF + m * 16) * D + col0;
; #pragma unroll
;                 for (int bj = 0; bj < 2; ++bj) {
;                     f32x4 x0, x1;
;                     if constexpr (IB) { const u32x4 w = *(const u32x4*)((const bf16_t*)Xin + ro + bj * HALF);
;                         x0 = (f32x4){bflo(w[0]), bfhi(w[0]), bflo(w[1]), bfhi(w[1])}; x1 = (f32x4){bflo(w[2]), bfhi(w[2]), bflo(w[3]), bfhi(w[3])}; }
;                     else { x0 = *(const f32x4*)((const float*)Xin + ro + bj * HALF); x1 = *(const f32x4*)((const float*)Xin + ro + bj * HALF + 4); }
;                     x0 += acc[ai][bj][m][0] * sc[bj][0]; x1 += acc[ai][bj][m][1] * sc[bj][1];
;                     if constexpr (OB) { u32x4 o; o[0] = pack2(x0[0], x0[1]); o[1] = pack2(x0[2], x0[3]); o[2] = pack2(x1[0], x1[1]); o[3] = pack2(x1[2], x1[3]);
;                         *(u32x4*)((bf16_t*)Xout + ro + bj * HALF) = o; }
;                     else { *(f32x4*)((float*)Xout + ro + bj * HALF) = x0; *(f32x4*)((float*)Xout + ro + bj * HALF + 4) = x1; } } }
	s_nop 1
	v_mov_b32_e32 v120, v164
	v_mov_b32_e32 v121, v165
	v_mov_b32_e32 v122, v166
	v_mov_b32_e32 v123, v167
	s_waitcnt lgkmcnt(0)
	v_lshlrev_b32_e32 v124, 16, v120
	v_and_b32_e32 v125, 0xffff0000, v120
	v_lshlrev_b32_e32 v120, 16, v121
	v_and_b32_e32 v121, 0xffff0000, v121
	v_lshlrev_b32_e32 v126, 16, v122
	v_and_b32_e32 v127, 0xffff0000, v122
	v_lshlrev_b32_e32 v122, 16, v123
	v_and_b32_e32 v123, 0xffff0000, v123
	v_pk_add_f32 v[116:117], v[116:117], v[124:125]
	v_pk_add_f32 v[118:119], v[118:119], v[120:121]
	v_pk_add_f32 v[120:121], v[114:115], v[122:123]
	v_pk_add_f32 v[114:115], v[112:113], v[126:127]
	v_cvt_pk_bf16_f32 v112, v116, v117
	v_lshl_add_u64 v[116:117], v[144:145], 0, s[2:3]
	s_mov_b32 s2, 0x10000
	v_cvt_pk_bf16_f32 v113, v118, v119
	v_add_co_u32_e32 v118, vcc, s2, v144
	v_cvt_pk_bf16_f32 v114, v114, v115
	v_cvt_pk_bf16_f32 v115, v120, v121
	v_addc_co_u32_e32 v119, vcc, 0, v145, vcc
	global_store_dwordx4 v[144:145], v[112:115], off offset:256
	s_waitcnt vmcnt(15)
	s_nop 1
	v_mov_b32_e32 v112, v168
	v_mov_b32_e32 v113, v169
	v_mov_b32_e32 v114, v170
	v_mov_b32_e32 v115, v171
	s_mov_b64 s[2:3], 0x20000
	s_waitcnt lgkmcnt(0)
	v_lshlrev_b32_e32 v120, 16, v112
	v_and_b32_e32 v121, 0xffff0000, v112
	v_lshlrev_b32_e32 v112, 16, v113
	v_and_b32_e32 v113, 0xffff0000, v113
	v_lshlrev_b32_e32 v122, 16, v114
	v_and_b32_e32 v123, 0xffff0000, v114
	v_lshlrev_b32_e32 v114, 16, v115
	v_and_b32_e32 v115, 0xffff0000, v115
	v_pk_add_f32 v[110:111], v[110:111], v[112:113]
	v_pk_add_f32 v[108:109], v[108:109], v[120:121]
	v_pk_add_f32 v[112:113], v[106:107], v[114:115]
	v_pk_add_f32 v[106:107], v[104:105], v[122:123]
	v_cvt_pk_bf16_f32 v104, v108, v109
	v_cvt_pk_bf16_f32 v105, v110, v111
	v_cvt_pk_bf16_f32 v106, v106, v107
	v_cvt_pk_bf16_f32 v107, v112, v113
	global_store_dwordx4 v[118:119], v[104:107], off
	s_waitcnt vmcnt(15)
	s_nop 1
	v_mov_b32_e32 v104, v172
	v_mov_b32_e32 v105, v173
	v_mov_b32_e32 v106, v174
	v_mov_b32_e32 v107, v175
	s_waitcnt lgkmcnt(0)
	v_lshlrev_b32_e32 v108, 16, v104
	v_and_b32_e32 v109, 0xffff0000, v104
	v_lshlrev_b32_e32 v104, 16, v105
	v_and_b32_e32 v105, 0xffff0000, v105
	v_lshlrev_b32_e32 v110, 16, v106
	v_and_b32_e32 v111, 0xffff0000, v106
	v_lshlrev_b32_e32 v106, 16, v107
	v_and_b32_e32 v107, 0xffff0000, v107
	v_pk_add_f32 v[100:101], v[100:101], v[108:109]
	v_pk_add_f32 v[102:103], v[102:103], v[104:105]
	v_pk_add_f32 v[104:105], v[98:99], v[106:107]
	v_pk_add_f32 v[98:99], v[96:97], v[110:111]
	v_cvt_pk_bf16_f32 v96, v100, v101
	v_lshl_add_u64 v[100:101], v[144:145], 0, s[2:3]
	s_mov_b32 s2, 0x20000
	v_cvt_pk_bf16_f32 v97, v102, v103
	v_add_co_u32_e32 v102, vcc, s2, v144
	v_cvt_pk_bf16_f32 v98, v98, v99
	v_cvt_pk_bf16_f32 v99, v104, v105
	v_addc_co_u32_e32 v103, vcc, 0, v145, vcc
	global_store_dwordx4 v[116:117], v[96:99], off offset:256
	s_waitcnt vmcnt(15)
	s_nop 1
	v_mov_b32_e32 v96, v176
	v_mov_b32_e32 v97, v177
	v_mov_b32_e32 v98, v178
	v_mov_b32_e32 v99, v179
	s_mov_b64 s[2:3], 0x30000
	s_waitcnt lgkmcnt(0)
	v_lshlrev_b32_e32 v104, 16, v96
	v_and_b32_e32 v105, 0xffff0000, v96
	v_lshlrev_b32_e32 v96, 16, v97
	v_and_b32_e32 v97, 0xffff0000, v97
	v_lshlrev_b32_e32 v106, 16, v98
	v_and_b32_e32 v107, 0xffff0000, v98
	v_lshlrev_b32_e32 v98, 16, v99
	v_and_b32_e32 v99, 0xffff0000, v99
	v_pk_add_f32 v[94:95], v[94:95], v[96:97]
	v_pk_add_f32 v[92:93], v[92:93], v[104:105]
	v_pk_add_f32 v[96:97], v[90:91], v[98:99]
	v_pk_add_f32 v[90:91], v[88:89], v[106:107]
	v_cvt_pk_bf16_f32 v88, v92, v93
	v_cvt_pk_bf16_f32 v89, v94, v95
	v_cvt_pk_bf16_f32 v90, v90, v91
	v_cvt_pk_bf16_f32 v91, v96, v97
	global_store_dwordx4 v[102:103], v[88:91], off
	s_waitcnt vmcnt(15)
	s_nop 1
	v_mov_b32_e32 v88, v180
	v_mov_b32_e32 v89, v181
	v_mov_b32_e32 v90, v182
	v_mov_b32_e32 v91, v183
	s_waitcnt lgkmcnt(0)
	v_lshlrev_b32_e32 v92, 16, v88
	v_and_b32_e32 v93, 0xffff0000, v88
	v_lshlrev_b32_e32 v88, 16, v89
	v_and_b32_e32 v89, 0xffff0000, v89
	v_lshlrev_b32_e32 v94, 16, v90
	v_and_b32_e32 v95, 0xffff0000, v90
	v_lshlrev_b32_e32 v90, 16, v91
	v_and_b32_e32 v91, 0xffff0000, v91
	v_pk_add_f32 v[86:87], v[86:87], v[88:89]
	v_pk_add_f32 v[84:85], v[84:85], v[92:93]
	v_pk_add_f32 v[88:89], v[82:83], v[90:91]
	v_pk_add_f32 v[82:83], v[80:81], v[94:95]
	v_cvt_pk_bf16_f32 v80, v84, v85
	v_cvt_pk_bf16_f32 v81, v86, v87
	v_cvt_pk_bf16_f32 v82, v82, v83
	v_cvt_pk_bf16_f32 v83, v88, v89
	global_store_dwordx4 v[100:101], v[80:83], off offset:256
	s_nop 1
	v_lshl_add_u64 v[80:81], v[144:145], 0, s[2:3]
	s_mov_b32 s2, 0x30000
	v_add_co_u32_e32 v86, vcc, s2, v144
	s_mov_b64 s[2:3], 0x80000
	s_nop 0
	v_addc_co_u32_e32 v87, vcc, 0, v145, vcc
	s_waitcnt vmcnt(15)
	s_nop 1
	v_mov_b32_e32 v82, v184
	v_mov_b32_e32 v83, v185
	v_mov_b32_e32 v84, v186
	v_mov_b32_e32 v85, v187
	s_waitcnt lgkmcnt(0)
	v_lshlrev_b32_e32 v88, 16, v82
	v_and_b32_e32 v89, 0xffff0000, v82
	v_lshlrev_b32_e32 v82, 16, v83
	v_and_b32_e32 v83, 0xffff0000, v83
	v_lshlrev_b32_e32 v90, 16, v84
	v_and_b32_e32 v91, 0xffff0000, v84
	v_lshlrev_b32_e32 v84, 16, v85
	v_and_b32_e32 v85, 0xffff0000, v85
	v_pk_add_f32 v[78:79], v[78:79], v[82:83]
	v_pk_add_f32 v[76:77], v[76:77], v[88:89]
	v_pk_add_f32 v[82:83], v[74:75], v[84:85]
	v_pk_add_f32 v[74:75], v[72:73], v[90:91]
	v_cvt_pk_bf16_f32 v72, v76, v77
	v_cvt_pk_bf16_f32 v73, v78, v79
	v_cvt_pk_bf16_f32 v74, v74, v75
	v_cvt_pk_bf16_f32 v75, v82, v83
	global_store_dwordx4 v[86:87], v[72:75], off
	s_waitcnt vmcnt(15)
	s_nop 1
	v_mov_b32_e32 v72, v188
	v_mov_b32_e32 v73, v189
	v_mov_b32_e32 v74, v190
	v_mov_b32_e32 v75, v191
	s_waitcnt lgkmcnt(0)
; DI unsigned pack2(float a, float b) { f32x2 v = {a, b}; hwbf16x2 r = __builtin_convertvector(v, hwbf16x2); return __builtin_bit_cast(unsigned, r); }
; DI float bflo(unsigned w) { return __uint_as_float(w << 16); }
; DI float bfhi(unsigned w) { return __uint_as_float(w & 0xffff0000u); }
;     DI void operator()(const f32x4 (&acc)[2][2][4][2], const Unit& u, int wr, int wc, int fr, int fq) const {
;     ...
;             for (int m = 0; m < 4; ++m) { const size_t ro = (size_t)(row0 + ai * HALF + m * 16) * D + col0;
; #pragma unroll
;                 for (int bj = 0; bj < 2; ++bj) {
;                     f32x4 x0, x1;
;                     if constexpr (IB) { const u32x4 w = *(const u32x4*)((const bf16_t*)Xin + ro + bj * HALF);
;                         x0 = (f32x4){bflo(w[0]), bfhi(w[0]), bflo(w[1]), bfhi(w[1])}; x1 = (f32x4){bflo(w[2]), bfhi(w[2]), bflo(w[3]), bfhi(w[3])}; }
;                     else { x0 = *(const f32x4*)((const float*)Xin + ro + bj * HALF); x1 = *(const f32x4*)((const float*)Xin + ro + bj * HALF + 4); }
;                     x0 += acc[ai][bj][m][0] * sc[bj][0]; x1 += acc[ai][bj][m][1] * sc[bj][1];
;                     if constexpr (OB) { u32x4 o; o[0] = pack2(x0[0], x0[1]); o[1] = pack2(x0[2], x0[3]); o[2] = pack2(x1[0], x1[1]); o[3] = pack2(x1[2], x1[3]);
;                         *(u32x4*)((bf16_t*)Xout + ro + bj * HALF) = o; }
;                     else { *(f32x4*)((float*)Xout + ro + bj * HALF) = x0; *(f32x4*)((float*)Xout + ro + bj * HALF + 4) = x1; } } }
	v_lshlrev_b32_e32 v76, 16, v72
	v_and_b32_e32 v77, 0xffff0000, v72
	v_lshlrev_b32_e32 v72, 16, v73
	v_and_b32_e32 v73, 0xffff0000, v73
	v_lshlrev_b32_e32 v78, 16, v74
	v_and_b32_e32 v79, 0xffff0000, v74
	v_lshlrev_b32_e32 v74, 16, v75
	v_and_b32_e32 v75, 0xffff0000, v75
	v_pk_add_f32 v[70:71], v[70:71], v[72:73]
	v_pk_add_f32 v[68:69], v[68:69], v[76:77]
	v_pk_add_f32 v[72:73], v[66:67], v[74:75]
	v_pk_add_f32 v[66:67], v[64:65], v[78:79]
	v_cvt_pk_bf16_f32 v64, v68, v69
	v_cvt_pk_bf16_f32 v65, v70, v71
	v_cvt_pk_bf16_f32 v66, v66, v67
	v_cvt_pk_bf16_f32 v67, v72, v73
	global_store_dwordx4 v[80:81], v[64:67], off offset:256
	s_nop 1
	v_lshl_add_u64 v[64:65], v[144:145], 0, s[2:3]
	s_mov_b32 s2, 0x80000
	v_add_co_u32_e32 v70, vcc, s2, v144
	s_mov_b64 s[2:3], 0x90000
	s_nop 0
	v_addc_co_u32_e32 v71, vcc, 0, v145, vcc
	s_waitcnt vmcnt(15)
	s_nop 1
	v_mov_b32_e32 v66, v192
	v_mov_b32_e32 v67, v193
	v_mov_b32_e32 v68, v194
	v_mov_b32_e32 v69, v195
	s_waitcnt lgkmcnt(0)
	v_lshlrev_b32_e32 v72, 16, v66
	v_and_b32_e32 v73, 0xffff0000, v66
	v_lshlrev_b32_e32 v66, 16, v67
	v_and_b32_e32 v67, 0xffff0000, v67
	v_lshlrev_b32_e32 v74, 16, v68
	v_and_b32_e32 v75, 0xffff0000, v68
	v_lshlrev_b32_e32 v68, 16, v69
	v_and_b32_e32 v69, 0xffff0000, v69
	v_pk_add_f32 v[62:63], v[62:63], v[66:67]
	v_pk_add_f32 v[60:61], v[60:61], v[72:73]
	v_pk_add_f32 v[66:67], v[58:59], v[68:69]
	v_pk_add_f32 v[58:59], v[56:57], v[74:75]
	v_cvt_pk_bf16_f32 v56, v60, v61
	v_cvt_pk_bf16_f32 v57, v62, v63
	v_cvt_pk_bf16_f32 v58, v58, v59
	v_cvt_pk_bf16_f32 v59, v66, v67
	global_store_dwordx4 v[70:71], v[56:59], off
	s_waitcnt vmcnt(15)
	s_nop 1
	v_mov_b32_e32 v56, v198
	v_mov_b32_e32 v57, v199
	v_mov_b32_e32 v58, v200
	v_mov_b32_e32 v59, v201
	s_waitcnt lgkmcnt(0)
	v_lshlrev_b32_e32 v60, 16, v56
	v_and_b32_e32 v61, 0xffff0000, v56
	v_lshlrev_b32_e32 v56, 16, v57
	v_and_b32_e32 v57, 0xffff0000, v57
	v_lshlrev_b32_e32 v62, 16, v58
	v_and_b32_e32 v63, 0xffff0000, v58
	v_lshlrev_b32_e32 v58, 16, v59
	v_and_b32_e32 v59, 0xffff0000, v59
	v_pk_add_f32 v[54:55], v[54:55], v[56:57]
	v_pk_add_f32 v[52:53], v[52:53], v[60:61]
	v_pk_add_f32 v[56:57], v[50:51], v[58:59]
	v_pk_add_f32 v[50:51], v[48:49], v[62:63]
	v_cvt_pk_bf16_f32 v48, v52, v53
	v_cvt_pk_bf16_f32 v49, v54, v55
	v_cvt_pk_bf16_f32 v50, v50, v51
	v_cvt_pk_bf16_f32 v51, v56, v57
	global_store_dwordx4 v[64:65], v[48:51], off offset:256
	s_nop 1
	v_lshl_add_u64 v[48:49], v[144:145], 0, s[2:3]
	s_mov_b32 s2, 0x90000
	v_add_co_u32_e32 v54, vcc, s2, v144
	s_mov_b64 s[2:3], 0xa0000
	s_nop 0
	v_addc_co_u32_e32 v55, vcc, 0, v145, vcc
	s_waitcnt vmcnt(15)
	s_nop 1
	v_mov_b32_e32 v50, v202
	v_mov_b32_e32 v51, v203
	v_mov_b32_e32 v52, v204
	v_mov_b32_e32 v53, v205
	s_waitcnt lgkmcnt(0)
	v_lshlrev_b32_e32 v56, 16, v50
	v_and_b32_e32 v57, 0xffff0000, v50
	v_lshlrev_b32_e32 v50, 16, v51
	v_and_b32_e32 v51, 0xffff0000, v51
	v_lshlrev_b32_e32 v58, 16, v52
	v_and_b32_e32 v59, 0xffff0000, v52
	v_lshlrev_b32_e32 v52, 16, v53
	v_and_b32_e32 v53, 0xffff0000, v53
	v_pk_add_f32 v[46:47], v[46:47], v[50:51]
	v_pk_add_f32 v[44:45], v[44:45], v[56:57]
	v_pk_add_f32 v[50:51], v[42:43], v[52:53]
	v_pk_add_f32 v[42:43], v[40:41], v[58:59]
	v_cvt_pk_bf16_f32 v40, v44, v45
	v_cvt_pk_bf16_f32 v41, v46, v47
	v_cvt_pk_bf16_f32 v42, v42, v43
	v_cvt_pk_bf16_f32 v43, v50, v51
	global_store_dwordx4 v[54:55], v[40:43], off
	s_waitcnt vmcnt(15)
	s_nop 1
	v_mov_b32_e32 v40, v206
	v_mov_b32_e32 v41, v207
	v_mov_b32_e32 v42, v208
	v_mov_b32_e32 v43, v209
	s_waitcnt lgkmcnt(0)
; DI unsigned pack2(float a, float b) { f32x2 v = {a, b}; hwbf16x2 r = __builtin_convertvector(v, hwbf16x2); return __builtin_bit_cast(unsigned, r); }
; DI float bflo(unsigned w) { return __uint_as_float(w << 16); }
; DI float bfhi(unsigned w) { return __uint_as_float(w & 0xffff0000u); }
;     DI const char* a(const Unit& u) const { return (const char*)(A + (size_t)u.pm * BM * lda); }
;     DI const char* a(const Unit& u) const { return (const char*)(A + (size_t)u.pm * BM * 2048 + (u.pn >> 1) * 512); }
; #define PG8_BAR __builtin_amdgcn_s_barrier()
;     DI void operator()(const f32x4 (&acc)[2][2][4][2], const Unit& u, int wr, int wc, int fr, int fq) const {
;     ...
;             for (int m = 0; m < 4; ++m) { const size_t ro = (size_t)(row0 + ai * HALF + m * 16) * D + col0;
; #pragma unroll
;                 for (int bj = 0; bj < 2; ++bj) {
;                     f32x4 x0, x1;
;                     if constexpr (IB) { const u32x4 w = *(const u32x4*)((const bf16_t*)Xin + ro + bj * HALF);
;                         x0 = (f32x4){bflo(w[0]), bfhi(w[0]), bflo(w[1]), bfhi(w[1])}; x1 = (f32x4){bflo(w[2]), bfhi(w[2]), bflo(w[3]), bfhi(w[3])}; }
;                     else { x0 = *(const f32x4*)((const float*)Xin + ro + bj * HALF); x1 = *(const f32x4*)((const float*)Xin + ro + bj * HALF + 4); }
;                     x0 += acc[ai][bj][m][0] * sc[bj][0]; x1 += acc[ai][bj][m][1] * sc[bj][1];
;                     if constexpr (OB) { u32x4 o; o[0] = pack2(x0[0], x0[1]); o[1] = pack2(x0[2], x0[3]); o[2] = pack2(x1[0], x1[1]); o[3] = pack2(x1[2], x1[3]);
;                         *(u32x4*)((bf16_t*)Xout + ro + bj * HALF) = o; }
;                     else { *(f32x4*)((float*)Xout + ro + bj * HALF) = x0; *(f32x4*)((float*)Xout + ro + bj * HALF + 4) = x1; } } }
; template <class Map, class Epi>
; DI void gemm_phase(LAS unsigned char* lds, const Map& MP, const Epi& E, const int nM, const int nN, const int K, const int lda, const int ldb) {
;     ...
;         if (!has_next) break;
; #pragma unroll
;         for (int a = 0; a < 2; ++a)
; #pragma unroll
;             for (int b = 0; b < 2; ++b)
; #pragma unroll
;                 for (int m = 0; m < 4; ++m)
; #pragma unroll
;                     for (int n = 0; n < 2; ++n) acc[a][b][m][n] = (f32x4){0.f, 0.f, 0.f, 0.f};
;         cur = nxt; cA = nA; cB = nB; ++ui;
;     }
;     PG8_WAIT_V(0);
;     if (wr == 0) PG8_BAR;
;     PG8_BAR;
	v_lshlrev_b32_e32 v44, 16, v40
	v_and_b32_e32 v45, 0xffff0000, v40
	v_lshlrev_b32_e32 v40, 16, v41
	v_and_b32_e32 v41, 0xffff0000, v41
	v_lshlrev_b32_e32 v46, 16, v42
	v_and_b32_e32 v47, 0xffff0000, v42
	v_lshlrev_b32_e32 v42, 16, v43
	v_and_b32_e32 v43, 0xffff0000, v43
	v_pk_add_f32 v[38:39], v[38:39], v[40:41]
	v_pk_add_f32 v[36:37], v[36:37], v[44:45]
	v_pk_add_f32 v[40:41], v[34:35], v[42:43]
	v_pk_add_f32 v[34:35], v[32:33], v[46:47]
	v_cvt_pk_bf16_f32 v32, v36, v37
	v_cvt_pk_bf16_f32 v33, v38, v39
	v_cvt_pk_bf16_f32 v34, v34, v35
	v_cvt_pk_bf16_f32 v35, v40, v41
	global_store_dwordx4 v[48:49], v[32:35], off offset:256
	s_nop 1
	v_lshl_add_u64 v[32:33], v[144:145], 0, s[2:3]
	s_mov_b32 s2, 0xa0000
	v_add_co_u32_e32 v38, vcc, s2, v144
	s_mov_b64 s[2:3], 0xb0000
	s_nop 0
	v_addc_co_u32_e32 v39, vcc, 0, v145, vcc
	s_waitcnt vmcnt(15)
	s_nop 1
	v_mov_b32_e32 v34, v210
	v_mov_b32_e32 v35, v211
	v_mov_b32_e32 v36, v212
	v_mov_b32_e32 v37, v213
	s_waitcnt lgkmcnt(0)
	v_lshlrev_b32_e32 v40, 16, v34
	v_and_b32_e32 v41, 0xffff0000, v34
	v_lshlrev_b32_e32 v34, 16, v35
	v_and_b32_e32 v35, 0xffff0000, v35
	v_lshlrev_b32_e32 v42, 16, v36
	v_and_b32_e32 v43, 0xffff0000, v36
	v_lshlrev_b32_e32 v36, 16, v37
	v_and_b32_e32 v37, 0xffff0000, v37
	v_pk_add_f32 v[30:31], v[30:31], v[34:35]
	v_pk_add_f32 v[28:29], v[28:29], v[40:41]
	v_pk_add_f32 v[34:35], v[26:27], v[36:37]
	v_pk_add_f32 v[26:27], v[24:25], v[42:43]
	v_cvt_pk_bf16_f32 v24, v28, v29
	v_cvt_pk_bf16_f32 v25, v30, v31
	v_cvt_pk_bf16_f32 v26, v26, v27
	v_cvt_pk_bf16_f32 v27, v34, v35
	global_store_dwordx4 v[38:39], v[24:27], off
	s_waitcnt vmcnt(15)
	s_nop 1
	v_mov_b32_e32 v24, v214
	v_mov_b32_e32 v25, v215
	v_mov_b32_e32 v26, v216
	v_mov_b32_e32 v27, v217
	s_waitcnt lgkmcnt(0)
	v_lshlrev_b32_e32 v28, 16, v24
	v_and_b32_e32 v29, 0xffff0000, v24
	v_lshlrev_b32_e32 v24, 16, v25
	v_and_b32_e32 v25, 0xffff0000, v25
	v_lshlrev_b32_e32 v30, 16, v26
	v_and_b32_e32 v31, 0xffff0000, v26
	v_lshlrev_b32_e32 v26, 16, v27
	v_and_b32_e32 v27, 0xffff0000, v27
	v_pk_add_f32 v[22:23], v[22:23], v[24:25]
	v_pk_add_f32 v[20:21], v[20:21], v[28:29]
	v_pk_add_f32 v[24:25], v[18:19], v[26:27]
	v_pk_add_f32 v[18:19], v[16:17], v[30:31]
	v_cvt_pk_bf16_f32 v16, v20, v21
	v_cvt_pk_bf16_f32 v17, v22, v23
	v_cvt_pk_bf16_f32 v18, v18, v19
	v_cvt_pk_bf16_f32 v19, v24, v25
	global_store_dwordx4 v[32:33], v[16:19], off offset:256
	s_nop 1
	v_lshl_add_u64 v[16:17], v[144:145], 0, s[2:3]
	s_mov_b32 s2, 0xb0000
	v_add_co_u32_e32 v22, vcc, s2, v144
	s_mov_b32 s2, s53
	s_nop 0
	v_addc_co_u32_e32 v23, vcc, 0, v145, vcc
	s_waitcnt vmcnt(15)
	s_nop 1
	v_mov_b32_e32 v18, v248
	v_mov_b32_e32 v19, v249
	v_mov_b32_e32 v20, v250
	v_mov_b32_e32 v21, v251
	s_and_b64 vcc, exec, s[40:41]
	s_waitcnt lgkmcnt(0)
	v_lshlrev_b32_e32 v24, 16, v18
	v_and_b32_e32 v25, 0xffff0000, v18
	v_lshlrev_b32_e32 v18, 16, v19
	v_and_b32_e32 v19, 0xffff0000, v19
	v_lshlrev_b32_e32 v26, 16, v20
	v_and_b32_e32 v27, 0xffff0000, v20
	v_lshlrev_b32_e32 v20, 16, v21
	v_and_b32_e32 v21, 0xffff0000, v21
	v_pk_add_f32 v[14:15], v[14:15], v[18:19]
	v_pk_add_f32 v[12:13], v[12:13], v[24:25]
	v_pk_add_f32 v[18:19], v[10:11], v[20:21]
	v_pk_add_f32 v[10:11], v[8:9], v[26:27]
	v_cvt_pk_bf16_f32 v8, v12, v13
	v_cvt_pk_bf16_f32 v9, v14, v15
	v_cvt_pk_bf16_f32 v10, v10, v11
	v_cvt_pk_bf16_f32 v11, v18, v19
	global_store_dwordx4 v[22:23], v[8:11], off
	s_waitcnt vmcnt(15)
	s_nop 1
	v_mov_b32_e32 v8, v252
	v_mov_b32_e32 v9, v253
	v_mov_b32_e32 v10, v254
	v_mov_b32_e32 v11, v255
	s_waitcnt lgkmcnt(0)
	v_lshlrev_b32_e32 v12, 16, v8
	v_and_b32_e32 v13, 0xffff0000, v8
	v_lshlrev_b32_e32 v8, 16, v9
	v_and_b32_e32 v9, 0xffff0000, v9
	v_lshlrev_b32_e32 v14, 16, v10
	v_and_b32_e32 v15, 0xffff0000, v10
	v_lshlrev_b32_e32 v10, 16, v11
	v_and_b32_e32 v11, 0xffff0000, v11
	v_pk_add_f32 v[6:7], v[6:7], v[8:9]
	v_pk_add_f32 v[4:5], v[4:5], v[12:13]
	v_pk_add_f32 v[8:9], v[2:3], v[10:11]
	v_pk_add_f32 v[2:3], v[0:1], v[14:15]
	v_cvt_pk_bf16_f32 v0, v4, v5
	v_cvt_pk_bf16_f32 v1, v6, v7
	v_cvt_pk_bf16_f32 v2, v2, v3
	v_cvt_pk_bf16_f32 v3, v8, v9
	global_store_dwordx4 v[16:17], v[0:3], off offset:256
	s_cbranch_vccz .LBB1_2071
	s_waitcnt vmcnt(0)
	s_cmpk_gt_u32 s17, 0xff
	s_cbranch_scc1 .LBB1_2082
	s_barrier

; #define PG8_STAGE(bufoff, gbase, voff) do { _Pragma("unroll") for (int _i = 0; _i < 2; ++_i) \
;         __builtin_amdgcn_global_load_lds((const unsigned*)((const char*)(gbase) + (voff)[_i]), (LAS unsigned*)(lds + (bufoff) + ldsw + _i * 8192), 16, 0, 0); } while (0)
; #define PG8_LDA(dst, b, h) do { _Pragma("unroll") for (int m = 0; m < 4; ++m) _Pragma("unroll") for (int k = 0; k < 2; ++k) dst[m][k] = *(const LAS bf16x8*)(lds + PG8_SA(b, h) + aoff + m * 2048 + k * 1024); } while (0)
; #define PG8_LDB(dst, b, h) do { _Pragma("unroll") for (int n = 0; n < 2; ++n) _Pragma("unroll") for (int k = 0; k < 2; ++k) dst[n][k] = *(const LAS bf16x8*)(lds + PG8_SB(b, h) + boff + n * 2048 + k * 1024); } while (0)
; #define PG8_MMA(ai, bj, At, Bt) do { __builtin_amdgcn_s_setprio(1); _Pragma("unroll") for (int m = 0; m < 4; ++m) _Pragma("unroll") for (int n = 0; n < 2; ++n) _Pragma("unroll") for (int k = 0; k < 2; ++k) \
;         acc[ai][bj][m][n] = __builtin_amdgcn_mfma_f32_16x16x32_bf16(Bt[n][k], At[m][k], acc[ai][bj][m][n], 0, 0, 0); __builtin_amdgcn_s_setprio(0); } while (0)
; #define PG8_WAIT_V(n) asm volatile("s_waitcnt vmcnt(" #n ")" ::: "memory")
; #define PG8_WAIT_L(n) asm volatile("s_waitcnt lgkmcnt(" #n ")" ::: "memory")
; template <class Map, class Epi>
; DI void gemm_phase(LAS unsigned char* lds, const Map& MP, const Epi& E, const int nM, const int nN, const int K, const int lda, const int ldb) {
;     ...
;             const bool last = (t == nt - 2);
;             const char* a1 = cA + (size_t)(t + 1) * kstep;
;             const char* a2 = last ? nA : cA + (size_t)(t + 2) * kstep; const char* b2 = last ? nB : cB + (size_t)(t + 2) * kstep;
;             const char* a3 = a2 + kstep; const char* b3 = b2 + kstep;
;             PG8_LDB(B0, 0, 0); PG8_SCHED; PG8_LDA(At, 0, 0); PG8_STAGE(PG8_SA(1, 1), a1 + hstepA, voffA);
;             PG8_WAIT_L(8); PG8_BAR; PG8_WAIT_L(0); PG8_MMA(0, 0, At, B0); PG8_BAR; PG8_SCHED;
;             PG8_LDB(B1, 0, 1); PG8_STAGE(PG8_SB(0, 0), b2, voffB);
;             PG8_BAR; PG8_WAIT_L(0); PG8_MMA(0, 1, At, B1); PG8_BAR;
;             PG8_LDA(At, 0, 1); PG8_STAGE(PG8_SA(0, 0), a2, voffA);
;             PG8_BAR; PG8_WAIT_L(0); PG8_MMA(1, 0, At, B0); PG8_BAR; PG8_SCHED;
;             PG8_STAGE(PG8_SB(0, 1), b2 + hstepB, voffB);
;             PG8_WAIT_V(6); PG8_BAR; PG8_MMA(1, 1, At, B1); PG8_BAR;
.LBB1_2339:
	s_add_u32 s12, s10, 0xfff80080
	s_addc_u32 s13, s11, -1
	s_cmp_eq_u32 s3, 4
	s_cselect_b32 s15, s38, s13
	s_cselect_b32 s14, s39, s12
	s_cselect_b32 s13, s48, s56
	s_cselect_b32 s12, s49, s53
	s_add_i32 m0, s9, 0xc000
	ds_read_b128 v[168:171], v166
	ds_read_b128 v[172:175], v166 offset:1024
	ds_read_b128 v[176:179], v166 offset:2048
	ds_read_b128 v[180:183], v166 offset:3072
	ds_read_b128 v[184:187], v166 offset:4096
	ds_read_b128 v[188:191], v166 offset:5120
	ds_read_b128 v[192:195], v166 offset:6144
	ds_read_b128 v[198:201], v166 offset:7168
	global_load_lds_dwordx4 v154, s[10:11]
	s_add_i32 m0, s9, 0xe000
	s_nop 0
	global_load_lds_dwordx4 v152, s[10:11]
	s_waitcnt lgkmcnt(8)
	s_setprio 1
	s_barrier
	s_waitcnt lgkmcnt(7)
	v_mfma_f32_16x16x32_bf16 v[140:143], v[40:43], v[168:171], v[140:143]
	v_mfma_f32_16x16x32_bf16 v[136:139], v[56:59], v[168:171], v[136:139]
	s_waitcnt lgkmcnt(5)
	v_mfma_f32_16x16x32_bf16 v[124:127], v[40:43], v[176:179], v[124:127]
	v_mfma_f32_16x16x32_bf16 v[120:123], v[56:59], v[176:179], v[120:123]
	s_waitcnt lgkmcnt(3)
	v_mfma_f32_16x16x32_bf16 v[108:111], v[40:43], v[184:187], v[108:111]
	v_mfma_f32_16x16x32_bf16 v[104:107], v[56:59], v[184:187], v[104:107]
	s_waitcnt lgkmcnt(1)
	v_mfma_f32_16x16x32_bf16 v[92:95], v[40:43], v[192:195], v[92:95]
	v_mfma_f32_16x16x32_bf16 v[88:91], v[56:59], v[192:195], v[88:91]
	v_mfma_f32_16x16x32_bf16 v[140:143], v[44:47], v[172:175], v[140:143]
	s_add_i32 s57, s35, s22
	v_mfma_f32_16x16x32_bf16 v[136:139], v[60:63], v[172:175], v[136:139]
	v_lshl_add_u64 v[160:161], s[12:13], 0, v[148:149]
	v_mfma_f32_16x16x32_bf16 v[124:127], v[44:47], v[180:183], v[124:127]
	v_lshl_add_u64 v[218:219], s[12:13], 0, v[144:145]
	v_mfma_f32_16x16x32_bf16 v[120:123], v[60:63], v[180:183], v[120:123]
	v_mfma_f32_16x16x32_bf16 v[108:111], v[44:47], v[188:191], v[108:111]
	v_mfma_f32_16x16x32_bf16 v[104:107], v[60:63], v[188:191], v[104:107]
	s_waitcnt lgkmcnt(0)
	v_mfma_f32_16x16x32_bf16 v[92:95], v[44:47], v[198:201], v[92:95]
	v_mfma_f32_16x16x32_bf16 v[88:91], v[60:63], v[198:201], v[88:91]
	s_barrier
	s_setprio 0
	s_mov_b32 m0, s57
	ds_read_b128 v[202:205], v167
	ds_read_b128 v[206:209], v167 offset:1024
	ds_read_b128 v[210:213], v167 offset:2048
	ds_read_b128 v[214:217], v167 offset:3072
	global_load_lds_dwordx4 v[160:161], off
	s_add_i32 m0, s57, 0x2000
	s_nop 0
	global_load_lds_dwordx4 v[218:219], off
	s_setprio 1
	s_barrier
	s_waitcnt lgkmcnt(3)
	v_mfma_f32_16x16x32_bf16 v[132:135], v[202:205], v[168:171], v[132:135]
	s_waitcnt lgkmcnt(1)
	v_mfma_f32_16x16x32_bf16 v[128:131], v[210:213], v[168:171], v[128:131]
	v_mfma_f32_16x16x32_bf16 v[116:119], v[202:205], v[176:179], v[116:119]
	v_mfma_f32_16x16x32_bf16 v[112:115], v[210:213], v[176:179], v[112:115]
	v_mfma_f32_16x16x32_bf16 v[100:103], v[202:205], v[184:187], v[100:103]
	v_mfma_f32_16x16x32_bf16 v[96:99], v[210:213], v[184:187], v[96:99]
	v_mfma_f32_16x16x32_bf16 v[84:87], v[202:205], v[192:195], v[84:87]
	v_mfma_f32_16x16x32_bf16 v[80:83], v[210:213], v[192:195], v[80:83]
	v_mfma_f32_16x16x32_bf16 v[132:135], v[206:209], v[172:175], v[132:135]
	v_lshl_add_u64 v[222:223], s[14:15], 0, v[146:147]
	s_mov_b32 m0, s9
	s_waitcnt lgkmcnt(0)
	v_mfma_f32_16x16x32_bf16 v[128:131], v[214:217], v[172:175], v[128:131]
	v_lshl_add_u64 v[220:221], s[14:15], 0, v[150:151]
	v_mfma_f32_16x16x32_bf16 v[116:119], v[206:209], v[180:183], v[116:119]
	v_mfma_f32_16x16x32_bf16 v[112:115], v[214:217], v[180:183], v[112:115]
	v_mfma_f32_16x16x32_bf16 v[100:103], v[206:209], v[188:191], v[100:103]
	v_mfma_f32_16x16x32_bf16 v[96:99], v[214:217], v[188:191], v[96:99]
	v_mfma_f32_16x16x32_bf16 v[84:87], v[206:209], v[198:201], v[84:87]
	v_mfma_f32_16x16x32_bf16 v[80:83], v[214:217], v[198:201], v[80:83]
	s_barrier
	s_setprio 0
	ds_read_b128 v[168:171], v166 offset:16384
	ds_read_b128 v[172:175], v166 offset:17408
	ds_read_b128 v[176:179], v166 offset:18432
	ds_read_b128 v[180:183], v166 offset:19456
	ds_read_b128 v[184:187], v166 offset:20480
	ds_read_b128 v[188:191], v166 offset:21504
	ds_read_b128 v[192:195], v166 offset:22528
	ds_read_b128 v[198:201], v166 offset:23552
	global_load_lds_dwordx4 v[220:221], off
	s_mov_b32 m0, s24
	s_nop 0
	global_load_lds_dwordx4 v[222:223], off
	s_waitcnt vmcnt(10)
	s_setprio 1
	s_barrier
	s_waitcnt lgkmcnt(7)
	v_mfma_f32_16x16x32_bf16 v[76:79], v[40:43], v[168:171], v[76:79]
	v_mfma_f32_16x16x32_bf16 v[72:75], v[56:59], v[168:171], v[72:75]
	s_waitcnt lgkmcnt(5)
	v_mfma_f32_16x16x32_bf16 v[52:55], v[40:43], v[176:179], v[52:55]
	v_mfma_f32_16x16x32_bf16 v[48:51], v[56:59], v[176:179], v[48:51]
	s_waitcnt lgkmcnt(3)
	v_mfma_f32_16x16x32_bf16 v[28:31], v[40:43], v[184:187], v[28:31]
	v_mfma_f32_16x16x32_bf16 v[24:27], v[56:59], v[184:187], v[24:27]
	s_waitcnt lgkmcnt(1)
	v_mfma_f32_16x16x32_bf16 v[12:15], v[40:43], v[192:195], v[12:15]
	v_mfma_f32_16x16x32_bf16 v[8:11], v[56:59], v[192:195], v[8:11]
	v_mfma_f32_16x16x32_bf16 v[76:79], v[44:47], v[172:175], v[76:79]
	s_add_u32 s58, s12, 0x20000
	s_addc_u32 s59, s13, 0
	v_mfma_f32_16x16x32_bf16 v[72:75], v[60:63], v[172:175], v[72:75]
	s_add_i32 s57, s36, s22
	v_mfma_f32_16x16x32_bf16 v[52:55], v[44:47], v[180:183], v[52:55]
	v_mfma_f32_16x16x32_bf16 v[48:51], v[60:63], v[180:183], v[48:51]
	v_mfma_f32_16x16x32_bf16 v[28:31], v[44:47], v[188:191], v[28:31]
	v_mfma_f32_16x16x32_bf16 v[24:27], v[60:63], v[188:191], v[24:27]
	s_waitcnt lgkmcnt(0)
	v_mfma_f32_16x16x32_bf16 v[12:15], v[44:47], v[198:201], v[12:15]
	v_mfma_f32_16x16x32_bf16 v[8:11], v[60:63], v[198:201], v[8:11]
	s_barrier
; #define PG8_STAGE(bufoff, gbase, voff) do { _Pragma("unroll") for (int _i = 0; _i < 2; ++_i) \
;         __builtin_amdgcn_global_load_lds((const unsigned*)((const char*)(gbase) + (voff)[_i]), (LAS unsigned*)(lds + (bufoff) + ldsw + _i * 8192), 16, 0, 0); } while (0)
; #define PG8_LDA(dst, b, h) do { _Pragma("unroll") for (int m = 0; m < 4; ++m) _Pragma("unroll") for (int k = 0; k < 2; ++k) dst[m][k] = *(const LAS bf16x8*)(lds + PG8_SA(b, h) + aoff + m * 2048 + k * 1024); } while (0)
; #define PG8_LDB(dst, b, h) do { _Pragma("unroll") for (int n = 0; n < 2; ++n) _Pragma("unroll") for (int k = 0; k < 2; ++k) dst[n][k] = *(const LAS bf16x8*)(lds + PG8_SB(b, h) + boff + n * 2048 + k * 1024); } while (0)
; #define PG8_MMA(ai, bj, At, Bt) do { __builtin_amdgcn_s_setprio(1); _Pragma("unroll") for (int m = 0; m < 4; ++m) _Pragma("unroll") for (int n = 0; n < 2; ++n) _Pragma("unroll") for (int k = 0; k < 2; ++k) \
;         acc[ai][bj][m][n] = __builtin_amdgcn_mfma_f32_16x16x32_bf16(Bt[n][k], At[m][k], acc[ai][bj][m][n], 0, 0, 0); __builtin_amdgcn_s_setprio(0); } while (0)
; #define PG8_WAIT_V(n) asm volatile("s_waitcnt vmcnt(" #n ")" ::: "memory")
; #define PG8_WAIT_L(n) asm volatile("s_waitcnt lgkmcnt(" #n ")" ::: "memory")
; #define PG8_BAR __builtin_amdgcn_s_barrier()
; #define PG8_SCHED __builtin_amdgcn_sched_barrier(0)
; template <class Map, class Epi>
; DI void gemm_phase(LAS unsigned char* lds, const Map& MP, const Epi& E, const int nM, const int nN, const int K, const int lda, const int ldb) {
;     ...
;             PG8_WAIT_V(6); PG8_BAR; PG8_MMA(1, 1, At, B1); PG8_BAR;
;             PG8_LDB(B0, 1, 0); PG8_SCHED; PG8_LDA(At, 1, 0); PG8_STAGE(PG8_SA(0, 1), a2 + hstepA, voffA);
;             PG8_WAIT_L(8); PG8_BAR; PG8_WAIT_L(0); PG8_MMA(0, 0, At, B0); PG8_BAR; PG8_SCHED;
;             PG8_LDB(B1, 1, 1); PG8_STAGE(PG8_SB(1, 0), b3, voffB);
;             PG8_BAR; PG8_WAIT_L(0); PG8_MMA(0, 1, At, B1); PG8_BAR;
;             PG8_LDA(At, 1, 1); PG8_STAGE(PG8_SA(1, 0), a3, voffA);
;             PG8_BAR; PG8_WAIT_L(0); PG8_MMA(1, 0, At, B0); PG8_BAR; PG8_SCHED;
	s_setprio 0
	s_mov_b32 m0, s57
	s_nop 0
	global_load_lds_dwordx4 v148, s[58:59]
	s_add_i32 m0, s57, 0x2000
	s_nop 0
	global_load_lds_dwordx4 v144, s[58:59]
	s_waitcnt vmcnt(6)
	s_setprio 1
	s_barrier
	v_mfma_f32_16x16x32_bf16 v[36:39], v[202:205], v[176:179], v[36:39]
	v_mfma_f32_16x16x32_bf16 v[32:35], v[210:213], v[176:179], v[32:35]
	v_mfma_f32_16x16x32_bf16 v[20:23], v[202:205], v[184:187], v[20:23]
	v_mfma_f32_16x16x32_bf16 v[16:19], v[210:213], v[184:187], v[16:19]
	v_mfma_f32_16x16x32_bf16 v[4:7], v[202:205], v[192:195], v[4:7]
	v_mfma_f32_16x16x32_bf16 v[0:3], v[210:213], v[192:195], v[0:3]
	v_mfma_f32_16x16x32_bf16 v[40:43], v[202:205], v[168:171], v[68:71]
	s_add_i32 s57, 0, 0x18000
	v_add_u32_e32 v68, s57, v164
	ds_read_b128 v[56:59], v68
	ds_read_b128 v[60:63], v68 offset:1024
	v_mfma_f32_16x16x32_bf16 v[44:47], v[210:213], v[168:171], v[64:67]
	ds_read_b128 v[64:67], v68 offset:2048
	ds_read_b128 v[68:71], v68 offset:3072
	v_mfma_f32_16x16x32_bf16 v[36:39], v[206:209], v[180:183], v[36:39]
	s_add_u32 s14, s14, 0x80000
	s_addc_u32 s15, s15, 0
	v_mfma_f32_16x16x32_bf16 v[32:35], v[214:217], v[180:183], v[32:35]
	v_mfma_f32_16x16x32_bf16 v[20:23], v[206:209], v[188:191], v[20:23]
	v_mfma_f32_16x16x32_bf16 v[16:19], v[214:217], v[188:191], v[16:19]
	v_mfma_f32_16x16x32_bf16 v[4:7], v[206:209], v[198:201], v[4:7]
	v_mfma_f32_16x16x32_bf16 v[0:3], v[214:217], v[198:201], v[0:3]
	v_mfma_f32_16x16x32_bf16 v[40:43], v[206:209], v[172:175], v[40:43]
	v_mfma_f32_16x16x32_bf16 v[44:47], v[214:217], v[172:175], v[44:47]
	s_barrier
	s_setprio 0
	s_mov_b32 m0, s25
	ds_read_b128 v[168:171], v166 offset:32768
	ds_read_b128 v[172:175], v166 offset:33792
	ds_read_b128 v[176:179], v166 offset:34816
	ds_read_b128 v[180:183], v166 offset:35840
	ds_read_b128 v[184:187], v166 offset:36864
	ds_read_b128 v[188:191], v166 offset:37888
	ds_read_b128 v[192:195], v166 offset:38912
	ds_read_b128 v[198:201], v166 offset:39936
	global_load_lds_dwordx4 v150, s[14:15]
	s_mov_b32 m0, s26
	s_nop 0
	global_load_lds_dwordx4 v146, s[14:15]
	s_waitcnt lgkmcnt(8)
	s_setprio 1
	s_barrier
	s_waitcnt lgkmcnt(7)
	v_mfma_f32_16x16x32_bf16 v[140:143], v[56:59], v[168:171], v[140:143]
	v_mfma_f32_16x16x32_bf16 v[136:139], v[64:67], v[168:171], v[136:139]
	s_waitcnt lgkmcnt(5)
	v_mfma_f32_16x16x32_bf16 v[124:127], v[56:59], v[176:179], v[124:127]
	v_mfma_f32_16x16x32_bf16 v[120:123], v[64:67], v[176:179], v[120:123]
	s_waitcnt lgkmcnt(3)
	v_mfma_f32_16x16x32_bf16 v[108:111], v[56:59], v[184:187], v[108:111]
	v_mfma_f32_16x16x32_bf16 v[104:107], v[64:67], v[184:187], v[104:107]
	s_waitcnt lgkmcnt(1)
	v_mfma_f32_16x16x32_bf16 v[92:95], v[56:59], v[192:195], v[92:95]
	v_mfma_f32_16x16x32_bf16 v[88:91], v[64:67], v[192:195], v[88:91]
	v_mfma_f32_16x16x32_bf16 v[140:143], v[60:63], v[172:175], v[140:143]
	s_add_i32 s14, 0, 0x1c000
	v_mfma_f32_16x16x32_bf16 v[136:139], v[68:71], v[172:175], v[136:139]
	s_add_i32 s15, s57, s22
	v_mfma_f32_16x16x32_bf16 v[124:127], v[60:63], v[180:183], v[124:127]
	v_add_u32_e32 v196, s14, v164
	v_mfma_f32_16x16x32_bf16 v[120:123], v[68:71], v[180:183], v[120:123]
	v_lshl_add_u64 v[160:161], v[160:161], 0, s[46:47]
	v_mfma_f32_16x16x32_bf16 v[108:111], v[60:63], v[188:191], v[108:111]
	v_mfma_f32_16x16x32_bf16 v[104:107], v[68:71], v[188:191], v[104:107]
	s_waitcnt lgkmcnt(0)
	v_mfma_f32_16x16x32_bf16 v[92:95], v[60:63], v[198:201], v[92:95]
	v_mfma_f32_16x16x32_bf16 v[88:91], v[68:71], v[198:201], v[88:91]
	s_barrier
	s_setprio 0
	s_mov_b32 m0, s15
	ds_read_b128 v[202:205], v196
	ds_read_b128 v[206:209], v196 offset:1024
	ds_read_b128 v[210:213], v196 offset:2048
	ds_read_b128 v[214:217], v196 offset:3072
	global_load_lds_dwordx4 v[160:161], off
	v_lshl_add_u64 v[160:161], v[218:219], 0, s[46:47]
	s_add_i32 m0, s15, 0x2000
	s_nop 0
	global_load_lds_dwordx4 v[160:161], off
	s_setprio 1
	s_barrier
	s_waitcnt lgkmcnt(3)
	v_mfma_f32_16x16x32_bf16 v[132:135], v[202:205], v[168:171], v[132:135]
	s_waitcnt lgkmcnt(1)
	v_mfma_f32_16x16x32_bf16 v[128:131], v[210:213], v[168:171], v[128:131]
	v_mfma_f32_16x16x32_bf16 v[116:119], v[202:205], v[176:179], v[116:119]
	v_mfma_f32_16x16x32_bf16 v[112:115], v[210:213], v[176:179], v[112:115]
	v_mfma_f32_16x16x32_bf16 v[100:103], v[202:205], v[184:187], v[100:103]
	v_mfma_f32_16x16x32_bf16 v[96:99], v[210:213], v[184:187], v[96:99]
	v_mfma_f32_16x16x32_bf16 v[84:87], v[202:205], v[192:195], v[84:87]
	v_mfma_f32_16x16x32_bf16 v[80:83], v[210:213], v[192:195], v[80:83]
	v_mfma_f32_16x16x32_bf16 v[132:135], v[206:209], v[172:175], v[132:135]
	s_mov_b32 m0, s30
	s_waitcnt lgkmcnt(0)
	v_mfma_f32_16x16x32_bf16 v[128:131], v[214:217], v[172:175], v[128:131]
	v_lshl_add_u64 v[160:161], v[220:221], 0, s[46:47]
	v_mfma_f32_16x16x32_bf16 v[116:119], v[206:209], v[180:183], v[116:119]
	v_mfma_f32_16x16x32_bf16 v[112:115], v[214:217], v[180:183], v[112:115]
	v_mfma_f32_16x16x32_bf16 v[100:103], v[206:209], v[188:191], v[100:103]
	v_mfma_f32_16x16x32_bf16 v[96:99], v[214:217], v[188:191], v[96:99]
	v_mfma_f32_16x16x32_bf16 v[84:87], v[206:209], v[198:201], v[84:87]
	v_mfma_f32_16x16x32_bf16 v[80:83], v[214:217], v[198:201], v[80:83]
	s_barrier
	s_setprio 0
	ds_read_b128 v[168:171], v166 offset:49152
	ds_read_b128 v[172:175], v166 offset:50176
	ds_read_b128 v[176:179], v166 offset:51200
	ds_read_b128 v[180:183], v166 offset:52224
	ds_read_b128 v[184:187], v166 offset:53248
	ds_read_b128 v[188:191], v166 offset:54272
	ds_read_b128 v[192:195], v166 offset:55296
	ds_read_b128 v[198:201], v166 offset:56320
	global_load_lds_dwordx4 v[160:161], off
	v_lshl_add_u64 v[160:161], v[222:223], 0, s[46:47]
	s_mov_b32 m0, s31
	s_nop 0
	global_load_lds_dwordx4 v[160:161], off
	s_waitcnt vmcnt(10)
	s_setprio 1
	s_barrier
; DI float bflo(unsigned w) { return __uint_as_float(w << 16); }
; DI float bfhi(unsigned w) { return __uint_as_float(w & 0xffff0000u); }
; #define PG8_STAGE(bufoff, gbase, voff) do { _Pragma("unroll") for (int _i = 0; _i < 2; ++_i) \
;         __builtin_amdgcn_global_load_lds((const unsigned*)((const char*)(gbase) + (voff)[_i]), (LAS unsigned*)(lds + (bufoff) + ldsw + _i * 8192), 16, 0, 0); } while (0)
; #define PG8_WAIT_V(n) asm volatile("s_waitcnt vmcnt(" #n ")" ::: "memory")
; #define PG8_WAIT_L(n) asm volatile("s_waitcnt lgkmcnt(" #n ")" ::: "memory")
; #define PG8_BAR __builtin_amdgcn_s_barrier()
; #define PG8_SCHED __builtin_amdgcn_sched_barrier(0)
;     DI void operator()(const f32x4 (&acc)[2][2][4][2], const Unit& u, int wr, int wc, int fr, int fq) const {
;         const int row0 = u.pm * BM + wr * 64 + fr, col0 = u.pn * BM + wc * 32 + 8 * fq;
;         f32x4 sc[2][2];
; #pragma unroll
;         for (int bj = 0; bj < 2; ++bj)
; #pragma unroll
;             for (int n = 0; n < 2; ++n) sc[bj][n] = scale ? *(const f32x4*)(scale + col0 + bj * HALF + 4 * n) : (f32x4){1.f, 1.f, 1.f, 1.f};
; #pragma unroll
;         for (int ai = 0; ai < 2; ++ai)
; #pragma unroll
;             for (int m = 0; m < 4; ++m) { const size_t ro = (size_t)(row0 + ai * HALF + m * 16) * D + col0;
; #pragma unroll
;                 for (int bj = 0; bj < 2; ++bj) {
;                     f32x4 x0, x1;
;                     if constexpr (IB) { const u32x4 w = *(const u32x4*)((const bf16_t*)Xin + ro + bj * HALF);
;                         x0 = (f32x4){bflo(w[0]), bfhi(w[0]), bflo(w[1]), bfhi(w[1])}; x1 = (f32x4){bflo(w[2]), bfhi(w[2]), bflo(w[3]), bfhi(w[3])}; }
;                     else { x0 = *(const f32x4*)((const float*)Xin + ro + bj * HALF); x1 = *(const f32x4*)((const float*)Xin + ro + bj * HALF + 4); }
;                     x0 += acc[ai][bj][m][0] * sc[bj][0]; x1 += acc[ai][bj][m][1] * sc[bj][1];
; template <class Map, class Epi>
; DI void gemm_phase(LAS unsigned char* lds, const Map& MP, const Epi& E, const int nM, const int nN, const int K, const int lda, const int ldb) {
;     ...
;             PG8_BAR; PG8_WAIT_L(0); PG8_MMA(1, 0, At, B0); PG8_BAR; PG8_SCHED;
;             PG8_STAGE(PG8_SB(1, 1), b3 + hstepB, voffB);
;             PG8_WAIT_V(6); PG8_BAR; PG8_MMA(1, 1, At, B1); PG8_BAR;
	s_waitcnt lgkmcnt(7)
	v_mfma_f32_16x16x32_bf16 v[76:79], v[56:59], v[168:171], v[76:79]
	v_mfma_f32_16x16x32_bf16 v[72:75], v[64:67], v[168:171], v[72:75]
	s_waitcnt lgkmcnt(5)
	v_mfma_f32_16x16x32_bf16 v[52:55], v[56:59], v[176:179], v[52:55]
	v_mfma_f32_16x16x32_bf16 v[48:51], v[64:67], v[176:179], v[48:51]
	s_waitcnt lgkmcnt(3)
	v_mfma_f32_16x16x32_bf16 v[28:31], v[56:59], v[184:187], v[28:31]
	v_mfma_f32_16x16x32_bf16 v[24:27], v[64:67], v[184:187], v[24:27]
	s_waitcnt lgkmcnt(1)
	v_mfma_f32_16x16x32_bf16 v[12:15], v[56:59], v[192:195], v[12:15]
	v_mfma_f32_16x16x32_bf16 v[8:11], v[64:67], v[192:195], v[8:11]
	v_mfma_f32_16x16x32_bf16 v[76:79], v[60:63], v[172:175], v[76:79]
	s_add_u32 s12, s12, 0x20080
	s_addc_u32 s13, s13, 0
	v_mfma_f32_16x16x32_bf16 v[72:75], v[68:71], v[172:175], v[72:75]
	s_add_i32 s14, s14, s22
	v_mfma_f32_16x16x32_bf16 v[52:55], v[60:63], v[180:183], v[52:55]
	v_mfma_f32_16x16x32_bf16 v[48:51], v[68:71], v[180:183], v[48:51]
	v_mfma_f32_16x16x32_bf16 v[28:31], v[60:63], v[188:191], v[28:31]
	v_mfma_f32_16x16x32_bf16 v[24:27], v[68:71], v[188:191], v[24:27]
	s_waitcnt lgkmcnt(0)
	v_mfma_f32_16x16x32_bf16 v[12:15], v[60:63], v[198:201], v[12:15]
	v_mfma_f32_16x16x32_bf16 v[8:11], v[68:71], v[198:201], v[8:11]
	s_barrier
	s_setprio 0
	s_mov_b32 m0, s14
	s_nop 0
	global_load_lds_dwordx4 v148, s[12:13]
	s_add_i32 m0, s14, 0x2000
	s_nop 0
	global_load_lds_dwordx4 v144, s[12:13]
	s_waitcnt vmcnt(6)
	s_setprio 1
	s_barrier
	v_mfma_f32_16x16x32_bf16 v[40:43], v[202:205], v[168:171], v[40:43]
	v_mfma_f32_16x16x32_bf16 v[68:71], v[206:209], v[172:175], v[40:43]
	v_mfma_f32_16x16x32_bf16 v[40:43], v[210:213], v[168:171], v[44:47]
	v_mfma_f32_16x16x32_bf16 v[36:39], v[202:205], v[176:179], v[36:39]
	v_mfma_f32_16x16x32_bf16 v[32:35], v[210:213], v[176:179], v[32:35]
	v_mfma_f32_16x16x32_bf16 v[20:23], v[202:205], v[184:187], v[20:23]
	v_mfma_f32_16x16x32_bf16 v[16:19], v[210:213], v[184:187], v[16:19]
	v_mfma_f32_16x16x32_bf16 v[4:7], v[202:205], v[192:195], v[4:7]
	v_mfma_f32_16x16x32_bf16 v[0:3], v[210:213], v[192:195], v[0:3]
	s_add_i32 s3, s3, 2
	v_mfma_f32_16x16x32_bf16 v[64:67], v[214:217], v[172:175], v[40:43]
	s_add_u32 s53, s53, 0x100
	s_addc_u32 s56, s56, 0
	ds_read_b128 v[40:43], v165
	ds_read_b128 v[44:47], v165 offset:1024
	ds_read_b128 v[56:59], v165 offset:2048
	ds_read_b128 v[60:63], v165 offset:3072
	v_mfma_f32_16x16x32_bf16 v[36:39], v[206:209], v[180:183], v[36:39]
	s_add_u32 s10, s10, 0x100
	s_addc_u32 s11, s11, 0
	v_mfma_f32_16x16x32_bf16 v[32:35], v[214:217], v[180:183], v[32:35]
	s_cmp_gt_u32 s3, 5
	v_mfma_f32_16x16x32_bf16 v[20:23], v[206:209], v[188:191], v[20:23]
	v_mfma_f32_16x16x32_bf16 v[16:19], v[214:217], v[188:191], v[16:19]
	v_mfma_f32_16x16x32_bf16 v[4:7], v[206:209], v[198:201], v[4:7]
	v_mfma_f32_16x16x32_bf16 v[0:3], v[214:217], v[198:201], v[0:3]
	s_barrier
	s_setprio 0
	s_cbranch_scc0 .LBB1_2339
	s_waitcnt lgkmcnt(0)
	s_lshl_b32 s2, s2, 8
	v_mov_b32_e32 v40, v163
	v_mov_b32_e32 v168, v162
	s_or_b32 s2, s2, s29
	s_and_b64 vcc, exec, s[40:41]
	v_lshl_add_u32 v160, v40, 3, s2
	s_lshl_b32 s2, s8, 8
	s_add_i32 s2, s2, s28
	v_add_u32_e32 v168, s2, v168
	v_ashrrev_i32_e32 v169, 31, v168
	v_ashrrev_i32_e32 v161, 31, v160
	v_lshlrev_b64 v[168:169], 11, v[168:169]
	v_lshl_add_u64 v[44:45], v[160:161], 2, s[44:45]
	v_lshl_add_u64 v[160:161], v[168:169], 0, v[160:161]
	v_lshlrev_b64 v[160:161], 1, v[160:161]
	v_lshl_add_u64 v[172:173], s[4:5], 0, v[160:161]
	global_load_dwordx4 v[56:59], v[44:45], off offset:16
	global_load_dwordx4 v[60:63], v[44:45], off
	global_load_dwordx4 v[40:43], v[44:45], off offset:528
	s_nop 0
	global_load_dwordx4 v[44:47], v[44:45], off offset:512
	s_mov_b64 s[2:3], 0x10000
	global_load_dwordx4 v[178:181], v[172:173], off
	global_load_dwordx4 v[182:185], v[172:173], off offset:256
	s_mov_b64 s[98:99], 0x10000
	v_lshl_add_u64 v[170:171], v[172:173], 0, s[98:99]
	global_load_dwordx4 v[186:189], v[170:171], off
	global_load_dwordx4 v[190:193], v[170:171], off offset:256
	s_mov_b64 s[98:99], 0x20000
	v_lshl_add_u64 v[170:171], v[172:173], 0, s[98:99]
	global_load_dwordx4 v[198:201], v[170:171], off
	global_load_dwordx4 v[202:205], v[170:171], off offset:256
	s_mov_b64 s[98:99], 0x30000
	v_lshl_add_u64 v[170:171], v[172:173], 0, s[98:99]
	global_load_dwordx4 v[206:209], v[170:171], off
	global_load_dwordx4 v[210:213], v[170:171], off offset:256
	s_mov_b64 s[98:99], 0x80000
	v_lshl_add_u64 v[170:171], v[172:173], 0, s[98:99]
	global_load_dwordx4 v[214:217], v[170:171], off
	global_load_dwordx4 v[248:251], v[170:171], off offset:256
	s_mov_b64 s[98:99], 0x90000
	v_lshl_add_u64 v[170:171], v[172:173], 0, s[98:99]
	global_load_dwordx4 v[252:255], v[170:171], off
	s_waitcnt vmcnt(10)
	s_nop 1
	v_mov_b32_e32 v168, v178
	v_mov_b32_e32 v169, v179
	v_mov_b32_e32 v170, v180
	v_mov_b32_e32 v171, v181
	s_mov_b32 s8, s52
	s_mov_b64 s[10:11], s[54:55]
	s_mov_b64 s[12:13], s[6:7]
	s_waitcnt lgkmcnt(0)
	v_lshlrev_b32_e32 v174, 16, v168
	v_and_b32_e32 v175, 0xffff0000, v168
	v_lshlrev_b32_e32 v168, 16, v169
	v_and_b32_e32 v169, 0xffff0000, v169
	v_lshlrev_b32_e32 v176, 16, v170
	v_and_b32_e32 v177, 0xffff0000, v170
	v_lshlrev_b32_e32 v170, 16, v171
	v_and_b32_e32 v171, 0xffff0000, v171
	v_pk_fma_f32 v[142:143], v[142:143], v[62:63], v[168:169]
	v_pk_fma_f32 v[140:141], v[140:141], v[60:61], v[174:175]
	v_pk_fma_f32 v[168:169], v[138:139], v[58:59], v[170:171]
	v_pk_fma_f32 v[138:139], v[136:137], v[56:57], v[176:177]
	v_cvt_pk_bf16_f32 v136, v140, v141
	v_cvt_pk_bf16_f32 v137, v142, v143
	v_cvt_pk_bf16_f32 v138, v138, v139
	v_cvt_pk_bf16_f32 v139, v168, v169
	v_lshl_add_u64 v[140:141], s[42:43], 0, v[160:161]
	global_store_dwordx4 v[140:141], v[136:139], off
	s_waitcnt vmcnt(10)
; DI unsigned pack2(float a, float b) { f32x2 v = {a, b}; hwbf16x2 r = __builtin_convertvector(v, hwbf16x2); return __builtin_bit_cast(unsigned, r); }
; DI float bflo(unsigned w) { return __uint_as_float(w << 16); }
; DI float bfhi(unsigned w) { return __uint_as_float(w & 0xffff0000u); }
;     DI void operator()(const f32x4 (&acc)[2][2][4][2], const Unit& u, int wr, int wc, int fr, int fq) const {
;     ...
;         for (int ai = 0; ai < 2; ++ai)
; #pragma unroll
;             for (int m = 0; m < 4; ++m) { const size_t ro = (size_t)(row0 + ai * HALF + m * 16) * D + col0;
; #pragma unroll
;                 for (int bj = 0; bj < 2; ++bj) {
;                     f32x4 x0, x1;
;                     if constexpr (IB) { const u32x4 w = *(const u32x4*)((const bf16_t*)Xin + ro + bj * HALF);
;                         x0 = (f32x4){bflo(w[0]), bfhi(w[0]), bflo(w[1]), bfhi(w[1])}; x1 = (f32x4){bflo(w[2]), bfhi(w[2]), bflo(w[3]), bfhi(w[3])}; }
;                     else { x0 = *(const f32x4*)((const float*)Xin + ro + bj * HALF); x1 = *(const f32x4*)((const float*)Xin + ro + bj * HALF + 4); }
;                     x0 += acc[ai][bj][m][0] * sc[bj][0]; x1 += acc[ai][bj][m][1] * sc[bj][1];
;                     if constexpr (OB) { u32x4 o; o[0] = pack2(x0[0], x0[1]); o[1] = pack2(x0[2], x0[3]); o[2] = pack2(x1[0], x1[1]); o[3] = pack2(x1[2], x1[3]);
;                         *(u32x4*)((bf16_t*)Xout + ro + bj * HALF) = o; }
;                     else { *(f32x4*)((float*)Xout + ro + bj * HALF) = x0; *(f32x4*)((float*)Xout + ro + bj * HALF + 4) = x1; } } }
	s_nop 1
	v_mov_b32_e32 v136, v182
	v_mov_b32_e32 v137, v183
	v_mov_b32_e32 v138, v184
	v_mov_b32_e32 v139, v185
	s_waitcnt lgkmcnt(0)
	v_lshlrev_b32_e32 v142, 16, v136
	v_and_b32_e32 v143, 0xffff0000, v136
	v_lshlrev_b32_e32 v136, 16, v137
	v_and_b32_e32 v137, 0xffff0000, v137
	v_lshlrev_b32_e32 v168, 16, v138
	v_and_b32_e32 v169, 0xffff0000, v138
	v_lshlrev_b32_e32 v138, 16, v139
	v_and_b32_e32 v139, 0xffff0000, v139
	v_pk_fma_f32 v[134:135], v[134:135], v[46:47], v[136:137]
	v_pk_fma_f32 v[132:133], v[132:133], v[44:45], v[142:143]
	v_pk_fma_f32 v[136:137], v[130:131], v[42:43], v[138:139]
	v_pk_fma_f32 v[130:131], v[128:129], v[40:41], v[168:169]
	v_cvt_pk_bf16_f32 v128, v132, v133
	v_cvt_pk_bf16_f32 v129, v134, v135
	v_cvt_pk_bf16_f32 v130, v130, v131
	v_cvt_pk_bf16_f32 v131, v136, v137
	v_lshl_add_u64 v[132:133], v[160:161], 0, s[2:3]
	global_store_dwordx4 v[140:141], v[128:131], off offset:256
	v_lshl_add_u64 v[134:135], s[4:5], 0, v[132:133]
	s_waitcnt vmcnt(10)
	s_nop 1
	v_mov_b32_e32 v128, v186
	v_mov_b32_e32 v129, v187
	v_mov_b32_e32 v130, v188
	v_mov_b32_e32 v131, v189
	s_mov_b64 s[2:3], 0x20000
	s_waitcnt lgkmcnt(0)
	v_lshlrev_b32_e32 v136, 16, v128
	v_and_b32_e32 v137, 0xffff0000, v128
	v_lshlrev_b32_e32 v128, 16, v129
	v_and_b32_e32 v129, 0xffff0000, v129
	v_lshlrev_b32_e32 v138, 16, v130
	v_and_b32_e32 v139, 0xffff0000, v130
	v_lshlrev_b32_e32 v130, 16, v131
	v_and_b32_e32 v131, 0xffff0000, v131
	v_pk_fma_f32 v[126:127], v[126:127], v[62:63], v[128:129]
	v_pk_fma_f32 v[124:125], v[124:125], v[60:61], v[136:137]
	v_pk_fma_f32 v[128:129], v[122:123], v[58:59], v[130:131]
	v_pk_fma_f32 v[122:123], v[120:121], v[56:57], v[138:139]
	v_cvt_pk_bf16_f32 v120, v124, v125
	v_cvt_pk_bf16_f32 v121, v126, v127
	v_cvt_pk_bf16_f32 v122, v122, v123
	v_cvt_pk_bf16_f32 v123, v128, v129
	v_lshl_add_u64 v[124:125], s[42:43], 0, v[132:133]
	global_store_dwordx4 v[124:125], v[120:123], off
	s_waitcnt vmcnt(10)
	s_nop 1
	v_mov_b32_e32 v120, v190
	v_mov_b32_e32 v121, v191
	v_mov_b32_e32 v122, v192
	v_mov_b32_e32 v123, v193
	s_waitcnt lgkmcnt(0)
	v_lshlrev_b32_e32 v126, 16, v120
	v_and_b32_e32 v127, 0xffff0000, v120
	v_lshlrev_b32_e32 v120, 16, v121
	v_and_b32_e32 v121, 0xffff0000, v121
	v_lshlrev_b32_e32 v128, 16, v122
	v_and_b32_e32 v129, 0xffff0000, v122
	v_lshlrev_b32_e32 v122, 16, v123
	v_and_b32_e32 v123, 0xffff0000, v123
	v_pk_fma_f32 v[118:119], v[118:119], v[46:47], v[120:121]
	v_pk_fma_f32 v[116:117], v[116:117], v[44:45], v[126:127]
	v_pk_fma_f32 v[120:121], v[114:115], v[42:43], v[122:123]
	v_pk_fma_f32 v[114:115], v[112:113], v[40:41], v[128:129]
	v_cvt_pk_bf16_f32 v112, v116, v117
	v_cvt_pk_bf16_f32 v113, v118, v119
	v_cvt_pk_bf16_f32 v114, v114, v115
	v_cvt_pk_bf16_f32 v115, v120, v121
	v_lshl_add_u64 v[116:117], v[160:161], 0, s[2:3]
	global_store_dwordx4 v[124:125], v[112:115], off offset:256
	v_lshl_add_u64 v[118:119], s[4:5], 0, v[116:117]
	s_waitcnt vmcnt(10)
	s_nop 1
	v_mov_b32_e32 v112, v198
	v_mov_b32_e32 v113, v199
	v_mov_b32_e32 v114, v200
	v_mov_b32_e32 v115, v201
	s_mov_b64 s[2:3], 0x30000
	s_waitcnt lgkmcnt(0)
	v_lshlrev_b32_e32 v120, 16, v112
	v_and_b32_e32 v121, 0xffff0000, v112
	v_lshlrev_b32_e32 v112, 16, v113
	v_and_b32_e32 v113, 0xffff0000, v113
	v_lshlrev_b32_e32 v122, 16, v114
	v_and_b32_e32 v123, 0xffff0000, v114
	v_lshlrev_b32_e32 v114, 16, v115
	v_and_b32_e32 v115, 0xffff0000, v115
	v_pk_fma_f32 v[110:111], v[110:111], v[62:63], v[112:113]
	v_pk_fma_f32 v[108:109], v[108:109], v[60:61], v[120:121]
	v_pk_fma_f32 v[112:113], v[106:107], v[58:59], v[114:115]
	v_pk_fma_f32 v[106:107], v[104:105], v[56:57], v[122:123]
	v_cvt_pk_bf16_f32 v104, v108, v109
	v_cvt_pk_bf16_f32 v105, v110, v111
	v_cvt_pk_bf16_f32 v106, v106, v107
	v_cvt_pk_bf16_f32 v107, v112, v113
	v_lshl_add_u64 v[108:109], s[42:43], 0, v[116:117]
	global_store_dwordx4 v[108:109], v[104:107], off
	s_waitcnt vmcnt(10)
	s_nop 1
	v_mov_b32_e32 v104, v202
	v_mov_b32_e32 v105, v203
	v_mov_b32_e32 v106, v204
	v_mov_b32_e32 v107, v205
	s_waitcnt lgkmcnt(0)
	v_lshlrev_b32_e32 v110, 16, v104
	v_and_b32_e32 v111, 0xffff0000, v104
	v_lshlrev_b32_e32 v104, 16, v105
	v_and_b32_e32 v105, 0xffff0000, v105
	v_lshlrev_b32_e32 v112, 16, v106
	v_and_b32_e32 v113, 0xffff0000, v106
	v_lshlrev_b32_e32 v106, 16, v107
	v_and_b32_e32 v107, 0xffff0000, v107
	v_pk_fma_f32 v[102:103], v[102:103], v[46:47], v[104:105]
	v_pk_fma_f32 v[100:101], v[100:101], v[44:45], v[110:111]
	v_pk_fma_f32 v[104:105], v[98:99], v[42:43], v[106:107]
	v_pk_fma_f32 v[98:99], v[96:97], v[40:41], v[112:113]
	v_cvt_pk_bf16_f32 v96, v100, v101
	v_cvt_pk_bf16_f32 v97, v102, v103
	v_cvt_pk_bf16_f32 v98, v98, v99
	v_cvt_pk_bf16_f32 v99, v104, v105
	v_lshl_add_u64 v[100:101], v[160:161], 0, s[2:3]
	global_store_dwordx4 v[108:109], v[96:99], off offset:256
	v_lshl_add_u64 v[102:103], s[4:5], 0, v[100:101]
	s_waitcnt vmcnt(10)
	s_nop 1
	v_mov_b32_e32 v96, v206
	v_mov_b32_e32 v97, v207
	v_mov_b32_e32 v98, v208
	v_mov_b32_e32 v99, v209
	s_mov_b64 s[2:3], 0x80000
	s_waitcnt lgkmcnt(0)
	v_lshlrev_b32_e32 v104, 16, v96
	v_and_b32_e32 v105, 0xffff0000, v96
	v_lshlrev_b32_e32 v96, 16, v97
	v_and_b32_e32 v97, 0xffff0000, v97
	v_lshlrev_b32_e32 v106, 16, v98
	v_and_b32_e32 v107, 0xffff0000, v98
	v_lshlrev_b32_e32 v98, 16, v99
	v_and_b32_e32 v99, 0xffff0000, v99
	v_pk_fma_f32 v[94:95], v[94:95], v[62:63], v[96:97]
	v_pk_fma_f32 v[92:93], v[92:93], v[60:61], v[104:105]
	v_pk_fma_f32 v[96:97], v[90:91], v[58:59], v[98:99]
	v_pk_fma_f32 v[90:91], v[88:89], v[56:57], v[106:107]
	v_cvt_pk_bf16_f32 v88, v92, v93
	v_cvt_pk_bf16_f32 v89, v94, v95
	v_cvt_pk_bf16_f32 v90, v90, v91
	v_cvt_pk_bf16_f32 v91, v96, v97
	v_lshl_add_u64 v[92:93], s[42:43], 0, v[100:101]
	global_store_dwordx4 v[92:93], v[88:91], off
	s_waitcnt vmcnt(10)
; DI unsigned pack2(float a, float b) { f32x2 v = {a, b}; hwbf16x2 r = __builtin_convertvector(v, hwbf16x2); return __builtin_bit_cast(unsigned, r); }
; DI float bflo(unsigned w) { return __uint_as_float(w << 16); }
; DI float bfhi(unsigned w) { return __uint_as_float(w & 0xffff0000u); }
;     DI void operator()(const f32x4 (&acc)[2][2][4][2], const Unit& u, int wr, int wc, int fr, int fq) const {
;     ...
;         for (int ai = 0; ai < 2; ++ai)
; #pragma unroll
;             for (int m = 0; m < 4; ++m) { const size_t ro = (size_t)(row0 + ai * HALF + m * 16) * D + col0;
; #pragma unroll
;                 for (int bj = 0; bj < 2; ++bj) {
;                     f32x4 x0, x1;
;                     if constexpr (IB) { const u32x4 w = *(const u32x4*)((const bf16_t*)Xin + ro + bj * HALF);
;                         x0 = (f32x4){bflo(w[0]), bfhi(w[0]), bflo(w[1]), bfhi(w[1])}; x1 = (f32x4){bflo(w[2]), bfhi(w[2]), bflo(w[3]), bfhi(w[3])}; }
;                     else { x0 = *(const f32x4*)((const float*)Xin + ro + bj * HALF); x1 = *(const f32x4*)((const float*)Xin + ro + bj * HALF + 4); }
;                     x0 += acc[ai][bj][m][0] * sc[bj][0]; x1 += acc[ai][bj][m][1] * sc[bj][1];
;                     if constexpr (OB) { u32x4 o; o[0] = pack2(x0[0], x0[1]); o[1] = pack2(x0[2], x0[3]); o[2] = pack2(x1[0], x1[1]); o[3] = pack2(x1[2], x1[3]);
;                         *(u32x4*)((bf16_t*)Xout + ro + bj * HALF) = o; }
;                     else { *(f32x4*)((float*)Xout + ro + bj * HALF) = x0; *(f32x4*)((float*)Xout + ro + bj * HALF + 4) = x1; } } }
	s_nop 1
	v_mov_b32_e32 v88, v210
	v_mov_b32_e32 v89, v211
	v_mov_b32_e32 v90, v212
	v_mov_b32_e32 v91, v213
	s_waitcnt lgkmcnt(0)
	v_lshlrev_b32_e32 v94, 16, v88
	v_and_b32_e32 v95, 0xffff0000, v88
	v_lshlrev_b32_e32 v88, 16, v89
	v_and_b32_e32 v89, 0xffff0000, v89
	v_lshlrev_b32_e32 v96, 16, v90
	v_and_b32_e32 v97, 0xffff0000, v90
	v_lshlrev_b32_e32 v90, 16, v91
	v_and_b32_e32 v91, 0xffff0000, v91
	v_pk_fma_f32 v[86:87], v[86:87], v[46:47], v[88:89]
	v_pk_fma_f32 v[84:85], v[84:85], v[44:45], v[94:95]
	v_pk_fma_f32 v[88:89], v[82:83], v[42:43], v[90:91]
	v_pk_fma_f32 v[82:83], v[80:81], v[40:41], v[96:97]
	v_cvt_pk_bf16_f32 v80, v84, v85
	v_cvt_pk_bf16_f32 v81, v86, v87
	v_cvt_pk_bf16_f32 v82, v82, v83
	v_cvt_pk_bf16_f32 v83, v88, v89
	v_lshl_add_u64 v[84:85], v[160:161], 0, s[2:3]
	global_store_dwordx4 v[92:93], v[80:83], off offset:256
	v_lshl_add_u64 v[86:87], s[4:5], 0, v[84:85]
	s_waitcnt vmcnt(10)
	s_nop 1
	v_mov_b32_e32 v80, v214
	v_mov_b32_e32 v81, v215
	v_mov_b32_e32 v82, v216
	v_mov_b32_e32 v83, v217
	s_mov_b64 s[2:3], 0x90000
	s_waitcnt lgkmcnt(0)
	v_lshlrev_b32_e32 v88, 16, v80
	v_and_b32_e32 v89, 0xffff0000, v80
	v_lshlrev_b32_e32 v80, 16, v81
	v_and_b32_e32 v81, 0xffff0000, v81
	v_lshlrev_b32_e32 v90, 16, v82
	v_and_b32_e32 v91, 0xffff0000, v82
	v_lshlrev_b32_e32 v82, 16, v83
	v_and_b32_e32 v83, 0xffff0000, v83
	v_pk_fma_f32 v[78:79], v[78:79], v[62:63], v[80:81]
	v_pk_fma_f32 v[76:77], v[76:77], v[60:61], v[88:89]
	v_pk_fma_f32 v[80:81], v[74:75], v[58:59], v[82:83]
	v_pk_fma_f32 v[74:75], v[72:73], v[56:57], v[90:91]
	v_cvt_pk_bf16_f32 v72, v76, v77
	v_cvt_pk_bf16_f32 v73, v78, v79
	v_cvt_pk_bf16_f32 v74, v74, v75
	v_cvt_pk_bf16_f32 v75, v80, v81
	v_lshl_add_u64 v[76:77], s[42:43], 0, v[84:85]
	global_store_dwordx4 v[76:77], v[72:75], off
	s_waitcnt vmcnt(10)
	s_nop 1
	v_mov_b32_e32 v72, v248
	v_mov_b32_e32 v73, v249
	v_mov_b32_e32 v74, v250
	v_mov_b32_e32 v75, v251
	s_waitcnt lgkmcnt(0)
	v_lshlrev_b32_e32 v78, 16, v72
	v_and_b32_e32 v79, 0xffff0000, v72
	v_lshlrev_b32_e32 v72, 16, v73
	v_and_b32_e32 v73, 0xffff0000, v73
	v_lshlrev_b32_e32 v80, 16, v74
	v_and_b32_e32 v81, 0xffff0000, v74
	v_lshlrev_b32_e32 v74, 16, v75
	v_and_b32_e32 v75, 0xffff0000, v75
	v_pk_fma_f32 v[70:71], v[70:71], v[46:47], v[72:73]
	v_pk_fma_f32 v[68:69], v[68:69], v[44:45], v[78:79]
	v_pk_fma_f32 v[72:73], v[66:67], v[42:43], v[74:75]
	v_pk_fma_f32 v[66:67], v[64:65], v[40:41], v[80:81]
	v_cvt_pk_bf16_f32 v64, v68, v69
	v_cvt_pk_bf16_f32 v65, v70, v71
	v_cvt_pk_bf16_f32 v66, v66, v67
	v_cvt_pk_bf16_f32 v67, v72, v73
	v_lshl_add_u64 v[68:69], v[160:161], 0, s[2:3]
	global_store_dwordx4 v[76:77], v[64:67], off offset:256
	v_lshl_add_u64 v[70:71], s[4:5], 0, v[68:69]
	s_waitcnt vmcnt(10)
	s_nop 1
	v_mov_b32_e32 v64, v252
	v_mov_b32_e32 v65, v253
	v_mov_b32_e32 v66, v254
	v_mov_b32_e32 v67, v255
	s_mov_b64 s[2:3], 0xa0000
	s_waitcnt lgkmcnt(0)
	v_lshlrev_b32_e32 v72, 16, v64
	v_and_b32_e32 v73, 0xffff0000, v64
	v_lshlrev_b32_e32 v64, 16, v65
	v_and_b32_e32 v65, 0xffff0000, v65
	v_lshlrev_b32_e32 v74, 16, v66
	v_and_b32_e32 v75, 0xffff0000, v66
	v_lshlrev_b32_e32 v66, 16, v67
	v_and_b32_e32 v67, 0xffff0000, v67
	v_pk_fma_f32 v[54:55], v[54:55], v[62:63], v[64:65]
	v_pk_fma_f32 v[52:53], v[52:53], v[60:61], v[72:73]
	v_pk_fma_f32 v[64:65], v[50:51], v[58:59], v[66:67]
	v_pk_fma_f32 v[50:51], v[48:49], v[56:57], v[74:75]
	v_cvt_pk_bf16_f32 v48, v52, v53
	v_cvt_pk_bf16_f32 v49, v54, v55
	v_cvt_pk_bf16_f32 v50, v50, v51
	v_cvt_pk_bf16_f32 v51, v64, v65
	v_lshl_add_u64 v[52:53], s[42:43], 0, v[68:69]
	global_store_dwordx4 v[52:53], v[48:51], off
	global_load_dwordx4 v[48:51], v[70:71], off offset:256
	s_waitcnt vmcnt(0) lgkmcnt(0)
; DI unsigned pack2(float a, float b) { f32x2 v = {a, b}; hwbf16x2 r = __builtin_convertvector(v, hwbf16x2); return __builtin_bit_cast(unsigned, r); }
; DI float bflo(unsigned w) { return __uint_as_float(w << 16); }
; DI float bfhi(unsigned w) { return __uint_as_float(w & 0xffff0000u); }
;     DI const char* a(const Unit& u) const { return (const char*)(A + (size_t)u.pm * BM * lda); }
;     DI const char* a(const Unit& u) const { return (const char*)(A + (size_t)u.pm * BM * 2048 + (u.pn >> 1) * 512); }
;     DI void operator()(const f32x4 (&acc)[2][2][4][2], const Unit& u, int wr, int wc, int fr, int fq) const {
;     ...
;         for (int ai = 0; ai < 2; ++ai)
; #pragma unroll
;             for (int m = 0; m < 4; ++m) { const size_t ro = (size_t)(row0 + ai * HALF + m * 16) * D + col0;
; #pragma unroll
;                 for (int bj = 0; bj < 2; ++bj) {
;                     f32x4 x0, x1;
;                     if constexpr (IB) { const u32x4 w = *(const u32x4*)((const bf16_t*)Xin + ro + bj * HALF);
;                         x0 = (f32x4){bflo(w[0]), bfhi(w[0]), bflo(w[1]), bfhi(w[1])}; x1 = (f32x4){bflo(w[2]), bfhi(w[2]), bflo(w[3]), bfhi(w[3])}; }
;                     else { x0 = *(const f32x4*)((const float*)Xin + ro + bj * HALF); x1 = *(const f32x4*)((const float*)Xin + ro + bj * HALF + 4); }
;                     x0 += acc[ai][bj][m][0] * sc[bj][0]; x1 += acc[ai][bj][m][1] * sc[bj][1];
;                     if constexpr (OB) { u32x4 o; o[0] = pack2(x0[0], x0[1]); o[1] = pack2(x0[2], x0[3]); o[2] = pack2(x1[0], x1[1]); o[3] = pack2(x1[2], x1[3]);
;                         *(u32x4*)((bf16_t*)Xout + ro + bj * HALF) = o; }
;                     else { *(f32x4*)((float*)Xout + ro + bj * HALF) = x0; *(f32x4*)((float*)Xout + ro + bj * HALF + 4) = x1; } } }
; template <class Map, class Epi>
; DI void gemm_phase(LAS unsigned char* lds, const Map& MP, const Epi& E, const int nM, const int nN, const int K, const int lda, const int ldb) {
;     ...
;         if (!has_next) break;
; #pragma unroll
;         for (int a = 0; a < 2; ++a)
; #pragma unroll
;             for (int b = 0; b < 2; ++b)
; #pragma unroll
;                 for (int m = 0; m < 4; ++m)
; #pragma unroll
;                     for (int n = 0; n < 2; ++n) acc[a][b][m][n] = (f32x4){0.f, 0.f, 0.f, 0.f};
;         cur = nxt; cA = nA; cB = nB; ++ui;
;     }
;     PG8_WAIT_V(0);
;     if (wr == 0) PG8_BAR;
;     PG8_BAR;
	v_lshlrev_b32_e32 v54, 16, v48
	v_and_b32_e32 v55, 0xffff0000, v48
	v_lshlrev_b32_e32 v48, 16, v49
	v_and_b32_e32 v49, 0xffff0000, v49
	v_lshlrev_b32_e32 v64, 16, v50
	v_and_b32_e32 v65, 0xffff0000, v50
	v_lshlrev_b32_e32 v50, 16, v51
	v_and_b32_e32 v51, 0xffff0000, v51
	v_pk_fma_f32 v[38:39], v[38:39], v[46:47], v[48:49]
	v_pk_fma_f32 v[36:37], v[36:37], v[44:45], v[54:55]
	v_pk_fma_f32 v[48:49], v[34:35], v[42:43], v[50:51]
	v_pk_fma_f32 v[34:35], v[32:33], v[40:41], v[64:65]
	v_cvt_pk_bf16_f32 v32, v36, v37
	v_cvt_pk_bf16_f32 v33, v38, v39
	v_cvt_pk_bf16_f32 v34, v34, v35
	v_cvt_pk_bf16_f32 v35, v48, v49
	v_lshl_add_u64 v[36:37], v[160:161], 0, s[2:3]
	global_store_dwordx4 v[52:53], v[32:35], off offset:256
	v_lshl_add_u64 v[38:39], s[4:5], 0, v[36:37]
	global_load_dwordx4 v[32:35], v[38:39], off
	s_mov_b64 s[2:3], 0xb0000
	s_waitcnt vmcnt(0) lgkmcnt(0)
	v_lshlrev_b32_e32 v48, 16, v32
	v_and_b32_e32 v49, 0xffff0000, v32
	v_lshlrev_b32_e32 v32, 16, v33
	v_and_b32_e32 v33, 0xffff0000, v33
	v_lshlrev_b32_e32 v50, 16, v34
	v_and_b32_e32 v51, 0xffff0000, v34
	v_lshlrev_b32_e32 v34, 16, v35
	v_and_b32_e32 v35, 0xffff0000, v35
	v_pk_fma_f32 v[30:31], v[30:31], v[62:63], v[32:33]
	v_pk_fma_f32 v[28:29], v[28:29], v[60:61], v[48:49]
	v_pk_fma_f32 v[32:33], v[26:27], v[58:59], v[34:35]
	v_pk_fma_f32 v[26:27], v[24:25], v[56:57], v[50:51]
	v_cvt_pk_bf16_f32 v24, v28, v29
	v_cvt_pk_bf16_f32 v25, v30, v31
	v_cvt_pk_bf16_f32 v26, v26, v27
	v_cvt_pk_bf16_f32 v27, v32, v33
	v_lshl_add_u64 v[28:29], s[42:43], 0, v[36:37]
	global_store_dwordx4 v[28:29], v[24:27], off
	global_load_dwordx4 v[24:27], v[38:39], off offset:256
	s_waitcnt vmcnt(0) lgkmcnt(0)
	v_lshlrev_b32_e32 v30, 16, v24
	v_and_b32_e32 v31, 0xffff0000, v24
	v_lshlrev_b32_e32 v24, 16, v25
	v_and_b32_e32 v25, 0xffff0000, v25
	v_lshlrev_b32_e32 v32, 16, v26
	v_and_b32_e32 v33, 0xffff0000, v26
	v_lshlrev_b32_e32 v26, 16, v27
	v_and_b32_e32 v27, 0xffff0000, v27
	v_pk_fma_f32 v[22:23], v[22:23], v[46:47], v[24:25]
	v_pk_fma_f32 v[20:21], v[20:21], v[44:45], v[30:31]
	v_pk_fma_f32 v[24:25], v[18:19], v[42:43], v[26:27]
	v_pk_fma_f32 v[18:19], v[16:17], v[40:41], v[32:33]
	v_cvt_pk_bf16_f32 v16, v20, v21
	v_cvt_pk_bf16_f32 v17, v22, v23
	v_cvt_pk_bf16_f32 v18, v18, v19
	v_cvt_pk_bf16_f32 v19, v24, v25
	v_lshl_add_u64 v[20:21], v[160:161], 0, s[2:3]
	global_store_dwordx4 v[28:29], v[16:19], off offset:256
	v_lshl_add_u64 v[22:23], s[4:5], 0, v[20:21]
	global_load_dwordx4 v[16:19], v[22:23], off
	s_mov_b32 s2, s37
	s_waitcnt vmcnt(0) lgkmcnt(0)
	v_lshlrev_b32_e32 v24, 16, v16
	v_and_b32_e32 v25, 0xffff0000, v16
	v_lshlrev_b32_e32 v16, 16, v17
	v_and_b32_e32 v17, 0xffff0000, v17
	v_lshlrev_b32_e32 v26, 16, v18
	v_and_b32_e32 v27, 0xffff0000, v18
	v_lshlrev_b32_e32 v18, 16, v19
	v_and_b32_e32 v19, 0xffff0000, v19
	v_pk_fma_f32 v[14:15], v[14:15], v[62:63], v[16:17]
	v_pk_fma_f32 v[12:13], v[12:13], v[60:61], v[24:25]
	v_pk_fma_f32 v[16:17], v[10:11], v[58:59], v[18:19]
	v_pk_fma_f32 v[10:11], v[8:9], v[56:57], v[26:27]
	v_cvt_pk_bf16_f32 v8, v12, v13
	v_cvt_pk_bf16_f32 v9, v14, v15
	v_cvt_pk_bf16_f32 v10, v10, v11
	v_cvt_pk_bf16_f32 v11, v16, v17
	v_lshl_add_u64 v[12:13], s[42:43], 0, v[20:21]
	global_store_dwordx4 v[12:13], v[8:11], off
	global_load_dwordx4 v[8:11], v[22:23], off offset:256
	s_waitcnt vmcnt(0) lgkmcnt(0)
	v_lshlrev_b32_e32 v14, 16, v8
	v_and_b32_e32 v15, 0xffff0000, v8
	v_lshlrev_b32_e32 v8, 16, v9
	v_and_b32_e32 v9, 0xffff0000, v9
	v_lshlrev_b32_e32 v16, 16, v10
	v_and_b32_e32 v17, 0xffff0000, v10
	v_lshlrev_b32_e32 v10, 16, v11
	v_and_b32_e32 v11, 0xffff0000, v11
	v_pk_fma_f32 v[6:7], v[6:7], v[46:47], v[8:9]
	v_pk_fma_f32 v[4:5], v[4:5], v[44:45], v[14:15]
	v_pk_fma_f32 v[8:9], v[2:3], v[42:43], v[10:11]
	v_pk_fma_f32 v[2:3], v[0:1], v[40:41], v[16:17]
	v_cvt_pk_bf16_f32 v0, v4, v5
	v_cvt_pk_bf16_f32 v1, v6, v7
	v_cvt_pk_bf16_f32 v2, v2, v3
	v_cvt_pk_bf16_f32 v3, v8, v9
	global_store_dwordx4 v[12:13], v[0:3], off offset:256
	s_cbranch_vccz .LBB1_2336
	s_waitcnt vmcnt(0)
	s_cmpk_gt_u32 s17, 0xff
	s_cbranch_scc1 .LBB1_2343
	s_barrier

; #define PG8_STAGE(bufoff, gbase, voff) do { _Pragma("unroll") for (int _i = 0; _i < 2; ++_i) \
;         __builtin_amdgcn_global_load_lds((const unsigned*)((const char*)(gbase) + (voff)[_i]), (LAS unsigned*)(lds + (bufoff) + ldsw + _i * 8192), 16, 0, 0); } while (0)
; #define PG8_LDA(dst, b, h) do { _Pragma("unroll") for (int m = 0; m < 4; ++m) _Pragma("unroll") for (int k = 0; k < 2; ++k) dst[m][k] = *(const LAS bf16x8*)(lds + PG8_SA(b, h) + aoff + m * 2048 + k * 1024); } while (0)
; #define PG8_LDB(dst, b, h) do { _Pragma("unroll") for (int n = 0; n < 2; ++n) _Pragma("unroll") for (int k = 0; k < 2; ++k) dst[n][k] = *(const LAS bf16x8*)(lds + PG8_SB(b, h) + boff + n * 2048 + k * 1024); } while (0)
; #define PG8_MMA(ai, bj, At, Bt) do { __builtin_amdgcn_s_setprio(1); _Pragma("unroll") for (int m = 0; m < 4; ++m) _Pragma("unroll") for (int n = 0; n < 2; ++n) _Pragma("unroll") for (int k = 0; k < 2; ++k) \
;         acc[ai][bj][m][n] = __builtin_amdgcn_mfma_f32_16x16x32_bf16(Bt[n][k], At[m][k], acc[ai][bj][m][n], 0, 0, 0); __builtin_amdgcn_s_setprio(0); } while (0)
; #define PG8_WAIT_V(n) asm volatile("s_waitcnt vmcnt(" #n ")" ::: "memory")
; #define PG8_WAIT_L(n) asm volatile("s_waitcnt lgkmcnt(" #n ")" ::: "memory")
; template <class Map, class Epi>
; DI void gemm_phase(LAS unsigned char* lds, const Map& MP, const Epi& E, const int nM, const int nN, const int K, const int lda, const int ldb) {
;     ...
;             const bool last = (t == nt - 2);
;             const char* a1 = cA + (size_t)(t + 1) * kstep;
;             const char* a2 = last ? nA : cA + (size_t)(t + 2) * kstep; const char* b2 = last ? nB : cB + (size_t)(t + 2) * kstep;
;             const char* a3 = a2 + kstep; const char* b3 = b2 + kstep;
;             PG8_LDB(B0, 0, 0); PG8_SCHED; PG8_LDA(At, 0, 0); PG8_STAGE(PG8_SA(1, 1), a1 + hstepA, voffA);
;             PG8_WAIT_L(8); PG8_BAR; PG8_WAIT_L(0); PG8_MMA(0, 0, At, B0); PG8_BAR; PG8_SCHED;
;             PG8_LDB(B1, 0, 1); PG8_STAGE(PG8_SB(0, 0), b2, voffB);
;             PG8_BAR; PG8_WAIT_L(0); PG8_MMA(0, 1, At, B1); PG8_BAR;
;             PG8_LDA(At, 0, 1); PG8_STAGE(PG8_SA(0, 0), a2, voffA);
;             PG8_BAR; PG8_WAIT_L(0); PG8_MMA(1, 0, At, B0); PG8_BAR; PG8_SCHED;
;             PG8_STAGE(PG8_SB(0, 1), b2 + hstepB, voffB);
;             PG8_WAIT_V(6); PG8_BAR; PG8_MMA(1, 1, At, B1); PG8_BAR;
.LBB1_2483:
	s_add_u32 s28, s42, 0xfff80080
	s_addc_u32 s29, s43, -1
	s_cmp_eq_u32 s3, 28
	s_cselect_b32 s47, s23, s29
	s_cselect_b32 s46, s58, s28
	s_cselect_b32 s29, s21, vcc_hi
	s_cselect_b32 s28, s59, vcc_lo
	s_add_i32 m0, s38, 0xc000
	ds_read_b128 v[96:99], v190
	ds_read_b128 v[100:103], v190 offset:1024
	ds_read_b128 v[108:111], v190 offset:2048
	ds_read_b128 v[112:115], v190 offset:3072
	ds_read_b128 v[160:163], v190 offset:4096
	ds_read_b128 v[164:167], v190 offset:5120
	ds_read_b128 v[198:201], v190 offset:6144
	ds_read_b128 v[202:205], v190 offset:7168
	global_load_lds_dwordx4 v178, s[42:43]
	s_add_i32 m0, s38, 0xe000
	s_nop 0
	global_load_lds_dwordx4 v176, s[42:43]
	s_waitcnt lgkmcnt(8)
	s_setprio 1
	s_barrier
	s_waitcnt lgkmcnt(7)
	v_mfma_f32_16x16x32_bf16 v[148:151], v[80:83], v[96:99], v[148:151]
	v_mfma_f32_16x16x32_bf16 v[144:147], v[88:91], v[96:99], v[144:147]
	s_waitcnt lgkmcnt(5)
	v_mfma_f32_16x16x32_bf16 v[136:139], v[80:83], v[108:111], v[136:139]
	v_mfma_f32_16x16x32_bf16 v[128:131], v[88:91], v[108:111], v[128:131]
	s_waitcnt lgkmcnt(3)
	v_mfma_f32_16x16x32_bf16 v[120:123], v[80:83], v[160:163], v[120:123]
	v_mfma_f32_16x16x32_bf16 v[104:107], v[88:91], v[160:163], v[104:107]
	s_waitcnt lgkmcnt(1)
	v_mfma_f32_16x16x32_bf16 v[76:79], v[80:83], v[198:201], v[76:79]
	v_mfma_f32_16x16x32_bf16 v[72:75], v[88:91], v[198:201], v[72:75]
	v_mfma_f32_16x16x32_bf16 v[148:151], v[84:87], v[100:103], v[148:151]
	s_add_i32 s68, s2, s37
	v_mfma_f32_16x16x32_bf16 v[144:147], v[92:95], v[100:103], v[144:147]
	v_lshl_add_u64 v[184:185], s[28:29], 0, v[172:173]
	v_mfma_f32_16x16x32_bf16 v[136:139], v[84:87], v[112:115], v[136:139]
	v_lshl_add_u64 v[194:195], s[28:29], 0, v[168:169]
	v_mfma_f32_16x16x32_bf16 v[128:131], v[92:95], v[112:115], v[128:131]
	v_mfma_f32_16x16x32_bf16 v[120:123], v[84:87], v[164:167], v[120:123]
	v_mfma_f32_16x16x32_bf16 v[104:107], v[92:95], v[164:167], v[104:107]
	s_waitcnt lgkmcnt(0)
	v_mfma_f32_16x16x32_bf16 v[76:79], v[84:87], v[202:205], v[76:79]
	v_mfma_f32_16x16x32_bf16 v[72:75], v[92:95], v[202:205], v[72:75]
	s_barrier
	s_setprio 0
	s_mov_b32 m0, s68
	ds_read_b128 v[206:209], v191
	ds_read_b128 v[210:213], v191 offset:1024
	ds_read_b128 v[214:217], v191 offset:2048
	ds_read_b128 v[218:221], v191 offset:3072
	global_load_lds_dwordx4 v[184:185], off
	s_add_i32 m0, s68, 0x2000
	s_nop 0
	global_load_lds_dwordx4 v[194:195], off
	s_setprio 1
	s_barrier
	s_waitcnt lgkmcnt(3)
	v_mfma_f32_16x16x32_bf16 v[156:159], v[206:209], v[96:99], v[156:159]
	s_waitcnt lgkmcnt(1)
	v_mfma_f32_16x16x32_bf16 v[96:99], v[214:217], v[96:99], v[152:155]
	v_mfma_f32_16x16x32_bf16 v[156:159], v[210:213], v[100:103], v[156:159]
	s_waitcnt lgkmcnt(0)
	v_mfma_f32_16x16x32_bf16 v[96:99], v[218:221], v[100:103], v[96:99]
	v_mfma_f32_16x16x32_bf16 v[100:103], v[206:209], v[108:111], v[140:143]
	v_mfma_f32_16x16x32_bf16 v[108:111], v[214:217], v[108:111], v[132:135]
	v_mfma_f32_16x16x32_bf16 v[116:119], v[214:217], v[160:163], v[116:119]
	v_mfma_f32_16x16x32_bf16 v[68:71], v[206:209], v[198:201], v[68:71]
	v_mfma_f32_16x16x32_bf16 v[64:67], v[214:217], v[198:201], v[64:67]
	v_lshl_add_u64 v[232:233], s[46:47], 0, v[170:171]
	s_mov_b32 m0, s38
	v_mfma_f32_16x16x32_bf16 v[100:103], v[210:213], v[112:115], v[100:103]
	v_lshl_add_u64 v[230:231], s[46:47], 0, v[174:175]
	v_mfma_f32_16x16x32_bf16 v[108:111], v[218:221], v[112:115], v[108:111]
	v_mfma_f32_16x16x32_bf16 v[112:115], v[206:209], v[160:163], v[124:127]
	v_mfma_f32_16x16x32_bf16 v[116:119], v[218:221], v[164:167], v[116:119]
	v_mfma_f32_16x16x32_bf16 v[68:71], v[210:213], v[202:205], v[68:71]
	v_mfma_f32_16x16x32_bf16 v[64:67], v[218:221], v[202:205], v[64:67]
	v_mfma_f32_16x16x32_bf16 v[112:115], v[210:213], v[164:167], v[112:115]
	s_barrier
	s_setprio 0
	ds_read_b128 v[124:127], v190 offset:16384
	ds_read_b128 v[132:135], v190 offset:17408
	ds_read_b128 v[140:143], v190 offset:18432
	ds_read_b128 v[152:155], v190 offset:19456
	ds_read_b128 v[160:163], v190 offset:20480
	ds_read_b128 v[164:167], v190 offset:21504
	ds_read_b128 v[198:201], v190 offset:22528
	ds_read_b128 v[202:205], v190 offset:23552
	global_load_lds_dwordx4 v[230:231], off
	s_mov_b32 m0, s39
	s_nop 0
	global_load_lds_dwordx4 v[232:233], off
	s_waitcnt vmcnt(10)
	s_setprio 1
	s_barrier
	s_waitcnt lgkmcnt(7)
	v_mfma_f32_16x16x32_bf16 v[60:63], v[80:83], v[124:127], v[60:63]
	v_mfma_f32_16x16x32_bf16 v[48:51], v[88:91], v[124:127], v[48:51]
	s_waitcnt lgkmcnt(5)
	v_mfma_f32_16x16x32_bf16 v[40:43], v[80:83], v[140:143], v[40:43]
	v_mfma_f32_16x16x32_bf16 v[32:35], v[88:91], v[140:143], v[32:35]
	s_waitcnt lgkmcnt(3)
	v_mfma_f32_16x16x32_bf16 v[24:27], v[80:83], v[160:163], v[24:27]
	v_mfma_f32_16x16x32_bf16 v[16:19], v[88:91], v[160:163], v[16:19]
	s_waitcnt lgkmcnt(1)
	v_mfma_f32_16x16x32_bf16 v[12:15], v[80:83], v[198:201], v[12:15]
	v_mfma_f32_16x16x32_bf16 v[8:11], v[88:91], v[198:201], v[8:11]
	v_mfma_f32_16x16x32_bf16 v[60:63], v[84:87], v[132:135], v[60:63]
	s_add_u32 s68, s28, 0x80000
	s_addc_u32 s69, s29, 0
	v_mfma_f32_16x16x32_bf16 v[48:51], v[92:95], v[132:135], v[48:51]
	s_add_i32 s70, s67, s37
	v_mfma_f32_16x16x32_bf16 v[40:43], v[84:87], v[152:155], v[40:43]
	v_mfma_f32_16x16x32_bf16 v[32:35], v[92:95], v[152:155], v[32:35]
	v_mfma_f32_16x16x32_bf16 v[24:27], v[84:87], v[164:167], v[24:27]
	v_mfma_f32_16x16x32_bf16 v[16:19], v[92:95], v[164:167], v[16:19]
	s_waitcnt lgkmcnt(0)
	v_mfma_f32_16x16x32_bf16 v[12:15], v[84:87], v[202:205], v[12:15]
	v_mfma_f32_16x16x32_bf16 v[8:11], v[92:95], v[202:205], v[8:11]
	s_barrier
; #define PG8_STAGE(bufoff, gbase, voff) do { _Pragma("unroll") for (int _i = 0; _i < 2; ++_i) \
;         __builtin_amdgcn_global_load_lds((const unsigned*)((const char*)(gbase) + (voff)[_i]), (LAS unsigned*)(lds + (bufoff) + ldsw + _i * 8192), 16, 0, 0); } while (0)
; #define PG8_LDA(dst, b, h) do { _Pragma("unroll") for (int m = 0; m < 4; ++m) _Pragma("unroll") for (int k = 0; k < 2; ++k) dst[m][k] = *(const LAS bf16x8*)(lds + PG8_SA(b, h) + aoff + m * 2048 + k * 1024); } while (0)
; #define PG8_LDB(dst, b, h) do { _Pragma("unroll") for (int n = 0; n < 2; ++n) _Pragma("unroll") for (int k = 0; k < 2; ++k) dst[n][k] = *(const LAS bf16x8*)(lds + PG8_SB(b, h) + boff + n * 2048 + k * 1024); } while (0)
; #define PG8_MMA(ai, bj, At, Bt) do { __builtin_amdgcn_s_setprio(1); _Pragma("unroll") for (int m = 0; m < 4; ++m) _Pragma("unroll") for (int n = 0; n < 2; ++n) _Pragma("unroll") for (int k = 0; k < 2; ++k) \
;         acc[ai][bj][m][n] = __builtin_amdgcn_mfma_f32_16x16x32_bf16(Bt[n][k], At[m][k], acc[ai][bj][m][n], 0, 0, 0); __builtin_amdgcn_s_setprio(0); } while (0)
; #define PG8_WAIT_V(n) asm volatile("s_waitcnt vmcnt(" #n ")" ::: "memory")
; #define PG8_WAIT_L(n) asm volatile("s_waitcnt lgkmcnt(" #n ")" ::: "memory")
; #define PG8_BAR __builtin_amdgcn_s_barrier()
; #define PG8_SCHED __builtin_amdgcn_sched_barrier(0)
; template <class Map, class Epi>
; DI void gemm_phase(LAS unsigned char* lds, const Map& MP, const Epi& E, const int nM, const int nN, const int K, const int lda, const int ldb) {
;     ...
;             PG8_WAIT_V(6); PG8_BAR; PG8_MMA(1, 1, At, B1); PG8_BAR;
;             PG8_LDB(B0, 1, 0); PG8_SCHED; PG8_LDA(At, 1, 0); PG8_STAGE(PG8_SA(0, 1), a2 + hstepA, voffA);
;             PG8_WAIT_L(8); PG8_BAR; PG8_WAIT_L(0); PG8_MMA(0, 0, At, B0); PG8_BAR; PG8_SCHED;
;             PG8_LDB(B1, 1, 1); PG8_STAGE(PG8_SB(1, 0), b3, voffB);
;             PG8_BAR; PG8_WAIT_L(0); PG8_MMA(0, 1, At, B1); PG8_BAR;
;             PG8_LDA(At, 1, 1); PG8_STAGE(PG8_SA(1, 0), a3, voffA);
;             PG8_BAR; PG8_WAIT_L(0); PG8_MMA(1, 0, At, B0); PG8_BAR; PG8_SCHED;
	s_setprio 0
	s_mov_b32 m0, s70
	s_nop 0
	global_load_lds_dwordx4 v172, s[68:69]
	s_add_i32 m0, s70, 0x2000
	s_nop 0
	global_load_lds_dwordx4 v168, s[68:69]
	s_waitcnt vmcnt(6)
	s_setprio 1
	s_barrier
	v_mfma_f32_16x16x32_bf16 v[56:59], v[206:209], v[124:127], v[56:59]
	v_mfma_f32_16x16x32_bf16 v[52:55], v[214:217], v[124:127], v[52:55]
	s_add_i32 s68, 0, 0x18000
	v_add_u32_e32 v92, s68, v188
	ds_read_b128 v[80:83], v92
	v_mfma_f32_16x16x32_bf16 v[44:47], v[206:209], v[140:143], v[44:47]
	v_mfma_f32_16x16x32_bf16 v[36:39], v[214:217], v[140:143], v[36:39]
	ds_read_b128 v[84:87], v92 offset:1024
	v_mfma_f32_16x16x32_bf16 v[28:31], v[206:209], v[160:163], v[28:31]
	v_mfma_f32_16x16x32_bf16 v[20:23], v[214:217], v[160:163], v[20:23]
	ds_read_b128 v[88:91], v92 offset:2048
	v_mfma_f32_16x16x32_bf16 v[4:7], v[206:209], v[198:201], v[4:7]
	v_mfma_f32_16x16x32_bf16 v[0:3], v[214:217], v[198:201], v[0:3]
	ds_read_b128 v[92:95], v92 offset:3072
	v_mfma_f32_16x16x32_bf16 v[56:59], v[210:213], v[132:135], v[56:59]
	s_add_u32 s46, s46, 0x80000
	s_addc_u32 s47, s47, 0
	v_mfma_f32_16x16x32_bf16 v[52:55], v[218:221], v[132:135], v[52:55]
	v_mfma_f32_16x16x32_bf16 v[44:47], v[210:213], v[152:155], v[44:47]
	v_mfma_f32_16x16x32_bf16 v[36:39], v[218:221], v[152:155], v[36:39]
	v_mfma_f32_16x16x32_bf16 v[28:31], v[210:213], v[164:167], v[28:31]
	v_mfma_f32_16x16x32_bf16 v[20:23], v[218:221], v[164:167], v[20:23]
	v_mfma_f32_16x16x32_bf16 v[4:7], v[210:213], v[202:205], v[4:7]
	v_mfma_f32_16x16x32_bf16 v[0:3], v[218:221], v[202:205], v[0:3]
	s_barrier
	s_setprio 0
	s_mov_b32 m0, s55
	ds_read_b128 v[124:127], v190 offset:32768
	ds_read_b128 v[132:135], v190 offset:33792
	ds_read_b128 v[160:163], v190 offset:34816
	ds_read_b128 v[164:167], v190 offset:35840
	ds_read_b128 v[198:201], v190 offset:36864
	ds_read_b128 v[202:205], v190 offset:37888
	ds_read_b128 v[206:209], v190 offset:38912
	ds_read_b128 v[210:213], v190 offset:39936
	global_load_lds_dwordx4 v174, s[46:47]
	s_mov_b32 m0, s56
	s_nop 0
	global_load_lds_dwordx4 v170, s[46:47]
	s_waitcnt lgkmcnt(8)
	s_setprio 1
	s_barrier
	s_waitcnt lgkmcnt(7)
	v_mfma_f32_16x16x32_bf16 v[140:143], v[80:83], v[124:127], v[148:151]
	s_waitcnt lgkmcnt(6)
	v_mfma_f32_16x16x32_bf16 v[148:151], v[84:87], v[132:135], v[140:143]
	v_mfma_f32_16x16x32_bf16 v[140:143], v[88:91], v[124:127], v[144:147]
	s_waitcnt lgkmcnt(5)
	v_mfma_f32_16x16x32_bf16 v[136:139], v[80:83], v[160:163], v[136:139]
	v_mfma_f32_16x16x32_bf16 v[128:131], v[88:91], v[160:163], v[128:131]
	s_waitcnt lgkmcnt(3)
	v_mfma_f32_16x16x32_bf16 v[120:123], v[80:83], v[198:201], v[120:123]
	v_mfma_f32_16x16x32_bf16 v[104:107], v[88:91], v[198:201], v[104:107]
	s_waitcnt lgkmcnt(1)
	v_mfma_f32_16x16x32_bf16 v[76:79], v[80:83], v[206:209], v[76:79]
	v_mfma_f32_16x16x32_bf16 v[72:75], v[88:91], v[206:209], v[72:75]
	s_add_i32 s46, 0, 0x1c000
	v_mfma_f32_16x16x32_bf16 v[144:147], v[92:95], v[132:135], v[140:143]
	v_add_u32_e32 v140, s46, v188
	v_mfma_f32_16x16x32_bf16 v[136:139], v[84:87], v[164:167], v[136:139]
	s_add_i32 s47, s68, s37
	v_mfma_f32_16x16x32_bf16 v[128:131], v[92:95], v[164:167], v[128:131]
	v_mfma_f32_16x16x32_bf16 v[120:123], v[84:87], v[202:205], v[120:123]
	v_mfma_f32_16x16x32_bf16 v[104:107], v[92:95], v[202:205], v[104:107]
	s_waitcnt lgkmcnt(0)
	v_mfma_f32_16x16x32_bf16 v[76:79], v[84:87], v[210:213], v[76:79]
	v_mfma_f32_16x16x32_bf16 v[72:75], v[92:95], v[210:213], v[72:75]
	s_barrier
	s_setprio 0
	ds_read_b128 v[214:217], v140
	ds_read_b128 v[218:221], v140 offset:1024
	ds_read_b128 v[222:225], v140 offset:2048
	ds_read_b128 v[226:229], v140 offset:3072
	v_lshl_add_u64 v[140:141], v[184:185], 0, s[14:15]
	s_mov_b32 m0, s47
	s_nop 0
	global_load_lds_dwordx4 v[140:141], off
	v_lshl_add_u64 v[140:141], v[194:195], 0, s[14:15]
	s_add_i32 m0, s47, 0x2000
	s_nop 0
	global_load_lds_dwordx4 v[140:141], off
	s_setprio 1
	s_barrier
	s_waitcnt lgkmcnt(1)
	v_mfma_f32_16x16x32_bf16 v[96:99], v[222:225], v[124:127], v[96:99]
	v_mfma_f32_16x16x32_bf16 v[140:143], v[214:217], v[124:127], v[156:159]
	s_waitcnt lgkmcnt(0)
	v_mfma_f32_16x16x32_bf16 v[152:155], v[226:229], v[132:135], v[96:99]
	v_mfma_f32_16x16x32_bf16 v[96:99], v[214:217], v[160:163], v[100:103]
	v_mfma_f32_16x16x32_bf16 v[156:159], v[218:221], v[132:135], v[140:143]
	v_mfma_f32_16x16x32_bf16 v[140:143], v[218:221], v[164:167], v[96:99]
	v_mfma_f32_16x16x32_bf16 v[96:99], v[222:225], v[160:163], v[108:111]
	v_mfma_f32_16x16x32_bf16 v[132:135], v[226:229], v[164:167], v[96:99]
	v_mfma_f32_16x16x32_bf16 v[96:99], v[214:217], v[198:201], v[112:115]
	s_mov_b32 m0, s62
	v_mfma_f32_16x16x32_bf16 v[124:127], v[218:221], v[202:205], v[96:99]
	v_lshl_add_u64 v[184:185], v[230:231], 0, s[14:15]
	v_mfma_f32_16x16x32_bf16 v[96:99], v[222:225], v[198:201], v[116:119]
	v_mfma_f32_16x16x32_bf16 v[68:71], v[214:217], v[206:209], v[68:71]
	v_mfma_f32_16x16x32_bf16 v[64:67], v[222:225], v[206:209], v[64:67]
	v_mfma_f32_16x16x32_bf16 v[116:119], v[226:229], v[202:205], v[96:99]
	v_mfma_f32_16x16x32_bf16 v[68:71], v[218:221], v[210:213], v[68:71]
	v_mfma_f32_16x16x32_bf16 v[64:67], v[226:229], v[210:213], v[64:67]
	s_barrier
	s_setprio 0
	ds_read_b128 v[96:99], v190 offset:49152
	ds_read_b128 v[100:103], v190 offset:50176
	ds_read_b128 v[108:111], v190 offset:51200
	ds_read_b128 v[112:115], v190 offset:52224
	ds_read_b128 v[160:163], v190 offset:53248
	ds_read_b128 v[164:167], v190 offset:54272
	ds_read_b128 v[198:201], v190 offset:55296
	ds_read_b128 v[202:205], v190 offset:56320
	global_load_lds_dwordx4 v[184:185], off
	v_lshl_add_u64 v[184:185], v[232:233], 0, s[14:15]
	s_mov_b32 m0, s63
	s_nop 0
	global_load_lds_dwordx4 v[184:185], off
	s_waitcnt vmcnt(10)
	s_setprio 1
	s_barrier
; #define PG8_STAGE(bufoff, gbase, voff) do { _Pragma("unroll") for (int _i = 0; _i < 2; ++_i) \
;         __builtin_amdgcn_global_load_lds((const unsigned*)((const char*)(gbase) + (voff)[_i]), (LAS unsigned*)(lds + (bufoff) + ldsw + _i * 8192), 16, 0, 0); } while (0)
; #define PG8_MMA(ai, bj, At, Bt) do { __builtin_amdgcn_s_setprio(1); _Pragma("unroll") for (int m = 0; m < 4; ++m) _Pragma("unroll") for (int n = 0; n < 2; ++n) _Pragma("unroll") for (int k = 0; k < 2; ++k) \
;         acc[ai][bj][m][n] = __builtin_amdgcn_mfma_f32_16x16x32_bf16(Bt[n][k], At[m][k], acc[ai][bj][m][n], 0, 0, 0); __builtin_amdgcn_s_setprio(0); } while (0)
; #define PG8_WAIT_V(n) asm volatile("s_waitcnt vmcnt(" #n ")" ::: "memory")
; #define PG8_WAIT_L(n) asm volatile("s_waitcnt lgkmcnt(" #n ")" ::: "memory")
; #define PG8_BAR __builtin_amdgcn_s_barrier()
; #define PG8_SCHED __builtin_amdgcn_sched_barrier(0)
; template <class Map, class Epi>
; DI void gemm_phase(LAS unsigned char* lds, const Map& MP, const Epi& E, const int nM, const int nN, const int K, const int lda, const int ldb) {
;     ...
;             PG8_BAR; PG8_WAIT_L(0); PG8_MMA(1, 0, At, B0); PG8_BAR; PG8_SCHED;
;             PG8_STAGE(PG8_SB(1, 1), b3 + hstepB, voffB);
;             PG8_WAIT_V(6); PG8_BAR; PG8_MMA(1, 1, At, B1); PG8_BAR;
	s_waitcnt lgkmcnt(7)
	v_mfma_f32_16x16x32_bf16 v[60:63], v[80:83], v[96:99], v[60:63]
	v_mfma_f32_16x16x32_bf16 v[48:51], v[88:91], v[96:99], v[48:51]
	s_waitcnt lgkmcnt(5)
	v_mfma_f32_16x16x32_bf16 v[40:43], v[80:83], v[108:111], v[40:43]
	v_mfma_f32_16x16x32_bf16 v[32:35], v[88:91], v[108:111], v[32:35]
	s_waitcnt lgkmcnt(3)
	v_mfma_f32_16x16x32_bf16 v[24:27], v[80:83], v[160:163], v[24:27]
	v_mfma_f32_16x16x32_bf16 v[16:19], v[88:91], v[160:163], v[16:19]
	s_waitcnt lgkmcnt(1)
	v_mfma_f32_16x16x32_bf16 v[12:15], v[80:83], v[198:201], v[12:15]
	v_mfma_f32_16x16x32_bf16 v[8:11], v[88:91], v[198:201], v[8:11]
	v_mfma_f32_16x16x32_bf16 v[60:63], v[84:87], v[100:103], v[60:63]
	s_add_u32 s28, s28, 0x80080
	s_addc_u32 s29, s29, 0
	v_mfma_f32_16x16x32_bf16 v[48:51], v[92:95], v[100:103], v[48:51]
	s_add_i32 s46, s46, s37
	v_mfma_f32_16x16x32_bf16 v[40:43], v[84:87], v[112:115], v[40:43]
	v_mfma_f32_16x16x32_bf16 v[32:35], v[92:95], v[112:115], v[32:35]
	v_mfma_f32_16x16x32_bf16 v[24:27], v[84:87], v[164:167], v[24:27]
	v_mfma_f32_16x16x32_bf16 v[16:19], v[92:95], v[164:167], v[16:19]
	s_waitcnt lgkmcnt(0)
	v_mfma_f32_16x16x32_bf16 v[12:15], v[84:87], v[202:205], v[12:15]
	v_mfma_f32_16x16x32_bf16 v[8:11], v[92:95], v[202:205], v[8:11]
	s_barrier
	s_setprio 0
	s_mov_b32 m0, s46
	s_nop 0
	global_load_lds_dwordx4 v172, s[28:29]
	s_add_i32 m0, s46, 0x2000
	s_nop 0
	global_load_lds_dwordx4 v168, s[28:29]
	s_waitcnt vmcnt(6)
	s_setprio 1
	s_barrier
	v_mfma_f32_16x16x32_bf16 v[56:59], v[214:217], v[96:99], v[56:59]
	v_mfma_f32_16x16x32_bf16 v[52:55], v[222:225], v[96:99], v[52:55]
	ds_read_b128 v[80:83], v189
	v_mfma_f32_16x16x32_bf16 v[44:47], v[214:217], v[108:111], v[44:47]
	v_mfma_f32_16x16x32_bf16 v[36:39], v[222:225], v[108:111], v[36:39]
	ds_read_b128 v[84:87], v189 offset:1024
	v_mfma_f32_16x16x32_bf16 v[28:31], v[214:217], v[160:163], v[28:31]
	v_mfma_f32_16x16x32_bf16 v[20:23], v[222:225], v[160:163], v[20:23]
	ds_read_b128 v[88:91], v189 offset:2048
	v_mfma_f32_16x16x32_bf16 v[4:7], v[214:217], v[198:201], v[4:7]
	v_mfma_f32_16x16x32_bf16 v[0:3], v[222:225], v[198:201], v[0:3]
	ds_read_b128 v[92:95], v189 offset:3072
	v_mfma_f32_16x16x32_bf16 v[56:59], v[218:221], v[100:103], v[56:59]
	s_add_i32 s3, s3, 2
	v_mfma_f32_16x16x32_bf16 v[52:55], v[226:229], v[100:103], v[52:55]
	s_add_u32 vcc_lo, vcc_lo, 0x100
	s_addc_u32 vcc_hi, vcc_hi, 0
	v_mfma_f32_16x16x32_bf16 v[44:47], v[218:221], v[112:115], v[44:47]
	s_add_u32 s42, s42, 0x100
	s_addc_u32 s43, s43, 0
	v_mfma_f32_16x16x32_bf16 v[36:39], v[226:229], v[112:115], v[36:39]
	s_cmp_gt_u32 s3, 29
	v_mfma_f32_16x16x32_bf16 v[28:31], v[218:221], v[164:167], v[28:31]
	v_mfma_f32_16x16x32_bf16 v[20:23], v[226:229], v[164:167], v[20:23]
	v_mfma_f32_16x16x32_bf16 v[4:7], v[218:221], v[202:205], v[4:7]
	v_mfma_f32_16x16x32_bf16 v[0:3], v[226:229], v[202:205], v[0:3]
	s_barrier
	s_setprio 0
	s_cbranch_scc0 .LBB1_2483
; DI float silu_mul(float g, float v) { return g * v * __builtin_amdgcn_rcpf(1.0f + __builtin_amdgcn_exp2f(-LOG2E * g)); }
;     DI void operator()(const f32x4 (&acc)[2][2][4][2], const Unit& u, int wr, int wc, int fr, int fq) const {
;         const int row0 = u.pm * BM + wr * 64 + fr, ch0 = u.pn * 128 + wc * 32 + 8 * fq;
;         f32x4 w0[2], w1[2], w2[2], bb[2];
; #pragma unroll
;         for (int n = 0; n < 2; ++n) { w0[n] = *(const f32x4*)(cw + ch0 + 4 * n); w1[n] = *(const f32x4*)(cw + DFF + ch0 + 4 * n); w2[n] = *(const f32x4*)(cw + 2 * DFF + ch0 + 4 * n); bb[n] = *(const f32x4*)(cb + ch0 + 4 * n); }
; #pragma unroll
;         for (int ai = 0; ai < 2; ++ai)
; #pragma unroll
;             for (int m = 0; m < 4; ++m) {
;                 const bool efirst = (m == 0) && (fr == 0), elast = (m == 3) && (fr == 15);
;                 const int row = row0 + ai * HALF + m * 16;
;                 f32x4 gc[2];
; #pragma unroll
;                 for (int n = 0; n < 2; ++n) {
;                     const f32x4 g = acc[ai][0][m][n];
;                     const f32x4 gprev = acc[ai][0][m > 0 ? m - 1 : 0][n], gnext = acc[ai][0][m < 3 ? m + 1 : 3][n];
;                     f32x4 up, dn;
; #pragma unroll
;                     for (int e = 0; e < 4; ++e) {
;                         const float pu = (m > 0 && fr == 15) ? gprev[e] : g[e];
;                         const float pd = (m < 3 && fr == 0) ? gnext[e] : g[e];
;                         up[e] = dpp_ror1(pu); dn[e] = dpp_ror15(pd);
;                     }
;                     if (efirst) up = (f32x4){0.f, 0.f, 0.f, 0.f};
;                     if (elast) dn = (f32x4){0.f, 0.f, 0.f, 0.f};
;                     gc[n] = w0[n] * up + w1[n] * g + w2[n] * dn + bb[n];
;                 }
;                 if (efirst || elast) {
;                     const size_t eo = (size_t)((row >> 6) * 2 + (elast ? 1 : 0)) * DFF + ch0;
; #pragma unroll
;                     for (int n = 0; n < 2; ++n) { *(f32x4*)(EP + eo + 4 * n) = gc[n]; *(f32x4*)(ER + eo + 4 * n) = acc[ai][0][m][n]; *(f32x4*)(EV + eo + 4 * n) = acc[ai][1][m][n]; }
;                 } else {
;                     const f32x4 v0 = acc[ai][1][m][0], v1 = acc[ai][1][m][1];
;                     u32x4 o;
;                     o[0] = pack2(silu_mul(gc[0][0], v0[0]), silu_mul(gc[0][1], v0[1])); o[1] = pack2(silu_mul(gc[0][2], v0[2]), silu_mul(gc[0][3], v0[3]));
	s_waitcnt lgkmcnt(0)
	s_lshl_b32 s21, s45, 7
	v_mov_b32_e32 v80, v187
	v_mov_b32_e32 v194, v186
	s_or_b32 s21, s21, s57
	v_lshl_add_u32 v184, v80, 3, s21
	v_ashrrev_i32_e32 v185, 31, v184
	v_lshlrev_b64 v[80:81], 2, v[184:185]
	v_lshl_add_u64 v[84:85], s[4:5], 0, v[80:81]
	v_lshl_add_u64 v[88:89], s[16:17], 0, v[80:81]
	v_lshl_add_u64 v[92:93], s[18:19], 0, v[80:81]
	v_lshl_add_u64 v[112:113], s[6:7], 0, v[80:81]
	global_load_dwordx4 v[80:83], v[84:85], off offset:16
	global_load_dwordx4 v[96:99], v[84:85], off
	s_nop 0
	global_load_dwordx4 v[84:87], v[88:89], off offset:16
	global_load_dwordx4 v[100:103], v[88:89], off
	s_nop 0
	global_load_dwordx4 v[88:91], v[92:93], off offset:16
	global_load_dwordx4 v[108:111], v[92:93], off
	s_nop 0
	global_load_dwordx4 v[92:95], v[112:113], off offset:16
	s_nop 0
	global_load_dwordx4 v[112:115], v[112:113], off
	v_cmp_eq_u32_e32 vcc, 0, v194
	s_nop 0
	s_nop 0
	v_cndmask_b32_e32 v161, v148, v136, vcc
	v_cndmask_b32_e32 v162, v149, v137, vcc
	v_cndmask_b32_e32 v163, v150, v138, vcc
	v_mov_b32_dpp v160, v161 row_ror:15 row_mask:0xf bank_mask:0xf
	s_nop 0
	s_nop 0
	v_mov_b32_dpp v161, v162 row_ror:15 row_mask:0xf bank_mask:0xf
	v_mov_b32_dpp v164, v150 row_ror:1 row_mask:0xf bank_mask:0xf
	v_cndmask_b32_e32 v165, v151, v139, vcc
	v_mov_b32_dpp v162, v163 row_ror:15 row_mask:0xf bank_mask:0xf
	v_mov_b32_dpp v195, v151 row_ror:1 row_mask:0xf bank_mask:0xf
	v_mov_b32_dpp v166, v148 row_ror:1 row_mask:0xf bank_mask:0xf
	v_mov_b32_dpp v167, v149 row_ror:1 row_mask:0xf bank_mask:0xf
	v_mov_b32_dpp v163, v165 row_ror:15 row_mask:0xf bank_mask:0xf
	v_cndmask_b32_e64 v165, v195, 0, vcc
	v_cndmask_b32_e64 v164, v164, 0, vcc
	v_cndmask_b32_e64 v167, v167, 0, vcc
	v_cndmask_b32_e64 v166, v166, 0, vcc
	s_nop 0
	s_nop 0
	v_mov_b32_dpp v195, v144 row_ror:1 row_mask:0xf bank_mask:0xf
	v_mov_b32_dpp v196, v145 row_ror:1 row_mask:0xf bank_mask:0xf
	v_mov_b32_dpp v198, v146 row_ror:1 row_mask:0xf bank_mask:0xf
	v_cndmask_b32_e32 v199, v147, v131, vcc
	v_mov_b32_dpp v200, v147 row_ror:1 row_mask:0xf bank_mask:0xf
	v_cndmask_b32_e64 v198, v198, 0, vcc
	v_cndmask_b32_e64 v201, v196, 0, vcc
	s_lshl_b32 s3, s44, 8
	s_add_i32 s3, s3, s49
	v_add_u32_e32 v193, s3, v194
	v_cmp_ne_u32_e64 s[46:47], 0, v194
	s_waitcnt vmcnt(0)
	v_pk_mul_f32 v[164:165], v[98:99], v[164:165]
	v_pk_mul_f32 v[166:167], v[96:97], v[166:167]
	v_pk_fma_f32 v[164:165], v[150:151], v[102:103], v[164:165]
	v_pk_fma_f32 v[166:167], v[148:149], v[100:101], v[166:167]
	v_pk_fma_f32 v[162:163], v[110:111], v[162:163], v[164:165]
	v_cndmask_b32_e32 v165, v144, v128, vcc
	v_pk_fma_f32 v[160:161], v[108:109], v[160:161], v[166:167]
	v_cndmask_b32_e32 v166, v145, v129, vcc
	v_mov_b32_dpp v164, v165 row_ror:15 row_mask:0xf bank_mask:0xf
	v_cndmask_b32_e32 v167, v146, v130, vcc
	v_pk_add_f32 v[162:163], v[114:115], v[162:163]
	v_mov_b32_dpp v165, v166 row_ror:15 row_mask:0xf bank_mask:0xf
	v_pk_add_f32 v[160:161], v[112:113], v[160:161]
	s_nop 0
	v_mov_b32_dpp v166, v167 row_ror:15 row_mask:0xf bank_mask:0xf
	s_nop 1
	v_mov_b32_dpp v167, v199 row_ror:15 row_mask:0xf bank_mask:0xf
	v_cndmask_b32_e64 v199, v200, 0, vcc
	v_cndmask_b32_e64 v200, v195, 0, vcc
	v_pk_mul_f32 v[200:201], v[80:81], v[200:201]
	v_pk_mul_f32 v[198:199], v[82:83], v[198:199]
	v_pk_fma_f32 v[200:201], v[144:145], v[84:85], v[200:201]
	v_pk_fma_f32 v[198:199], v[146:147], v[86:87], v[198:199]
	v_pk_fma_f32 v[164:165], v[88:89], v[164:165], v[200:201]
	v_pk_fma_f32 v[166:167], v[90:91], v[166:167], v[198:199]
	v_pk_add_f32 v[164:165], v[92:93], v[164:165]
	v_pk_add_f32 v[166:167], v[94:95], v[166:167]
	s_and_saveexec_b64 s[28:29], s[46:47]
	s_xor_b64 s[28:29], exec, s[28:29]
	s_cbranch_execz .LBB1_2486
	v_mul_f32_e32 v195, 0xbfb8aa3b, v160
	v_exp_f32_e32 v195, v195
	v_mul_f32_e32 v196, 0xbfb8aa3b, v161
	v_exp_f32_e32 v196, v196
	v_pk_mul_f32 v[160:161], v[156:157], v[160:161]
	v_add_f32_e32 v195, 1.0, v195
	v_rcp_f32_e32 v198, v195
	v_add_f32_e32 v196, 1.0, v196
	v_mul_f32_e32 v195, 0xbfb8aa3b, v162
	v_rcp_f32_e32 v199, v196
	v_exp_f32_e32 v195, v195
	v_mul_f32_e32 v196, 0xbfb8aa3b, v163
	v_exp_f32_e32 v196, v196
	v_pk_mul_f32 v[160:161], v[160:161], v[198:199]
	v_add_f32_e32 v195, 1.0, v195
	v_rcp_f32_e32 v200, v195
	v_add_f32_e32 v195, 1.0, v196
	v_rcp_f32_e32 v201, v195
	v_cvt_pk_bf16_f32 v160, v160, v161
	v_mul_f32_e32 v161, 0xbfb8aa3b, v164
	v_exp_f32_e32 v195, v161
	v_mul_f32_e32 v161, 0xbfb8aa3b, v165
	v_exp_f32_e32 v196, v161
	v_pk_mul_f32 v[162:163], v[158:159], v[162:163]
	v_pk_mul_f32 v[164:165], v[152:153], v[164:165]
	v_pk_mul_f32 v[162:163], v[162:163], v[200:201]
	s_nop 0
	v_cvt_pk_bf16_f32 v161, v162, v163
	v_add_f32_e32 v162, 1.0, v195
	v_mul_f32_e32 v195, 0xbfb8aa3b, v166
	v_add_f32_e32 v163, 1.0, v196
	v_exp_f32_e32 v195, v195
	v_mul_f32_e32 v196, 0xbfb8aa3b, v167
	v_exp_f32_e32 v196, v196
	v_rcp_f32_e32 v162, v162
	v_add_f32_e32 v195, 1.0, v195
	v_rcp_f32_e32 v198, v195
	v_add_f32_e32 v195, 1.0, v196
	v_rcp_f32_e32 v163, v163
	v_rcp_f32_e32 v199, v195
	v_pk_mul_f32 v[166:167], v[154:155], v[166:167]
	v_pk_mul_f32 v[162:163], v[164:165], v[162:163]
	v_pk_mul_f32 v[164:165], v[166:167], v[198:199]
	v_cvt_pk_bf16_f32 v162, v162, v163
	v_cvt_pk_bf16_f32 v163, v164, v165
	v_mov_b64_e32 v[164:165], s[52:53]
	v_mad_i64_i32 v[164:165], s[42:43], v193, s60, v[164:165]
	v_lshl_add_u64 v[164:165], v[184:185], 1, v[164:165]
	global_store_dwordx4 v[164:165], v[160:163], off

; #define PG8_STAGE(bufoff, gbase, voff) do { _Pragma("unroll") for (int _i = 0; _i < 2; ++_i) \
;         __builtin_amdgcn_global_load_lds((const unsigned*)((const char*)(gbase) + (voff)[_i]), (LAS unsigned*)(lds + (bufoff) + ldsw + _i * 8192), 16, 0, 0); } while (0)
; #define PG8_LDA(dst, b, h) do { _Pragma("unroll") for (int m = 0; m < 4; ++m) _Pragma("unroll") for (int k = 0; k < 2; ++k) dst[m][k] = *(const LAS bf16x8*)(lds + PG8_SA(b, h) + aoff + m * 2048 + k * 1024); } while (0)
; #define PG8_LDB(dst, b, h) do { _Pragma("unroll") for (int n = 0; n < 2; ++n) _Pragma("unroll") for (int k = 0; k < 2; ++k) dst[n][k] = *(const LAS bf16x8*)(lds + PG8_SB(b, h) + boff + n * 2048 + k * 1024); } while (0)
; #define PG8_MMA(ai, bj, At, Bt) do { __builtin_amdgcn_s_setprio(1); _Pragma("unroll") for (int m = 0; m < 4; ++m) _Pragma("unroll") for (int n = 0; n < 2; ++n) _Pragma("unroll") for (int k = 0; k < 2; ++k) \
;         acc[ai][bj][m][n] = __builtin_amdgcn_mfma_f32_16x16x32_bf16(Bt[n][k], At[m][k], acc[ai][bj][m][n], 0, 0, 0); __builtin_amdgcn_s_setprio(0); } while (0)
; #define PG8_WAIT_V(n) asm volatile("s_waitcnt vmcnt(" #n ")" ::: "memory")
; #define PG8_WAIT_L(n) asm volatile("s_waitcnt lgkmcnt(" #n ")" ::: "memory")
; template <class Map, class Epi>
; DI void gemm_phase(LAS unsigned char* lds, const Map& MP, const Epi& E, const int nM, const int nN, const int K, const int lda, const int ldb) {
;     ...
;             const bool last = (t == nt - 2);
;             const char* a1 = cA + (size_t)(t + 1) * kstep;
;             const char* a2 = last ? nA : cA + (size_t)(t + 2) * kstep; const char* b2 = last ? nB : cB + (size_t)(t + 2) * kstep;
;             const char* a3 = a2 + kstep; const char* b3 = b2 + kstep;
;             PG8_LDB(B0, 0, 0); PG8_SCHED; PG8_LDA(At, 0, 0); PG8_STAGE(PG8_SA(1, 1), a1 + hstepA, voffA);
;             PG8_WAIT_L(8); PG8_BAR; PG8_WAIT_L(0); PG8_MMA(0, 0, At, B0); PG8_BAR; PG8_SCHED;
;             PG8_LDB(B1, 0, 1); PG8_STAGE(PG8_SB(0, 0), b2, voffB);
;             PG8_BAR; PG8_WAIT_L(0); PG8_MMA(0, 1, At, B1); PG8_BAR;
;             PG8_LDA(At, 0, 1); PG8_STAGE(PG8_SA(0, 0), a2, voffA);
;             PG8_BAR; PG8_WAIT_L(0); PG8_MMA(1, 0, At, B0); PG8_BAR; PG8_SCHED;
;             PG8_STAGE(PG8_SB(0, 1), b2 + hstepB, voffB);
;             PG8_WAIT_V(6); PG8_BAR; PG8_MMA(1, 1, At, B1); PG8_BAR;
.LBB1_2653:
	s_add_u32 s10, s8, 0x100
	s_addc_u32 s11, s9, 0
	s_cmpk_eq_i32 s48, 0x54
	s_cselect_b32 s15, s43, s11
	s_cselect_b32 s14, s42, s10
	s_cselect_b32 s13, s45, s39
	s_cselect_b32 s12, s44, s38
	s_add_i32 m0, s22, 0xc000
	ds_read_b128 v[168:171], v150
	ds_read_b128 v[172:175], v150 offset:1024
	ds_read_b128 v[176:179], v150 offset:2048
	ds_read_b128 v[180:183], v150 offset:3072
	ds_read_b128 v[184:187], v150 offset:4096
	ds_read_b128 v[188:191], v150 offset:5120
	ds_read_b128 v[192:195], v150 offset:6144
	ds_read_b128 v[196:199], v150 offset:7168
	global_load_lds_dwordx4 v138, s[8:9]
	s_add_i32 m0, s22, 0xe000
	s_nop 0
	global_load_lds_dwordx4 v136, s[8:9]
	s_waitcnt lgkmcnt(8)
	s_setprio 1
	s_barrier
	s_waitcnt lgkmcnt(7)
	v_mfma_f32_16x16x32_bf16 v[124:127], v[152:155], v[168:171], v[124:127]
	v_mfma_f32_16x16x32_bf16 v[120:123], v[160:163], v[168:171], v[120:123]
	s_waitcnt lgkmcnt(5)
	v_mfma_f32_16x16x32_bf16 v[108:111], v[152:155], v[176:179], v[108:111]
	v_mfma_f32_16x16x32_bf16 v[104:107], v[160:163], v[176:179], v[104:107]
	s_waitcnt lgkmcnt(3)
	v_mfma_f32_16x16x32_bf16 v[92:95], v[152:155], v[184:187], v[92:95]
	v_mfma_f32_16x16x32_bf16 v[88:91], v[160:163], v[184:187], v[88:91]
	s_waitcnt lgkmcnt(1)
	v_mfma_f32_16x16x32_bf16 v[76:79], v[152:155], v[192:195], v[76:79]
	v_mfma_f32_16x16x32_bf16 v[72:75], v[160:163], v[192:195], v[72:75]
	v_mfma_f32_16x16x32_bf16 v[124:127], v[156:159], v[172:175], v[124:127]
	s_add_i32 s8, s33, s20
	v_mfma_f32_16x16x32_bf16 v[120:123], v[164:167], v[172:175], v[120:123]
	v_lshl_add_u64 v[144:145], s[12:13], 0, v[132:133]
	v_mfma_f32_16x16x32_bf16 v[108:111], v[156:159], v[180:183], v[108:111]
	v_lshl_add_u64 v[216:217], s[12:13], 0, v[128:129]
	v_mfma_f32_16x16x32_bf16 v[104:107], v[164:167], v[180:183], v[104:107]
	v_mfma_f32_16x16x32_bf16 v[92:95], v[156:159], v[188:191], v[92:95]
	v_mfma_f32_16x16x32_bf16 v[88:91], v[164:167], v[188:191], v[88:91]
	s_waitcnt lgkmcnt(0)
	v_mfma_f32_16x16x32_bf16 v[76:79], v[156:159], v[196:199], v[76:79]
	v_mfma_f32_16x16x32_bf16 v[72:75], v[164:167], v[196:199], v[72:75]
	s_barrier
	s_setprio 0
	s_mov_b32 m0, s8
	ds_read_b128 v[200:203], v151
	ds_read_b128 v[204:207], v151 offset:1024
	ds_read_b128 v[208:211], v151 offset:2048
	ds_read_b128 v[212:215], v151 offset:3072
	global_load_lds_dwordx4 v[144:145], off
	s_add_i32 m0, s8, 0x2000
	s_nop 0
	global_load_lds_dwordx4 v[216:217], off
	s_setprio 1
	s_barrier
	s_waitcnt lgkmcnt(3)
	v_mfma_f32_16x16x32_bf16 v[116:119], v[200:203], v[168:171], v[116:119]
	s_waitcnt lgkmcnt(1)
	v_mfma_f32_16x16x32_bf16 v[112:115], v[208:211], v[168:171], v[112:115]
	v_mfma_f32_16x16x32_bf16 v[100:103], v[200:203], v[176:179], v[100:103]
	v_mfma_f32_16x16x32_bf16 v[96:99], v[208:211], v[176:179], v[96:99]
	v_mfma_f32_16x16x32_bf16 v[84:87], v[200:203], v[184:187], v[84:87]
	v_mfma_f32_16x16x32_bf16 v[80:83], v[208:211], v[184:187], v[80:83]
	v_mfma_f32_16x16x32_bf16 v[68:71], v[200:203], v[192:195], v[68:71]
	v_mfma_f32_16x16x32_bf16 v[64:67], v[208:211], v[192:195], v[64:67]
	v_mfma_f32_16x16x32_bf16 v[116:119], v[204:207], v[172:175], v[116:119]
	v_lshl_add_u64 v[220:221], s[14:15], 0, v[130:131]
	s_mov_b32 m0, s22
	s_waitcnt lgkmcnt(0)
	v_mfma_f32_16x16x32_bf16 v[112:115], v[212:215], v[172:175], v[112:115]
	v_lshl_add_u64 v[218:219], s[14:15], 0, v[134:135]
	v_mfma_f32_16x16x32_bf16 v[100:103], v[204:207], v[180:183], v[100:103]
	v_mfma_f32_16x16x32_bf16 v[96:99], v[212:215], v[180:183], v[96:99]
	v_mfma_f32_16x16x32_bf16 v[84:87], v[204:207], v[188:191], v[84:87]
	v_mfma_f32_16x16x32_bf16 v[80:83], v[212:215], v[188:191], v[80:83]
	v_mfma_f32_16x16x32_bf16 v[68:71], v[204:207], v[196:199], v[68:71]
	v_mfma_f32_16x16x32_bf16 v[64:67], v[212:215], v[196:199], v[64:67]
	s_barrier
	s_setprio 0
	ds_read_b128 v[168:171], v150 offset:16384
	ds_read_b128 v[172:175], v150 offset:17408
	ds_read_b128 v[176:179], v150 offset:18432
	ds_read_b128 v[180:183], v150 offset:19456
	ds_read_b128 v[184:187], v150 offset:20480
	ds_read_b128 v[188:191], v150 offset:21504
	ds_read_b128 v[192:195], v150 offset:22528
	ds_read_b128 v[196:199], v150 offset:23552
	global_load_lds_dwordx4 v[218:219], off
	s_mov_b32 m0, s23
	s_nop 0
	global_load_lds_dwordx4 v[220:221], off
	s_waitcnt vmcnt(10)
	s_setprio 1
	s_barrier
	s_waitcnt lgkmcnt(7)
	v_mfma_f32_16x16x32_bf16 v[60:63], v[152:155], v[168:171], v[60:63]
	v_mfma_f32_16x16x32_bf16 v[56:59], v[160:163], v[168:171], v[56:59]
	s_waitcnt lgkmcnt(5)
	v_mfma_f32_16x16x32_bf16 v[44:47], v[152:155], v[176:179], v[44:47]
	v_mfma_f32_16x16x32_bf16 v[40:43], v[160:163], v[176:179], v[40:43]
	s_waitcnt lgkmcnt(3)
	v_mfma_f32_16x16x32_bf16 v[28:31], v[152:155], v[184:187], v[28:31]
	v_mfma_f32_16x16x32_bf16 v[24:27], v[160:163], v[184:187], v[24:27]
	s_waitcnt lgkmcnt(1)
	v_mfma_f32_16x16x32_bf16 v[12:15], v[152:155], v[192:195], v[12:15]
	v_mfma_f32_16x16x32_bf16 v[8:11], v[160:163], v[192:195], v[8:11]
	v_mfma_f32_16x16x32_bf16 v[60:63], v[156:159], v[172:175], v[60:63]
	s_add_u32 s8, s12, 0x160000
	s_addc_u32 s9, s13, 0
	v_mfma_f32_16x16x32_bf16 v[56:59], v[164:167], v[172:175], v[56:59]
	s_add_i32 s49, s34, s20
	v_mfma_f32_16x16x32_bf16 v[44:47], v[156:159], v[180:183], v[44:47]
	v_mfma_f32_16x16x32_bf16 v[40:43], v[164:167], v[180:183], v[40:43]
	v_mfma_f32_16x16x32_bf16 v[28:31], v[156:159], v[188:191], v[28:31]
	v_mfma_f32_16x16x32_bf16 v[24:27], v[164:167], v[188:191], v[24:27]
	s_waitcnt lgkmcnt(0)
	v_mfma_f32_16x16x32_bf16 v[12:15], v[156:159], v[196:199], v[12:15]
	v_mfma_f32_16x16x32_bf16 v[8:11], v[164:167], v[196:199], v[8:11]
	s_barrier
; #define PG8_STAGE(bufoff, gbase, voff) do { _Pragma("unroll") for (int _i = 0; _i < 2; ++_i) \
;         __builtin_amdgcn_global_load_lds((const unsigned*)((const char*)(gbase) + (voff)[_i]), (LAS unsigned*)(lds + (bufoff) + ldsw + _i * 8192), 16, 0, 0); } while (0)
; #define PG8_LDA(dst, b, h) do { _Pragma("unroll") for (int m = 0; m < 4; ++m) _Pragma("unroll") for (int k = 0; k < 2; ++k) dst[m][k] = *(const LAS bf16x8*)(lds + PG8_SA(b, h) + aoff + m * 2048 + k * 1024); } while (0)
; #define PG8_LDB(dst, b, h) do { _Pragma("unroll") for (int n = 0; n < 2; ++n) _Pragma("unroll") for (int k = 0; k < 2; ++k) dst[n][k] = *(const LAS bf16x8*)(lds + PG8_SB(b, h) + boff + n * 2048 + k * 1024); } while (0)
; #define PG8_MMA(ai, bj, At, Bt) do { __builtin_amdgcn_s_setprio(1); _Pragma("unroll") for (int m = 0; m < 4; ++m) _Pragma("unroll") for (int n = 0; n < 2; ++n) _Pragma("unroll") for (int k = 0; k < 2; ++k) \
;         acc[ai][bj][m][n] = __builtin_amdgcn_mfma_f32_16x16x32_bf16(Bt[n][k], At[m][k], acc[ai][bj][m][n], 0, 0, 0); __builtin_amdgcn_s_setprio(0); } while (0)
; #define PG8_WAIT_V(n) asm volatile("s_waitcnt vmcnt(" #n ")" ::: "memory")
; #define PG8_WAIT_L(n) asm volatile("s_waitcnt lgkmcnt(" #n ")" ::: "memory")
; #define PG8_BAR __builtin_amdgcn_s_barrier()
; #define PG8_SCHED __builtin_amdgcn_sched_barrier(0)
; template <class Map, class Epi>
; DI void gemm_phase(LAS unsigned char* lds, const Map& MP, const Epi& E, const int nM, const int nN, const int K, const int lda, const int ldb) {
;     ...
;             PG8_WAIT_V(6); PG8_BAR; PG8_MMA(1, 1, At, B1); PG8_BAR;
;             PG8_LDB(B0, 1, 0); PG8_SCHED; PG8_LDA(At, 1, 0); PG8_STAGE(PG8_SA(0, 1), a2 + hstepA, voffA);
;             PG8_WAIT_L(8); PG8_BAR; PG8_WAIT_L(0); PG8_MMA(0, 0, At, B0); PG8_BAR; PG8_SCHED;
;             PG8_LDB(B1, 1, 1); PG8_STAGE(PG8_SB(1, 0), b3, voffB);
;             PG8_BAR; PG8_WAIT_L(0); PG8_MMA(0, 1, At, B1); PG8_BAR;
;             PG8_LDA(At, 1, 1); PG8_STAGE(PG8_SA(1, 0), a3, voffA);
;             PG8_BAR; PG8_WAIT_L(0); PG8_MMA(1, 0, At, B0); PG8_BAR; PG8_SCHED;
	s_setprio 0
	s_mov_b32 m0, s49
	s_nop 0
	global_load_lds_dwordx4 v132, s[8:9]
	s_add_i32 m0, s49, 0x2000
	s_nop 0
	global_load_lds_dwordx4 v128, s[8:9]
	s_waitcnt vmcnt(6)
	s_setprio 1
	s_barrier
	v_mfma_f32_16x16x32_bf16 v[52:55], v[200:203], v[168:171], v[52:55]
	v_mfma_f32_16x16x32_bf16 v[48:51], v[208:211], v[168:171], v[48:51]
	s_add_i32 s49, 0, 0x18000
	v_add_u32_e32 v164, s49, v148
	ds_read_b128 v[152:155], v164
	v_mfma_f32_16x16x32_bf16 v[36:39], v[200:203], v[176:179], v[36:39]
	v_mfma_f32_16x16x32_bf16 v[32:35], v[208:211], v[176:179], v[32:35]
	ds_read_b128 v[156:159], v164 offset:1024
	v_mfma_f32_16x16x32_bf16 v[20:23], v[200:203], v[184:187], v[20:23]
	v_mfma_f32_16x16x32_bf16 v[16:19], v[208:211], v[184:187], v[16:19]
	ds_read_b128 v[160:163], v164 offset:2048
	v_mfma_f32_16x16x32_bf16 v[4:7], v[200:203], v[192:195], v[4:7]
	v_mfma_f32_16x16x32_bf16 v[0:3], v[208:211], v[192:195], v[0:3]
	ds_read_b128 v[164:167], v164 offset:3072
	v_mfma_f32_16x16x32_bf16 v[52:55], v[204:207], v[172:175], v[52:55]
	s_add_u32 s8, s14, 0x160000
	s_addc_u32 s9, s15, 0
	v_mfma_f32_16x16x32_bf16 v[48:51], v[212:215], v[172:175], v[48:51]
	v_mfma_f32_16x16x32_bf16 v[36:39], v[204:207], v[180:183], v[36:39]
	v_mfma_f32_16x16x32_bf16 v[32:35], v[212:215], v[180:183], v[32:35]
	v_mfma_f32_16x16x32_bf16 v[20:23], v[204:207], v[188:191], v[20:23]
	v_mfma_f32_16x16x32_bf16 v[16:19], v[212:215], v[188:191], v[16:19]
	v_mfma_f32_16x16x32_bf16 v[4:7], v[204:207], v[196:199], v[4:7]
	v_mfma_f32_16x16x32_bf16 v[0:3], v[212:215], v[196:199], v[0:3]
	s_barrier
	s_setprio 0
	s_mov_b32 m0, s24
	ds_read_b128 v[168:171], v150 offset:32768
	ds_read_b128 v[172:175], v150 offset:33792
	ds_read_b128 v[176:179], v150 offset:34816
	ds_read_b128 v[180:183], v150 offset:35840
	ds_read_b128 v[184:187], v150 offset:36864
	ds_read_b128 v[188:191], v150 offset:37888
	ds_read_b128 v[192:195], v150 offset:38912
	ds_read_b128 v[196:199], v150 offset:39936
	global_load_lds_dwordx4 v134, s[8:9]
	s_mov_b32 m0, s25
	s_nop 0
	global_load_lds_dwordx4 v130, s[8:9]
	s_waitcnt lgkmcnt(8)
	s_setprio 1
	s_barrier
	s_waitcnt lgkmcnt(7)
	v_mfma_f32_16x16x32_bf16 v[124:127], v[152:155], v[168:171], v[124:127]
	v_mfma_f32_16x16x32_bf16 v[120:123], v[160:163], v[168:171], v[120:123]
	s_waitcnt lgkmcnt(5)
	v_mfma_f32_16x16x32_bf16 v[108:111], v[152:155], v[176:179], v[108:111]
	v_mfma_f32_16x16x32_bf16 v[104:107], v[160:163], v[176:179], v[104:107]
	s_waitcnt lgkmcnt(3)
	v_mfma_f32_16x16x32_bf16 v[92:95], v[152:155], v[184:187], v[92:95]
	v_mfma_f32_16x16x32_bf16 v[88:91], v[160:163], v[184:187], v[88:91]
	s_waitcnt lgkmcnt(1)
	v_mfma_f32_16x16x32_bf16 v[76:79], v[152:155], v[192:195], v[76:79]
	v_mfma_f32_16x16x32_bf16 v[72:75], v[160:163], v[192:195], v[72:75]
	v_mfma_f32_16x16x32_bf16 v[124:127], v[156:159], v[172:175], v[124:127]
	s_add_i32 s14, 0, 0x1c000
	v_mfma_f32_16x16x32_bf16 v[120:123], v[164:167], v[172:175], v[120:123]
	s_add_i32 s8, s49, s20
	v_mfma_f32_16x16x32_bf16 v[108:111], v[156:159], v[180:183], v[108:111]
	v_add_u32_e32 v212, s14, v148
	v_mfma_f32_16x16x32_bf16 v[104:107], v[164:167], v[180:183], v[104:107]
	v_lshl_add_u64 v[144:145], v[144:145], 0, s[46:47]
	v_mfma_f32_16x16x32_bf16 v[92:95], v[156:159], v[188:191], v[92:95]
	v_mfma_f32_16x16x32_bf16 v[88:91], v[164:167], v[188:191], v[88:91]
	s_waitcnt lgkmcnt(0)
	v_mfma_f32_16x16x32_bf16 v[76:79], v[156:159], v[196:199], v[76:79]
	v_mfma_f32_16x16x32_bf16 v[72:75], v[164:167], v[196:199], v[72:75]
	s_barrier
	s_setprio 0
	s_mov_b32 m0, s8
	ds_read_b128 v[200:203], v212
	ds_read_b128 v[204:207], v212 offset:1024
	ds_read_b128 v[208:211], v212 offset:2048
	ds_read_b128 v[212:215], v212 offset:3072
	global_load_lds_dwordx4 v[144:145], off
	v_lshl_add_u64 v[144:145], v[216:217], 0, s[46:47]
	s_add_i32 m0, s8, 0x2000
	s_nop 0
	global_load_lds_dwordx4 v[144:145], off
	s_setprio 1
	s_barrier
	s_waitcnt lgkmcnt(3)
	v_mfma_f32_16x16x32_bf16 v[116:119], v[200:203], v[168:171], v[116:119]
	s_waitcnt lgkmcnt(1)
	v_mfma_f32_16x16x32_bf16 v[112:115], v[208:211], v[168:171], v[112:115]
	v_mfma_f32_16x16x32_bf16 v[100:103], v[200:203], v[176:179], v[100:103]
	v_mfma_f32_16x16x32_bf16 v[96:99], v[208:211], v[176:179], v[96:99]
	v_mfma_f32_16x16x32_bf16 v[84:87], v[200:203], v[184:187], v[84:87]
	v_mfma_f32_16x16x32_bf16 v[80:83], v[208:211], v[184:187], v[80:83]
	v_mfma_f32_16x16x32_bf16 v[68:71], v[200:203], v[192:195], v[68:71]
	v_mfma_f32_16x16x32_bf16 v[64:67], v[208:211], v[192:195], v[64:67]
	v_mfma_f32_16x16x32_bf16 v[116:119], v[204:207], v[172:175], v[116:119]
	s_mov_b32 m0, s29
	s_waitcnt lgkmcnt(0)
	v_mfma_f32_16x16x32_bf16 v[112:115], v[212:215], v[172:175], v[112:115]
	v_lshl_add_u64 v[144:145], v[218:219], 0, s[46:47]
	v_mfma_f32_16x16x32_bf16 v[100:103], v[204:207], v[180:183], v[100:103]
	v_mfma_f32_16x16x32_bf16 v[96:99], v[212:215], v[180:183], v[96:99]
	v_mfma_f32_16x16x32_bf16 v[84:87], v[204:207], v[188:191], v[84:87]
	v_mfma_f32_16x16x32_bf16 v[80:83], v[212:215], v[188:191], v[80:83]
	v_mfma_f32_16x16x32_bf16 v[68:71], v[204:207], v[196:199], v[68:71]
	v_mfma_f32_16x16x32_bf16 v[64:67], v[212:215], v[196:199], v[64:67]
	s_barrier
	s_setprio 0
	ds_read_b128 v[168:171], v150 offset:49152
	ds_read_b128 v[172:175], v150 offset:50176
	ds_read_b128 v[176:179], v150 offset:51200
	ds_read_b128 v[180:183], v150 offset:52224
	ds_read_b128 v[184:187], v150 offset:53248
	ds_read_b128 v[188:191], v150 offset:54272
	ds_read_b128 v[192:195], v150 offset:55296
	ds_read_b128 v[196:199], v150 offset:56320
	global_load_lds_dwordx4 v[144:145], off
	v_lshl_add_u64 v[144:145], v[220:221], 0, s[46:47]
	s_mov_b32 m0, s30
	s_nop 0
	global_load_lds_dwordx4 v[144:145], off
	s_waitcnt vmcnt(10)
	s_setprio 1
	s_barrier
; DI unsigned pack2(float a, float b) { f32x2 v = {a, b}; hwbf16x2 r = __builtin_convertvector(v, hwbf16x2); return __builtin_bit_cast(unsigned, r); }
; DI float bflo(unsigned w) { return __uint_as_float(w << 16); }
; DI float bfhi(unsigned w) { return __uint_as_float(w & 0xffff0000u); }
; #define PG8_WAIT_V(n) asm volatile("s_waitcnt vmcnt(" #n ")" ::: "memory")
;     DI void operator()(const f32x4 (&acc)[2][2][4][2], const Unit& u, int wr, int wc, int fr, int fq) const {
;         const int row0 = u.pm * BM + wr * 64 + fr, col0 = u.pn * BM + wc * 32 + 8 * fq;
;         f32x4 sc[2][2];
; #pragma unroll
;         for (int bj = 0; bj < 2; ++bj)
; #pragma unroll
;             for (int n = 0; n < 2; ++n) sc[bj][n] = scale ? *(const f32x4*)(scale + col0 + bj * HALF + 4 * n) : (f32x4){1.f, 1.f, 1.f, 1.f};
; #pragma unroll
;         for (int ai = 0; ai < 2; ++ai)
; #pragma unroll
;             for (int m = 0; m < 4; ++m) { const size_t ro = (size_t)(row0 + ai * HALF + m * 16) * D + col0;
; #pragma unroll
;                 for (int bj = 0; bj < 2; ++bj) {
;                     f32x4 x0, x1;
;                     if constexpr (IB) { const u32x4 w = *(const u32x4*)((const bf16_t*)Xin + ro + bj * HALF);
;                         x0 = (f32x4){bflo(w[0]), bfhi(w[0]), bflo(w[1]), bfhi(w[1])}; x1 = (f32x4){bflo(w[2]), bfhi(w[2]), bflo(w[3]), bfhi(w[3])}; }
;                     else { x0 = *(const f32x4*)((const float*)Xin + ro + bj * HALF); x1 = *(const f32x4*)((const float*)Xin + ro + bj * HALF + 4); }
;                     x0 += acc[ai][bj][m][0] * sc[bj][0]; x1 += acc[ai][bj][m][1] * sc[bj][1];
;                     if constexpr (OB) { u32x4 o; o[0] = pack2(x0[0], x0[1]); o[1] = pack2(x0[2], x0[3]); o[2] = pack2(x1[0], x1[1]); o[3] = pack2(x1[2], x1[3]);
;                         *(u32x4*)((bf16_t*)Xout + ro + bj * HALF) = o; }
;                     else { *(f32x4*)((float*)Xout + ro + bj * HALF) = x0; *(f32x4*)((float*)Xout + ro + bj * HALF + 4) = x1; } } }
; template <class Map, class Epi>
; DI void gemm_phase(LAS unsigned char* lds, const Map& MP, const Epi& E, const int nM, const int nN, const int K, const int lda, const int ldb) {
;     ...
;             PG8_BAR; PG8_WAIT_L(0); PG8_MMA(1, 0, At, B0); PG8_BAR; PG8_SCHED;
;             PG8_STAGE(PG8_SB(1, 1), b3 + hstepB, voffB);
;             PG8_WAIT_V(6); PG8_BAR; PG8_MMA(1, 1, At, B1); PG8_BAR;
	s_waitcnt lgkmcnt(7)
	v_mfma_f32_16x16x32_bf16 v[60:63], v[152:155], v[168:171], v[60:63]
	v_mfma_f32_16x16x32_bf16 v[56:59], v[160:163], v[168:171], v[56:59]
	s_waitcnt lgkmcnt(5)
	v_mfma_f32_16x16x32_bf16 v[44:47], v[152:155], v[176:179], v[44:47]
	v_mfma_f32_16x16x32_bf16 v[40:43], v[160:163], v[176:179], v[40:43]
	s_waitcnt lgkmcnt(3)
	v_mfma_f32_16x16x32_bf16 v[28:31], v[152:155], v[184:187], v[28:31]
	v_mfma_f32_16x16x32_bf16 v[24:27], v[160:163], v[184:187], v[24:27]
	s_waitcnt lgkmcnt(1)
	v_mfma_f32_16x16x32_bf16 v[12:15], v[152:155], v[192:195], v[12:15]
	v_mfma_f32_16x16x32_bf16 v[8:11], v[160:163], v[192:195], v[8:11]
	v_mfma_f32_16x16x32_bf16 v[60:63], v[156:159], v[172:175], v[60:63]
	s_add_u32 s8, s12, 0x160080
	s_addc_u32 s9, s13, 0
	v_mfma_f32_16x16x32_bf16 v[56:59], v[164:167], v[172:175], v[56:59]
	s_add_i32 s12, s14, s20
	v_mfma_f32_16x16x32_bf16 v[44:47], v[156:159], v[180:183], v[44:47]
	v_mfma_f32_16x16x32_bf16 v[40:43], v[164:167], v[180:183], v[40:43]
	v_mfma_f32_16x16x32_bf16 v[28:31], v[156:159], v[188:191], v[28:31]
	v_mfma_f32_16x16x32_bf16 v[24:27], v[164:167], v[188:191], v[24:27]
	s_waitcnt lgkmcnt(0)
	v_mfma_f32_16x16x32_bf16 v[12:15], v[156:159], v[196:199], v[12:15]
	v_mfma_f32_16x16x32_bf16 v[8:11], v[164:167], v[196:199], v[8:11]
	s_barrier
	s_setprio 0
	s_mov_b32 m0, s12
	s_nop 0
	global_load_lds_dwordx4 v132, s[8:9]
	s_add_i32 m0, s12, 0x2000
	s_nop 0
	global_load_lds_dwordx4 v128, s[8:9]
	s_waitcnt vmcnt(6)
	s_setprio 1
	s_barrier
	v_mfma_f32_16x16x32_bf16 v[52:55], v[200:203], v[168:171], v[52:55]
	v_mfma_f32_16x16x32_bf16 v[48:51], v[208:211], v[168:171], v[48:51]
	ds_read_b128 v[152:155], v149
	v_mfma_f32_16x16x32_bf16 v[36:39], v[200:203], v[176:179], v[36:39]
	v_mfma_f32_16x16x32_bf16 v[32:35], v[208:211], v[176:179], v[32:35]
	ds_read_b128 v[156:159], v149 offset:1024
	v_mfma_f32_16x16x32_bf16 v[20:23], v[200:203], v[184:187], v[20:23]
	v_mfma_f32_16x16x32_bf16 v[16:19], v[208:211], v[184:187], v[16:19]
	ds_read_b128 v[160:163], v149 offset:2048
	v_mfma_f32_16x16x32_bf16 v[4:7], v[200:203], v[192:195], v[4:7]
	v_mfma_f32_16x16x32_bf16 v[0:3], v[208:211], v[192:195], v[0:3]
	ds_read_b128 v[164:167], v149 offset:3072
	v_mfma_f32_16x16x32_bf16 v[52:55], v[204:207], v[172:175], v[52:55]
	s_add_i32 s48, s48, 2
	v_mfma_f32_16x16x32_bf16 v[48:51], v[212:215], v[172:175], v[48:51]
	s_add_u32 s38, s38, 0x100
	s_addc_u32 s39, s39, 0
	v_mfma_f32_16x16x32_bf16 v[36:39], v[204:207], v[180:183], v[36:39]
	s_cmpk_gt_u32 s48, 0x55
	v_mfma_f32_16x16x32_bf16 v[32:35], v[212:215], v[180:183], v[32:35]
	s_mov_b64 s[8:9], s[10:11]
	v_mfma_f32_16x16x32_bf16 v[20:23], v[204:207], v[188:191], v[20:23]
	v_mfma_f32_16x16x32_bf16 v[16:19], v[212:215], v[188:191], v[16:19]
	v_mfma_f32_16x16x32_bf16 v[4:7], v[204:207], v[196:199], v[4:7]
	v_mfma_f32_16x16x32_bf16 v[0:3], v[212:215], v[196:199], v[0:3]
	s_barrier
	s_setprio 0
	s_cbranch_scc0 .LBB1_2653
	s_waitcnt lgkmcnt(0)
	v_mov_b32_e32 v144, v147
	v_mov_b32_e32 v152, v146
	s_lshl_b32 s2, s2, 8
	s_lshl_b32 s8, s37, 8
	s_add_i32 s2, s2, s27
	s_or_b32 s8, s8, s28
	v_add_u32_e32 v152, s2, v152
	v_lshl_add_u32 v144, v144, 3, s8
	v_ashrrev_i32_e32 v153, 31, v152
	v_ashrrev_i32_e32 v145, 31, v144
	v_lshlrev_b64 v[152:153], 11, v[152:153]
	v_lshl_add_u64 v[144:145], v[152:153], 0, v[144:145]
	v_lshl_add_u64 v[156:157], v[144:145], 1, s[6:7]
	global_load_dwordx4 v[162:165], v[156:157], off
	global_load_dwordx4 v[166:169], v[156:157], off offset:256
	s_mov_b64 s[98:99], 0x10000
	v_lshl_add_u64 v[154:155], v[156:157], 0, s[98:99]
	global_load_dwordx4 v[170:173], v[154:155], off
	global_load_dwordx4 v[174:177], v[154:155], off offset:256
	s_mov_b64 s[98:99], 0x20000
	v_lshl_add_u64 v[154:155], v[156:157], 0, s[98:99]
	global_load_dwordx4 v[178:181], v[154:155], off
	global_load_dwordx4 v[182:185], v[154:155], off offset:256
	s_mov_b64 s[98:99], 0x30000
	v_lshl_add_u64 v[154:155], v[156:157], 0, s[98:99]
	global_load_dwordx4 v[186:189], v[154:155], off
	global_load_dwordx4 v[190:193], v[154:155], off offset:256
	s_mov_b64 s[98:99], 0x80000
	v_lshl_add_u64 v[154:155], v[156:157], 0, s[98:99]
	global_load_dwordx4 v[194:197], v[154:155], off
	global_load_dwordx4 v[198:201], v[154:155], off offset:256
	s_mov_b64 s[98:99], 0x90000
	v_lshl_add_u64 v[154:155], v[156:157], 0, s[98:99]
	global_load_dwordx4 v[202:205], v[154:155], off
	global_load_dwordx4 v[206:209], v[154:155], off offset:256
	s_mov_b64 s[98:99], 0xa0000
	v_lshl_add_u64 v[154:155], v[156:157], 0, s[98:99]
	global_load_dwordx4 v[210:213], v[154:155], off
	global_load_dwordx4 v[248:251], v[154:155], off offset:256
	s_mov_b64 s[98:99], 0xb0000
	v_lshl_add_u64 v[154:155], v[156:157], 0, s[98:99]
	global_load_dwordx4 v[252:255], v[154:155], off
	s_waitcnt vmcnt(14)
	s_nop 1
	v_mov_b32_e32 v152, v162
	v_mov_b32_e32 v153, v163
	v_mov_b32_e32 v154, v164
	v_mov_b32_e32 v155, v165
	s_mov_b64 s[8:9], 0x8000
	s_and_b64 vcc, exec, s[40:41]
	s_mov_b32 s37, s35
	s_mov_b32 s2, s36
	s_mov_b64 s[10:11], s[44:45]
	s_waitcnt lgkmcnt(0)
	v_lshlrev_b32_e32 v158, 16, v152
	v_and_b32_e32 v159, 0xffff0000, v152
	v_lshlrev_b32_e32 v152, 16, v153
	v_and_b32_e32 v153, 0xffff0000, v153
	v_lshlrev_b32_e32 v160, 16, v154
	v_and_b32_e32 v161, 0xffff0000, v154
	v_lshlrev_b32_e32 v154, 16, v155
	v_and_b32_e32 v155, 0xffff0000, v155
	v_pk_add_f32 v[126:127], v[126:127], v[152:153]
	v_pk_add_f32 v[124:125], v[124:125], v[158:159]
	v_lshl_add_u64 v[152:153], v[144:145], 2, s[4:5]
	v_pk_add_f32 v[122:123], v[122:123], v[154:155]
	v_pk_add_f32 v[120:121], v[120:121], v[160:161]
	global_store_dwordx4 v[152:153], v[124:127], off
	global_store_dwordx4 v[152:153], v[120:123], off offset:16
	s_waitcnt vmcnt(15)
; DI unsigned pack2(float a, float b) { f32x2 v = {a, b}; hwbf16x2 r = __builtin_convertvector(v, hwbf16x2); return __builtin_bit_cast(unsigned, r); }
; DI float bflo(unsigned w) { return __uint_as_float(w << 16); }
; DI float bfhi(unsigned w) { return __uint_as_float(w & 0xffff0000u); }
;     DI void operator()(const f32x4 (&acc)[2][2][4][2], const Unit& u, int wr, int wc, int fr, int fq) const {
;     ...
;         for (int ai = 0; ai < 2; ++ai)
; #pragma unroll
;             for (int m = 0; m < 4; ++m) { const size_t ro = (size_t)(row0 + ai * HALF + m * 16) * D + col0;
; #pragma unroll
;                 for (int bj = 0; bj < 2; ++bj) {
;                     f32x4 x0, x1;
;                     if constexpr (IB) { const u32x4 w = *(const u32x4*)((const bf16_t*)Xin + ro + bj * HALF);
;                         x0 = (f32x4){bflo(w[0]), bfhi(w[0]), bflo(w[1]), bfhi(w[1])}; x1 = (f32x4){bflo(w[2]), bfhi(w[2]), bflo(w[3]), bfhi(w[3])}; }
;                     else { x0 = *(const f32x4*)((const float*)Xin + ro + bj * HALF); x1 = *(const f32x4*)((const float*)Xin + ro + bj * HALF + 4); }
;                     x0 += acc[ai][bj][m][0] * sc[bj][0]; x1 += acc[ai][bj][m][1] * sc[bj][1];
;                     if constexpr (OB) { u32x4 o; o[0] = pack2(x0[0], x0[1]); o[1] = pack2(x0[2], x0[3]); o[2] = pack2(x1[0], x1[1]); o[3] = pack2(x1[2], x1[3]);
;                         *(u32x4*)((bf16_t*)Xout + ro + bj * HALF) = o; }
;                     else { *(f32x4*)((float*)Xout + ro + bj * HALF) = x0; *(f32x4*)((float*)Xout + ro + bj * HALF + 4) = x1; } } }
	s_nop 1
	v_mov_b32_e32 v120, v166
	v_mov_b32_e32 v121, v167
	v_mov_b32_e32 v122, v168
	v_mov_b32_e32 v123, v169
	s_waitcnt lgkmcnt(0)
	v_lshlrev_b32_e32 v124, 16, v120
	v_and_b32_e32 v125, 0xffff0000, v120
	v_lshlrev_b32_e32 v120, 16, v121
	v_and_b32_e32 v121, 0xffff0000, v121
	v_lshlrev_b32_e32 v126, 16, v122
	v_and_b32_e32 v127, 0xffff0000, v122
	v_lshlrev_b32_e32 v122, 16, v123
	v_and_b32_e32 v123, 0xffff0000, v123
	v_pk_add_f32 v[118:119], v[118:119], v[120:121]
	v_pk_add_f32 v[116:117], v[116:117], v[124:125]
	v_pk_add_f32 v[114:115], v[114:115], v[122:123]
	v_pk_add_f32 v[112:113], v[112:113], v[126:127]
	global_store_dwordx4 v[152:153], v[116:119], off offset:512
	global_store_dwordx4 v[152:153], v[112:115], off offset:528
	s_nop 0
	v_lshl_add_u64 v[116:117], v[144:145], 0, s[8:9]
	v_lshl_add_u64 v[118:119], v[116:117], 1, s[6:7]
	s_waitcnt vmcnt(16)
	s_nop 1
	v_mov_b32_e32 v112, v170
	v_mov_b32_e32 v113, v171
	v_mov_b32_e32 v114, v172
	v_mov_b32_e32 v115, v173
	s_mov_b64 s[8:9], 0x10000
	s_waitcnt lgkmcnt(0)
	v_lshlrev_b32_e32 v120, 16, v112
	v_and_b32_e32 v121, 0xffff0000, v112
	v_lshlrev_b32_e32 v112, 16, v113
	v_and_b32_e32 v113, 0xffff0000, v113
	v_lshlrev_b32_e32 v122, 16, v114
	v_and_b32_e32 v123, 0xffff0000, v114
	v_lshlrev_b32_e32 v114, 16, v115
	v_and_b32_e32 v115, 0xffff0000, v115
	v_pk_add_f32 v[110:111], v[110:111], v[112:113]
	v_pk_add_f32 v[108:109], v[108:109], v[120:121]
	v_lshl_add_u64 v[112:113], v[116:117], 2, s[4:5]
	v_pk_add_f32 v[106:107], v[106:107], v[114:115]
	v_pk_add_f32 v[104:105], v[104:105], v[122:123]
	global_store_dwordx4 v[112:113], v[108:111], off
	global_store_dwordx4 v[112:113], v[104:107], off offset:16
	s_waitcnt vmcnt(17)
	s_nop 1
	v_mov_b32_e32 v104, v174
	v_mov_b32_e32 v105, v175
	v_mov_b32_e32 v106, v176
	v_mov_b32_e32 v107, v177
	s_waitcnt lgkmcnt(0)
	v_lshlrev_b32_e32 v108, 16, v104
	v_and_b32_e32 v109, 0xffff0000, v104
	v_lshlrev_b32_e32 v104, 16, v105
	v_and_b32_e32 v105, 0xffff0000, v105
	v_lshlrev_b32_e32 v110, 16, v106
	v_and_b32_e32 v111, 0xffff0000, v106
	v_lshlrev_b32_e32 v106, 16, v107
	v_and_b32_e32 v107, 0xffff0000, v107
	v_pk_add_f32 v[102:103], v[102:103], v[104:105]
	v_pk_add_f32 v[100:101], v[100:101], v[108:109]
	v_pk_add_f32 v[98:99], v[98:99], v[106:107]
	v_pk_add_f32 v[96:97], v[96:97], v[110:111]
	global_store_dwordx4 v[112:113], v[100:103], off offset:512
	global_store_dwordx4 v[112:113], v[96:99], off offset:528
	s_nop 0
	v_lshl_add_u64 v[100:101], v[144:145], 0, s[8:9]
	v_lshl_add_u64 v[102:103], v[100:101], 1, s[6:7]
	s_waitcnt vmcnt(18)
	s_nop 1
	v_mov_b32_e32 v96, v178
	v_mov_b32_e32 v97, v179
	v_mov_b32_e32 v98, v180
	v_mov_b32_e32 v99, v181
	s_mov_b64 s[8:9], 0x18000
	s_waitcnt lgkmcnt(0)
	v_lshlrev_b32_e32 v104, 16, v96
	v_and_b32_e32 v105, 0xffff0000, v96
	v_lshlrev_b32_e32 v96, 16, v97
	v_and_b32_e32 v97, 0xffff0000, v97
	v_lshlrev_b32_e32 v106, 16, v98
	v_and_b32_e32 v107, 0xffff0000, v98
	v_lshlrev_b32_e32 v98, 16, v99
	v_and_b32_e32 v99, 0xffff0000, v99
	v_pk_add_f32 v[94:95], v[94:95], v[96:97]
	v_pk_add_f32 v[92:93], v[92:93], v[104:105]
	v_lshl_add_u64 v[96:97], v[100:101], 2, s[4:5]
	v_pk_add_f32 v[90:91], v[90:91], v[98:99]
	v_pk_add_f32 v[88:89], v[88:89], v[106:107]
	global_store_dwordx4 v[96:97], v[92:95], off
	global_store_dwordx4 v[96:97], v[88:91], off offset:16
	s_waitcnt vmcnt(19)
	s_nop 1
	v_mov_b32_e32 v88, v182
	v_mov_b32_e32 v89, v183
	v_mov_b32_e32 v90, v184
	v_mov_b32_e32 v91, v185
	s_waitcnt lgkmcnt(0)
	v_lshlrev_b32_e32 v92, 16, v88
	v_and_b32_e32 v93, 0xffff0000, v88
	v_lshlrev_b32_e32 v88, 16, v89
	v_and_b32_e32 v89, 0xffff0000, v89
	v_lshlrev_b32_e32 v94, 16, v90
	v_and_b32_e32 v95, 0xffff0000, v90
	v_lshlrev_b32_e32 v90, 16, v91
	v_and_b32_e32 v91, 0xffff0000, v91
	v_pk_add_f32 v[86:87], v[86:87], v[88:89]
	v_pk_add_f32 v[84:85], v[84:85], v[92:93]
	v_pk_add_f32 v[82:83], v[82:83], v[90:91]
	v_pk_add_f32 v[80:81], v[80:81], v[94:95]
	global_store_dwordx4 v[96:97], v[84:87], off offset:512
	global_store_dwordx4 v[96:97], v[80:83], off offset:528
	s_nop 0
	v_lshl_add_u64 v[84:85], v[144:145], 0, s[8:9]
	v_lshl_add_u64 v[86:87], v[84:85], 1, s[6:7]
	s_waitcnt vmcnt(20)
	s_nop 1
	v_mov_b32_e32 v80, v186
	v_mov_b32_e32 v81, v187
	v_mov_b32_e32 v82, v188
	v_mov_b32_e32 v83, v189
	s_mov_b64 s[8:9], 0x40000
	s_waitcnt lgkmcnt(0)
	v_lshlrev_b32_e32 v88, 16, v80
	v_and_b32_e32 v89, 0xffff0000, v80
	v_lshlrev_b32_e32 v80, 16, v81
	v_and_b32_e32 v81, 0xffff0000, v81
	v_lshlrev_b32_e32 v90, 16, v82
	v_and_b32_e32 v91, 0xffff0000, v82
	v_lshlrev_b32_e32 v82, 16, v83
	v_and_b32_e32 v83, 0xffff0000, v83
	v_pk_add_f32 v[78:79], v[78:79], v[80:81]
	v_pk_add_f32 v[76:77], v[76:77], v[88:89]
	v_lshl_add_u64 v[80:81], v[84:85], 2, s[4:5]
	v_pk_add_f32 v[74:75], v[74:75], v[82:83]
	v_pk_add_f32 v[72:73], v[72:73], v[90:91]
	global_store_dwordx4 v[80:81], v[76:79], off
	global_store_dwordx4 v[80:81], v[72:75], off offset:16
	s_waitcnt vmcnt(21)
	s_nop 1
	v_mov_b32_e32 v72, v190
	v_mov_b32_e32 v73, v191
	v_mov_b32_e32 v74, v192
	v_mov_b32_e32 v75, v193
	s_waitcnt lgkmcnt(0)
	v_lshlrev_b32_e32 v76, 16, v72
	v_and_b32_e32 v77, 0xffff0000, v72
	v_lshlrev_b32_e32 v72, 16, v73
	v_and_b32_e32 v73, 0xffff0000, v73
	v_lshlrev_b32_e32 v78, 16, v74
	v_and_b32_e32 v79, 0xffff0000, v74
	v_lshlrev_b32_e32 v74, 16, v75
	v_and_b32_e32 v75, 0xffff0000, v75
	v_pk_add_f32 v[70:71], v[70:71], v[72:73]
	v_pk_add_f32 v[68:69], v[68:69], v[76:77]
	v_pk_add_f32 v[66:67], v[66:67], v[74:75]
	v_pk_add_f32 v[64:65], v[64:65], v[78:79]
	global_store_dwordx4 v[80:81], v[68:71], off offset:512
	global_store_dwordx4 v[80:81], v[64:67], off offset:528
	s_nop 0
	v_lshl_add_u64 v[68:69], v[144:145], 0, s[8:9]
	v_lshl_add_u64 v[70:71], v[68:69], 1, s[6:7]
	s_waitcnt vmcnt(22)
; DI unsigned pack2(float a, float b) { f32x2 v = {a, b}; hwbf16x2 r = __builtin_convertvector(v, hwbf16x2); return __builtin_bit_cast(unsigned, r); }
; DI float bflo(unsigned w) { return __uint_as_float(w << 16); }
; DI float bfhi(unsigned w) { return __uint_as_float(w & 0xffff0000u); }
;     DI const char* a(const Unit& u) const { return (const char*)(A + (size_t)u.pm * BM * lda); }
;     DI const char* a(const Unit& u) const { return (const char*)(A + (size_t)u.pm * BM * 2048 + (u.pn >> 1) * 512); }
;     DI void operator()(const f32x4 (&acc)[2][2][4][2], const Unit& u, int wr, int wc, int fr, int fq) const {
;     ...
;         for (int ai = 0; ai < 2; ++ai)
; #pragma unroll
;             for (int m = 0; m < 4; ++m) { const size_t ro = (size_t)(row0 + ai * HALF + m * 16) * D + col0;
; #pragma unroll
;                 for (int bj = 0; bj < 2; ++bj) {
;                     f32x4 x0, x1;
;                     if constexpr (IB) { const u32x4 w = *(const u32x4*)((const bf16_t*)Xin + ro + bj * HALF);
;                         x0 = (f32x4){bflo(w[0]), bfhi(w[0]), bflo(w[1]), bfhi(w[1])}; x1 = (f32x4){bflo(w[2]), bfhi(w[2]), bflo(w[3]), bfhi(w[3])}; }
;                     else { x0 = *(const f32x4*)((const float*)Xin + ro + bj * HALF); x1 = *(const f32x4*)((const float*)Xin + ro + bj * HALF + 4); }
;                     x0 += acc[ai][bj][m][0] * sc[bj][0]; x1 += acc[ai][bj][m][1] * sc[bj][1];
;                     if constexpr (OB) { u32x4 o; o[0] = pack2(x0[0], x0[1]); o[1] = pack2(x0[2], x0[3]); o[2] = pack2(x1[0], x1[1]); o[3] = pack2(x1[2], x1[3]);
;                         *(u32x4*)((bf16_t*)Xout + ro + bj * HALF) = o; }
;                     else { *(f32x4*)((float*)Xout + ro + bj * HALF) = x0; *(f32x4*)((float*)Xout + ro + bj * HALF + 4) = x1; } } }
; template <class Map, class Epi>
; DI void gemm_phase(LAS unsigned char* lds, const Map& MP, const Epi& E, const int nM, const int nN, const int K, const int lda, const int ldb) {
;     ...
;         if (!has_next) break;
; #pragma unroll
;         for (int a = 0; a < 2; ++a)
; #pragma unroll
;             for (int b = 0; b < 2; ++b)
; #pragma unroll
;                 for (int m = 0; m < 4; ++m)
; #pragma unroll
;                     for (int n = 0; n < 2; ++n) acc[a][b][m][n] = (f32x4){0.f, 0.f, 0.f, 0.f};
;         cur = nxt; cA = nA; cB = nB; ++ui;
;     }
;     PG8_WAIT_V(0);
;     if (wr == 0) PG8_BAR;
;     PG8_BAR;
	s_nop 1
	v_mov_b32_e32 v64, v194
	v_mov_b32_e32 v65, v195
	v_mov_b32_e32 v66, v196
	v_mov_b32_e32 v67, v197
	s_mov_b64 s[8:9], 0x48000
	s_waitcnt lgkmcnt(0)
	v_lshlrev_b32_e32 v72, 16, v64
	v_and_b32_e32 v73, 0xffff0000, v64
	v_lshlrev_b32_e32 v64, 16, v65
	v_and_b32_e32 v65, 0xffff0000, v65
	v_lshlrev_b32_e32 v74, 16, v66
	v_and_b32_e32 v75, 0xffff0000, v66
	v_lshlrev_b32_e32 v66, 16, v67
	v_and_b32_e32 v67, 0xffff0000, v67
	v_pk_add_f32 v[62:63], v[62:63], v[64:65]
	v_pk_add_f32 v[60:61], v[60:61], v[72:73]
	v_lshl_add_u64 v[64:65], v[68:69], 2, s[4:5]
	v_pk_add_f32 v[58:59], v[58:59], v[66:67]
	v_pk_add_f32 v[56:57], v[56:57], v[74:75]
	global_store_dwordx4 v[64:65], v[60:63], off
	global_store_dwordx4 v[64:65], v[56:59], off offset:16
	s_waitcnt vmcnt(23)
	s_nop 1
	v_mov_b32_e32 v56, v198
	v_mov_b32_e32 v57, v199
	v_mov_b32_e32 v58, v200
	v_mov_b32_e32 v59, v201
	s_waitcnt lgkmcnt(0)
	v_lshlrev_b32_e32 v60, 16, v56
	v_and_b32_e32 v61, 0xffff0000, v56
	v_lshlrev_b32_e32 v56, 16, v57
	v_and_b32_e32 v57, 0xffff0000, v57
	v_lshlrev_b32_e32 v62, 16, v58
	v_and_b32_e32 v63, 0xffff0000, v58
	v_lshlrev_b32_e32 v58, 16, v59
	v_and_b32_e32 v59, 0xffff0000, v59
	v_pk_add_f32 v[54:55], v[54:55], v[56:57]
	v_pk_add_f32 v[52:53], v[52:53], v[60:61]
	v_pk_add_f32 v[50:51], v[50:51], v[58:59]
	v_pk_add_f32 v[48:49], v[48:49], v[62:63]
	global_store_dwordx4 v[64:65], v[52:55], off offset:512
	global_store_dwordx4 v[64:65], v[48:51], off offset:528
	s_nop 0
	v_lshl_add_u64 v[52:53], v[144:145], 0, s[8:9]
	v_lshl_add_u64 v[54:55], v[52:53], 1, s[6:7]
	s_waitcnt vmcnt(24)
	s_nop 1
	v_mov_b32_e32 v48, v202
	v_mov_b32_e32 v49, v203
	v_mov_b32_e32 v50, v204
	v_mov_b32_e32 v51, v205
	s_mov_b64 s[8:9], 0x50000
	s_waitcnt lgkmcnt(0)
	v_lshlrev_b32_e32 v56, 16, v48
	v_and_b32_e32 v57, 0xffff0000, v48
	v_lshlrev_b32_e32 v48, 16, v49
	v_and_b32_e32 v49, 0xffff0000, v49
	v_lshlrev_b32_e32 v58, 16, v50
	v_and_b32_e32 v59, 0xffff0000, v50
	v_lshlrev_b32_e32 v50, 16, v51
	v_and_b32_e32 v51, 0xffff0000, v51
	v_pk_add_f32 v[46:47], v[46:47], v[48:49]
	v_pk_add_f32 v[44:45], v[44:45], v[56:57]
	v_lshl_add_u64 v[48:49], v[52:53], 2, s[4:5]
	v_pk_add_f32 v[42:43], v[42:43], v[50:51]
	v_pk_add_f32 v[40:41], v[40:41], v[58:59]
	global_store_dwordx4 v[48:49], v[44:47], off
	global_store_dwordx4 v[48:49], v[40:43], off offset:16
	s_waitcnt vmcnt(25)
	s_nop 1
	v_mov_b32_e32 v40, v206
	v_mov_b32_e32 v41, v207
	v_mov_b32_e32 v42, v208
	v_mov_b32_e32 v43, v209
	s_waitcnt lgkmcnt(0)
	v_lshlrev_b32_e32 v44, 16, v40
	v_and_b32_e32 v45, 0xffff0000, v40
	v_lshlrev_b32_e32 v40, 16, v41
	v_and_b32_e32 v41, 0xffff0000, v41
	v_lshlrev_b32_e32 v46, 16, v42
	v_and_b32_e32 v47, 0xffff0000, v42
	v_lshlrev_b32_e32 v42, 16, v43
	v_and_b32_e32 v43, 0xffff0000, v43
	v_pk_add_f32 v[38:39], v[38:39], v[40:41]
	v_pk_add_f32 v[36:37], v[36:37], v[44:45]
	v_pk_add_f32 v[34:35], v[34:35], v[42:43]
	v_pk_add_f32 v[32:33], v[32:33], v[46:47]
	global_store_dwordx4 v[48:49], v[36:39], off offset:512
	global_store_dwordx4 v[48:49], v[32:35], off offset:528
	s_nop 0
	v_lshl_add_u64 v[36:37], v[144:145], 0, s[8:9]
	v_lshl_add_u64 v[38:39], v[36:37], 1, s[6:7]
	s_waitcnt vmcnt(26)
	s_nop 1
	v_mov_b32_e32 v32, v210
	v_mov_b32_e32 v33, v211
	v_mov_b32_e32 v34, v212
	v_mov_b32_e32 v35, v213
	s_mov_b64 s[8:9], 0x58000
	s_waitcnt lgkmcnt(0)
	v_lshlrev_b32_e32 v40, 16, v32
	v_and_b32_e32 v41, 0xffff0000, v32
	v_lshlrev_b32_e32 v32, 16, v33
	v_and_b32_e32 v33, 0xffff0000, v33
	v_lshlrev_b32_e32 v42, 16, v34
	v_and_b32_e32 v43, 0xffff0000, v34
	v_lshlrev_b32_e32 v34, 16, v35
	v_and_b32_e32 v35, 0xffff0000, v35
	v_pk_add_f32 v[30:31], v[30:31], v[32:33]
	v_pk_add_f32 v[28:29], v[28:29], v[40:41]
	v_lshl_add_u64 v[32:33], v[36:37], 2, s[4:5]
	v_pk_add_f32 v[26:27], v[26:27], v[34:35]
	v_pk_add_f32 v[24:25], v[24:25], v[42:43]
	global_store_dwordx4 v[32:33], v[28:31], off
	global_store_dwordx4 v[32:33], v[24:27], off offset:16
	s_waitcnt vmcnt(27)
	s_nop 1
	v_mov_b32_e32 v24, v248
	v_mov_b32_e32 v25, v249
	v_mov_b32_e32 v26, v250
	v_mov_b32_e32 v27, v251
	s_waitcnt lgkmcnt(0)
	v_lshlrev_b32_e32 v28, 16, v24
	v_and_b32_e32 v29, 0xffff0000, v24
	v_lshlrev_b32_e32 v24, 16, v25
	v_and_b32_e32 v25, 0xffff0000, v25
	v_lshlrev_b32_e32 v30, 16, v26
	v_and_b32_e32 v31, 0xffff0000, v26
	v_lshlrev_b32_e32 v26, 16, v27
	v_and_b32_e32 v27, 0xffff0000, v27
	v_pk_add_f32 v[22:23], v[22:23], v[24:25]
	v_pk_add_f32 v[20:21], v[20:21], v[28:29]
	v_pk_add_f32 v[18:19], v[18:19], v[26:27]
	v_pk_add_f32 v[16:17], v[16:17], v[30:31]
	global_store_dwordx4 v[32:33], v[20:23], off offset:512
	global_store_dwordx4 v[32:33], v[16:19], off offset:528
	s_nop 0
	v_lshl_add_u64 v[20:21], v[144:145], 0, s[8:9]
	v_lshl_add_u64 v[22:23], v[20:21], 1, s[6:7]
	s_waitcnt vmcnt(28)
	s_nop 1
	v_mov_b32_e32 v16, v252
	v_mov_b32_e32 v17, v253
	v_mov_b32_e32 v18, v254
	v_mov_b32_e32 v19, v255
	s_mov_b64 s[8:9], s[42:43]
	s_waitcnt lgkmcnt(0)
	v_lshlrev_b32_e32 v24, 16, v16
	v_and_b32_e32 v25, 0xffff0000, v16
	v_lshlrev_b32_e32 v16, 16, v17
	v_and_b32_e32 v17, 0xffff0000, v17
	v_lshlrev_b32_e32 v26, 16, v18
	v_and_b32_e32 v27, 0xffff0000, v18
	v_lshlrev_b32_e32 v18, 16, v19
	v_and_b32_e32 v19, 0xffff0000, v19
	v_pk_add_f32 v[14:15], v[14:15], v[16:17]
	v_pk_add_f32 v[12:13], v[12:13], v[24:25]
	v_lshl_add_u64 v[16:17], v[20:21], 2, s[4:5]
	v_pk_add_f32 v[10:11], v[10:11], v[18:19]
	v_pk_add_f32 v[8:9], v[8:9], v[26:27]
	global_store_dwordx4 v[16:17], v[12:15], off
	global_store_dwordx4 v[16:17], v[8:11], off offset:16
	global_load_dwordx4 v[8:11], v[22:23], off offset:256
	s_waitcnt vmcnt(0) lgkmcnt(0)
	v_lshlrev_b32_e32 v12, 16, v8
	v_and_b32_e32 v13, 0xffff0000, v8
	v_lshlrev_b32_e32 v8, 16, v9
	v_and_b32_e32 v9, 0xffff0000, v9
	v_lshlrev_b32_e32 v14, 16, v10
	v_and_b32_e32 v15, 0xffff0000, v10
	v_lshlrev_b32_e32 v10, 16, v11
	v_and_b32_e32 v11, 0xffff0000, v11
	v_pk_add_f32 v[6:7], v[6:7], v[8:9]
	v_pk_add_f32 v[4:5], v[4:5], v[12:13]
	v_pk_add_f32 v[2:3], v[2:3], v[10:11]
	v_pk_add_f32 v[0:1], v[0:1], v[14:15]
	global_store_dwordx4 v[16:17], v[4:7], off offset:512
	global_store_dwordx4 v[16:17], v[0:3], off offset:528
	s_cbranch_vccz .LBB1_2646
	s_waitcnt vmcnt(0)
	s_cmpk_gt_u32 s3, 0xff
	s_cbranch_scc1 .LBB1_2657
	s_barrier
